# attention phase: one static s_setprio 1 for waves 4-7 (younger half), per-cluster priority flips neutralised to s_nop 0
# baseline (speedup 1.0000x reference)
; #define LAS __attribute__((address_space(3)))
; #define UNIT_LOOP(BODY) _Pragma("unroll 1") for (int k = 0; k * G < 512; ++k) { const int j = k * G + ((k & 1) ? (G - 1 - cblk) : cblk); if (j >= 512) continue; __syncthreads(); \
;     int tid_ = wave_s * 64 + fresh_lane(); const int tid = tid_, lane = tid & 63, wave = wave_s; (void)tid; \
;     const int bh = j & 31, qb = 15 - (j >> 5), b = bh >> 2, hd = bh & 3; (void)qb; (void)b; (void)hd; BODY; }
; DI void nsa_unit(const Params& P, int l, LAS char* lds, int b, int qt, int tid, int wave, int lane) {
;     ...
;     { const float f = g_w / lsum;
; #pragma unroll
;       for (int i = 0; i < 16; ++i) { otot[0][i] = stash[i * 64] + f * o[0][i]; otot[1][i] = stash[(16 + i) * 64] + f * o[1][i]; } }
;     store_o((bf16_t*)(P.ws + WS_O) + ((size_t)3 * TOK + (size_t)b * SEQ + qpos) * 256 + 64 * hd, otot, h);
; }
; DI void attn_phase(const Params& P, int l, LAS char* lds, int G, int cblk, const int wave_s) {
;     if (PH_MASK & 16u) { UNIT_LOOP(nsa_unit(P, l, lds, j & 7, 63 - (j >> 3), tid, wave, lane)) }
.LBB0_492:
	s_lshl_b32 s22, s74, 6
	v_readlane_b32 s48, v255, 2
	s_lshl_b64 s[0:1], s[22:23], 2
	v_readlane_b32 s50, v255, 4
	v_readlane_b32 s60, v255, 14
	v_readlane_b32 s49, v255, 3
	v_readlane_b32 s51, v255, 5
	v_readlane_b32 s52, v255, 6
	v_readlane_b32 s53, v255, 7
	v_readlane_b32 s54, v255, 8
	v_readlane_b32 s55, v255, 9
	v_readlane_b32 s56, v255, 10
	v_readlane_b32 s57, v255, 11
	v_readlane_b32 s58, v255, 12
	v_readlane_b32 s59, v255, 13
	v_readlane_b32 s61, v255, 15
	v_readlane_b32 s62, v255, 16
	v_readlane_b32 s63, v255, 17
	s_add_u32 s50, s60, s0
	v_writelane_b32 v255, s0, 23
	s_addc_u32 s51, s61, s1
	s_mov_b32 s22, 0
	v_writelane_b32 v255, s1, 24
	s_mov_b32 s0, 0
	s_waitcnt lgkmcnt(0)
	s_barrier
	s_bitcmp1_b32 s33, 8
	s_cbranch_scc0 .Lattn_prio_done
	s_setprio 1
.Lattn_prio_done:
	s_branch .LBB0_495
.LBB0_493:
	v_lshlrev_b32_e32 v32, 16, v163
	v_mul_f32_e32 v32, 0xbfb8aa3b, v32
	v_exp_f32_e32 v32, v32
	v_add_u32_e32 v168, 0x18000, v161
	v_add_f32_e32 v32, 1.0, v32
	v_rcp_f32_e32 v32, v32
	s_nop 0
	v_div_scale_f32 v33, s[0:1], v184, v184, v32
	v_rcp_f32_e32 v34, v33
	v_readlane_b32 s0, v254, 15
	v_readlane_b32 s1, v254, 16
	v_fma_f32 v35, -v33, v34, 1.0
	v_fmac_f32_e32 v34, v35, v34
	v_div_scale_f32 v35, vcc, v32, v184, v32
	v_mul_f32_e32 v36, v35, v34
	v_fma_f32 v37, -v33, v36, v35
	v_fmac_f32_e32 v36, v37, v34
	v_fma_f32 v33, -v33, v36, v35
	v_div_fmas_f32 v33, v33, v34, v36
	ds_read2st64_b32 v[34:35], v188 offset1:1
	ds_read2st64_b32 v[36:37], v188 offset0:16 offset1:17
	v_div_fixup_f32 v32, v33, v184, v32
	s_waitcnt lgkmcnt(1)
	v_pk_fma_f32 v[34:35], v[32:33], v[0:1], v[34:35] op_sel_hi:[0,1,1]
	s_waitcnt lgkmcnt(0)
	v_pk_fma_f32 v[0:1], v[32:33], v[16:17], v[36:37] op_sel_hi:[0,1,1]
	ds_read2st64_b32 v[16:17], v188 offset0:2 offset1:3
	ds_read2st64_b32 v[36:37], v188 offset0:18 offset1:19
	v_cvt_pk_bf16_f32 v0, v0, v1
	s_waitcnt lgkmcnt(1)
	v_pk_fma_f32 v[16:17], v[32:33], v[2:3], v[16:17] op_sel_hi:[0,1,1]
	s_waitcnt lgkmcnt(0)
	v_pk_fma_f32 v[2:3], v[32:33], v[18:19], v[36:37] op_sel_hi:[0,1,1]
	ds_read2st64_b32 v[18:19], v188 offset0:4 offset1:5
	ds_read2st64_b32 v[36:37], v188 offset0:20 offset1:21
	v_cvt_pk_bf16_f32 v1, v2, v3
	s_waitcnt lgkmcnt(1)
	v_pk_fma_f32 v[18:19], v[32:33], v[4:5], v[18:19] op_sel_hi:[0,1,1]
	s_waitcnt lgkmcnt(0)
	v_pk_fma_f32 v[4:5], v[32:33], v[20:21], v[36:37] op_sel_hi:[0,1,1]
	ds_read2st64_b32 v[20:21], v188 offset0:6 offset1:7
	ds_read2st64_b32 v[36:37], v188 offset0:22 offset1:23
	s_waitcnt lgkmcnt(1)
	v_pk_fma_f32 v[6:7], v[32:33], v[6:7], v[20:21] op_sel_hi:[0,1,1]
	s_waitcnt lgkmcnt(0)
	v_pk_fma_f32 v[20:21], v[32:33], v[22:23], v[36:37] op_sel_hi:[0,1,1]
	ds_read2st64_b32 v[22:23], v188 offset0:8 offset1:9
	ds_read2st64_b32 v[36:37], v188 offset0:24 offset1:25
	s_waitcnt lgkmcnt(1)
	v_pk_fma_f32 v[8:9], v[32:33], v[8:9], v[22:23] op_sel_hi:[0,1,1]
	s_waitcnt lgkmcnt(0)
	v_pk_fma_f32 v[22:23], v[32:33], v[24:25], v[36:37] op_sel_hi:[0,1,1]
	ds_read2st64_b32 v[24:25], v188 offset0:10 offset1:11
	ds_read2st64_b32 v[36:37], v188 offset0:26 offset1:27
	s_waitcnt lgkmcnt(1)
	v_pk_fma_f32 v[10:11], v[32:33], v[10:11], v[24:25] op_sel_hi:[0,1,1]
	s_waitcnt lgkmcnt(0)
	v_pk_fma_f32 v[24:25], v[32:33], v[26:27], v[36:37] op_sel_hi:[0,1,1]
	ds_read2st64_b32 v[26:27], v188 offset0:12 offset1:13
	ds_read2st64_b32 v[36:37], v188 offset0:28 offset1:29
	s_waitcnt lgkmcnt(1)
	v_pk_fma_f32 v[12:13], v[32:33], v[12:13], v[26:27] op_sel_hi:[0,1,1]
	s_waitcnt lgkmcnt(0)
	v_pk_fma_f32 v[26:27], v[32:33], v[28:29], v[36:37] op_sel_hi:[0,1,1]
	ds_read2st64_b32 v[28:29], v188 offset0:14 offset1:15
	ds_read2st64_b32 v[36:37], v188 offset0:30 offset1:31
	s_waitcnt lgkmcnt(1)
	v_pk_fma_f32 v[14:15], v[32:33], v[14:15], v[28:29] op_sel_hi:[0,1,1]
	s_waitcnt lgkmcnt(0)
	v_pk_fma_f32 v[28:29], v[32:33], v[30:31], v[36:37] op_sel_hi:[0,1,1]
	v_lshlrev_b64 v[30:31], 9, v[168:169]
	v_lshl_add_u64 v[30:31], s[0:1], 0, v[30:31]
	v_lshlrev_b32_e32 v168, 1, v167
	v_lshl_add_u64 v[30:31], v[30:31], 0, v[168:169]
	global_store_dwordx2 v[30:31], v[0:1], off offset:64
	v_cvt_pk_bf16_f32 v0, v4, v5
	v_cvt_pk_bf16_f32 v1, v20, v21
	v_cvt_pk_bf16_f32 v33, v16, v17
	v_cvt_pk_bf16_f32 v17, v6, v7
	v_cvt_pk_bf16_f32 v6, v8, v9
	v_cvt_pk_bf16_f32 v7, v10, v11
	global_store_dwordx2 v[30:31], v[0:1], off offset:80
	v_cvt_pk_bf16_f32 v0, v22, v23
	v_cvt_pk_bf16_f32 v1, v24, v25
	v_cvt_pk_bf16_f32 v32, v34, v35
	v_cvt_pk_bf16_f32 v16, v18, v19
	global_store_dwordx2 v[30:31], v[6:7], off offset:32
	v_cvt_pk_bf16_f32 v6, v12, v13
	v_cvt_pk_bf16_f32 v7, v14, v15
	global_store_dwordx2 v[30:31], v[0:1], off offset:96
	v_cvt_pk_bf16_f32 v0, v26, v27
	v_cvt_pk_bf16_f32 v1, v28, v29
	global_store_dwordx2 v[30:31], v[32:33], off
	global_store_dwordx2 v[30:31], v[16:17], off offset:16
	global_store_dwordx2 v[30:31], v[6:7], off offset:48
	global_store_dwordx2 v[30:31], v[0:1], off offset:112

; DI float ex2(float x) { return __builtin_amdgcn_exp2f(x); }
; DI void nsa_unit(const Params& P, int l, LAS char* lds, int b, int qt, int tid, int wave, int lane) {
;     ...
;     for (int st = 0; st < nst; ++st) {
;         const f32x16 s = qk_rows<0, 4>(kcL, 32 * st, qf, r, h);
;         float t[16], mx = -1e30f;
; #pragma unroll
;         for (int i = 0; i < 16; ++i) { const int n = 32 * st + (i & 3) + 8 * (i >> 2) + 4 * h; const bool ok = (16 * n + 31 <= qpos); t[i] = ok ? s[i] * c : -1e30f; mx = fmaxf(mx, t[i]); }
;         mx = fmaxf(mx, shx32(mx, lane));
;         const float mn = fmaxf(m, mx), alpha = ex2(m - mn);
;         float rs = 0.f;
; #pragma unroll
;         for (int i = 0; i < 16; ++i) rs += (t[i] > -1e29f) ? ex2(t[i] - mn) : 0.f;
;         rs += shx32(rs, lane);
;         lsum = lsum * alpha + rs; m = mn;
;     }
.LBB0_513:
	v_mov_b32_e32 v30, v0
	ds_read_b128 v[0:3], v16
	ds_read_b128 v[18:21], v16 offset:32
	ds_read_b128 v[22:25], v16 offset:64
	ds_read_b128 v[26:29], v16 offset:96
	s_nop 0
	s_waitcnt lgkmcnt(3)
	v_mfma_f32_32x32x16_bf16 v[0:15], v[0:3], v[96:99], 0
	s_waitcnt lgkmcnt(2)
	v_mfma_f32_32x32x16_bf16 v[0:15], v[18:21], v[100:103], v[0:15]
	s_waitcnt lgkmcnt(1)
	v_mfma_f32_32x32x16_bf16 v[0:15], v[22:25], v[104:107], v[0:15]
	s_waitcnt lgkmcnt(0)
	v_mfma_f32_32x32x16_bf16 v[0:15], v[26:29], v[108:111], v[0:15]
	s_nop 0
	v_add_u32_e32 v18, 0xfffffe50, v17
	v_cmp_le_i32_e32 vcc, v18, v160
	v_add_u32_e32 v18, 0xfffffe60, v17
	v_add_u32_e32 v19, 0xfffffe70, v17
	s_nop 6
	v_cndmask_b32_e32 v0, v208, v0, vcc
	v_cmp_le_i32_e32 vcc, v18, v160
	s_add_i32 s1, s1, -1
	v_add_u32_e32 v16, 0x1200, v16
	v_cndmask_b32_e32 v1, v208, v1, vcc
	v_cmp_le_i32_e32 vcc, v19, v160
	v_add_u32_e32 v19, 0xfffffe80, v17
	v_max3_f32 v18, v0, s15, v1
	v_cndmask_b32_e32 v2, v208, v2, vcc
	v_cmp_le_i32_e32 vcc, v19, v160
	v_add_u32_e32 v19, 0xfffffed0, v17
	s_cmp_eq_u32 s1, 0
	v_cndmask_b32_e32 v3, v208, v3, vcc
	v_cmp_le_i32_e32 vcc, v19, v160
	v_add_u32_e32 v19, 0xfffffee0, v17
	v_max3_f32 v18, v18, v2, v3
	v_cndmask_b32_e32 v4, v208, v4, vcc
	v_cmp_le_i32_e32 vcc, v19, v160
	v_add_u32_e32 v19, 0xfffffef0, v17
	s_nop 0
	v_cndmask_b32_e32 v5, v208, v5, vcc
	v_cmp_le_i32_e32 vcc, v19, v160
	v_add_u32_e32 v19, 0xffffff00, v17
	v_max3_f32 v18, v18, v4, v5
	v_cndmask_b32_e32 v6, v208, v6, vcc
	v_cmp_le_i32_e32 vcc, v19, v160
	v_add_u32_e32 v19, 0xffffff50, v17
	s_nop 0
	v_cndmask_b32_e32 v7, v208, v7, vcc
	v_cmp_le_i32_e32 vcc, v19, v160
	v_add_u32_e32 v19, 0xffffff60, v17
	v_max3_f32 v18, v18, v6, v7
	v_cndmask_b32_e32 v8, v208, v8, vcc
	v_cmp_le_i32_e32 vcc, v19, v160
	v_add_u32_e32 v19, 0xffffff70, v17
	s_nop 0
	v_cndmask_b32_e32 v9, v208, v9, vcc
	v_cmp_le_i32_e32 vcc, v19, v160
	v_add_u32_e32 v19, 0xffffff80, v17
	v_max3_f32 v18, v18, v8, v9
	v_cndmask_b32_e32 v10, v208, v10, vcc
	v_cmp_le_i32_e32 vcc, v19, v160
	v_subrev_u32_e32 v19, 48, v17
	s_nop 0
	v_cndmask_b32_e32 v11, v208, v11, vcc
	v_cmp_le_i32_e32 vcc, v19, v160
	v_subrev_u32_e32 v19, 32, v17
	v_max3_f32 v18, v18, v10, v11
	v_cndmask_b32_e32 v12, v208, v12, vcc
	v_cmp_le_i32_e32 vcc, v19, v160
	v_add_u32_e32 v19, -16, v17
	s_nop 0
	v_cndmask_b32_e32 v13, v208, v13, vcc
	v_cmp_le_i32_e32 vcc, v19, v160
	v_max3_f32 v18, v18, v12, v13
	s_nop 0
	v_cndmask_b32_e32 v14, v208, v14, vcc
	v_cmp_le_i32_e32 vcc, v17, v160
	v_add_u32_e32 v17, 0x200, v17
	s_nop 0
	v_cndmask_b32_e32 v15, v208, v15, vcc
	v_max3_f32 v18, v18, v14, v15
	v_mov_b32_e32 v19, v18
	v_mov_b32_e32 v20, v18
	s_nop 1
	v_permlane32_swap_b32_e32 v19, v20
	v_cndmask_b32_e64 v19, v19, v20, s[36:37]
	v_mov_b32_e32 v20, v54
	v_max3_f32 v54, v20, v18, v19
	v_cmp_lt_f32_e32 vcc, s16, v0
	v_sub_f32_e32 v0, v0, v54
	v_exp_f32_e32 v0, v0
	v_sub_f32_e32 v18, v20, v54
	v_add_f32_e32 v0, 0, v0
	v_cndmask_b32_e32 v0, 0, v0, vcc
	v_cmp_lt_f32_e32 vcc, s16, v1
	v_sub_f32_e32 v1, v1, v54
	v_exp_f32_e32 v1, v1
	s_nop 0
	v_cndmask_b32_e32 v1, 0, v1, vcc
	v_add_f32_e32 v0, v1, v0
	v_sub_f32_e32 v1, v2, v54
	v_exp_f32_e32 v1, v1
	v_cmp_lt_f32_e32 vcc, s16, v2
	s_nop 1
	v_cndmask_b32_e32 v1, 0, v1, vcc
	v_add_f32_e32 v0, v1, v0
	v_sub_f32_e32 v1, v3, v54
	v_exp_f32_e32 v1, v1
	v_cmp_lt_f32_e32 vcc, s16, v3
	s_nop 1
	v_cndmask_b32_e32 v1, 0, v1, vcc
	v_add_f32_e32 v0, v1, v0
	v_sub_f32_e32 v1, v4, v54
	v_exp_f32_e32 v1, v1
	v_cmp_lt_f32_e32 vcc, s16, v4
	s_nop 1
	v_cndmask_b32_e32 v1, 0, v1, vcc
	v_add_f32_e32 v0, v1, v0
	v_sub_f32_e32 v1, v5, v54
	v_exp_f32_e32 v1, v1
	v_cmp_lt_f32_e32 vcc, s16, v5
	s_nop 1
	v_cndmask_b32_e32 v1, 0, v1, vcc
	v_add_f32_e32 v0, v1, v0
	v_sub_f32_e32 v1, v6, v54
	v_exp_f32_e32 v1, v1
	v_cmp_lt_f32_e32 vcc, s16, v6
	s_nop 1
	v_cndmask_b32_e32 v1, 0, v1, vcc
	v_add_f32_e32 v0, v1, v0
	v_sub_f32_e32 v1, v7, v54
	v_exp_f32_e32 v1, v1
	v_cmp_lt_f32_e32 vcc, s16, v7
	s_nop 1
	v_cndmask_b32_e32 v1, 0, v1, vcc
	v_add_f32_e32 v0, v1, v0
	v_sub_f32_e32 v1, v8, v54
	v_exp_f32_e32 v1, v1
	v_cmp_lt_f32_e32 vcc, s16, v8
	s_nop 1
	v_cndmask_b32_e32 v1, 0, v1, vcc
	v_add_f32_e32 v0, v1, v0
	v_sub_f32_e32 v1, v9, v54
	v_exp_f32_e32 v1, v1
	v_cmp_lt_f32_e32 vcc, s16, v9
	s_nop 1
	v_cndmask_b32_e32 v1, 0, v1, vcc
	v_add_f32_e32 v0, v1, v0
	v_sub_f32_e32 v1, v10, v54
	v_exp_f32_e32 v1, v1
	v_cmp_lt_f32_e32 vcc, s16, v10
	s_nop 1
	v_cndmask_b32_e32 v1, 0, v1, vcc
	v_add_f32_e32 v0, v1, v0
	v_sub_f32_e32 v1, v11, v54
	v_exp_f32_e32 v1, v1
	v_cmp_lt_f32_e32 vcc, s16, v11
	s_nop 1
	v_cndmask_b32_e32 v1, 0, v1, vcc
	v_add_f32_e32 v0, v1, v0
	v_sub_f32_e32 v1, v12, v54
	v_exp_f32_e32 v1, v1
	v_cmp_lt_f32_e32 vcc, s16, v12
	s_nop 1
	v_cndmask_b32_e32 v1, 0, v1, vcc
	v_add_f32_e32 v0, v1, v0
	v_sub_f32_e32 v1, v13, v54
	v_exp_f32_e32 v1, v1
	v_cmp_lt_f32_e32 vcc, s16, v13
	s_nop 1
	v_cndmask_b32_e32 v1, 0, v1, vcc
	v_add_f32_e32 v0, v1, v0
	v_sub_f32_e32 v1, v14, v54
	v_exp_f32_e32 v1, v1
	v_cmp_lt_f32_e32 vcc, s16, v14
	s_nop 1
	v_cndmask_b32_e32 v1, 0, v1, vcc
	v_add_f32_e32 v0, v1, v0
	v_sub_f32_e32 v1, v15, v54
	v_exp_f32_e32 v1, v1
	v_cmp_lt_f32_e32 vcc, s16, v15
	s_nop 1
	v_cndmask_b32_e32 v1, 0, v1, vcc
	v_add_f32_e32 v0, v1, v0
	v_exp_f32_e32 v1, v18
	v_mov_b32_e32 v2, v0
	v_mov_b32_e32 v3, v0
	s_nop 1
	v_permlane32_swap_b32_e32 v2, v3
	v_add_f32_e32 v0, v2, v3
	v_fmac_f32_e32 v0, v30, v1
	s_cbranch_scc0 .LBB0_513
	v_div_scale_f32 v1, s[10:11], v0, v0, 1.0
	v_rcp_f32_e32 v2, v1
	v_bfe_u32 v50, v86, 2, 2
	s_movk_i32 s1, 0x240
	v_lshlrev_b32_e32 v167, 2, v120
	v_fma_f32 v3, -v1, v2, 1.0
	v_fmac_f32_e32 v2, v3, v2
	v_div_scale_f32 v3, vcc, 1.0, v0, 1.0
	v_mul_f32_e32 v4, v3, v2
	v_fma_f32 v5, -v1, v4, v3
	v_fmac_f32_e32 v4, v5, v2
	v_fma_f32 v1, -v1, v4, v3
	v_div_fmas_f32 v1, v1, v2, v4
	v_div_fixup_f32 v1, v1, v0, 1.0
	v_cmp_lt_f32_e32 vcc, 0, v0
	v_lshlrev_b32_e32 v0, 1, v88
	v_and_b32_e32 v171, 32, v0
	v_lshlrev_b32_e32 v0, 3, v88
	v_and_b32_e32 v186, 24, v0
	v_mul_u32_u24_e32 v0, 0x90, v50
	v_mad_u32_u24 v0, v120, s1, v0
	v_readlane_b32 s1, v254, 51
	v_mov_b32_e32 v58, 0
	v_cndmask_b32_e32 v48, 0, v1, vcc
	v_add3_u32 v55, v0, v171, v186
	v_add_u32_e32 v0, s1, v64
	v_mov_b32_e32 v51, v160
	v_mov_b32_e32 v49, v48
	v_lshl_or_b32 v57, v0, 8, v167
	v_mov_b32_e32 v0, 0
	v_mov_b32_e32 v1, v58
	v_mov_b32_e32 v2, v58
	v_mov_b32_e32 v3, v58
	v_mov_b32_e32 v4, v58
	v_mov_b32_e32 v5, v58
	v_mov_b32_e32 v6, v58
	v_mov_b32_e32 v7, v58
	v_mov_b32_e32 v8, v58
	v_mov_b32_e32 v9, v58
	v_mov_b32_e32 v10, v58
	v_mov_b32_e32 v11, v58
	v_mov_b32_e32 v12, v58
	v_mov_b32_e32 v13, v58
	v_mov_b32_e32 v14, v58
	v_mov_b32_e32 v15, v58
	v_mov_b32_e32 v16, 0
	v_mov_b32_e32 v17, v58
	v_mov_b32_e32 v18, v58
	v_mov_b32_e32 v19, v58
	v_mov_b32_e32 v20, v58
	v_mov_b32_e32 v21, v58
	v_mov_b32_e32 v22, v58
	v_mov_b32_e32 v23, v58
	v_mov_b32_e32 v24, v58
	v_mov_b32_e32 v25, v58
	v_mov_b32_e32 v26, v58
	v_mov_b32_e32 v27, v58
	v_mov_b32_e32 v28, v58
	v_mov_b32_e32 v29, v58
	v_mov_b32_e32 v30, v58
	v_mov_b32_e32 v31, v58
; DI float ex2(float x) { return __builtin_amdgcn_exp2f(x); }
; DI void nsa_unit(const Params& P, int l, LAS char* lds, int b, int qt, int tid, int wave, int lane) {
;     ...
;     for (int st = 0; st < nst; ++st) {
;         const f32x16 s = qk_rows<0, 4>(kcL, 32 * st, qf, r, h);
;         float p[16];
; #pragma unroll
;         for (int i = 0; i < 16; ++i) { const int n = 32 * st + (i & 3) + 8 * (i >> 2) + 4 * h; const bool ok = (16 * n + 31 <= qpos); p[i] = ok ? ex2(s[i] * c - m) * linv : 0.f; }
;         float pc[4];
; #pragma unroll
;         for (int g = 0; g < 4; ++g) pc[g] = shx32(p[4 * g + 3], lane);
; #pragma unroll
;         for (int g = 0; g < 4; ++g) {
;             const float a = 2.0f * ((p[4 * g] + p[4 * g + 1]) + p[4 * g + 2]) + p[4 * g + 3];
;             const float pred = (h == 1) ? pc[g] : (g > 0 ? pc[g > 0 ? g - 1 : 0] : prevpc3);
;             impH[(hd * 64 + 32 * qh + r) * 64 + 8 * st + 2 * g + h] = a + pred;
;         }
;         prevpc3 = pc[3];
;         bf16x8 pf[2]; pack_p(p, pf);
;         pv_rows(o, vcL, 32 * st, pf, lane);
;     }
.LBB0_515:
	v_add_u32_e32 v36, 0, v52
	ds_read_b128 v[32:35], v36
	ds_read_b128 v[60:63], v36 offset:32
	ds_read_b128 v[66:69], v36 offset:64
	ds_read_b128 v[70:73], v36 offset:96
	s_nop 0
	s_waitcnt lgkmcnt(3)
	v_mfma_f32_32x32x16_bf16 v[32:47], v[32:35], v[96:99], 0
	s_waitcnt lgkmcnt(2)
	v_mfma_f32_32x32x16_bf16 v[32:47], v[60:63], v[100:103], v[32:47]
	s_waitcnt lgkmcnt(1)
	v_mfma_f32_32x32x16_bf16 v[32:47], v[66:69], v[104:107], v[32:47]
	s_waitcnt lgkmcnt(0)
	v_mfma_f32_32x32x16_bf16 v[32:47], v[70:73], v[108:111], v[32:47]
	s_nop 0
	s_nop 10
	v_sub_f32_e32 v32, v32, v54
	v_sub_f32_e32 v33, v33, v54
	v_exp_f32_e32 v32, v32
	v_exp_f32_e32 v33, v33
	v_or_b32_e32 v59, 47, v53
	v_cmp_le_i32_e32 vcc, v59, v51
	v_or_b32_e32 v60, 31, v53
	v_pk_mul_f32 v[32:33], v[48:49], v[32:33]
	s_nop 0
	v_cndmask_b32_e32 v59, 0, v33, vcc
	v_sub_f32_e32 v33, v34, v54
	v_exp_f32_e32 v33, v33
	v_cmp_le_i32_e32 vcc, v60, v160
	v_mul_f32_e32 v33, v48, v33
	s_nop 0
	v_cndmask_b32_e32 v60, 0, v32, vcc
	v_add_u32_e32 v32, 63, v53
	v_cmp_le_i32_e32 vcc, v32, v160
	v_add_u32_e32 v32, 0x4f, v53
	v_add_f32_e32 v66, v60, v59
	v_cndmask_b32_e32 v34, 0, v33, vcc
	v_sub_f32_e32 v33, v35, v54
	v_exp_f32_e32 v33, v33
	v_cmp_le_i32_e32 vcc, v32, v160
	v_sub_f32_e32 v32, v36, v54
	v_exp_f32_e32 v32, v32
	v_mul_f32_e32 v33, v48, v33
	v_cndmask_b32_e32 v35, 0, v33, vcc
	v_sub_f32_e32 v33, v37, v54
	v_exp_f32_e32 v33, v33
	v_or_b32_e32 v36, 0xaf, v53
	v_cmp_le_i32_e32 vcc, v36, v51
	v_or_b32_e32 v37, 0x9f, v53
	v_pk_mul_f32 v[32:33], v[48:49], v[32:33]
	v_add_f32_e32 v66, v34, v66
	v_cndmask_b32_e32 v36, 0, v33, vcc
	v_sub_f32_e32 v33, v38, v54
	v_exp_f32_e32 v33, v33
	v_cmp_le_i32_e32 vcc, v37, v160
	v_fma_f32 v66, 2.0, v66, v35
	v_mul_f32_e32 v33, v48, v33
	v_cndmask_b32_e32 v37, 0, v32, vcc
	v_add_u32_e32 v32, 0xbf, v53
	v_cmp_le_i32_e32 vcc, v32, v160
	v_add_u32_e32 v32, 0xcf, v53
	s_nop 0
	v_cndmask_b32_e32 v38, 0, v33, vcc
	v_sub_f32_e32 v33, v39, v54
	v_exp_f32_e32 v33, v33
	v_cmp_le_i32_e32 vcc, v32, v160
	v_sub_f32_e32 v32, v40, v54
	v_exp_f32_e32 v32, v32
	v_mul_f32_e32 v33, v48, v33
	v_cndmask_b32_e32 v39, 0, v33, vcc
	v_sub_f32_e32 v33, v41, v54
	v_exp_f32_e32 v33, v33
	v_or_b32_e32 v40, 0x12f, v53
	v_cmp_le_i32_e32 vcc, v40, v51
	v_or_b32_e32 v41, 0x11f, v53
	v_pk_mul_f32 v[32:33], v[48:49], v[32:33]
	v_mov_b32_e32 v61, v39
	v_cndmask_b32_e32 v40, 0, v33, vcc
	v_sub_f32_e32 v33, v42, v54
	v_exp_f32_e32 v33, v33
	v_cmp_le_i32_e32 vcc, v41, v160
	v_mul_f32_e32 v33, v48, v33
	s_nop 0
	v_cndmask_b32_e32 v41, 0, v32, vcc
	v_add_u32_e32 v32, 0x13f, v53
	v_cmp_le_i32_e32 vcc, v32, v160
	v_add_u32_e32 v32, 0x14f, v53
	s_nop 0
	v_cndmask_b32_e32 v42, 0, v33, vcc
	v_sub_f32_e32 v33, v43, v54
	v_exp_f32_e32 v33, v33
	v_cmp_le_i32_e32 vcc, v32, v160
	v_sub_f32_e32 v32, v44, v54
	v_exp_f32_e32 v32, v32
	v_mul_f32_e32 v33, v48, v33
	v_cndmask_b32_e32 v43, 0, v33, vcc
	v_sub_f32_e32 v33, v45, v54
	v_exp_f32_e32 v33, v33
	v_or_b32_e32 v44, 0x1af, v53
	v_cmp_le_i32_e32 vcc, v44, v51
	v_or_b32_e32 v45, 0x19f, v53
	v_pk_mul_f32 v[32:33], v[48:49], v[32:33]
	v_mov_b32_e32 v62, v43
	v_cndmask_b32_e32 v44, 0, v33, vcc
	v_sub_f32_e32 v33, v46, v54
	v_exp_f32_e32 v33, v33
	v_cmp_le_i32_e32 vcc, v45, v160
	v_mul_f32_e32 v33, v48, v33
	s_nop 0
	v_cndmask_b32_e32 v45, 0, v32, vcc
	v_add_u32_e32 v32, 0x1bf, v53
	v_cmp_le_i32_e32 vcc, v32, v160
	v_add_u32_e32 v32, 0x1cf, v53
	s_nop 0
	v_cndmask_b32_e32 v46, 0, v33, vcc
	v_sub_f32_e32 v33, v47, v54
	v_exp_f32_e32 v33, v33
	v_cmp_le_i32_e32 vcc, v32, v160
	v_mov_b32_e32 v32, v35
	v_mul_f32_e32 v33, v48, v33
	v_cndmask_b32_e32 v47, 0, v33, vcc
	v_mov_b32_e32 v33, v35
	s_nop 1
	v_permlane32_swap_b32_e32 v32, v33
	v_cndmask_b32_e64 v32, v32, v33, s[36:37]
	v_mov_b32_e32 v33, v39
	s_nop 1
	v_permlane32_swap_b32_e32 v33, v61
	v_cndmask_b32_e64 v33, v33, v61, s[36:37]
	v_mov_b32_e32 v61, v43
	s_nop 1
	v_permlane32_swap_b32_e32 v61, v62
	v_cndmask_b32_e64 v61, v61, v62, s[36:37]
	v_mov_b32_e32 v62, v47
	v_mov_b32_e32 v63, v47
	s_nop 1
	v_permlane32_swap_b32_e32 v62, v63
	v_cndmask_b32_e64 v62, v62, v63, s[36:37]
	v_add_u32_e32 v63, 0, v57
	v_cndmask_b32_e64 v58, v32, v58, s[36:37]
	v_add_u32_e32 v65, 0x12000, v63
	v_add_f32_e32 v58, v58, v66
	ds_write_b32 v65, v58
	v_add_f32_e32 v58, v37, v36
	v_add_f32_e32 v58, v38, v58
	v_fma_f32 v58, 2.0, v58, v39
	v_cndmask_b32_e64 v32, v33, v32, s[36:37]
	v_add_f32_e32 v32, v32, v58
	v_add_u32_e32 v58, 0x12008, v63
	ds_write_b32 v58, v32
	v_add_f32_e32 v32, v41, v40
	v_add_f32_e32 v32, v42, v32
	v_fma_f32 v32, 2.0, v32, v43
	v_cndmask_b32_e64 v33, v61, v33, s[36:37]
	v_add_f32_e32 v32, v33, v32
	v_add_u32_e32 v33, 0x12010, v63
	ds_write_b32 v33, v32
	v_add_f32_e32 v32, v45, v44
	v_add_f32_e32 v32, v46, v32
	v_fma_f32 v32, 2.0, v32, v47
	v_cndmask_b32_e64 v33, v62, v61, s[36:37]
	v_add_f32_e32 v32, v32, v33
	v_add_u32_e32 v33, 0x12018, v63
	ds_write_b32 v33, v32
	v_add_u32_e32 v63, 0, v55
	v_cvt_pk_bf16_f32 v32, v60, v59
	v_cvt_pk_bf16_f32 v33, v34, v35
	v_cvt_pk_bf16_f32 v34, v37, v36
	v_cvt_pk_bf16_f32 v35, v38, v39
	v_cvt_pk_bf16_f32 v36, v41, v40
	v_cvt_pk_bf16_f32 v37, v42, v43
	v_cvt_pk_bf16_f32 v38, v45, v44
	v_cvt_pk_bf16_f32 v39, v46, v47
	ds_read_b64_tr_b16 v[40:41], v63 offset:36864
	ds_read_b64_tr_b16 v[42:43], v63 offset:38016
	ds_read_b64_tr_b16 v[44:45], v63 offset:39168
	ds_read_b64_tr_b16 v[46:47], v63 offset:40320
	ds_read_b64_tr_b16 v[58:59], v63 offset:36928
	ds_read_b64_tr_b16 v[60:61], v63 offset:38080
	ds_read_b64_tr_b16 v[66:67], v63 offset:39232
	ds_read_b64_tr_b16 v[68:69], v63 offset:40384
	s_nop 0
	s_waitcnt lgkmcnt(6)
	v_mfma_f32_32x32x16_bf16 v[0:15], v[40:43], v[32:35], v[0:15]
	s_waitcnt lgkmcnt(2)
	v_mfma_f32_32x32x16_bf16 v[16:31], v[58:61], v[32:35], v[16:31]
	v_mfma_f32_32x32x16_bf16 v[0:15], v[44:47], v[36:39], v[0:15]
	s_waitcnt lgkmcnt(0)
	v_mfma_f32_32x32x16_bf16 v[16:31], v[66:69], v[36:39], v[16:31]
	s_nop 0
	s_add_i32 s0, s0, -1
	v_add_u32_e32 v55, 0x1200, v55
	v_add_u32_e32 v52, 0x1200, v52
	v_add_u32_e32 v57, 32, v57
	v_add_u32_e32 v53, 0x200, v53
	s_cmp_eq_u32 s0, 0
	v_mov_b32_e32 v58, v62
	s_cbranch_scc0 .LBB0_515
; #define LAS __attribute__((address_space(3)))
; DI void nsa_unit(const Params& P, int l, LAS char* lds, int b, int qt, int tid, int wave, int lane) {
;     ...
;     Stage2 stS; flash_prefetch(stS, hb + (size_t)b * SEQ * NIN + C_KS, hb + (size_t)b * SEQ * NIN + C_VS, NIN, 0, qt, tid);
;     {
;         LAS float* impS = (LAS float*)lds;
;         LAS unsigned long long* selm = (LAS unsigned long long*)(lds + NSA_SELM);
;         const int q = tid >> 3, s8 = tid & 7;
;         if (qt <= 15) { if (s8 == 0) selm[q] = (2ull << qt) - 1ull; }
;         else {
; #pragma unroll
;             for (int e = 0; e < 8; ++e) { const int J = 8 * s8 + e; impS[q * 65 + J] = ((impH[(0 * 64 + q) * 64 + J] + impH[(1 * 64 + q) * 64 + J]) + impH[(2 * 64 + q) * 64 + J]) + impH[(3 * 64 + q) * 64 + J]; }
;             __syncthreads();
;             unsigned bits = 0;
; #pragma unroll
;             for (int e = 0; e < 8; ++e) {
;                 const int J = 8 * s8 + e;
;                 if (J >= 1 && J <= qt - 2) {
;                     const float v = impS[q * 65 + J]; int cnt = 0;
;                     for (int J2 = 1; J2 <= qt - 2; ++J2) { const float v2 = impS[q * 65 + J2]; cnt += (v2 > v || (v2 == v && J2 < J)) ? 1 : 0; }
	s_mul_i32 s48, s48, 0x1800000
	s_add_u32 s61, s28, s48
	s_addc_u32 s27, s29, 0
	s_add_u32 s52, s61, 0x1500
	s_addc_u32 s53, s27, 0
	s_add_u32 s54, s61, 0x1580
	s_addc_u32 s55, s27, 0
	v_ashrrev_i32_e32 v187, 3, v56
	s_cmp_eq_u32 s60, 63
	v_mad_i64_i32 v[32:33], s[0:1], v187, s18, 0
	v_lshlrev_b32_e32 v34, 3, v86
	v_and_b32_e32 v212, 56, v34
	s_cselect_b32 s0, 0, 64
	v_or_b32_e32 v32, v32, v212
	v_add_u32_e32 v34, s0, v187
	v_mad_i64_i32 v[34:35], s[0:1], v34, s18, 0
	v_lshlrev_b64 v[32:33], 1, v[32:33]
	v_or_b32_e32 v34, v34, v212
	v_lshl_add_u64 v[36:37], s[52:53], 0, v[32:33]
	v_lshl_add_u64 v[32:33], s[54:55], 0, v[32:33]
	s_barrier
	global_load_dwordx4 v[112:115], v[36:37], off
	global_load_dwordx4 v[116:119], v[32:33], off
	v_lshlrev_b64 v[32:33], 1, v[34:35]
	v_lshl_add_u64 v[34:35], s[52:53], 0, v[32:33]
	v_lshl_add_u64 v[32:33], s[54:55], 0, v[32:33]
	global_load_dwordx4 v[120:123], v[34:35], off
	global_load_dwordx4 v[124:127], v[32:33], off
	v_and_b32_e32 v36, 7, v86
	s_cmp_gt_u32 s58, 15
	v_lshlrev_b32_e32 v162, 3, v36
	v_cmp_eq_u32_e64 s[0:1], 0, v36
	s_cbranch_scc0 .LBB0_522
	v_lshlrev_b32_e32 v32, 8, v187
	s_add_i32 s10, 0, 0x12000
	v_lshlrev_b32_e32 v33, 5, v36
	v_add3_u32 v32, s10, v32, v33
	ds_read_b32 v34, v32
	ds_read_b32 v35, v32 offset:16384
	s_movk_i32 s11, 0x104
	v_mul_lo_u32 v37, v187, s11
	v_add3_u32 v38, 0, v37, v33
	s_sub_i32 s11, 61, s60
	s_waitcnt lgkmcnt(0)
	v_add_f32_e32 v34, v34, v35
	ds_read_b32 v35, v32 offset:32768
	v_cmp_ne_u32_e32 vcc, 0, v36
	v_cmp_ge_u32_e64 s[38:39], s11, v162
	s_sub_i32 s10, 62, s60
	v_mov_b32_e32 v39, 0
	s_waitcnt lgkmcnt(0)
	v_add_f32_e32 v34, v34, v35
	ds_read_b32 v35, v32 offset:49152
	s_and_b64 s[24:25], vcc, s[38:39]
	s_waitcnt lgkmcnt(0)
	v_add_f32_e32 v34, v34, v35
	ds_write_b32 v38, v34
	ds_read_b32 v33, v32 offset:4
	ds_read_b32 v34, v32 offset:16388
	s_waitcnt lgkmcnt(0)
	v_add_f32_e32 v33, v33, v34
	ds_read_b32 v34, v32 offset:32772
	s_waitcnt lgkmcnt(0)
	v_add_f32_e32 v33, v33, v34
	ds_read_b32 v34, v32 offset:49156
	s_waitcnt lgkmcnt(0)
	v_add_f32_e32 v33, v33, v34
	ds_write_b32 v38, v33 offset:4
	ds_read_b32 v33, v32 offset:8
	ds_read_b32 v34, v32 offset:16392
	s_waitcnt lgkmcnt(0)
	v_add_f32_e32 v33, v33, v34
	ds_read_b32 v34, v32 offset:32776
	s_waitcnt lgkmcnt(0)
	v_add_f32_e32 v33, v33, v34
	ds_read_b32 v34, v32 offset:49160
	s_waitcnt lgkmcnt(0)
	v_add_f32_e32 v33, v33, v34
	ds_write_b32 v38, v33 offset:8
	ds_read_b32 v33, v32 offset:12
	ds_read_b32 v34, v32 offset:16396
	s_waitcnt lgkmcnt(0)
	v_add_f32_e32 v33, v33, v34
	ds_read_b32 v34, v32 offset:32780
	s_waitcnt lgkmcnt(0)
	v_add_f32_e32 v33, v33, v34
	ds_read_b32 v34, v32 offset:49164
	s_waitcnt lgkmcnt(0)
	v_add_f32_e32 v33, v33, v34
	ds_write_b32 v38, v33 offset:12
	ds_read_b32 v33, v32 offset:16
	ds_read_b32 v34, v32 offset:16400
	s_waitcnt lgkmcnt(0)
	v_add_f32_e32 v33, v33, v34
	ds_read_b32 v34, v32 offset:32784
	s_waitcnt lgkmcnt(0)
	v_add_f32_e32 v33, v33, v34
	ds_read_b32 v34, v32 offset:49168
	s_waitcnt lgkmcnt(0)
	v_add_f32_e32 v33, v33, v34
	ds_write_b32 v38, v33 offset:16
	ds_read_b32 v33, v32 offset:20
	ds_read_b32 v34, v32 offset:16404
	s_waitcnt lgkmcnt(0)
	v_add_f32_e32 v33, v33, v34
	ds_read_b32 v34, v32 offset:32788
	s_waitcnt lgkmcnt(0)
	v_add_f32_e32 v33, v33, v34
	ds_read_b32 v34, v32 offset:49172
	s_waitcnt lgkmcnt(0)
	v_add_f32_e32 v33, v33, v34
	ds_write_b32 v38, v33 offset:20
	ds_read_b32 v33, v32 offset:24
	ds_read_b32 v34, v32 offset:16408
	s_waitcnt lgkmcnt(0)
	v_add_f32_e32 v33, v33, v34
	ds_read_b32 v34, v32 offset:32792
	s_waitcnt lgkmcnt(0)
	v_add_f32_e32 v33, v33, v34
	ds_read_b32 v34, v32 offset:49176
	s_waitcnt lgkmcnt(0)
	v_add_f32_e32 v33, v33, v34
	ds_write_b32 v38, v33 offset:24
	ds_read_b32 v33, v32 offset:28
	ds_read_b32 v34, v32 offset:16412
	s_waitcnt lgkmcnt(0)
	v_add_f32_e32 v33, v33, v34
	ds_read_b32 v34, v32 offset:32796
	ds_read_b32 v32, v32 offset:49180
	s_waitcnt lgkmcnt(1)
	v_add_f32_e32 v33, v33, v34
	s_waitcnt lgkmcnt(0)
	v_add_f32_e32 v32, v33, v32
	ds_write_b32 v38, v32 offset:28
	s_waitcnt lgkmcnt(0)
	s_barrier
	s_and_saveexec_b64 s[34:35], s[24:25]
	s_cbranch_execz .LBB0_527
	ds_read_b32 v32, v38
	s_cmp_lt_u32 s11, 2
	s_cbranch_scc1 .LBB0_523
	s_and_b32 s24, s11, -2
	s_waitcnt lgkmcnt(0)
	v_mov_b32_e32 v33, v32
	v_mov_b32_e32 v35, v162
	v_add3_u32 v39, 0, 4, v37
	v_mov_b32_e32 v34, 0
	s_mov_b32 s25, 2
	s_mov_b32 s26, 1
	s_mov_b32 s56, s24
	v_mov_b32_e32 v40, 0
	ds_read2_b32 v[250:251], v39 offset1:1

; #define LAS __attribute__((address_space(3)))
; DI float ex2(float x) { return __builtin_amdgcn_exp2f(x); }
; template <int MM> DI void smax_step_nb(const f32x16& s, unsigned vm, float& m, float& l, f32x16 (&o)[2], bf16x8 (&pf)[2], int lane) {
;     float mx = -1e30f;
; #pragma unroll
;     for (int i = 0; i < 16; ++i) mx = fmaxf(mx, s[i]);
;     if (MM == 1) mx = vm ? mx : -1e30f;
;     mx = fmaxf(mx, shx32(mx, lane));
;     const float mn = (mx > m + 8.0f) ? mx : m;
;     float mref = fmaxf(mn, -1e29f);
;     if (MM == 1) mref = vm ? mref : 3e38f;
;     const float alpha = ex2(m - mn);
;     float p[16], rs = 0.f;
; #pragma unroll
;     for (int i = 0; i < 16; ++i) { p[i] = ex2(s[i] - mref); rs += p[i]; }
;     rs += shx32(rs, lane);
;     l = l * alpha + rs;
;     if (__builtin_amdgcn_ballot_w64(mn != m) != 0ull) {
; #pragma unroll
;         for (int i = 0; i < 16; ++i) { o[0][i] *= alpha; o[1][i] *= alpha; }
;     }
;     m = mn;
;     pack_p(p, pf);
; }
; template <int MODE, bool PRE = false> ...
;     ...
;             const int kt0 = kt_lo + 2 * sti;
;             bool both = (kt0 + 1 <= kt_hi) && (64 * kt0 + 127 <= q0w);
;             if (MODE == MODE_NWIN) both = both && (64 * kt0 > q0w + 31 - 512);
;             if (both) {
;                 bool ls0 = true, ls1 = true;
;                 if (MODE == MODE_MOBA) { ls0 = ((sel >> (kt0 >> 2)) & 1ull) != 0ull; ls1 = ((sel >> ((kt0 + 1) >> 2)) & 1ull) != 0ull; }
;                 if (MODE == MODE_NSEL) { ls0 = ((sel >> kt0) & 1ull) != 0ull; ls1 = ((sel >> (kt0 + 1)) & 1ull) != 0ull; }
;                 const unsigned long long b0 = __builtin_amdgcn_ballot_w64(ls0), b1 = __builtin_amdgcn_ballot_w64(ls1);
;                 if (b0 != 0ull && b1 != 0ull) {
;                     LAS char* K0 = lds + (sti & 1) * 4 * TILE_B;
;                     if ((b0 & b1) == ~0ull) tile128_pipe<0>(K0, K0 + TILE_B, K0 + 2 * TILE_B, K0 + 3 * TILE_B, qf, 1u, 1u, m1, l1, o1, r, h, lane);
;                     else tile128_pipe<1>(K0, K0 + TILE_B, K0 + 2 * TILE_B, K0 + 3 * TILE_B, qf, ls0 ? 1u : 0u, ls1 ? 1u : 0u, m1, l1, o1, r, h, lane);
.LBB0_589:
	s_lshl_b32 s64, s48, 1
	s_cmp_lt_u32 s64, s58
	s_cselect_b64 s[0:1], -1, 0
	s_lshl_b32 s10, s48, 7
	s_or_b32 s10, s10, 0x7f
	s_cmp_le_i32 s10, s59
	s_cselect_b64 s[10:11], -1, 0
	s_and_b64 s[0:1], s[0:1], s[10:11]
	s_andn2_b64 vcc, exec, s[0:1]
	s_mov_b32 s10, 0
	s_cbranch_vccnz .LBB0_612
	s_or_b32 s0, s64, 1
	v_lshrrev_b64 v[32:33], s64, v[164:165]
	v_and_b32_e32 v34, 1, v32
	v_lshrrev_b64 v[32:33], s0, v[164:165]
	v_and_b32_e32 v32, 1, v32
	v_cmp_ne_u32_e64 s[40:41], 0, v34
	v_cmp_ne_u32_e64 s[42:43], 0, v32
	s_cmp_eq_u64 s[40:41], 0
	s_cselect_b64 s[34:35], -1, 0
	s_cmp_eq_u64 s[42:43], 0
	s_cselect_b64 s[56:57], -1, 0
	s_or_b64 s[34:35], s[34:35], s[56:57]
	v_cmp_eq_u32_e64 s[38:39], 1, v34
	v_cmp_eq_u32_e64 s[0:1], 1, v32
	s_and_b64 vcc, exec, s[34:35]
	s_cbranch_vccnz .LBB0_612
	s_lshl_b32 s10, s48, 2
	s_and_b32 s10, s10, 4
	s_mulk_i32 s10, 0x2400
	s_add_i32 s10, s10, 0
	v_add_u32_e32 v32, s10, v190
	v_add_u32_e32 v215, v32, v168
	s_waitcnt lgkmcnt(7)
	ds_read_b128 v[140:143], v215
	s_waitcnt lgkmcnt(7)
	ds_read_b128 v[136:139], v215 offset:32
	s_waitcnt lgkmcnt(7)
	ds_read_b128 v[132:135], v215 offset:64
	s_waitcnt lgkmcnt(7)
	ds_read_b128 v[128:131], v215 offset:96
	s_and_b64 s[34:35], s[42:43], s[40:41]
	s_cmp_lg_u64 s[34:35], -1
	s_nop 0
	s_nop 0
	s_waitcnt lgkmcnt(7)
	ds_read_b128 v[144:147], v215 offset:4608
	s_waitcnt lgkmcnt(7)
	ds_read_b128 v[148:151], v215 offset:4640
	s_waitcnt lgkmcnt(7)
	ds_read_b128 v[152:155], v215 offset:4672
	s_waitcnt lgkmcnt(7)
	ds_read_b128 v[156:159], v215 offset:4704
	s_nop 0
	s_nop 0
	v_add_f32_e32 v216, 0x41000000, v214
	s_cbranch_scc0 .LBB0_601
	s_waitcnt lgkmcnt(7)
	v_mfma_f32_32x32x16_bf16 v[32:47], v[140:143], v[96:99], 0
	s_waitcnt lgkmcnt(6)
	v_mfma_f32_32x32x16_bf16 v[32:47], v[136:139], v[100:103], v[32:47]
	s_waitcnt lgkmcnt(5)
	v_mfma_f32_32x32x16_bf16 v[32:47], v[132:135], v[104:107], v[32:47]
	s_waitcnt lgkmcnt(4)
	v_mfma_f32_32x32x16_bf16 v[32:47], v[128:131], v[108:111], v[32:47]
	s_waitcnt lgkmcnt(3)
	v_mfma_f32_32x32x16_bf16 v[64:79], v[144:147], v[96:99], 0
	s_nop 9
	v_max3_f32 v48, v32, s15, v33
	v_max3_f32 v48, v48, v34, v35
	v_max3_f32 v48, v48, v36, v37
	v_max3_f32 v48, v48, v38, v39
	v_max3_f32 v48, v48, v40, v41
	v_max3_f32 v48, v48, v42, v43
	v_max3_f32 v48, v48, v44, v45
	v_max3_f32 v48, v48, v46, v47
	v_cndmask_b32_e64 v48, v208, v48, s[38:39]
	v_mov_b32_e32 v49, v48
	v_mov_b32_e32 v50, v48
	s_nop 1
	v_permlane32_swap_b32_e32 v49, v50
	v_max_f32_e32 v48, v49, v50
	v_cmp_gt_f32_e32 vcc, v48, v216
	s_waitcnt lgkmcnt(2)
	v_mfma_f32_32x32x16_bf16 v[64:79], v[148:151], v[100:103], v[64:79]
	v_cndmask_b32_e32 v224, v214, v48, vcc
	v_max_f32_e32 v48, 0xefa18f08, v224
	v_cndmask_b32_e64 v48, v209, v48, s[38:39]
	v_sub_f32_e32 v32, v32, v48
	v_sub_f32_e32 v33, v33, v48
	v_exp_f32_e32 v80, v32
	v_sub_f32_e32 v34, v34, v48
	v_exp_f32_e32 v81, v33
	v_sub_f32_e32 v35, v35, v48
	v_exp_f32_e32 v82, v34
	v_sub_f32_e32 v36, v36, v48
	v_exp_f32_e32 v83, v35
	v_sub_f32_e32 v37, v37, v48
	v_exp_f32_e32 v84, v36
	v_sub_f32_e32 v38, v38, v48
	v_exp_f32_e32 v85, v37
	v_add_f32_e32 v32, v81, v80
	v_sub_f32_e32 v39, v39, v48
	v_exp_f32_e32 v86, v38
	s_waitcnt lgkmcnt(1)
	v_mfma_f32_32x32x16_bf16 v[64:79], v[152:155], v[104:107], v[64:79]
	v_add_f32_e32 v32, v82, v32
	v_sub_f32_e32 v40, v40, v48
	v_exp_f32_e32 v87, v39
	v_add_f32_e32 v32, v83, v32
	v_sub_f32_e32 v41, v41, v48
	v_exp_f32_e32 v88, v40
	v_add_f32_e32 v32, v84, v32
	v_sub_f32_e32 v42, v42, v48
	v_exp_f32_e32 v89, v41
	v_add_f32_e32 v32, v85, v32
	v_sub_f32_e32 v43, v43, v48
	v_exp_f32_e32 v90, v42
	v_add_f32_e32 v32, v86, v32
	v_sub_f32_e32 v44, v44, v48
	v_exp_f32_e32 v91, v43
	v_add_f32_e32 v32, v87, v32
	v_add_f32_e32 v32, v88, v32
	v_exp_f32_e32 v92, v44
	v_sub_f32_e32 v33, v45, v48
	v_add_f32_e32 v32, v89, v32
	v_exp_f32_e32 v93, v33
	v_sub_f32_e32 v33, v46, v48
	s_waitcnt lgkmcnt(0)
	v_mfma_f32_32x32x16_bf16 v[64:79], v[156:159], v[108:111], v[64:79]
	v_add_f32_e32 v32, v90, v32
	v_exp_f32_e32 v94, v33
	v_sub_f32_e32 v33, v47, v48
	v_add_f32_e32 v32, v91, v32
	v_exp_f32_e32 v95, v33
	v_add_f32_e32 v32, v92, v32
	v_sub_f32_e32 v49, v214, v224
	v_add_f32_e32 v32, v93, v32
	v_add_f32_e32 v32, v94, v32
	v_exp_f32_e32 v166, v49
	v_add_f32_e32 v217, v95, v32
	v_mov_b32_e32 v218, v217
	v_mov_b32_e32 v219, v217
	s_nop 0
	s_nop 0
	v_permlane32_swap_b32_e32 v218, v219
	v_cmp_neq_f32_e32 vcc, v224, v214
	s_cbranch_vccz .LBB0_594
	v_pk_mul_f32 v[30:31], v[30:31], v[166:167] op_sel_hi:[1,0]
	v_pk_mul_f32 v[28:29], v[28:29], v[166:167] op_sel_hi:[1,0]
	v_pk_mul_f32 v[26:27], v[26:27], v[166:167] op_sel_hi:[1,0]
	v_pk_mul_f32 v[24:25], v[24:25], v[166:167] op_sel_hi:[1,0]
	v_pk_mul_f32 v[22:23], v[22:23], v[166:167] op_sel_hi:[1,0]
	v_pk_mul_f32 v[20:21], v[20:21], v[166:167] op_sel_hi:[1,0]
	v_pk_mul_f32 v[18:19], v[18:19], v[166:167] op_sel_hi:[1,0]
	v_pk_mul_f32 v[16:17], v[16:17], v[166:167] op_sel_hi:[1,0]
	v_pk_mul_f32 v[14:15], v[14:15], v[166:167] op_sel_hi:[1,0]
	v_pk_mul_f32 v[12:13], v[12:13], v[166:167] op_sel_hi:[1,0]
	v_pk_mul_f32 v[10:11], v[10:11], v[166:167] op_sel_hi:[1,0]
	v_pk_mul_f32 v[8:9], v[8:9], v[166:167] op_sel_hi:[1,0]
	v_pk_mul_f32 v[6:7], v[6:7], v[166:167] op_sel_hi:[1,0]
	v_pk_mul_f32 v[4:5], v[4:5], v[166:167] op_sel_hi:[1,0]
	v_pk_mul_f32 v[2:3], v[2:3], v[166:167] op_sel_hi:[1,0]
	v_pk_mul_f32 v[0:1], v[0:1], v[166:167] op_sel_hi:[1,0]
; #define LAS __attribute__((address_space(3)))
; DI float ex2(float x) { return __builtin_amdgcn_exp2f(x); }
; template <int MM> DI void smax_step_nb(const f32x16& s, unsigned vm, float& m, float& l, f32x16 (&o)[2], bf16x8 (&pf)[2], int lane) {
;     float mx = -1e30f;
; #pragma unroll
;     for (int i = 0; i < 16; ++i) mx = fmaxf(mx, s[i]);
;     if (MM == 1) mx = vm ? mx : -1e30f;
;     mx = fmaxf(mx, shx32(mx, lane));
;     const float mn = (mx > m + 8.0f) ? mx : m;
;     float mref = fmaxf(mn, -1e29f);
;     if (MM == 1) mref = vm ? mref : 3e38f;
;     const float alpha = ex2(m - mn);
;     float p[16], rs = 0.f;
; #pragma unroll
;     for (int i = 0; i < 16; ++i) { p[i] = ex2(s[i] - mref); rs += p[i]; }
;     rs += shx32(rs, lane);
;     l = l * alpha + rs;
;     if (__builtin_amdgcn_ballot_w64(mn != m) != 0ull) {
; #pragma unroll
;         for (int i = 0; i < 16; ++i) { o[0][i] *= alpha; o[1][i] *= alpha; }
;     }
;     m = mn;
;     pack_p(p, pf);
; }
; template <int MM> DI void tile128_pipe(LAS const char* K0, LAS const char* V0, LAS const char* K1, LAS const char* V1, const bf16x8 (&qf)[4], unsigned vm0, unsigned vm1,
;                                        float& m, float& l, f32x16 (&o)[2], int r, int h, int lane) {
;     f32x16 sa = qk_rows<0, 4>(K0, 0, qf, r, h), sb = qk_rows<0, 4>(K0, 32, qf, r, h);
;     bf16x8 pfa[2], pfb[2];
;     smax_step_nb<MM>(sa, vm0, m, l, o, pfa, lane);
;     sa = qk_rows<0, 4>(K1, 0, qf, r, h);
;     pv_rows(o, V0, 0, pfa, lane);
;     smax_step_nb<MM>(sb, vm0, m, l, o, pfb, lane);
;     sb = qk_rows<0, 4>(K1, 32, qf, r, h);
;     pv_rows(o, V0, 32, pfb, lane);
;     smax_step_nb<MM>(sa, vm1, m, l, o, pfa, lane);
;     pv_rows(o, V1, 0, pfa, lane);
;     smax_step_nb<MM>(sb, vm1, m, l, o, pfb, lane);
;     pv_rows(o, V1, 32, pfb, lane);
; }
.LBB0_594:
	v_cvt_pk_bf16_f32 v226, v80, v81
	v_cvt_pk_bf16_f32 v227, v82, v83
	ds_read_b128 v[80:83], v215 offset:18432
	ds_read_b128 v[220:223], v215 offset:18464
	ds_read_b128 v[234:237], v215 offset:18496
	ds_read_b128 v[238:241], v215 offset:18528
	v_cvt_pk_bf16_f32 v228, v84, v85
	v_cvt_pk_bf16_f32 v229, v86, v87
	v_cvt_pk_bf16_f32 v230, v88, v89
	v_cvt_pk_bf16_f32 v231, v90, v91
	v_cvt_pk_bf16_f32 v232, v92, v93
	v_cvt_pk_bf16_f32 v233, v94, v95
	s_nop 0
	s_waitcnt lgkmcnt(3)
	v_mfma_f32_32x32x16_bf16 v[80:95], v[80:83], v[96:99], 0
	s_waitcnt lgkmcnt(2)
	v_mfma_f32_32x32x16_bf16 v[80:95], v[220:223], v[100:103], v[80:95]
	s_waitcnt lgkmcnt(1)
	v_mfma_f32_32x32x16_bf16 v[80:95], v[234:237], v[104:107], v[80:95]
	s_waitcnt lgkmcnt(0)
	v_mfma_f32_32x32x16_bf16 v[80:95], v[238:241], v[108:111], v[80:95]
	s_nop 0
	v_add3_u32 v172, s10, v191, v171
	v_add_u32_e32 v220, v172, v186
	ds_read_b64_tr_b16 v[234:235], v220 offset:9216
	ds_read_b64_tr_b16 v[236:237], v220 offset:10368
	ds_read_b64_tr_b16 v[240:241], v220 offset:10432
	ds_read_b64_tr_b16 v[238:239], v220 offset:9280
	ds_read_b64_tr_b16 v[242:243], v220 offset:11520
	ds_read_b64_tr_b16 v[244:245], v220 offset:12672
	ds_read_b64_tr_b16 v[248:249], v220 offset:12736
	ds_read_b64_tr_b16 v[246:247], v220 offset:11584
	s_nop 0
	s_waitcnt lgkmcnt(6)
	v_mfma_f32_32x32x16_bf16 v[0:15], v[234:237], v[226:229], v[0:15]
	s_waitcnt lgkmcnt(4)
	v_mfma_f32_32x32x16_bf16 v[16:31], v[238:241], v[226:229], v[16:31]
	s_waitcnt lgkmcnt(2)
	v_mfma_f32_32x32x16_bf16 v[0:15], v[242:245], v[230:233], v[0:15]
	s_waitcnt lgkmcnt(0)
	v_mfma_f32_32x32x16_bf16 v[16:31], v[246:249], v[230:233], v[16:31]
	s_nop 0
	v_max3_f32 v172, v64, s15, v65
	v_max3_f32 v172, v172, v66, v67
	v_max3_f32 v172, v172, v68, v69
	v_max3_f32 v172, v172, v70, v71
	v_max3_f32 v172, v172, v72, v73
	v_max3_f32 v172, v172, v74, v75
	v_max3_f32 v172, v172, v76, v77
	v_max3_f32 v172, v172, v78, v79
	v_cndmask_b32_e64 v172, v208, v172, s[38:39]
	v_mov_b32_e32 v173, v172
	v_mov_b32_e32 v184, v172
	s_nop 1
	v_permlane32_swap_b32_e32 v173, v184
	v_max_f32_e32 v172, v173, v184
	v_add_f32_e32 v173, 0x41000000, v224
	v_cmp_gt_f32_e32 vcc, v172, v173
	s_nop 1
	v_cndmask_b32_e32 v225, v224, v172, vcc
	v_max_f32_e32 v172, 0xefa18f08, v225
	v_cndmask_b32_e64 v172, v209, v172, s[38:39]
	v_sub_f32_e32 v64, v64, v172
	v_exp_f32_e32 v64, v64
	v_sub_f32_e32 v65, v65, v172
	v_exp_f32_e32 v65, v65
	v_sub_f32_e32 v66, v66, v172
	v_exp_f32_e32 v66, v66
	v_sub_f32_e32 v67, v67, v172
	v_exp_f32_e32 v67, v67
	v_sub_f32_e32 v68, v68, v172
	v_exp_f32_e32 v68, v68
	v_sub_f32_e32 v69, v69, v172
	v_add_f32_e32 v184, v65, v64
	v_exp_f32_e32 v69, v69
	v_sub_f32_e32 v70, v70, v172
	v_add_f32_e32 v184, v66, v184
	v_exp_f32_e32 v70, v70
	v_sub_f32_e32 v71, v71, v172
	v_add_f32_e32 v184, v67, v184
	v_exp_f32_e32 v71, v71
	v_sub_f32_e32 v72, v72, v172
	v_add_f32_e32 v184, v68, v184
	v_exp_f32_e32 v72, v72
	v_sub_f32_e32 v73, v73, v172
	v_add_f32_e32 v184, v69, v184
	v_exp_f32_e32 v73, v73
	v_sub_f32_e32 v74, v74, v172
	v_add_f32_e32 v184, v70, v184
	v_exp_f32_e32 v74, v74
	v_sub_f32_e32 v75, v75, v172
	v_add_f32_e32 v184, v71, v184
	v_exp_f32_e32 v75, v75
	v_sub_f32_e32 v76, v76, v172
	v_add_f32_e32 v184, v72, v184
	v_exp_f32_e32 v76, v76
	v_sub_f32_e32 v77, v77, v172
	v_add_f32_e32 v184, v73, v184
	v_exp_f32_e32 v77, v77
	v_sub_f32_e32 v78, v78, v172
	v_add_f32_e32 v184, v74, v184
	v_exp_f32_e32 v78, v78
	v_sub_f32_e32 v79, v79, v172
	v_add_f32_e32 v184, v75, v184
	v_exp_f32_e32 v79, v79
	v_add_f32_e32 v172, v76, v184
	v_sub_f32_e32 v173, v224, v225
	v_add_f32_e32 v172, v77, v172
	v_add_f32_e32 v172, v78, v172
	v_exp_f32_e32 v184, v173
	v_add_f32_e32 v221, v79, v172
	v_mov_b32_e32 v222, v221
	v_mov_b32_e32 v223, v221
	s_nop 1
	v_permlane32_swap_b32_e32 v222, v223
	v_cmp_neq_f32_e32 vcc, v225, v224
	s_cbranch_vccz .LBB0_596
	v_pk_mul_f32 v[30:31], v[30:31], v[184:185] op_sel_hi:[1,0]
	v_pk_mul_f32 v[28:29], v[28:29], v[184:185] op_sel_hi:[1,0]
	v_pk_mul_f32 v[26:27], v[26:27], v[184:185] op_sel_hi:[1,0]
	v_pk_mul_f32 v[24:25], v[24:25], v[184:185] op_sel_hi:[1,0]
	v_pk_mul_f32 v[22:23], v[22:23], v[184:185] op_sel_hi:[1,0]
	v_pk_mul_f32 v[20:21], v[20:21], v[184:185] op_sel_hi:[1,0]
	v_pk_mul_f32 v[18:19], v[18:19], v[184:185] op_sel_hi:[1,0]
	v_pk_mul_f32 v[16:17], v[16:17], v[184:185] op_sel_hi:[1,0]
	v_pk_mul_f32 v[14:15], v[14:15], v[184:185] op_sel_hi:[1,0]
	v_pk_mul_f32 v[12:13], v[12:13], v[184:185] op_sel_hi:[1,0]
	v_pk_mul_f32 v[10:11], v[10:11], v[184:185] op_sel_hi:[1,0]
	v_pk_mul_f32 v[8:9], v[8:9], v[184:185] op_sel_hi:[1,0]
	v_pk_mul_f32 v[6:7], v[6:7], v[184:185] op_sel_hi:[1,0]
	v_pk_mul_f32 v[4:5], v[4:5], v[184:185] op_sel_hi:[1,0]
	v_pk_mul_f32 v[2:3], v[2:3], v[184:185] op_sel_hi:[1,0]
	v_pk_mul_f32 v[0:1], v[0:1], v[184:185] op_sel_hi:[1,0]
; #define LAS __attribute__((address_space(3)))
; DI float ex2(float x) { return __builtin_amdgcn_exp2f(x); }
; template <int MM> DI void smax_step_nb(const f32x16& s, unsigned vm, float& m, float& l, f32x16 (&o)[2], bf16x8 (&pf)[2], int lane) {
;     float mx = -1e30f;
; #pragma unroll
;     for (int i = 0; i < 16; ++i) mx = fmaxf(mx, s[i]);
;     if (MM == 1) mx = vm ? mx : -1e30f;
;     mx = fmaxf(mx, shx32(mx, lane));
;     const float mn = (mx > m + 8.0f) ? mx : m;
;     float mref = fmaxf(mn, -1e29f);
;     if (MM == 1) mref = vm ? mref : 3e38f;
;     const float alpha = ex2(m - mn);
;     float p[16], rs = 0.f;
; #pragma unroll
;     for (int i = 0; i < 16; ++i) { p[i] = ex2(s[i] - mref); rs += p[i]; }
;     rs += shx32(rs, lane);
;     l = l * alpha + rs;
;     if (__builtin_amdgcn_ballot_w64(mn != m) != 0ull) {
; #pragma unroll
;         for (int i = 0; i < 16; ++i) { o[0][i] *= alpha; o[1][i] *= alpha; }
;     }
;     m = mn;
;     pack_p(p, pf);
; }
; template <int MM> DI void tile128_pipe(LAS const char* K0, LAS const char* V0, LAS const char* K1, LAS const char* V1, const bf16x8 (&qf)[4], unsigned vm0, unsigned vm1,
;                                        float& m, float& l, f32x16 (&o)[2], int r, int h, int lane) {
;     f32x16 sa = qk_rows<0, 4>(K0, 0, qf, r, h), sb = qk_rows<0, 4>(K0, 32, qf, r, h);
;     bf16x8 pfa[2], pfb[2];
;     smax_step_nb<MM>(sa, vm0, m, l, o, pfa, lane);
;     sa = qk_rows<0, 4>(K1, 0, qf, r, h);
;     pv_rows(o, V0, 0, pfa, lane);
;     smax_step_nb<MM>(sb, vm0, m, l, o, pfb, lane);
;     sb = qk_rows<0, 4>(K1, 32, qf, r, h);
;     pv_rows(o, V0, 32, pfb, lane);
;     smax_step_nb<MM>(sa, vm1, m, l, o, pfa, lane);
;     pv_rows(o, V1, 0, pfa, lane);
;     smax_step_nb<MM>(sb, vm1, m, l, o, pfb, lane);
;     pv_rows(o, V1, 32, pfb, lane);
; }
.LBB0_596:
	v_cvt_pk_bf16_f32 v226, v64, v65
	v_cvt_pk_bf16_f32 v227, v66, v67
	ds_read_b128 v[64:67], v215 offset:23040
	ds_read_b128 v[234:237], v215 offset:23072
	ds_read_b128 v[238:241], v215 offset:23104
	ds_read_b128 v[242:245], v215 offset:23136
	v_cvt_pk_bf16_f32 v228, v68, v69
	v_cvt_pk_bf16_f32 v229, v70, v71
	v_cvt_pk_bf16_f32 v230, v72, v73
	v_cvt_pk_bf16_f32 v231, v74, v75
	v_cvt_pk_bf16_f32 v232, v76, v77
	v_cvt_pk_bf16_f32 v233, v78, v79
	s_nop 0
	s_waitcnt lgkmcnt(3)
	v_mfma_f32_32x32x16_bf16 v[64:79], v[64:67], v[96:99], 0
	s_waitcnt lgkmcnt(2)
	v_mfma_f32_32x32x16_bf16 v[64:79], v[234:237], v[100:103], v[64:79]
	s_waitcnt lgkmcnt(1)
	v_mfma_f32_32x32x16_bf16 v[64:79], v[238:241], v[104:107], v[64:79]
	s_waitcnt lgkmcnt(0)
	v_mfma_f32_32x32x16_bf16 v[64:79], v[242:245], v[108:111], v[64:79]
	s_nop 0
	ds_read_b64_tr_b16 v[234:235], v220 offset:13824
	ds_read_b64_tr_b16 v[236:237], v220 offset:14976
	ds_read_b64_tr_b16 v[240:241], v220 offset:15040
	ds_read_b64_tr_b16 v[238:239], v220 offset:13888
	ds_read_b64_tr_b16 v[242:243], v220 offset:16128
	ds_read_b64_tr_b16 v[244:245], v220 offset:17280
	ds_read_b64_tr_b16 v[248:249], v220 offset:17344
	ds_read_b64_tr_b16 v[246:247], v220 offset:16192
	s_nop 0
	s_waitcnt lgkmcnt(6)
	v_mfma_f32_32x32x16_bf16 v[0:15], v[234:237], v[226:229], v[0:15]
	s_waitcnt lgkmcnt(4)
	v_mfma_f32_32x32x16_bf16 v[16:31], v[238:241], v[226:229], v[16:31]
	s_waitcnt lgkmcnt(2)
	v_mfma_f32_32x32x16_bf16 v[0:15], v[242:245], v[230:233], v[0:15]
	s_waitcnt lgkmcnt(0)
	v_mfma_f32_32x32x16_bf16 v[16:31], v[246:249], v[230:233], v[16:31]
	s_nop 0
	v_max3_f32 v172, v80, s15, v81
	v_max3_f32 v172, v172, v82, v83
	v_max3_f32 v172, v172, v84, v85
	v_max3_f32 v172, v172, v86, v87
	v_max3_f32 v172, v172, v88, v89
	v_max3_f32 v172, v172, v90, v91
	v_max3_f32 v172, v172, v92, v93
	v_max3_f32 v172, v172, v94, v95
	v_cndmask_b32_e64 v172, v208, v172, s[0:1]
	v_mov_b32_e32 v173, v172
	v_mov_b32_e32 v206, v172
	s_nop 1
	v_permlane32_swap_b32_e32 v173, v206
	v_cndmask_b32_e64 v173, v173, v206, s[36:37]
	v_max_f32_e32 v173, v173, v173
	v_max_f32_e32 v172, v172, v173
	v_add_f32_e32 v173, 0x41000000, v225
	v_cmp_gt_f32_e32 vcc, v172, v173
	s_nop 1
	v_cndmask_b32_e32 v224, v225, v172, vcc
	v_max_f32_e32 v172, 0xefa18f08, v224
	v_cndmask_b32_e64 v172, v209, v172, s[0:1]
	v_sub_f32_e32 v80, v80, v172
	v_exp_f32_e32 v226, v80
	v_sub_f32_e32 v80, v81, v172
	v_exp_f32_e32 v81, v80
	v_sub_f32_e32 v80, v82, v172
	v_exp_f32_e32 v227, v80
	v_sub_f32_e32 v80, v83, v172
	v_exp_f32_e32 v228, v80
	v_sub_f32_e32 v82, v84, v172
	v_exp_f32_e32 v229, v82
	v_sub_f32_e32 v82, v85, v172
	v_add_f32_e32 v80, v81, v226
	v_exp_f32_e32 v85, v82
	v_sub_f32_e32 v82, v86, v172
	v_add_f32_e32 v80, v227, v80
	v_exp_f32_e32 v86, v82
	v_sub_f32_e32 v82, v87, v172
	v_add_f32_e32 v80, v228, v80
	v_exp_f32_e32 v87, v82
	v_sub_f32_e32 v82, v88, v172
	v_add_f32_e32 v80, v229, v80
	v_exp_f32_e32 v88, v82
	v_sub_f32_e32 v82, v89, v172
	v_add_f32_e32 v80, v85, v80
	v_exp_f32_e32 v89, v82
	v_sub_f32_e32 v82, v90, v172
	v_add_f32_e32 v80, v86, v80
	v_exp_f32_e32 v90, v82
	v_sub_f32_e32 v82, v91, v172
	v_add_f32_e32 v80, v87, v80
	v_exp_f32_e32 v91, v82
	v_sub_f32_e32 v82, v92, v172
	v_add_f32_e32 v80, v88, v80
	v_exp_f32_e32 v92, v82
	v_sub_f32_e32 v82, v93, v172
	v_add_f32_e32 v80, v89, v80
	v_exp_f32_e32 v93, v82
	v_sub_f32_e32 v82, v94, v172
	v_add_f32_e32 v80, v90, v80
	v_exp_f32_e32 v94, v82
	v_sub_f32_e32 v82, v95, v172
	v_add_f32_e32 v80, v91, v80
	v_exp_f32_e32 v95, v82
	v_add_f32_e32 v80, v92, v80
	v_add_f32_e32 v80, v93, v80
	v_sub_f32_e32 v173, v225, v224
	v_add_f32_e32 v80, v94, v80
	v_add_f32_e32 v82, v95, v80
	v_exp_f32_e32 v80, v173
	v_mov_b32_e32 v83, v82
	v_mov_b32_e32 v84, v82
	s_nop 1
	v_permlane32_swap_b32_e32 v83, v84
	v_cmp_neq_f32_e32 vcc, v224, v225
	s_cbranch_vccz .LBB0_598
	v_pk_mul_f32 v[30:31], v[30:31], v[80:81] op_sel_hi:[1,0]
	v_pk_mul_f32 v[28:29], v[28:29], v[80:81] op_sel_hi:[1,0]
	v_pk_mul_f32 v[26:27], v[26:27], v[80:81] op_sel_hi:[1,0]
	v_pk_mul_f32 v[24:25], v[24:25], v[80:81] op_sel_hi:[1,0]
	v_pk_mul_f32 v[22:23], v[22:23], v[80:81] op_sel_hi:[1,0]
	v_pk_mul_f32 v[20:21], v[20:21], v[80:81] op_sel_hi:[1,0]
	v_pk_mul_f32 v[18:19], v[18:19], v[80:81] op_sel_hi:[1,0]
	v_pk_mul_f32 v[16:17], v[16:17], v[80:81] op_sel_hi:[1,0]
	v_pk_mul_f32 v[14:15], v[14:15], v[80:81] op_sel_hi:[1,0]
	v_pk_mul_f32 v[12:13], v[12:13], v[80:81] op_sel_hi:[1,0]
	v_pk_mul_f32 v[10:11], v[10:11], v[80:81] op_sel_hi:[1,0]
	v_pk_mul_f32 v[8:9], v[8:9], v[80:81] op_sel_hi:[1,0]
	v_pk_mul_f32 v[6:7], v[6:7], v[80:81] op_sel_hi:[1,0]
	v_pk_mul_f32 v[4:5], v[4:5], v[80:81] op_sel_hi:[1,0]
	v_pk_mul_f32 v[2:3], v[2:3], v[80:81] op_sel_hi:[1,0]
	v_pk_mul_f32 v[0:1], v[0:1], v[80:81] op_sel_hi:[1,0]
; #define LAS __attribute__((address_space(3)))
; DI float ex2(float x) { return __builtin_amdgcn_exp2f(x); }
; template <int MM> DI void smax_step_nb(const f32x16& s, unsigned vm, float& m, float& l, f32x16 (&o)[2], bf16x8 (&pf)[2], int lane) {
;     float mx = -1e30f;
; #pragma unroll
;     for (int i = 0; i < 16; ++i) mx = fmaxf(mx, s[i]);
;     if (MM == 1) mx = vm ? mx : -1e30f;
;     mx = fmaxf(mx, shx32(mx, lane));
;     const float mn = (mx > m + 8.0f) ? mx : m;
;     float mref = fmaxf(mn, -1e29f);
;     if (MM == 1) mref = vm ? mref : 3e38f;
;     const float alpha = ex2(m - mn);
;     float p[16], rs = 0.f;
; #pragma unroll
;     for (int i = 0; i < 16; ++i) { p[i] = ex2(s[i] - mref); rs += p[i]; }
;     rs += shx32(rs, lane);
;     l = l * alpha + rs;
;     if (__builtin_amdgcn_ballot_w64(mn != m) != 0ull) {
; #pragma unroll
;         for (int i = 0; i < 16; ++i) { o[0][i] *= alpha; o[1][i] *= alpha; }
;     }
;     m = mn;
;     pack_p(p, pf);
; }
; template <int MM> DI void tile128_pipe(LAS const char* K0, LAS const char* V0, LAS const char* K1, LAS const char* V1, const bf16x8 (&qf)[4], unsigned vm0, unsigned vm1,
;                                        float& m, float& l, f32x16 (&o)[2], int r, int h, int lane) {
;     f32x16 sa = qk_rows<0, 4>(K0, 0, qf, r, h), sb = qk_rows<0, 4>(K0, 32, qf, r, h);
;     bf16x8 pfa[2], pfb[2];
;     smax_step_nb<MM>(sa, vm0, m, l, o, pfa, lane);
;     sa = qk_rows<0, 4>(K1, 0, qf, r, h);
;     pv_rows(o, V0, 0, pfa, lane);
;     smax_step_nb<MM>(sb, vm0, m, l, o, pfb, lane);
;     sb = qk_rows<0, 4>(K1, 32, qf, r, h);
;     pv_rows(o, V0, 32, pfb, lane);
;     smax_step_nb<MM>(sa, vm1, m, l, o, pfa, lane);
;     pv_rows(o, V1, 0, pfa, lane);
;     smax_step_nb<MM>(sb, vm1, m, l, o, pfb, lane);
;     pv_rows(o, V1, 32, pfb, lane);
; }
.LBB0_598:
	v_cvt_pk_bf16_f32 v227, v227, v228
	v_cvt_pk_bf16_f32 v228, v229, v85
	v_cvt_pk_bf16_f32 v229, v86, v87
	v_cvt_pk_bf16_f32 v86, v88, v89
	v_cvt_pk_bf16_f32 v87, v90, v91
	v_cvt_pk_bf16_f32 v88, v92, v93
	ds_read_b64_tr_b16 v[90:91], v220 offset:27648
	ds_read_b64_tr_b16 v[92:93], v220 offset:28800
	ds_read_b64_tr_b16 v[230:231], v220 offset:29952
	ds_read_b64_tr_b16 v[232:233], v220 offset:31104
	ds_read_b64_tr_b16 v[234:235], v220 offset:27712
	ds_read_b64_tr_b16 v[236:237], v220 offset:28864
	ds_read_b64_tr_b16 v[238:239], v220 offset:30016
	ds_read_b64_tr_b16 v[240:241], v220 offset:31168
	v_cvt_pk_bf16_f32 v89, v94, v95
	v_cvt_pk_bf16_f32 v226, v226, v81
	s_nop 0
	s_waitcnt lgkmcnt(6)
	v_mfma_f32_32x32x16_bf16 v[0:15], v[90:93], v[226:229], v[0:15]
	s_waitcnt lgkmcnt(2)
	v_mfma_f32_32x32x16_bf16 v[16:31], v[234:237], v[226:229], v[16:31]
	v_mfma_f32_32x32x16_bf16 v[0:15], v[230:233], v[86:89], v[0:15]
	s_waitcnt lgkmcnt(0)
	v_mfma_f32_32x32x16_bf16 v[16:31], v[238:241], v[86:89], v[16:31]
	s_nop 0
	v_max3_f32 v81, v64, s15, v65
	v_max3_f32 v81, v81, v66, v67
	v_max3_f32 v81, v81, v68, v69
	v_max3_f32 v81, v81, v70, v71
	v_max3_f32 v81, v81, v72, v73
	v_max3_f32 v81, v81, v74, v75
	v_max3_f32 v81, v81, v76, v77
	v_max3_f32 v81, v81, v78, v79
	v_cndmask_b32_e64 v81, v208, v81, s[0:1]
	v_mov_b32_e32 v85, v81
	v_mov_b32_e32 v86, v81
	s_nop 1
	v_permlane32_swap_b32_e32 v85, v86
	v_max_f32_e32 v81, v85, v86
	v_add_f32_e32 v85, 0x41000000, v224
	v_cmp_gt_f32_e32 vcc, v81, v85
	s_nop 1
	v_cndmask_b32_e32 v81, v224, v81, vcc
	v_max_f32_e32 v85, 0xefa18f08, v81
	v_cndmask_b32_e64 v93, v209, v85, s[0:1]
	v_sub_f32_e32 v64, v64, v93
	v_exp_f32_e32 v85, v64
	v_sub_f32_e32 v64, v65, v93
	v_exp_f32_e32 v86, v64
	v_sub_f32_e32 v64, v66, v93
	v_exp_f32_e32 v87, v64
	v_sub_f32_e32 v64, v67, v93
	v_exp_f32_e32 v88, v64
	v_sub_f32_e32 v65, v68, v93
	v_exp_f32_e32 v89, v65
	v_sub_f32_e32 v65, v69, v93
	v_add_f32_e32 v64, v86, v85
	v_exp_f32_e32 v90, v65
	v_sub_f32_e32 v65, v70, v93
	v_add_f32_e32 v64, v87, v64
	v_exp_f32_e32 v91, v65
	v_sub_f32_e32 v65, v71, v93
	v_add_f32_e32 v64, v88, v64
	v_exp_f32_e32 v92, v65
	v_sub_f32_e32 v65, v72, v93
	v_add_f32_e32 v64, v89, v64
	v_exp_f32_e32 v66, v65
	v_sub_f32_e32 v65, v73, v93
	v_add_f32_e32 v64, v90, v64
	v_exp_f32_e32 v67, v65
	v_sub_f32_e32 v65, v74, v93
	v_add_f32_e32 v64, v91, v64
	v_exp_f32_e32 v68, v65
	v_sub_f32_e32 v65, v75, v93
	v_add_f32_e32 v64, v92, v64
	v_exp_f32_e32 v69, v65
	v_sub_f32_e32 v65, v76, v93
	v_add_f32_e32 v64, v66, v64
	v_exp_f32_e32 v70, v65
	v_sub_f32_e32 v65, v77, v93
	v_add_f32_e32 v64, v67, v64
	v_exp_f32_e32 v71, v65
	v_sub_f32_e32 v65, v78, v93
	v_add_f32_e32 v64, v68, v64
	v_exp_f32_e32 v72, v65
	v_sub_f32_e32 v65, v79, v93
	v_add_f32_e32 v64, v69, v64
	v_exp_f32_e32 v73, v65
	v_add_f32_e32 v64, v70, v64
	v_add_f32_e32 v64, v71, v64
	v_sub_f32_e32 v94, v224, v81
	v_add_f32_e32 v64, v72, v64
	v_add_f32_e32 v65, v73, v64
	v_exp_f32_e32 v64, v94
	v_mov_b32_e32 v74, v65
	v_mov_b32_e32 v75, v65
	s_nop 1
	v_permlane32_swap_b32_e32 v74, v75
	v_cmp_neq_f32_e32 vcc, v81, v224
	s_cbranch_vccz .LBB0_600
	v_pk_mul_f32 v[30:31], v[30:31], v[64:65] op_sel_hi:[1,0]
	v_pk_mul_f32 v[28:29], v[28:29], v[64:65] op_sel_hi:[1,0]
	v_pk_mul_f32 v[26:27], v[26:27], v[64:65] op_sel_hi:[1,0]
	v_pk_mul_f32 v[24:25], v[24:25], v[64:65] op_sel_hi:[1,0]
	v_pk_mul_f32 v[22:23], v[22:23], v[64:65] op_sel_hi:[1,0]
	v_pk_mul_f32 v[20:21], v[20:21], v[64:65] op_sel_hi:[1,0]
	v_pk_mul_f32 v[18:19], v[18:19], v[64:65] op_sel_hi:[1,0]
	v_pk_mul_f32 v[16:17], v[16:17], v[64:65] op_sel_hi:[1,0]
	v_pk_mul_f32 v[14:15], v[14:15], v[64:65] op_sel_hi:[1,0]
	v_pk_mul_f32 v[12:13], v[12:13], v[64:65] op_sel_hi:[1,0]
	v_pk_mul_f32 v[10:11], v[10:11], v[64:65] op_sel_hi:[1,0]
	v_pk_mul_f32 v[8:9], v[8:9], v[64:65] op_sel_hi:[1,0]
	v_pk_mul_f32 v[6:7], v[6:7], v[64:65] op_sel_hi:[1,0]
	v_pk_mul_f32 v[4:5], v[4:5], v[64:65] op_sel_hi:[1,0]
	v_pk_mul_f32 v[2:3], v[2:3], v[64:65] op_sel_hi:[1,0]
	v_pk_mul_f32 v[0:1], v[0:1], v[64:65] op_sel_hi:[1,0]
.LBB0_600:
	v_cndmask_b32_e64 v76, v218, v219, s[36:37]
	v_add_f32_e32 v76, v217, v76
	v_cndmask_b32_e64 v77, v222, v223, s[36:37]
	v_fmac_f32_e32 v76, v213, v166
	v_add_f32_e32 v77, v221, v77
	v_fmac_f32_e32 v77, v76, v184
	v_cndmask_b32_e64 v76, v83, v84, s[36:37]
	v_add_f32_e32 v76, v82, v76
	v_cndmask_b32_e64 v74, v74, v75, s[36:37]
	v_fmac_f32_e32 v76, v77, v80
	v_add_f32_e32 v65, v65, v74
	v_fmac_f32_e32 v65, v76, v64
	v_cvt_pk_bf16_f32 v74, v85, v86
	v_cvt_pk_bf16_f32 v75, v87, v88
	v_cvt_pk_bf16_f32 v76, v89, v90
	v_cvt_pk_bf16_f32 v77, v91, v92
	ds_read_b64_tr_b16 v[84:85], v220 offset:33408
	ds_read_b64_tr_b16 v[86:87], v220 offset:34560
	ds_read_b64_tr_b16 v[90:91], v220 offset:34624
	ds_read_b64_tr_b16 v[224:225], v220 offset:33472
	ds_read_b64_tr_b16 v[82:83], v220 offset:32256
	ds_read_b64_tr_b16 v[88:89], v220 offset:35712
	ds_read_b64_tr_b16 v[222:223], v220 offset:32320
	ds_read_b64_tr_b16 v[92:93], v220 offset:35776
	v_cvt_pk_bf16_f32 v66, v66, v67
	v_cvt_pk_bf16_f32 v67, v68, v69
	v_cvt_pk_bf16_f32 v68, v70, v71
	v_cvt_pk_bf16_f32 v69, v72, v73
	s_nop 0
	s_waitcnt lgkmcnt(3)
	v_mfma_f32_32x32x16_bf16 v[0:15], v[82:85], v[74:77], v[0:15]
	s_waitcnt lgkmcnt(1)
	v_mfma_f32_32x32x16_bf16 v[16:31], v[222:225], v[74:77], v[16:31]
	v_mfma_f32_32x32x16_bf16 v[0:15], v[86:89], v[66:69], v[0:15]
	s_waitcnt lgkmcnt(0)
	v_mfma_f32_32x32x16_bf16 v[16:31], v[90:93], v[66:69], v[16:31]
	s_branch .LBB0_611

; #define LAS __attribute__((address_space(3)))
; DI float ex2(float x) { return __builtin_amdgcn_exp2f(x); }
; template <int MM> DI void smax_step_nb(const f32x16& s, unsigned vm, float& m, float& l, f32x16 (&o)[2], bf16x8 (&pf)[2], int lane) {
;     float mx = -1e30f;
; #pragma unroll
;     for (int i = 0; i < 16; ++i) mx = fmaxf(mx, s[i]);
;     if (MM == 1) mx = vm ? mx : -1e30f;
;     mx = fmaxf(mx, shx32(mx, lane));
;     const float mn = (mx > m + 8.0f) ? mx : m;
;     float mref = fmaxf(mn, -1e29f);
;     if (MM == 1) mref = vm ? mref : 3e38f;
;     const float alpha = ex2(m - mn);
;     float p[16], rs = 0.f;
; #pragma unroll
;     for (int i = 0; i < 16; ++i) { p[i] = ex2(s[i] - mref); rs += p[i]; }
;     rs += shx32(rs, lane);
;     l = l * alpha + rs;
;     if (__builtin_amdgcn_ballot_w64(mn != m) != 0ull) {
; #pragma unroll
;         for (int i = 0; i < 16; ++i) { o[0][i] *= alpha; o[1][i] *= alpha; }
;     }
;     m = mn;
;     pack_p(p, pf);
; }
; template <int MM> DI void tile128_pipe(LAS const char* K0, LAS const char* V0, LAS const char* K1, LAS const char* V1, const bf16x8 (&qf)[4], unsigned vm0, unsigned vm1,
;                                        float& m, float& l, f32x16 (&o)[2], int r, int h, int lane) {
;     f32x16 sa = qk_rows<0, 4>(K0, 0, qf, r, h), sb = qk_rows<0, 4>(K0, 32, qf, r, h);
;     bf16x8 pfa[2], pfb[2];
;     smax_step_nb<MM>(sa, vm0, m, l, o, pfa, lane);
;     sa = qk_rows<0, 4>(K1, 0, qf, r, h);
;     pv_rows(o, V0, 0, pfa, lane);
;     smax_step_nb<MM>(sb, vm0, m, l, o, pfb, lane);
;     sb = qk_rows<0, 4>(K1, 32, qf, r, h);
;     pv_rows(o, V0, 32, pfb, lane);
;     smax_step_nb<MM>(sa, vm1, m, l, o, pfa, lane);
;     pv_rows(o, V1, 0, pfa, lane);
;     smax_step_nb<MM>(sb, vm1, m, l, o, pfb, lane);
;     pv_rows(o, V1, 32, pfb, lane);
; }
.LBB0_604:
	v_cvt_pk_bf16_f32 v74, v48, v49
	v_cvt_pk_bf16_f32 v75, v50, v51
	ds_read_b128 v[48:51], v215 offset:18432
	ds_read_b128 v[82:85], v215 offset:18464
	ds_read_b128 v[86:89], v215 offset:18496
	ds_read_b128 v[90:93], v215 offset:18528
	v_cvt_pk_bf16_f32 v76, v52, v53
	v_cvt_pk_bf16_f32 v77, v54, v55
	v_cvt_pk_bf16_f32 v78, v56, v57
	v_cvt_pk_bf16_f32 v79, v58, v59
	v_cvt_pk_bf16_f32 v80, v60, v61
	v_cvt_pk_bf16_f32 v81, v62, v63
	s_nop 0
	s_waitcnt lgkmcnt(3)
	v_mfma_f32_32x32x16_bf16 v[48:63], v[48:51], v[96:99], 0
	s_waitcnt lgkmcnt(2)
	v_mfma_f32_32x32x16_bf16 v[48:63], v[82:85], v[100:103], v[48:63]
	s_waitcnt lgkmcnt(1)
	v_mfma_f32_32x32x16_bf16 v[48:63], v[86:89], v[104:107], v[48:63]
	s_waitcnt lgkmcnt(0)
	v_mfma_f32_32x32x16_bf16 v[48:63], v[90:93], v[108:111], v[48:63]
	s_nop 0
	v_add3_u32 v66, s10, v191, v171
	v_add_u32_e32 v69, v66, v186
	ds_read_b64_tr_b16 v[82:83], v69 offset:9216
	ds_read_b64_tr_b16 v[84:85], v69 offset:10368
	ds_read_b64_tr_b16 v[88:89], v69 offset:10432
	ds_read_b64_tr_b16 v[86:87], v69 offset:9280
	ds_read_b64_tr_b16 v[90:91], v69 offset:11520
	ds_read_b64_tr_b16 v[92:93], v69 offset:12672
	ds_read_b64_tr_b16 v[130:131], v69 offset:12736
	ds_read_b64_tr_b16 v[128:129], v69 offset:11584
	s_nop 0
	s_waitcnt lgkmcnt(6)
	v_mfma_f32_32x32x16_bf16 v[0:15], v[82:85], v[74:77], v[0:15]
	s_waitcnt lgkmcnt(4)
	v_mfma_f32_32x32x16_bf16 v[16:31], v[86:89], v[74:77], v[16:31]
	s_waitcnt lgkmcnt(2)
	v_mfma_f32_32x32x16_bf16 v[0:15], v[90:93], v[78:81], v[0:15]
	s_waitcnt lgkmcnt(0)
	v_mfma_f32_32x32x16_bf16 v[16:31], v[128:131], v[78:81], v[16:31]
	s_nop 0
	v_max3_f32 v66, v32, s15, v33
	v_max3_f32 v66, v66, v34, v35
	v_max3_f32 v66, v66, v36, v37
	v_max3_f32 v66, v66, v38, v39
	v_max3_f32 v66, v66, v40, v41
	v_max3_f32 v66, v66, v42, v43
	v_max3_f32 v66, v66, v44, v45
	v_max3_f32 v66, v66, v46, v47
	v_mov_b32_e32 v70, v66
	v_mov_b32_e32 v71, v66
	s_nop 1
	v_permlane32_swap_b32_e32 v70, v71
	v_max_f32_e32 v66, v70, v71
	v_add_f32_e32 v70, 0x41000000, v73
	v_cmp_gt_f32_e32 vcc, v66, v70
	s_nop 1
	v_cndmask_b32_e32 v74, v73, v66, vcc
	v_max_f32_e32 v66, 0xefa18f08, v74
	v_sub_f32_e32 v32, v32, v66
	v_exp_f32_e32 v32, v32
	v_sub_f32_e32 v33, v33, v66
	v_exp_f32_e32 v33, v33
	v_sub_f32_e32 v34, v34, v66
	v_exp_f32_e32 v34, v34
	v_sub_f32_e32 v35, v35, v66
	v_exp_f32_e32 v35, v35
	v_sub_f32_e32 v36, v36, v66
	v_exp_f32_e32 v36, v36
	v_sub_f32_e32 v37, v37, v66
	v_add_f32_e32 v70, v33, v32
	v_exp_f32_e32 v37, v37
	v_sub_f32_e32 v38, v38, v66
	v_add_f32_e32 v70, v34, v70
	v_exp_f32_e32 v38, v38
	v_sub_f32_e32 v39, v39, v66
	v_add_f32_e32 v70, v35, v70
	v_exp_f32_e32 v39, v39
	v_sub_f32_e32 v40, v40, v66
	v_add_f32_e32 v70, v36, v70
	v_exp_f32_e32 v40, v40
	v_sub_f32_e32 v41, v41, v66
	v_add_f32_e32 v70, v37, v70
	v_exp_f32_e32 v41, v41
	v_sub_f32_e32 v42, v42, v66
	v_add_f32_e32 v70, v38, v70
	v_exp_f32_e32 v42, v42
	v_sub_f32_e32 v43, v43, v66
	v_add_f32_e32 v70, v39, v70
	v_exp_f32_e32 v43, v43
	v_sub_f32_e32 v44, v44, v66
	v_add_f32_e32 v70, v40, v70
	v_exp_f32_e32 v44, v44
	v_sub_f32_e32 v45, v45, v66
	v_add_f32_e32 v70, v41, v70
	v_exp_f32_e32 v45, v45
	v_sub_f32_e32 v46, v46, v66
	v_add_f32_e32 v70, v42, v70
	v_exp_f32_e32 v46, v46
	v_sub_f32_e32 v47, v47, v66
	v_add_f32_e32 v70, v43, v70
	v_exp_f32_e32 v47, v47
	v_add_f32_e32 v66, v44, v70
	v_add_f32_e32 v66, v45, v66
	v_sub_f32_e32 v71, v73, v74
	v_add_f32_e32 v66, v46, v66
	v_add_f32_e32 v70, v47, v66
	v_exp_f32_e32 v66, v71
	v_mov_b32_e32 v71, v70
	v_mov_b32_e32 v72, v70
	s_nop 1
	v_permlane32_swap_b32_e32 v71, v72
	v_cmp_neq_f32_e32 vcc, v74, v73
	s_cbranch_vccz .LBB0_606
	v_pk_mul_f32 v[30:31], v[30:31], v[66:67] op_sel_hi:[1,0]
	v_pk_mul_f32 v[28:29], v[28:29], v[66:67] op_sel_hi:[1,0]
	v_pk_mul_f32 v[26:27], v[26:27], v[66:67] op_sel_hi:[1,0]
	v_pk_mul_f32 v[24:25], v[24:25], v[66:67] op_sel_hi:[1,0]
	v_pk_mul_f32 v[22:23], v[22:23], v[66:67] op_sel_hi:[1,0]
	v_pk_mul_f32 v[20:21], v[20:21], v[66:67] op_sel_hi:[1,0]
	v_pk_mul_f32 v[18:19], v[18:19], v[66:67] op_sel_hi:[1,0]
	v_pk_mul_f32 v[16:17], v[16:17], v[66:67] op_sel_hi:[1,0]
	v_pk_mul_f32 v[14:15], v[14:15], v[66:67] op_sel_hi:[1,0]
	v_pk_mul_f32 v[12:13], v[12:13], v[66:67] op_sel_hi:[1,0]
	v_pk_mul_f32 v[10:11], v[10:11], v[66:67] op_sel_hi:[1,0]
	v_pk_mul_f32 v[8:9], v[8:9], v[66:67] op_sel_hi:[1,0]
	v_pk_mul_f32 v[6:7], v[6:7], v[66:67] op_sel_hi:[1,0]
	v_pk_mul_f32 v[4:5], v[4:5], v[66:67] op_sel_hi:[1,0]
	v_pk_mul_f32 v[2:3], v[2:3], v[66:67] op_sel_hi:[1,0]
	v_pk_mul_f32 v[0:1], v[0:1], v[66:67] op_sel_hi:[1,0]
; #define LAS __attribute__((address_space(3)))
; DI float ex2(float x) { return __builtin_amdgcn_exp2f(x); }
; template <int MM> DI void smax_step_nb(const f32x16& s, unsigned vm, float& m, float& l, f32x16 (&o)[2], bf16x8 (&pf)[2], int lane) {
;     float mx = -1e30f;
; #pragma unroll
;     for (int i = 0; i < 16; ++i) mx = fmaxf(mx, s[i]);
;     if (MM == 1) mx = vm ? mx : -1e30f;
;     mx = fmaxf(mx, shx32(mx, lane));
;     const float mn = (mx > m + 8.0f) ? mx : m;
;     float mref = fmaxf(mn, -1e29f);
;     if (MM == 1) mref = vm ? mref : 3e38f;
;     const float alpha = ex2(m - mn);
;     float p[16], rs = 0.f;
; #pragma unroll
;     for (int i = 0; i < 16; ++i) { p[i] = ex2(s[i] - mref); rs += p[i]; }
;     rs += shx32(rs, lane);
;     l = l * alpha + rs;
;     if (__builtin_amdgcn_ballot_w64(mn != m) != 0ull) {
; #pragma unroll
;         for (int i = 0; i < 16; ++i) { o[0][i] *= alpha; o[1][i] *= alpha; }
;     }
;     m = mn;
;     pack_p(p, pf);
; }
; template <int MM> DI void tile128_pipe(LAS const char* K0, LAS const char* V0, LAS const char* K1, LAS const char* V1, const bf16x8 (&qf)[4], unsigned vm0, unsigned vm1,
;                                        float& m, float& l, f32x16 (&o)[2], int r, int h, int lane) {
;     f32x16 sa = qk_rows<0, 4>(K0, 0, qf, r, h), sb = qk_rows<0, 4>(K0, 32, qf, r, h);
;     bf16x8 pfa[2], pfb[2];
;     smax_step_nb<MM>(sa, vm0, m, l, o, pfa, lane);
;     sa = qk_rows<0, 4>(K1, 0, qf, r, h);
;     pv_rows(o, V0, 0, pfa, lane);
;     smax_step_nb<MM>(sb, vm0, m, l, o, pfb, lane);
;     sb = qk_rows<0, 4>(K1, 32, qf, r, h);
;     pv_rows(o, V0, 32, pfb, lane);
;     smax_step_nb<MM>(sa, vm1, m, l, o, pfa, lane);
;     pv_rows(o, V1, 0, pfa, lane);
;     smax_step_nb<MM>(sb, vm1, m, l, o, pfb, lane);
;     pv_rows(o, V1, 32, pfb, lane);
; }
.LBB0_606:
	v_cvt_pk_bf16_f32 v76, v32, v33
	v_cvt_pk_bf16_f32 v77, v34, v35
	ds_read_b128 v[32:35], v215 offset:23040
	ds_read_b128 v[84:87], v215 offset:23072
	ds_read_b128 v[88:91], v215 offset:23104
	ds_read_b128 v[92:95], v215 offset:23136
	v_cvt_pk_bf16_f32 v78, v36, v37
	v_cvt_pk_bf16_f32 v79, v38, v39
	v_cvt_pk_bf16_f32 v80, v40, v41
	v_cvt_pk_bf16_f32 v81, v42, v43
	v_cvt_pk_bf16_f32 v82, v44, v45
	v_cvt_pk_bf16_f32 v83, v46, v47
	s_nop 0
	s_waitcnt lgkmcnt(3)
	v_mfma_f32_32x32x16_bf16 v[32:47], v[32:35], v[96:99], 0
	s_waitcnt lgkmcnt(2)
	v_mfma_f32_32x32x16_bf16 v[32:47], v[84:87], v[100:103], v[32:47]
	s_waitcnt lgkmcnt(1)
	v_mfma_f32_32x32x16_bf16 v[32:47], v[88:91], v[104:107], v[32:47]
	s_waitcnt lgkmcnt(0)
	v_mfma_f32_32x32x16_bf16 v[32:47], v[92:95], v[108:111], v[32:47]
	s_nop 0
	ds_read_b64_tr_b16 v[84:85], v69 offset:13824
	ds_read_b64_tr_b16 v[86:87], v69 offset:14976
	ds_read_b64_tr_b16 v[90:91], v69 offset:15040
	ds_read_b64_tr_b16 v[88:89], v69 offset:13888
	ds_read_b64_tr_b16 v[92:93], v69 offset:16128
	ds_read_b64_tr_b16 v[94:95], v69 offset:17280
	ds_read_b64_tr_b16 v[130:131], v69 offset:17344
	ds_read_b64_tr_b16 v[128:129], v69 offset:16192
	s_nop 0
	s_waitcnt lgkmcnt(6)
	v_mfma_f32_32x32x16_bf16 v[0:15], v[84:87], v[76:79], v[0:15]
	s_waitcnt lgkmcnt(4)
	v_mfma_f32_32x32x16_bf16 v[16:31], v[88:91], v[76:79], v[16:31]
	s_waitcnt lgkmcnt(2)
	v_mfma_f32_32x32x16_bf16 v[0:15], v[92:95], v[80:83], v[0:15]
	s_waitcnt lgkmcnt(0)
	v_mfma_f32_32x32x16_bf16 v[16:31], v[128:131], v[80:83], v[16:31]
	s_nop 0
	v_max3_f32 v73, v48, s15, v49
	v_max3_f32 v73, v73, v50, v51
	v_max3_f32 v73, v73, v52, v53
	v_max3_f32 v73, v73, v54, v55
	v_max3_f32 v73, v73, v56, v57
	v_max3_f32 v73, v73, v58, v59
	v_max3_f32 v73, v73, v60, v61
	v_max3_f32 v73, v73, v62, v63
	v_mov_b32_e32 v75, v73
	v_mov_b32_e32 v76, v73
	s_nop 1
	v_permlane32_swap_b32_e32 v75, v76
	v_max_f32_e32 v73, v75, v76
	v_add_f32_e32 v75, 0x41000000, v74
	v_cmp_gt_f32_e32 vcc, v73, v75
	s_nop 1
	v_cndmask_b32_e32 v73, v74, v73, vcc
	v_max_f32_e32 v79, 0xefa18f08, v73
	v_sub_f32_e32 v48, v48, v79
	v_exp_f32_e32 v75, v48
	v_sub_f32_e32 v48, v49, v79
	v_exp_f32_e32 v76, v48
	v_sub_f32_e32 v48, v50, v79
	v_exp_f32_e32 v77, v48
	v_sub_f32_e32 v48, v51, v79
	v_exp_f32_e32 v78, v48
	v_sub_f32_e32 v49, v52, v79
	v_exp_f32_e32 v52, v49
	v_sub_f32_e32 v49, v53, v79
	v_add_f32_e32 v48, v76, v75
	v_exp_f32_e32 v53, v49
	v_sub_f32_e32 v49, v54, v79
	v_add_f32_e32 v48, v77, v48
	v_exp_f32_e32 v54, v49
	v_sub_f32_e32 v49, v55, v79
	v_add_f32_e32 v48, v78, v48
	v_exp_f32_e32 v55, v49
	v_sub_f32_e32 v49, v56, v79
	v_add_f32_e32 v48, v52, v48
	v_exp_f32_e32 v56, v49
	v_sub_f32_e32 v49, v57, v79
	v_add_f32_e32 v48, v53, v48
	v_exp_f32_e32 v57, v49
	v_sub_f32_e32 v49, v58, v79
	v_add_f32_e32 v48, v54, v48
	v_exp_f32_e32 v58, v49
	v_sub_f32_e32 v49, v59, v79
	v_add_f32_e32 v48, v55, v48
	v_exp_f32_e32 v59, v49
	v_sub_f32_e32 v49, v60, v79
	v_add_f32_e32 v48, v56, v48
	v_exp_f32_e32 v60, v49
	v_sub_f32_e32 v49, v61, v79
	v_add_f32_e32 v48, v57, v48
	v_exp_f32_e32 v61, v49
	v_sub_f32_e32 v49, v62, v79
	v_add_f32_e32 v48, v58, v48
	v_exp_f32_e32 v62, v49
	v_sub_f32_e32 v49, v63, v79
	v_add_f32_e32 v48, v59, v48
	v_exp_f32_e32 v63, v49
	v_add_f32_e32 v48, v60, v48
	v_add_f32_e32 v48, v61, v48
	v_sub_f32_e32 v80, v74, v73
	v_add_f32_e32 v48, v62, v48
	v_add_f32_e32 v49, v63, v48
	v_exp_f32_e32 v48, v80
	v_mov_b32_e32 v50, v49
	v_mov_b32_e32 v51, v49
	s_nop 1
	v_permlane32_swap_b32_e32 v50, v51
	v_cmp_neq_f32_e32 vcc, v73, v74
	s_cbranch_vccz .LBB0_608
	v_pk_mul_f32 v[30:31], v[30:31], v[48:49] op_sel_hi:[1,0]
	v_pk_mul_f32 v[28:29], v[28:29], v[48:49] op_sel_hi:[1,0]
	v_pk_mul_f32 v[26:27], v[26:27], v[48:49] op_sel_hi:[1,0]
	v_pk_mul_f32 v[24:25], v[24:25], v[48:49] op_sel_hi:[1,0]
	v_pk_mul_f32 v[22:23], v[22:23], v[48:49] op_sel_hi:[1,0]
	v_pk_mul_f32 v[20:21], v[20:21], v[48:49] op_sel_hi:[1,0]
	v_pk_mul_f32 v[18:19], v[18:19], v[48:49] op_sel_hi:[1,0]
	v_pk_mul_f32 v[16:17], v[16:17], v[48:49] op_sel_hi:[1,0]
	v_pk_mul_f32 v[14:15], v[14:15], v[48:49] op_sel_hi:[1,0]
	v_pk_mul_f32 v[12:13], v[12:13], v[48:49] op_sel_hi:[1,0]
	v_pk_mul_f32 v[10:11], v[10:11], v[48:49] op_sel_hi:[1,0]
	v_pk_mul_f32 v[8:9], v[8:9], v[48:49] op_sel_hi:[1,0]
	v_pk_mul_f32 v[6:7], v[6:7], v[48:49] op_sel_hi:[1,0]
	v_pk_mul_f32 v[4:5], v[4:5], v[48:49] op_sel_hi:[1,0]
	v_pk_mul_f32 v[2:3], v[2:3], v[48:49] op_sel_hi:[1,0]
	v_pk_mul_f32 v[0:1], v[0:1], v[48:49] op_sel_hi:[1,0]
; #define LAS __attribute__((address_space(3)))
; DI float ex2(float x) { return __builtin_amdgcn_exp2f(x); }
; template <int MM> DI void smax_step_nb(const f32x16& s, unsigned vm, float& m, float& l, f32x16 (&o)[2], bf16x8 (&pf)[2], int lane) {
;     float mx = -1e30f;
; #pragma unroll
;     for (int i = 0; i < 16; ++i) mx = fmaxf(mx, s[i]);
;     if (MM == 1) mx = vm ? mx : -1e30f;
;     mx = fmaxf(mx, shx32(mx, lane));
;     const float mn = (mx > m + 8.0f) ? mx : m;
;     float mref = fmaxf(mn, -1e29f);
;     if (MM == 1) mref = vm ? mref : 3e38f;
;     const float alpha = ex2(m - mn);
;     float p[16], rs = 0.f;
; #pragma unroll
;     for (int i = 0; i < 16; ++i) { p[i] = ex2(s[i] - mref); rs += p[i]; }
;     rs += shx32(rs, lane);
;     l = l * alpha + rs;
;     if (__builtin_amdgcn_ballot_w64(mn != m) != 0ull) {
; #pragma unroll
;         for (int i = 0; i < 16; ++i) { o[0][i] *= alpha; o[1][i] *= alpha; }
;     }
;     m = mn;
;     pack_p(p, pf);
; }
; template <int MM> DI void tile128_pipe(LAS const char* K0, LAS const char* V0, LAS const char* K1, LAS const char* V1, const bf16x8 (&qf)[4], unsigned vm0, unsigned vm1,
;                                        float& m, float& l, f32x16 (&o)[2], int r, int h, int lane) {
;     f32x16 sa = qk_rows<0, 4>(K0, 0, qf, r, h), sb = qk_rows<0, 4>(K0, 32, qf, r, h);
;     bf16x8 pfa[2], pfb[2];
;     smax_step_nb<MM>(sa, vm0, m, l, o, pfa, lane);
;     sa = qk_rows<0, 4>(K1, 0, qf, r, h);
;     pv_rows(o, V0, 0, pfa, lane);
;     smax_step_nb<MM>(sb, vm0, m, l, o, pfb, lane);
;     sb = qk_rows<0, 4>(K1, 32, qf, r, h);
;     pv_rows(o, V0, 32, pfb, lane);
;     smax_step_nb<MM>(sa, vm1, m, l, o, pfa, lane);
;     pv_rows(o, V1, 0, pfa, lane);
;     smax_step_nb<MM>(sb, vm1, m, l, o, pfb, lane);
;     pv_rows(o, V1, 32, pfb, lane);
; }
.LBB0_608:
	v_cvt_pk_bf16_f32 v74, v75, v76
	v_cvt_pk_bf16_f32 v75, v77, v78
	v_cvt_pk_bf16_f32 v76, v52, v53
	v_cvt_pk_bf16_f32 v77, v54, v55
	v_cvt_pk_bf16_f32 v52, v56, v57
	v_cvt_pk_bf16_f32 v53, v58, v59
	v_cvt_pk_bf16_f32 v54, v60, v61
	v_cvt_pk_bf16_f32 v55, v62, v63
	ds_read_b64_tr_b16 v[56:57], v69 offset:27648
	ds_read_b64_tr_b16 v[58:59], v69 offset:28800
	ds_read_b64_tr_b16 v[60:61], v69 offset:29952
	ds_read_b64_tr_b16 v[62:63], v69 offset:31104
	ds_read_b64_tr_b16 v[78:79], v69 offset:27712
	ds_read_b64_tr_b16 v[80:81], v69 offset:28864
	ds_read_b64_tr_b16 v[82:83], v69 offset:30016
	ds_read_b64_tr_b16 v[84:85], v69 offset:31168
	s_nop 0
	s_waitcnt lgkmcnt(6)
	v_mfma_f32_32x32x16_bf16 v[0:15], v[56:59], v[74:77], v[0:15]
	s_waitcnt lgkmcnt(2)
	v_mfma_f32_32x32x16_bf16 v[16:31], v[78:81], v[74:77], v[16:31]
	v_mfma_f32_32x32x16_bf16 v[0:15], v[60:63], v[52:55], v[0:15]
	s_waitcnt lgkmcnt(0)
	v_mfma_f32_32x32x16_bf16 v[16:31], v[82:85], v[52:55], v[16:31]
	s_nop 0
	v_max3_f32 v52, v32, s15, v33
	v_max3_f32 v52, v52, v34, v35
	v_max3_f32 v52, v52, v36, v37
	v_max3_f32 v52, v52, v38, v39
	v_max3_f32 v52, v52, v40, v41
	v_max3_f32 v52, v52, v42, v43
	v_max3_f32 v52, v52, v44, v45
	v_max3_f32 v52, v52, v46, v47
	v_mov_b32_e32 v53, v52
	v_mov_b32_e32 v54, v52
	s_nop 1
	v_permlane32_swap_b32_e32 v53, v54
	v_max_f32_e32 v52, v53, v54
	v_add_f32_e32 v53, 0x41000000, v73
	v_cmp_gt_f32_e32 vcc, v52, v53
	s_nop 1
	v_cndmask_b32_e32 v81, v73, v52, vcc
	v_max_f32_e32 v60, 0xefa18f08, v81
	v_sub_f32_e32 v32, v32, v60
	v_exp_f32_e32 v52, v32
	v_sub_f32_e32 v32, v33, v60
	v_exp_f32_e32 v53, v32
	v_sub_f32_e32 v32, v34, v60
	v_exp_f32_e32 v54, v32
	v_sub_f32_e32 v32, v35, v60
	v_exp_f32_e32 v55, v32
	v_sub_f32_e32 v33, v36, v60
	v_exp_f32_e32 v56, v33
	v_sub_f32_e32 v33, v37, v60
	v_add_f32_e32 v32, v53, v52
	v_exp_f32_e32 v57, v33
	v_sub_f32_e32 v33, v38, v60
	v_add_f32_e32 v32, v54, v32
	v_exp_f32_e32 v58, v33
	v_sub_f32_e32 v33, v39, v60
	v_add_f32_e32 v32, v55, v32
	v_exp_f32_e32 v59, v33
	v_sub_f32_e32 v33, v40, v60
	v_add_f32_e32 v32, v56, v32
	v_exp_f32_e32 v33, v33
	v_sub_f32_e32 v34, v41, v60
	v_add_f32_e32 v32, v57, v32
	v_exp_f32_e32 v34, v34
	v_sub_f32_e32 v35, v42, v60
	v_add_f32_e32 v32, v58, v32
	v_exp_f32_e32 v35, v35
	v_sub_f32_e32 v36, v43, v60
	v_add_f32_e32 v32, v59, v32
	v_exp_f32_e32 v36, v36
	v_sub_f32_e32 v37, v44, v60
	v_add_f32_e32 v32, v33, v32
	v_exp_f32_e32 v37, v37
	v_sub_f32_e32 v38, v45, v60
	v_add_f32_e32 v32, v34, v32
	v_exp_f32_e32 v38, v38
	v_sub_f32_e32 v39, v46, v60
	v_add_f32_e32 v32, v35, v32
	v_exp_f32_e32 v39, v39
	v_sub_f32_e32 v40, v47, v60
	v_add_f32_e32 v32, v36, v32
	v_exp_f32_e32 v40, v40
	v_add_f32_e32 v32, v37, v32
	v_add_f32_e32 v32, v38, v32
	v_sub_f32_e32 v61, v73, v81
	v_add_f32_e32 v32, v39, v32
	v_add_f32_e32 v41, v40, v32
	v_exp_f32_e32 v32, v61
	v_mov_b32_e32 v42, v41
	v_mov_b32_e32 v43, v41
	s_nop 1
	v_permlane32_swap_b32_e32 v42, v43
	v_cmp_neq_f32_e32 vcc, v81, v73
	s_cbranch_vccz .LBB0_610
	v_pk_mul_f32 v[30:31], v[30:31], v[32:33] op_sel_hi:[1,0]
	v_pk_mul_f32 v[28:29], v[28:29], v[32:33] op_sel_hi:[1,0]
	v_pk_mul_f32 v[26:27], v[26:27], v[32:33] op_sel_hi:[1,0]
	v_pk_mul_f32 v[24:25], v[24:25], v[32:33] op_sel_hi:[1,0]
	v_pk_mul_f32 v[22:23], v[22:23], v[32:33] op_sel_hi:[1,0]
	v_pk_mul_f32 v[20:21], v[20:21], v[32:33] op_sel_hi:[1,0]
	v_pk_mul_f32 v[18:19], v[18:19], v[32:33] op_sel_hi:[1,0]
	v_pk_mul_f32 v[16:17], v[16:17], v[32:33] op_sel_hi:[1,0]
	v_pk_mul_f32 v[14:15], v[14:15], v[32:33] op_sel_hi:[1,0]
	v_pk_mul_f32 v[12:13], v[12:13], v[32:33] op_sel_hi:[1,0]
	v_pk_mul_f32 v[10:11], v[10:11], v[32:33] op_sel_hi:[1,0]
	v_pk_mul_f32 v[8:9], v[8:9], v[32:33] op_sel_hi:[1,0]
	v_pk_mul_f32 v[6:7], v[6:7], v[32:33] op_sel_hi:[1,0]
	v_pk_mul_f32 v[4:5], v[4:5], v[32:33] op_sel_hi:[1,0]
	v_pk_mul_f32 v[2:3], v[2:3], v[32:33] op_sel_hi:[1,0]
	v_pk_mul_f32 v[0:1], v[0:1], v[32:33] op_sel_hi:[1,0]
.LBB0_610:
	v_cndmask_b32_e64 v44, v67, v68, s[36:37]
	v_add_f32_e32 v44, v65, v44
	v_cndmask_b32_e64 v45, v71, v72, s[36:37]
	v_fmac_f32_e32 v44, v213, v64
	v_add_f32_e32 v45, v70, v45
	v_fmac_f32_e32 v45, v44, v66
	v_cndmask_b32_e64 v44, v50, v51, s[36:37]
	v_add_f32_e32 v44, v49, v44
	v_cndmask_b32_e64 v42, v42, v43, s[36:37]
	v_fmac_f32_e32 v44, v45, v48
	v_add_f32_e32 v65, v41, v42
	v_fmac_f32_e32 v65, v44, v32
	v_cvt_pk_bf16_f32 v42, v52, v53
	v_cvt_pk_bf16_f32 v43, v54, v55
	v_cvt_pk_bf16_f32 v44, v56, v57
	v_cvt_pk_bf16_f32 v45, v58, v59
	ds_read_b64_tr_b16 v[48:49], v69 offset:33408
	ds_read_b64_tr_b16 v[50:51], v69 offset:34560
	ds_read_b64_tr_b16 v[54:55], v69 offset:34624
	ds_read_b64_tr_b16 v[60:61], v69 offset:33472
	ds_read_b64_tr_b16 v[46:47], v69 offset:32256
	ds_read_b64_tr_b16 v[52:53], v69 offset:35712
	ds_read_b64_tr_b16 v[58:59], v69 offset:32320
	ds_read_b64_tr_b16 v[56:57], v69 offset:35776
	v_cvt_pk_bf16_f32 v32, v33, v34
	v_cvt_pk_bf16_f32 v33, v35, v36
	v_cvt_pk_bf16_f32 v34, v37, v38
	v_cvt_pk_bf16_f32 v35, v39, v40
	s_nop 0
	s_waitcnt lgkmcnt(1)
	v_mfma_f32_32x32x16_bf16 v[16:31], v[58:61], v[42:45], v[16:31]
	v_mfma_f32_32x32x16_bf16 v[0:15], v[46:49], v[42:45], v[0:15]
	s_waitcnt lgkmcnt(0)
	v_mfma_f32_32x32x16_bf16 v[16:31], v[54:57], v[32:35], v[16:31]
	v_mfma_f32_32x32x16_bf16 v[0:15], v[50:53], v[32:35], v[0:15]
.LBB0_611:
	s_nop 0
	s_mov_b32 s10, 9
	v_mov_b32_e32 v214, v81
	v_mov_b32_e32 v213, v65

; template <int MM> DI void smax_step_nb(const f32x16& s, unsigned vm, float& m, float& l, f32x16 (&o)[2], bf16x8 (&pf)[2], int lane) {
;     float mx = -1e30f;
; #pragma unroll
;     for (int i = 0; i < 16; ++i) mx = fmaxf(mx, s[i]);
;     if (MM == 1) mx = vm ? mx : -1e30f;
;     mx = fmaxf(mx, shx32(mx, lane));
;     const float mn = (mx > m + 8.0f) ? mx : m;
;     float mref = fmaxf(mn, -1e29f);
;     if (MM == 1) mref = vm ? mref : 3e38f;
;     const float alpha = ex2(m - mn);
;     float p[16], rs = 0.f;
; #pragma unroll
;     for (int i = 0; i < 16; ++i) { p[i] = ex2(s[i] - mref); rs += p[i]; }
;     rs += shx32(rs, lane);
;     l = l * alpha + rs;
;     if (__builtin_amdgcn_ballot_w64(mn != m) != 0ull) {
; #pragma unroll
;         for (int i = 0; i < 16; ++i) { o[0][i] *= alpha; o[1][i] *= alpha; }
;     }
;     m = mn;
;     pack_p(p, pf);
; }
; template <int MODE, bool PRE = false> ...
;     ...
;         LAS char* Kl = lds + (sti & 1) * 4 * TILE_B + half * 2 * TILE_B; LAS char* Vl = Kl + TILE_B;
;         bool full2 = (64 * kt + 63 <= q0w);
;         if (MODE == MODE_NWIN) full2 = full2 && (64 * kt > q0w + 31 - 512);
;         if (full2 && (MODE != MODE_DIFF || DIFF_MERGED)) {
;             bool lsel = true;
;             if (MODE == MODE_MOBA) lsel = ((sel >> (kt >> 2)) & 1ull) != 0ull;
;             if (MODE == MODE_NSEL) lsel = ((sel >> kt) & 1ull) != 0ull;
;             const unsigned long long selb = __builtin_amdgcn_ballot_w64(lsel);
;             if (selb != 0ull) {
;                 const unsigned vm = lsel ? 1u : 0u; bf16x8 pf[4];
;                 if (MODE == MODE_DIFF) {
;                     { const f32x16 sa = qk_rows<0, 2>(Kl, 0, qf, r, h), sb = qk_rows<0, 2>(Kl, 32, qf, r, h);
;                       smax_step64<0>(sa, sb, vm, m1, l1, o1, pf, lane); __builtin_amdgcn_sched_barrier(0); pv_rows64(o1, Vl, pf, lane); }
;                     __builtin_amdgcn_sched_barrier(0);
;                     { const f32x16 sa = qk_rows<2, 4>(Kl, 0, qf, r, h), sb = qk_rows<2, 4>(Kl, 32, qf, r, h);
;                       smax_step64<0>(sa, sb, vm, m2, l2, o2, pf, lane); __builtin_amdgcn_sched_barrier(0); pv_rows64(o2, Vl, pf, lane); }
;                 } else {
;     ...
;                     if (selb == ~0ull) tile64_pipe<0>(Kl, Vl, qf, vm, m1, l1, o1, r, h, lane); else tile64_pipe<1>(Kl, Vl, qf, vm, m1, l1, o1, r, h, lane);
.LBB0_623:
	s_mov_b64 s[38:39], 0
	s_andn2_b64 vcc, exec, s[48:49]
	v_add3_u32 v83, s11, v190, v168
	v_mov_b32_e32 v65, v213
	v_mov_b32_e32 v82, v214
	s_cbranch_vccnz .LBB0_629
	ds_read_b128 v[32:35], v83
	ds_read_b128 v[48:51], v83 offset:32
	ds_read_b128 v[52:55], v83 offset:64
	ds_read_b128 v[56:59], v83 offset:96
	s_nop 0
	s_waitcnt lgkmcnt(3)
	v_mfma_f32_32x32x16_bf16 v[32:47], v[32:35], v[96:99], 0
	s_waitcnt lgkmcnt(2)
	v_mfma_f32_32x32x16_bf16 v[32:47], v[48:51], v[100:103], v[32:47]
	s_waitcnt lgkmcnt(1)
	v_mfma_f32_32x32x16_bf16 v[32:47], v[52:55], v[104:107], v[32:47]
	s_waitcnt lgkmcnt(0)
	v_mfma_f32_32x32x16_bf16 v[32:47], v[56:59], v[108:111], v[32:47]
	s_nop 0
	ds_read_b128 v[48:51], v83 offset:4608
	ds_read_b128 v[52:55], v83 offset:4640
	ds_read_b128 v[56:59], v83 offset:4672
	ds_read_b128 v[60:63], v83 offset:4704
	s_nop 0
	s_waitcnt lgkmcnt(3)
	v_mfma_f32_32x32x16_bf16 v[64:79], v[48:51], v[96:99], 0
	s_waitcnt lgkmcnt(2)
	v_mfma_f32_32x32x16_bf16 v[64:79], v[52:55], v[100:103], v[64:79]
	s_waitcnt lgkmcnt(1)
	v_mfma_f32_32x32x16_bf16 v[64:79], v[56:59], v[104:107], v[64:79]
	s_waitcnt lgkmcnt(0)
	v_mfma_f32_32x32x16_bf16 v[64:79], v[60:63], v[108:111], v[64:79]
	s_nop 0
	v_max3_f32 v48, v32, s15, v33
	v_max3_f32 v48, v48, v34, v35
	v_max3_f32 v48, v48, v36, v37
	v_max3_f32 v48, v48, v38, v39
	v_max3_f32 v48, v48, v40, v41
	v_max3_f32 v48, v48, v42, v43
	v_max3_f32 v48, v48, v44, v45
	v_max3_f32 v48, v48, v46, v47
	v_cndmask_b32_e64 v48, v208, v48, s[0:1]
	v_mov_b32_e32 v49, v48
	v_mov_b32_e32 v50, v48
	s_nop 1
	v_permlane32_swap_b32_e32 v49, v50
	v_max_f32_e32 v48, v49, v50
	v_add_f32_e32 v49, 0x41000000, v214
	v_cmp_gt_f32_e32 vcc, v48, v49
	s_nop 1
	v_cndmask_b32_e32 v88, v214, v48, vcc
	v_max_f32_e32 v48, 0xefa18f08, v88
	v_cndmask_b32_e64 v48, v209, v48, s[0:1]
	v_sub_f32_e32 v32, v32, v48
	v_exp_f32_e32 v82, v32
	v_sub_f32_e32 v32, v33, v48
	v_exp_f32_e32 v87, v32
	v_sub_f32_e32 v32, v34, v48
	v_exp_f32_e32 v89, v32
	v_sub_f32_e32 v32, v35, v48
	v_exp_f32_e32 v90, v32
	v_sub_f32_e32 v33, v36, v48
	v_exp_f32_e32 v91, v33
	v_sub_f32_e32 v33, v37, v48
	v_add_f32_e32 v32, v87, v82
	v_exp_f32_e32 v92, v33
	v_sub_f32_e32 v33, v38, v48
	v_add_f32_e32 v32, v89, v32
	v_exp_f32_e32 v93, v33
	v_sub_f32_e32 v33, v39, v48
	v_add_f32_e32 v32, v90, v32
	v_exp_f32_e32 v94, v33
	v_sub_f32_e32 v33, v40, v48
	v_add_f32_e32 v32, v91, v32
	v_exp_f32_e32 v95, v33
	v_sub_f32_e32 v33, v41, v48
	v_add_f32_e32 v32, v92, v32
	v_exp_f32_e32 v128, v33
	v_sub_f32_e32 v33, v42, v48
	v_add_f32_e32 v32, v93, v32
	v_exp_f32_e32 v129, v33
	v_sub_f32_e32 v33, v43, v48
	v_add_f32_e32 v32, v94, v32
	v_exp_f32_e32 v130, v33
	v_sub_f32_e32 v33, v44, v48
	v_add_f32_e32 v32, v95, v32
	v_exp_f32_e32 v131, v33
	v_sub_f32_e32 v33, v45, v48
	v_add_f32_e32 v32, v128, v32
	v_exp_f32_e32 v132, v33
	v_sub_f32_e32 v33, v46, v48
	v_add_f32_e32 v32, v129, v32
	v_exp_f32_e32 v133, v33
	v_sub_f32_e32 v33, v47, v48
	v_add_f32_e32 v32, v130, v32
	v_exp_f32_e32 v134, v33
	v_add_f32_e32 v32, v131, v32
	v_sub_f32_e32 v49, v214, v88
	v_add_f32_e32 v32, v132, v32
	v_add_f32_e32 v32, v133, v32
	v_exp_f32_e32 v80, v49
	v_add_f32_e32 v84, v134, v32
	v_mov_b32_e32 v85, v84
	v_mov_b32_e32 v86, v84
	v_mov_b64_e32 v[62:63], v[30:31]
	s_nop 0
	v_permlane32_swap_b32_e32 v85, v86
	v_cmp_neq_f32_e32 vcc, v88, v214
	v_mov_b64_e32 v[60:61], v[28:29]
	v_mov_b64_e32 v[58:59], v[26:27]
	v_mov_b64_e32 v[56:57], v[24:25]
	v_mov_b64_e32 v[54:55], v[22:23]
	v_mov_b64_e32 v[52:53], v[20:21]
	v_mov_b64_e32 v[50:51], v[18:19]
	v_mov_b64_e32 v[48:49], v[16:17]
	v_mov_b64_e32 v[46:47], v[14:15]
	v_mov_b64_e32 v[44:45], v[12:13]
	v_mov_b64_e32 v[42:43], v[10:11]
	v_mov_b64_e32 v[40:41], v[8:9]
	v_mov_b64_e32 v[38:39], v[6:7]
	v_mov_b64_e32 v[36:37], v[4:5]
	v_mov_b64_e32 v[34:35], v[2:3]
	v_mov_b64_e32 v[32:33], v[0:1]
	s_cbranch_vccz .LBB0_626
	v_pk_mul_f32 v[62:63], v[30:31], v[80:81] op_sel_hi:[1,0]
	v_pk_mul_f32 v[60:61], v[28:29], v[80:81] op_sel_hi:[1,0]
	v_pk_mul_f32 v[58:59], v[26:27], v[80:81] op_sel_hi:[1,0]
	v_pk_mul_f32 v[56:57], v[24:25], v[80:81] op_sel_hi:[1,0]
	v_pk_mul_f32 v[54:55], v[22:23], v[80:81] op_sel_hi:[1,0]
	v_pk_mul_f32 v[52:53], v[20:21], v[80:81] op_sel_hi:[1,0]
	v_pk_mul_f32 v[50:51], v[18:19], v[80:81] op_sel_hi:[1,0]
	v_pk_mul_f32 v[48:49], v[16:17], v[80:81] op_sel_hi:[1,0]
	v_pk_mul_f32 v[46:47], v[14:15], v[80:81] op_sel_hi:[1,0]
	v_pk_mul_f32 v[44:45], v[12:13], v[80:81] op_sel_hi:[1,0]
	v_pk_mul_f32 v[42:43], v[10:11], v[80:81] op_sel_hi:[1,0]
	v_pk_mul_f32 v[40:41], v[8:9], v[80:81] op_sel_hi:[1,0]
	v_pk_mul_f32 v[38:39], v[6:7], v[80:81] op_sel_hi:[1,0]
	v_pk_mul_f32 v[36:37], v[4:5], v[80:81] op_sel_hi:[1,0]
	v_pk_mul_f32 v[34:35], v[2:3], v[80:81] op_sel_hi:[1,0]
	v_pk_mul_f32 v[32:33], v[0:1], v[80:81] op_sel_hi:[1,0]
; #define LAS __attribute__((address_space(3)))
; #define MFMA32(a, b, c) __builtin_amdgcn_mfma_f32_32x32x16_bf16((a), (b), (c), 0, 0, 0)
; DI float ex2(float x) { return __builtin_amdgcn_exp2f(x); }
; DI void pv_rows(f32x16 (&o)[2], LAS const char* Vl, int row0, const bf16x8 (&pf)[2], int lane) {
;     const int h = lane >> 5, i = lane & 15, grp = (lane >> 4) & 1;
;     LAS const char* base = Vl + (row0 + 4 * h + (i >> 2)) * KP + grp * 32 + (i & 3) * 8;
;     bf16x8 vf[2][2];
; #pragma unroll
;     for (int dt = 0; dt < 2; ++dt)
; #pragma unroll
;         for (int s2 = 0; s2 < 2; ++s2) {
;             const s16x4 lo = vtr(base + (16 * s2) * KP + dt * 64), hi = vtr(base + (16 * s2 + 8) * KP + dt * 64);
;             vf[dt][s2] = (bf16x8){lo[0], lo[1], lo[2], lo[3], hi[0], hi[1], hi[2], hi[3]};
;         }
;     __builtin_amdgcn_s_setprio(1);
; #pragma unroll
;     for (int s2 = 0; s2 < 2; ++s2)
; #pragma unroll
;         for (int dt = 0; dt < 2; ++dt) o[dt] = MFMA32(vf[dt][s2], pf[s2], o[dt]);
;     __builtin_amdgcn_s_setprio(0);
; }
; template <int MM> DI void smax_step_nb(const f32x16& s, unsigned vm, float& m, float& l, f32x16 (&o)[2], bf16x8 (&pf)[2], int lane) {
;     float mx = -1e30f;
; #pragma unroll
;     for (int i = 0; i < 16; ++i) mx = fmaxf(mx, s[i]);
;     if (MM == 1) mx = vm ? mx : -1e30f;
;     mx = fmaxf(mx, shx32(mx, lane));
;     const float mn = (mx > m + 8.0f) ? mx : m;
;     float mref = fmaxf(mn, -1e29f);
;     if (MM == 1) mref = vm ? mref : 3e38f;
;     const float alpha = ex2(m - mn);
;     float p[16], rs = 0.f;
; #pragma unroll
;     for (int i = 0; i < 16; ++i) { p[i] = ex2(s[i] - mref); rs += p[i]; }
;     rs += shx32(rs, lane);
;     l = l * alpha + rs;
;     if (__builtin_amdgcn_ballot_w64(mn != m) != 0ull) {
; #pragma unroll
;         for (int i = 0; i < 16; ++i) { o[0][i] *= alpha; o[1][i] *= alpha; }
;     }
;     m = mn;
;     pack_p(p, pf);
; }
; template <int MM> DI void tile64_pipe(LAS const char* Kl, LAS const char* Vl, const bf16x8 (&qf)[4], unsigned vm, float& m, float& l, f32x16 (&o)[2], int r, int h, int lane) {
;     const f32x16 sa = qk_rows<0, 4>(Kl, 0, qf, r, h), sb = qk_rows<0, 4>(Kl, 32, qf, r, h);
;     bf16x8 pfa[2], pfb[2];
;     smax_step_nb<MM>(sa, vm, m, l, o, pfa, lane);
;     pv_rows(o, Vl, 0, pfa, lane);
;     smax_step_nb<MM>(sb, vm, m, l, o, pfb, lane);
;     pv_rows(o, Vl, 32, pfb, lane);
; }
.LBB0_626:
	v_cvt_pk_bf16_f32 v136, v82, v87
	v_add3_u32 v82, s11, v191, v171
	v_add_u32_e32 v87, v82, v186
	v_cvt_pk_bf16_f32 v137, v89, v90
	v_cvt_pk_bf16_f32 v138, v91, v92
	v_cvt_pk_bf16_f32 v139, v93, v94
	v_cvt_pk_bf16_f32 v90, v95, v128
	v_cvt_pk_bf16_f32 v91, v129, v130
	v_cvt_pk_bf16_f32 v92, v131, v132
	v_cvt_pk_bf16_f32 v93, v133, v134
	ds_read_b64_tr_b16 v[128:129], v87 offset:9216
	ds_read_b64_tr_b16 v[130:131], v87 offset:10368
	ds_read_b64_tr_b16 v[132:133], v87 offset:11520
	ds_read_b64_tr_b16 v[134:135], v87 offset:12672
	ds_read_b64_tr_b16 v[140:141], v87 offset:9280
	ds_read_b64_tr_b16 v[142:143], v87 offset:10432
	ds_read_b64_tr_b16 v[144:145], v87 offset:11584
	ds_read_b64_tr_b16 v[146:147], v87 offset:12736
	s_nop 0
	s_waitcnt lgkmcnt(6)
	v_mfma_f32_32x32x16_bf16 v[32:47], v[128:131], v[136:139], v[32:47]
	s_waitcnt lgkmcnt(2)
	v_mfma_f32_32x32x16_bf16 v[48:63], v[140:143], v[136:139], v[48:63]
	v_mfma_f32_32x32x16_bf16 v[32:47], v[132:135], v[90:93], v[32:47]
	s_waitcnt lgkmcnt(0)
	v_mfma_f32_32x32x16_bf16 v[48:63], v[144:147], v[90:93], v[48:63]
	s_nop 0
	v_max3_f32 v82, v64, s15, v65
	v_max3_f32 v82, v82, v66, v67
	v_max3_f32 v82, v82, v68, v69
	v_max3_f32 v82, v82, v70, v71
	v_max3_f32 v82, v82, v72, v73
	v_max3_f32 v82, v82, v74, v75
	v_max3_f32 v82, v82, v76, v77
	v_max3_f32 v82, v82, v78, v79
	v_cndmask_b32_e64 v82, v208, v82, s[0:1]
	v_mov_b32_e32 v89, v82
	v_mov_b32_e32 v90, v82
	s_nop 1
	v_permlane32_swap_b32_e32 v89, v90
	v_max_f32_e32 v82, v89, v90
	v_add_f32_e32 v89, 0x41000000, v88
	v_cmp_gt_f32_e32 vcc, v82, v89
	s_nop 1
	v_cndmask_b32_e32 v82, v88, v82, vcc
	v_max_f32_e32 v89, 0xefa18f08, v82
	v_cndmask_b32_e64 v91, v209, v89, s[0:1]
	v_sub_f32_e32 v64, v64, v91
	v_exp_f32_e32 v89, v64
	v_sub_f32_e32 v64, v65, v91
	v_exp_f32_e32 v90, v64
	v_sub_f32_e32 v64, v66, v91
	v_exp_f32_e32 v66, v64
	v_sub_f32_e32 v64, v67, v91
	v_exp_f32_e32 v67, v64
	v_sub_f32_e32 v65, v68, v91
	v_exp_f32_e32 v68, v65
	v_sub_f32_e32 v65, v69, v91
	v_add_f32_e32 v64, v90, v89
	v_exp_f32_e32 v69, v65
	v_sub_f32_e32 v65, v70, v91
	v_add_f32_e32 v64, v66, v64
	v_exp_f32_e32 v70, v65
	v_sub_f32_e32 v65, v71, v91
	v_add_f32_e32 v64, v67, v64
	v_exp_f32_e32 v71, v65
	v_sub_f32_e32 v65, v72, v91
	v_add_f32_e32 v64, v68, v64
	v_exp_f32_e32 v72, v65
	v_sub_f32_e32 v65, v73, v91
	v_add_f32_e32 v64, v69, v64
	v_exp_f32_e32 v73, v65
	v_sub_f32_e32 v65, v74, v91
	v_add_f32_e32 v64, v70, v64
	v_exp_f32_e32 v74, v65
	v_sub_f32_e32 v65, v75, v91
	v_add_f32_e32 v64, v71, v64
	v_exp_f32_e32 v75, v65
	v_sub_f32_e32 v65, v76, v91
	v_add_f32_e32 v64, v72, v64
	v_exp_f32_e32 v76, v65
	v_sub_f32_e32 v65, v77, v91
	v_add_f32_e32 v64, v73, v64
	v_exp_f32_e32 v77, v65
	v_sub_f32_e32 v65, v78, v91
	v_add_f32_e32 v64, v74, v64
	v_exp_f32_e32 v78, v65
	v_sub_f32_e32 v65, v79, v91
	v_add_f32_e32 v64, v75, v64
	v_exp_f32_e32 v79, v65
	v_add_f32_e32 v64, v76, v64
	v_add_f32_e32 v64, v77, v64
	v_sub_f32_e32 v92, v88, v82
	v_add_f32_e32 v64, v78, v64
	v_add_f32_e32 v65, v79, v64
	v_exp_f32_e32 v64, v92
	v_mov_b32_e32 v91, v65
	v_mov_b32_e32 v92, v65
	s_nop 1
	v_permlane32_swap_b32_e32 v91, v92
	v_cmp_neq_f32_e32 vcc, v82, v88
	s_cbranch_vccz .LBB0_628
	v_pk_mul_f32 v[62:63], v[62:63], v[64:65] op_sel_hi:[1,0]
	v_pk_mul_f32 v[60:61], v[60:61], v[64:65] op_sel_hi:[1,0]
	v_pk_mul_f32 v[58:59], v[58:59], v[64:65] op_sel_hi:[1,0]
	v_pk_mul_f32 v[56:57], v[56:57], v[64:65] op_sel_hi:[1,0]
	v_pk_mul_f32 v[54:55], v[54:55], v[64:65] op_sel_hi:[1,0]
	v_pk_mul_f32 v[52:53], v[52:53], v[64:65] op_sel_hi:[1,0]
	v_pk_mul_f32 v[50:51], v[50:51], v[64:65] op_sel_hi:[1,0]
	v_pk_mul_f32 v[48:49], v[48:49], v[64:65] op_sel_hi:[1,0]
	v_pk_mul_f32 v[46:47], v[46:47], v[64:65] op_sel_hi:[1,0]
	v_pk_mul_f32 v[44:45], v[44:45], v[64:65] op_sel_hi:[1,0]
	v_pk_mul_f32 v[42:43], v[42:43], v[64:65] op_sel_hi:[1,0]
	v_pk_mul_f32 v[40:41], v[40:41], v[64:65] op_sel_hi:[1,0]
	v_pk_mul_f32 v[38:39], v[38:39], v[64:65] op_sel_hi:[1,0]
	v_pk_mul_f32 v[36:37], v[36:37], v[64:65] op_sel_hi:[1,0]
	v_pk_mul_f32 v[34:35], v[34:35], v[64:65] op_sel_hi:[1,0]
	v_pk_mul_f32 v[32:33], v[32:33], v[64:65] op_sel_hi:[1,0]
.LBB0_628:
	v_cndmask_b32_e64 v85, v85, v86, s[36:37]
	v_add_f32_e32 v84, v84, v85
	v_fmac_f32_e32 v84, v213, v80
	v_cndmask_b32_e64 v80, v91, v92, s[36:37]
	v_add_f32_e32 v65, v65, v80
	v_fmac_f32_e32 v65, v84, v64
	v_cvt_pk_bf16_f32 v88, v89, v90
	v_cvt_pk_bf16_f32 v89, v66, v67
	v_cvt_pk_bf16_f32 v90, v68, v69
	v_cvt_pk_bf16_f32 v91, v70, v71
	v_cvt_pk_bf16_f32 v66, v72, v73
	v_cvt_pk_bf16_f32 v67, v74, v75
	v_cvt_pk_bf16_f32 v68, v76, v77
	ds_read_b64_tr_b16 v[70:71], v87 offset:13824
	ds_read_b64_tr_b16 v[72:73], v87 offset:14976
	ds_read_b64_tr_b16 v[74:75], v87 offset:16128
	ds_read_b64_tr_b16 v[76:77], v87 offset:17280
	ds_read_b64_tr_b16 v[92:93], v87 offset:13888
	ds_read_b64_tr_b16 v[94:95], v87 offset:15040
	ds_read_b64_tr_b16 v[84:85], v87 offset:16192
	ds_read_b64_tr_b16 v[86:87], v87 offset:17344
	v_cvt_pk_bf16_f32 v69, v78, v79
	s_nop 0
	s_waitcnt lgkmcnt(6)
	v_mfma_f32_32x32x16_bf16 v[32:47], v[70:73], v[88:91], v[32:47]
	s_mov_b64 s[42:43], 0
	s_mov_b64 s[38:39], -1
	s_waitcnt lgkmcnt(2)
	v_mfma_f32_32x32x16_bf16 v[48:63], v[92:95], v[88:91], v[48:63]
	v_mfma_f32_32x32x16_bf16 v[32:47], v[74:77], v[66:69], v[32:47]
	s_waitcnt lgkmcnt(0)
	v_mfma_f32_32x32x16_bf16 v[48:63], v[84:87], v[66:69], v[48:63]
; #define LAS __attribute__((address_space(3)))
; #define MFMA32(a, b, c) __builtin_amdgcn_mfma_f32_32x32x16_bf16((a), (b), (c), 0, 0, 0)
; DI float ex2(float x) { return __builtin_amdgcn_exp2f(x); }
; template <int KS0, int KS1> DI f32x16 qk_rows(LAS const char* Kl, int row0, const bf16x8 (&qf)[4], int r, int h) {
;     f32x16 s;
; #pragma unroll
;     for (int i = 0; i < 16; ++i) s[i] = 0.f;
;     LAS const char* p = Kl + (row0 + r) * KP + 16 * h;
;     bf16x8 kf[4];
; #pragma unroll
;     for (int ks = KS0; ks < KS1; ++ks) kf[ks] = *(LAS const bf16x8*)(p + 32 * ks);
;     __builtin_amdgcn_s_setprio(1);
; #pragma unroll
;     for (int ks = KS0; ks < KS1; ++ks) s = MFMA32(kf[ks], qf[ks], s);
;     __builtin_amdgcn_s_setprio(0);
;     return s;
; }
; template <int MM> DI void smax_step_nb(const f32x16& s, unsigned vm, float& m, float& l, f32x16 (&o)[2], bf16x8 (&pf)[2], int lane) {
;     float mx = -1e30f;
; #pragma unroll
;     for (int i = 0; i < 16; ++i) mx = fmaxf(mx, s[i]);
;     if (MM == 1) mx = vm ? mx : -1e30f;
;     mx = fmaxf(mx, shx32(mx, lane));
;     const float mn = (mx > m + 8.0f) ? mx : m;
;     float mref = fmaxf(mn, -1e29f);
;     if (MM == 1) mref = vm ? mref : 3e38f;
;     const float alpha = ex2(m - mn);
;     float p[16], rs = 0.f;
; #pragma unroll
;     for (int i = 0; i < 16; ++i) { p[i] = ex2(s[i] - mref); rs += p[i]; }
;     rs += shx32(rs, lane);
;     l = l * alpha + rs;
;     if (__builtin_amdgcn_ballot_w64(mn != m) != 0ull) {
; #pragma unroll
;         for (int i = 0; i < 16; ++i) { o[0][i] *= alpha; o[1][i] *= alpha; }
;     }
;     m = mn;
;     pack_p(p, pf);
; }
; template <int MM> DI void tile64_pipe(LAS const char* Kl, LAS const char* Vl, const bf16x8 (&qf)[4], unsigned vm, float& m, float& l, f32x16 (&o)[2], int r, int h, int lane) {
;     const f32x16 sa = qk_rows<0, 4>(Kl, 0, qf, r, h), sb = qk_rows<0, 4>(Kl, 32, qf, r, h);
;     bf16x8 pfa[2], pfb[2];
;     smax_step_nb<MM>(sa, vm, m, l, o, pfa, lane);
;     pv_rows(o, Vl, 0, pfa, lane);
.LBB0_629:
	s_and_b64 vcc, exec, s[42:43]
	s_cbranch_vccz .LBB0_635
	s_nop 7
	ds_read_b128 v[32:35], v83
	s_nop 0
	ds_read_b128 v[48:51], v83 offset:32
	ds_read_b128 v[52:55], v83 offset:64
	ds_read_b128 v[56:59], v83 offset:96
	s_nop 0
	s_waitcnt lgkmcnt(3)
	v_mfma_f32_32x32x16_bf16 v[32:47], v[32:35], v[96:99], 0
	s_waitcnt lgkmcnt(2)
	v_mfma_f32_32x32x16_bf16 v[32:47], v[48:51], v[100:103], v[32:47]
	s_waitcnt lgkmcnt(1)
	v_mfma_f32_32x32x16_bf16 v[32:47], v[52:55], v[104:107], v[32:47]
	s_waitcnt lgkmcnt(0)
	v_mfma_f32_32x32x16_bf16 v[32:47], v[56:59], v[108:111], v[32:47]
	s_nop 0
	ds_read_b128 v[48:51], v83 offset:4608
	ds_read_b128 v[52:55], v83 offset:4640
	ds_read_b128 v[56:59], v83 offset:4672
	ds_read_b128 v[60:63], v83 offset:4704
	s_nop 0
	s_waitcnt lgkmcnt(3)
	v_mfma_f32_32x32x16_bf16 v[64:79], v[48:51], v[96:99], 0
	s_waitcnt lgkmcnt(2)
	v_mfma_f32_32x32x16_bf16 v[64:79], v[52:55], v[100:103], v[64:79]
	s_waitcnt lgkmcnt(1)
	v_mfma_f32_32x32x16_bf16 v[64:79], v[56:59], v[104:107], v[64:79]
	s_waitcnt lgkmcnt(0)
	v_mfma_f32_32x32x16_bf16 v[64:79], v[60:63], v[108:111], v[64:79]
	s_nop 0
	v_max3_f32 v48, v32, s15, v33
	v_max3_f32 v48, v48, v34, v35
	v_max3_f32 v48, v48, v36, v37
	v_max3_f32 v48, v48, v38, v39
	v_max3_f32 v48, v48, v40, v41
	v_max3_f32 v48, v48, v42, v43
	v_max3_f32 v48, v48, v44, v45
	v_max3_f32 v48, v48, v46, v47
	v_mov_b32_e32 v49, v48
	v_mov_b32_e32 v50, v48
	s_nop 1
	v_permlane32_swap_b32_e32 v49, v50
	v_max_f32_e32 v48, v49, v50
	v_add_f32_e32 v49, 0x41000000, v214
	v_cmp_gt_f32_e32 vcc, v48, v49
	s_nop 1
	v_cndmask_b32_e32 v87, v214, v48, vcc
	v_max_f32_e32 v48, 0xefa18f08, v87
	v_sub_f32_e32 v32, v32, v48
	v_exp_f32_e32 v82, v32
	v_sub_f32_e32 v32, v33, v48
	v_exp_f32_e32 v86, v32
	v_sub_f32_e32 v32, v34, v48
	v_exp_f32_e32 v88, v32
	v_sub_f32_e32 v32, v35, v48
	v_exp_f32_e32 v89, v32
	v_sub_f32_e32 v33, v36, v48
	v_exp_f32_e32 v90, v33
	v_sub_f32_e32 v33, v37, v48
	v_add_f32_e32 v32, v86, v82
	v_exp_f32_e32 v91, v33
	v_sub_f32_e32 v33, v38, v48
	v_add_f32_e32 v32, v88, v32
	v_exp_f32_e32 v92, v33
	v_sub_f32_e32 v33, v39, v48
	v_add_f32_e32 v32, v89, v32
	v_exp_f32_e32 v93, v33
	v_sub_f32_e32 v33, v40, v48
	v_add_f32_e32 v32, v90, v32
	v_exp_f32_e32 v94, v33
	v_sub_f32_e32 v33, v41, v48
	v_add_f32_e32 v32, v91, v32
	v_exp_f32_e32 v95, v33
	v_sub_f32_e32 v33, v42, v48
	v_add_f32_e32 v32, v92, v32
	v_exp_f32_e32 v128, v33
	v_sub_f32_e32 v33, v43, v48
	v_add_f32_e32 v32, v93, v32
	v_exp_f32_e32 v129, v33
	v_sub_f32_e32 v33, v44, v48
	v_add_f32_e32 v32, v94, v32
	v_exp_f32_e32 v130, v33
	v_sub_f32_e32 v33, v45, v48
	v_add_f32_e32 v32, v95, v32
	v_exp_f32_e32 v131, v33
	v_sub_f32_e32 v33, v46, v48
	v_add_f32_e32 v32, v128, v32
	v_exp_f32_e32 v132, v33
	v_sub_f32_e32 v33, v47, v48
	v_add_f32_e32 v32, v129, v32
	v_exp_f32_e32 v133, v33
	v_add_f32_e32 v32, v130, v32
	v_sub_f32_e32 v49, v214, v87
	v_add_f32_e32 v32, v131, v32
	v_add_f32_e32 v32, v132, v32
	v_exp_f32_e32 v80, v49
	v_add_f32_e32 v83, v133, v32
	v_mov_b32_e32 v84, v83
	v_mov_b32_e32 v85, v83
	v_mov_b64_e32 v[62:63], v[30:31]
	s_nop 0
	v_permlane32_swap_b32_e32 v84, v85
	v_cmp_neq_f32_e32 vcc, v87, v214
	v_mov_b64_e32 v[60:61], v[28:29]
	v_mov_b64_e32 v[58:59], v[26:27]
	v_mov_b64_e32 v[56:57], v[24:25]
	v_mov_b64_e32 v[54:55], v[22:23]
	v_mov_b64_e32 v[52:53], v[20:21]
	v_mov_b64_e32 v[50:51], v[18:19]
	v_mov_b64_e32 v[48:49], v[16:17]
	v_mov_b64_e32 v[46:47], v[14:15]
	v_mov_b64_e32 v[44:45], v[12:13]
	v_mov_b64_e32 v[42:43], v[10:11]
	v_mov_b64_e32 v[40:41], v[8:9]
	v_mov_b64_e32 v[38:39], v[6:7]
	v_mov_b64_e32 v[36:37], v[4:5]
	v_mov_b64_e32 v[34:35], v[2:3]
	v_mov_b64_e32 v[32:33], v[0:1]
	s_cbranch_vccz .LBB0_632
	v_pk_mul_f32 v[62:63], v[30:31], v[80:81] op_sel_hi:[1,0]
	v_pk_mul_f32 v[60:61], v[28:29], v[80:81] op_sel_hi:[1,0]
	v_pk_mul_f32 v[58:59], v[26:27], v[80:81] op_sel_hi:[1,0]
	v_pk_mul_f32 v[56:57], v[24:25], v[80:81] op_sel_hi:[1,0]
	v_pk_mul_f32 v[54:55], v[22:23], v[80:81] op_sel_hi:[1,0]
	v_pk_mul_f32 v[52:53], v[20:21], v[80:81] op_sel_hi:[1,0]
	v_pk_mul_f32 v[50:51], v[18:19], v[80:81] op_sel_hi:[1,0]
	v_pk_mul_f32 v[48:49], v[16:17], v[80:81] op_sel_hi:[1,0]
	v_pk_mul_f32 v[46:47], v[14:15], v[80:81] op_sel_hi:[1,0]
	v_pk_mul_f32 v[44:45], v[12:13], v[80:81] op_sel_hi:[1,0]
	v_pk_mul_f32 v[42:43], v[10:11], v[80:81] op_sel_hi:[1,0]
	v_pk_mul_f32 v[40:41], v[8:9], v[80:81] op_sel_hi:[1,0]
	v_pk_mul_f32 v[38:39], v[6:7], v[80:81] op_sel_hi:[1,0]
	v_pk_mul_f32 v[36:37], v[4:5], v[80:81] op_sel_hi:[1,0]
	v_pk_mul_f32 v[34:35], v[2:3], v[80:81] op_sel_hi:[1,0]
	v_pk_mul_f32 v[32:33], v[0:1], v[80:81] op_sel_hi:[1,0]
; #define LAS __attribute__((address_space(3)))
; #define MFMA32(a, b, c) __builtin_amdgcn_mfma_f32_32x32x16_bf16((a), (b), (c), 0, 0, 0)
; DI float ex2(float x) { return __builtin_amdgcn_exp2f(x); }
; DI void pv_rows(f32x16 (&o)[2], LAS const char* Vl, int row0, const bf16x8 (&pf)[2], int lane) {
;     const int h = lane >> 5, i = lane & 15, grp = (lane >> 4) & 1;
;     LAS const char* base = Vl + (row0 + 4 * h + (i >> 2)) * KP + grp * 32 + (i & 3) * 8;
;     bf16x8 vf[2][2];
; #pragma unroll
;     for (int dt = 0; dt < 2; ++dt)
; #pragma unroll
;         for (int s2 = 0; s2 < 2; ++s2) {
;             const s16x4 lo = vtr(base + (16 * s2) * KP + dt * 64), hi = vtr(base + (16 * s2 + 8) * KP + dt * 64);
;             vf[dt][s2] = (bf16x8){lo[0], lo[1], lo[2], lo[3], hi[0], hi[1], hi[2], hi[3]};
;         }
;     __builtin_amdgcn_s_setprio(1);
; #pragma unroll
;     for (int s2 = 0; s2 < 2; ++s2)
; #pragma unroll
;         for (int dt = 0; dt < 2; ++dt) o[dt] = MFMA32(vf[dt][s2], pf[s2], o[dt]);
;     __builtin_amdgcn_s_setprio(0);
; }
; template <int MM> DI void smax_step_nb(const f32x16& s, unsigned vm, float& m, float& l, f32x16 (&o)[2], bf16x8 (&pf)[2], int lane) {
;     float mx = -1e30f;
; #pragma unroll
;     for (int i = 0; i < 16; ++i) mx = fmaxf(mx, s[i]);
;     if (MM == 1) mx = vm ? mx : -1e30f;
;     mx = fmaxf(mx, shx32(mx, lane));
;     const float mn = (mx > m + 8.0f) ? mx : m;
;     float mref = fmaxf(mn, -1e29f);
;     if (MM == 1) mref = vm ? mref : 3e38f;
;     const float alpha = ex2(m - mn);
;     float p[16], rs = 0.f;
; #pragma unroll
;     for (int i = 0; i < 16; ++i) { p[i] = ex2(s[i] - mref); rs += p[i]; }
;     rs += shx32(rs, lane);
;     l = l * alpha + rs;
;     if (__builtin_amdgcn_ballot_w64(mn != m) != 0ull) {
; #pragma unroll
;         for (int i = 0; i < 16; ++i) { o[0][i] *= alpha; o[1][i] *= alpha; }
;     }
;     m = mn;
;     pack_p(p, pf);
; }
; template <int MM> DI void tile64_pipe(LAS const char* Kl, LAS const char* Vl, const bf16x8 (&qf)[4], unsigned vm, float& m, float& l, f32x16 (&o)[2], int r, int h, int lane) {
;     const f32x16 sa = qk_rows<0, 4>(Kl, 0, qf, r, h), sb = qk_rows<0, 4>(Kl, 32, qf, r, h);
;     bf16x8 pfa[2], pfb[2];
;     smax_step_nb<MM>(sa, vm, m, l, o, pfa, lane);
;     pv_rows(o, Vl, 0, pfa, lane);
;     smax_step_nb<MM>(sb, vm, m, l, o, pfb, lane);
;     pv_rows(o, Vl, 32, pfb, lane);
; }
.LBB0_632:
	v_cvt_pk_bf16_f32 v134, v82, v86
	v_add3_u32 v82, s11, v191, v171
	v_add_u32_e32 v86, v82, v186
	v_cvt_pk_bf16_f32 v135, v88, v89
	v_cvt_pk_bf16_f32 v136, v90, v91
	v_cvt_pk_bf16_f32 v137, v92, v93
	v_cvt_pk_bf16_f32 v88, v94, v95
	v_cvt_pk_bf16_f32 v89, v128, v129
	v_cvt_pk_bf16_f32 v90, v130, v131
	ds_read_b64_tr_b16 v[92:93], v86 offset:9216
	ds_read_b64_tr_b16 v[94:95], v86 offset:10368
	ds_read_b64_tr_b16 v[128:129], v86 offset:11520
	ds_read_b64_tr_b16 v[130:131], v86 offset:12672
	ds_read_b64_tr_b16 v[138:139], v86 offset:9280
	ds_read_b64_tr_b16 v[140:141], v86 offset:10432
	ds_read_b64_tr_b16 v[142:143], v86 offset:11584
	ds_read_b64_tr_b16 v[144:145], v86 offset:12736
	v_cvt_pk_bf16_f32 v91, v132, v133
	s_nop 0
	s_waitcnt lgkmcnt(6)
	v_mfma_f32_32x32x16_bf16 v[32:47], v[92:95], v[134:137], v[32:47]
	s_waitcnt lgkmcnt(2)
	v_mfma_f32_32x32x16_bf16 v[48:63], v[138:141], v[134:137], v[48:63]
	v_mfma_f32_32x32x16_bf16 v[32:47], v[128:131], v[88:91], v[32:47]
	s_waitcnt lgkmcnt(0)
	v_mfma_f32_32x32x16_bf16 v[48:63], v[142:145], v[88:91], v[48:63]
	s_nop 0
	v_max3_f32 v82, v64, s15, v65
	v_max3_f32 v82, v82, v66, v67
	v_max3_f32 v82, v82, v68, v69
	v_max3_f32 v82, v82, v70, v71
	v_max3_f32 v82, v82, v72, v73
	v_max3_f32 v82, v82, v74, v75
	v_max3_f32 v82, v82, v76, v77
	v_max3_f32 v82, v82, v78, v79
	v_mov_b32_e32 v88, v82
	v_mov_b32_e32 v89, v82
	s_nop 1
	v_permlane32_swap_b32_e32 v88, v89
	v_max_f32_e32 v82, v88, v89
	v_add_f32_e32 v88, 0x41000000, v87
	v_cmp_gt_f32_e32 vcc, v82, v88
	s_nop 1
	v_cndmask_b32_e32 v82, v87, v82, vcc
	v_max_f32_e32 v90, 0xefa18f08, v82
	v_sub_f32_e32 v64, v64, v90
	v_exp_f32_e32 v88, v64
	v_sub_f32_e32 v64, v65, v90
	v_exp_f32_e32 v89, v64
	v_sub_f32_e32 v64, v66, v90
	v_exp_f32_e32 v66, v64
	v_sub_f32_e32 v64, v67, v90
	v_exp_f32_e32 v67, v64
	v_sub_f32_e32 v65, v68, v90
	v_exp_f32_e32 v68, v65
	v_sub_f32_e32 v65, v69, v90
	v_add_f32_e32 v64, v89, v88
	v_exp_f32_e32 v69, v65
	v_sub_f32_e32 v65, v70, v90
	v_add_f32_e32 v64, v66, v64
	v_exp_f32_e32 v70, v65
	v_sub_f32_e32 v65, v71, v90
	v_add_f32_e32 v64, v67, v64
	v_exp_f32_e32 v71, v65
	v_sub_f32_e32 v65, v72, v90
	v_add_f32_e32 v64, v68, v64
	v_exp_f32_e32 v72, v65
	v_sub_f32_e32 v65, v73, v90
	v_add_f32_e32 v64, v69, v64
	v_exp_f32_e32 v73, v65
	v_sub_f32_e32 v65, v74, v90
	v_add_f32_e32 v64, v70, v64
	v_exp_f32_e32 v74, v65
	v_sub_f32_e32 v65, v75, v90
	v_add_f32_e32 v64, v71, v64
	v_exp_f32_e32 v75, v65
	v_sub_f32_e32 v65, v76, v90
	v_add_f32_e32 v64, v72, v64
	v_exp_f32_e32 v76, v65
	v_sub_f32_e32 v65, v77, v90
	v_add_f32_e32 v64, v73, v64
	v_exp_f32_e32 v77, v65
	v_sub_f32_e32 v65, v78, v90
	v_add_f32_e32 v64, v74, v64
	v_exp_f32_e32 v78, v65
	v_sub_f32_e32 v65, v79, v90
	v_add_f32_e32 v64, v75, v64
	v_exp_f32_e32 v79, v65
	v_add_f32_e32 v64, v76, v64
	v_add_f32_e32 v64, v77, v64
	v_sub_f32_e32 v91, v87, v82
	v_add_f32_e32 v64, v78, v64
	v_add_f32_e32 v65, v79, v64
	v_exp_f32_e32 v64, v91
	v_mov_b32_e32 v90, v65
	v_mov_b32_e32 v91, v65
	s_nop 1
	v_permlane32_swap_b32_e32 v90, v91
	v_cmp_neq_f32_e32 vcc, v82, v87
	s_cbranch_vccz .LBB0_634
	v_pk_mul_f32 v[62:63], v[62:63], v[64:65] op_sel_hi:[1,0]
	v_pk_mul_f32 v[60:61], v[60:61], v[64:65] op_sel_hi:[1,0]
	v_pk_mul_f32 v[58:59], v[58:59], v[64:65] op_sel_hi:[1,0]
	v_pk_mul_f32 v[56:57], v[56:57], v[64:65] op_sel_hi:[1,0]
	v_pk_mul_f32 v[54:55], v[54:55], v[64:65] op_sel_hi:[1,0]
	v_pk_mul_f32 v[52:53], v[52:53], v[64:65] op_sel_hi:[1,0]
	v_pk_mul_f32 v[50:51], v[50:51], v[64:65] op_sel_hi:[1,0]
	v_pk_mul_f32 v[48:49], v[48:49], v[64:65] op_sel_hi:[1,0]
	v_pk_mul_f32 v[46:47], v[46:47], v[64:65] op_sel_hi:[1,0]
	v_pk_mul_f32 v[44:45], v[44:45], v[64:65] op_sel_hi:[1,0]
	v_pk_mul_f32 v[42:43], v[42:43], v[64:65] op_sel_hi:[1,0]
	v_pk_mul_f32 v[40:41], v[40:41], v[64:65] op_sel_hi:[1,0]
	v_pk_mul_f32 v[38:39], v[38:39], v[64:65] op_sel_hi:[1,0]
	v_pk_mul_f32 v[36:37], v[36:37], v[64:65] op_sel_hi:[1,0]
	v_pk_mul_f32 v[34:35], v[34:35], v[64:65] op_sel_hi:[1,0]
	v_pk_mul_f32 v[32:33], v[32:33], v[64:65] op_sel_hi:[1,0]
.LBB0_634:
	v_cndmask_b32_e64 v84, v84, v85, s[36:37]
	v_add_f32_e32 v83, v83, v84
	v_fmac_f32_e32 v83, v213, v80
	v_cndmask_b32_e64 v80, v90, v91, s[36:37]
	v_cvt_pk_bf16_f32 v88, v88, v89
	v_cvt_pk_bf16_f32 v89, v66, v67
	v_cvt_pk_bf16_f32 v90, v68, v69
	v_cvt_pk_bf16_f32 v91, v70, v71
	v_cvt_pk_bf16_f32 v66, v72, v73
	v_cvt_pk_bf16_f32 v67, v74, v75
	v_cvt_pk_bf16_f32 v68, v76, v77
	ds_read_b64_tr_b16 v[70:71], v86 offset:13824
	ds_read_b64_tr_b16 v[72:73], v86 offset:14976
	ds_read_b64_tr_b16 v[74:75], v86 offset:16128
	ds_read_b64_tr_b16 v[76:77], v86 offset:17280
	ds_read_b64_tr_b16 v[92:93], v86 offset:13888
	ds_read_b64_tr_b16 v[94:95], v86 offset:15040
	ds_read_b64_tr_b16 v[84:85], v86 offset:16192
	ds_read_b64_tr_b16 v[86:87], v86 offset:17344
	v_add_f32_e32 v65, v65, v80
	v_fmac_f32_e32 v65, v83, v64
	v_cvt_pk_bf16_f32 v69, v78, v79
	s_nop 0
	s_waitcnt lgkmcnt(6)
	v_mfma_f32_32x32x16_bf16 v[32:47], v[70:73], v[88:91], v[32:47]
	s_mov_b64 s[38:39], -1
	s_waitcnt lgkmcnt(2)
	v_mfma_f32_32x32x16_bf16 v[48:63], v[92:95], v[88:91], v[48:63]
	v_mfma_f32_32x32x16_bf16 v[32:47], v[74:77], v[66:69], v[32:47]
	s_waitcnt lgkmcnt(0)
	v_mfma_f32_32x32x16_bf16 v[48:63], v[84:87], v[66:69], v[48:63]

; #define MFMA32(a, b, c) __builtin_amdgcn_mfma_f32_32x32x16_bf16((a), (b), (c), 0, 0, 0)
; DI void pv_rows(f32x16 (&o)[2], LAS const char* Vl, int row0, const bf16x8 (&pf)[2], int lane) {
;     ...
;     __builtin_amdgcn_s_setprio(1);
; #pragma unroll
;     for (int s2 = 0; s2 < 2; ++s2)
; #pragma unroll
;         for (int dt = 0; dt < 2; ++dt) o[dt] = MFMA32(vf[dt][s2], pf[s2], o[dt]);
;     __builtin_amdgcn_s_setprio(0);
; template <int MODE, bool PRE = false> ...
;     ...
;                     if (selb == ~0ull) tile64_pipe<0>(Kl, Vl, qf, vm, m1, l1, o1, r, h, lane); else tile64_pipe<1>(Kl, Vl, qf, vm, m1, l1, o1, r, h, lane);
.LBB0_637:
	s_nop 0
	s_nop 6
	v_mov_b64_e32 v[0:1], v[32:33]
	v_mov_b64_e32 v[2:3], v[34:35]
	v_mov_b64_e32 v[4:5], v[36:37]
	v_mov_b64_e32 v[6:7], v[38:39]
	v_mov_b64_e32 v[8:9], v[40:41]
	v_mov_b64_e32 v[10:11], v[42:43]
	v_mov_b64_e32 v[12:13], v[44:45]
	v_mov_b64_e32 v[14:15], v[46:47]
	v_mov_b64_e32 v[16:17], v[48:49]
	v_mov_b64_e32 v[18:19], v[50:51]
	v_mov_b64_e32 v[20:21], v[52:53]
	v_mov_b64_e32 v[22:23], v[54:55]
	v_mov_b64_e32 v[24:25], v[56:57]
	v_mov_b64_e32 v[26:27], v[58:59]
	v_mov_b64_e32 v[28:29], v[60:61]
	v_mov_b64_e32 v[30:31], v[62:63]

; template <int MM> DI void smax_step(const f32x16& s, unsigned vm, float& m, float& l, f32x16 (&o)[2], bf16x8 (&pf)[2], int lane) {
;     float t[16], mx = -1e30f;
; #pragma unroll
;     for (int i = 0; i < 16; ++i) { t[i] = (MM == 0) ? s[i] : (MM == 1 ? (vm ? s[i] : -1e30f) : (((vm >> i) & 1u) ? s[i] : -1e30f)); mx = fmaxf(mx, t[i]); }
; template <int MODE, bool PRE = false> ...
;     ...
;         for (int sub = 0; sub < 2; ++sub) {
;             const int kbase = 64 * kt + 32 * sub;
;             if (kbase > q0w + 31) continue;
;             if (MODE == MODE_NWIN && kbase + 31 <= q0w - 512) continue;
;             bool full = (kbase + 31 <= q0w);
;             if (MODE == MODE_NWIN) full = full && (kbase > q0w + 31 - 512);
;             bool lsel = true;
;             if (MODE == MODE_MOBA) lsel = ((sel >> (kbase >> 8)) & 1ull) != 0ull;
;             if (MODE == MODE_NSEL) lsel = ((sel >> kt) & 1ull) != 0ull;
;             const unsigned long long selb = __builtin_amdgcn_ballot_w64(lsel);
;             if (selb == 0ull) continue;
;             int mm; unsigned vm;
;             if (full) { mm = (selb == ~0ull) ? 0 : 1; vm = lsel ? 1u : 0u; }
;             else { mm = 2; vm = 0;
; #pragma unroll
;                 for (int i = 0; i < 16; ++i) { const int kidx = kbase + (i & 3) + 8 * (i >> 2) + 4 * h; bool ok = kidx <= qpos; if (MODE == MODE_NWIN) ok = ok && (kidx > qpos - 512); vm |= ok ? (1u << i) : 0u; }
;                 if (!lsel) vm = 0;
;                 if (__builtin_amdgcn_ballot_w64(vm != 0) == 0ull) continue; }
;             bf16x8 pf[2];
;             if (MODE == MODE_DIFF) {
;                 const f32x16 s1 = qk_rows<0, 2>(Kl, 32 * sub, qf, r, h), s2 = qk_rows<2, 4>(Kl, 32 * sub, qf, r, h);
;                 bf16x8 pf2[2];
;                 if (mm == 0) { smax_step<0>(s1, vm, m1, l1, o1, pf, lane); smax_step<0>(s2, vm, m2, l2, o2, pf2, lane); }
;                 else { smax_step<2>(s1, vm, m1, l1, o1, pf, lane); smax_step<2>(s2, vm, m2, l2, o2, pf2, lane); }
;                 pv_rows(o1, Vl, 32 * sub, pf, lane);
;                 pv_rows(o2, Vl, 32 * sub, pf2, lane);
;             } else {
;                 const f32x16 s = qk_rows<0, 4>(Kl, 32 * sub, qf, r, h);
;                 if (mm == 0) smax_step<0>(s, vm, m1, l1, o1, pf, lane); else if (mm == 1) smax_step<1>(s, vm, m1, l1, o1, pf, lane); else smax_step<2>(s, vm, m1, l1, o1, pf, lane);
.LBB0_646:
	s_andn2_b64 vcc, exec, s[42:43]
	s_cbranch_vccnz .LBB0_658
	v_add_u32_e32 v36, v48, v190
	ds_read_b128 v[32:35], v36
	ds_read_b128 v[50:53], v36 offset:32
	ds_read_b128 v[54:57], v36 offset:64
	ds_read_b128 v[58:61], v36 offset:96
	s_nop 0
	s_waitcnt lgkmcnt(3)
	v_mfma_f32_32x32x16_bf16 v[32:47], v[32:35], v[96:99], 0
	s_waitcnt lgkmcnt(2)
	v_mfma_f32_32x32x16_bf16 v[32:47], v[50:53], v[100:103], v[32:47]
	s_waitcnt lgkmcnt(1)
	v_mfma_f32_32x32x16_bf16 v[32:47], v[54:57], v[104:107], v[32:47]
	s_waitcnt lgkmcnt(0)
	v_mfma_f32_32x32x16_bf16 v[32:47], v[58:61], v[108:111], v[32:47]
	s_nop 0
	v_cmp_gt_i32_e32 vcc, 1, v49
	s_cbranch_vccnz .LBB0_650
	v_cmp_ne_u32_e32 vcc, 1, v49
	s_cbranch_vccz .LBB0_651
	v_and_b32_e32 v49, 1, v70
	v_cmp_eq_u32_e32 vcc, 1, v49
	v_and_b32_e32 v49, 2, v70
	v_and_b32_e32 v52, 4, v70
	s_nop 2
	v_cndmask_b32_e32 v50, v208, v32, vcc
	v_cmp_ne_u32_e32 vcc, 0, v49
	v_and_b32_e32 v53, 8, v70
	v_and_b32_e32 v54, 16, v70
	v_cndmask_b32_e32 v51, v208, v33, vcc
	v_cmp_ne_u32_e32 vcc, 0, v52
	v_and_b32_e32 v55, 32, v70
	v_and_b32_e32 v56, 64, v70
	v_cndmask_b32_e32 v52, v208, v34, vcc
	v_cmp_ne_u32_e32 vcc, 0, v53
	v_and_b32_e32 v57, 0x80, v70
	v_and_b32_e32 v58, 0x100, v70
	v_cndmask_b32_e32 v53, v208, v35, vcc
	v_cmp_ne_u32_e32 vcc, 0, v54
	v_and_b32_e32 v59, 0x200, v70
	v_and_b32_e32 v60, 0x400, v70
	v_cndmask_b32_e32 v54, v208, v36, vcc
	v_cmp_ne_u32_e32 vcc, 0, v55
	v_max3_f32 v49, v50, s15, v51
	v_and_b32_e32 v61, 0x800, v70
	v_cndmask_b32_e32 v55, v208, v37, vcc
	v_cmp_ne_u32_e32 vcc, 0, v56
	v_max3_f32 v49, v49, v52, v53
	v_and_b32_e32 v62, 0x1000, v70
	v_cndmask_b32_e32 v56, v208, v38, vcc
	v_cmp_ne_u32_e32 vcc, 0, v57
	v_max3_f32 v49, v49, v54, v55
	v_and_b32_e32 v63, 0x2000, v70
	v_cndmask_b32_e32 v57, v208, v39, vcc
	v_cmp_ne_u32_e32 vcc, 0, v58
	v_max3_f32 v49, v49, v56, v57
	v_and_b32_e32 v65, 0x4000, v70
	v_cndmask_b32_e32 v58, v208, v40, vcc
	v_cmp_ne_u32_e32 vcc, 0, v59
	v_and_b32_e32 v66, 0x8000, v70
	s_nop 0
	v_cndmask_b32_e32 v59, v208, v41, vcc
	v_cmp_ne_u32_e32 vcc, 0, v60
	v_max3_f32 v49, v49, v58, v59
	s_nop 0
	v_cndmask_b32_e32 v60, v208, v42, vcc
	v_cmp_ne_u32_e32 vcc, 0, v61
	s_nop 1
	v_cndmask_b32_e32 v61, v208, v43, vcc
	v_cmp_ne_u32_e32 vcc, 0, v62
	v_max3_f32 v49, v49, v60, v61
	s_nop 0
	v_cndmask_b32_e32 v62, v208, v44, vcc
	v_cmp_ne_u32_e32 vcc, 0, v63
	s_nop 1
	v_cndmask_b32_e32 v63, v208, v45, vcc
	v_cmp_ne_u32_e32 vcc, 0, v65
	v_max3_f32 v49, v49, v62, v63
	s_nop 0
	v_cndmask_b32_e32 v65, v208, v46, vcc
	v_cmp_ne_u32_e32 vcc, 0, v66
	s_nop 1
	v_cndmask_b32_e32 v66, v208, v47, vcc
	v_max3_f32 v49, v49, v65, v66
	v_mov_b32_e32 v67, v49
	v_mov_b32_e32 v68, v49
	s_nop 1
	v_permlane32_swap_b32_e32 v67, v68
	v_max_f32_e32 v49, v67, v68
	v_add_f32_e32 v67, 0x41000000, v214
	v_cmp_gt_f32_e32 vcc, v49, v67
	s_nop 1
	v_cndmask_b32_e32 v49, v214, v49, vcc
	v_max_f32_e32 v67, 0xefa18f08, v49
	v_sub_f32_e32 v50, v50, v67
	v_exp_f32_e32 v50, v50
	v_sub_f32_e32 v51, v51, v67
	v_exp_f32_e32 v51, v51
	v_sub_f32_e32 v52, v52, v67
	v_exp_f32_e32 v52, v52
	v_sub_f32_e32 v53, v53, v67
	v_exp_f32_e32 v53, v53
	v_sub_f32_e32 v54, v54, v67
	v_exp_f32_e32 v54, v54
	v_sub_f32_e32 v55, v55, v67
	v_add_f32_e32 v68, v51, v50
	v_exp_f32_e32 v55, v55
	v_sub_f32_e32 v56, v56, v67
	v_add_f32_e32 v68, v52, v68
	v_exp_f32_e32 v56, v56
	v_sub_f32_e32 v57, v57, v67
	v_add_f32_e32 v68, v53, v68
	v_exp_f32_e32 v57, v57
	v_sub_f32_e32 v58, v58, v67
	v_add_f32_e32 v68, v54, v68
	v_exp_f32_e32 v58, v58
	v_sub_f32_e32 v59, v59, v67
	v_add_f32_e32 v68, v55, v68
	v_exp_f32_e32 v59, v59
	v_sub_f32_e32 v60, v60, v67
	v_add_f32_e32 v68, v56, v68
	v_exp_f32_e32 v60, v60
	v_sub_f32_e32 v61, v61, v67
	v_add_f32_e32 v68, v57, v68
	v_exp_f32_e32 v61, v61
	v_sub_f32_e32 v62, v62, v67
	v_add_f32_e32 v68, v58, v68
	v_exp_f32_e32 v62, v62
	v_sub_f32_e32 v63, v63, v67
	v_add_f32_e32 v68, v59, v68
	v_exp_f32_e32 v63, v63
	v_sub_f32_e32 v65, v65, v67
	v_add_f32_e32 v68, v60, v68
	v_exp_f32_e32 v65, v65
	v_sub_f32_e32 v66, v66, v67
	v_add_f32_e32 v68, v61, v68
	v_exp_f32_e32 v66, v66
	v_add_f32_e32 v67, v62, v68
	v_add_f32_e32 v67, v63, v67
	v_add_f32_e32 v67, v65, v67
	v_add_f32_e32 v67, v66, v67
	v_cmp_neq_f32_e32 vcc, v49, v214
	v_mov_b32_e32 v68, v67
	v_mov_b32_e32 v69, v67
	s_cmp_lg_u64 vcc, 0
	s_nop 0
	v_permlane32_swap_b32_e32 v68, v69
	s_cselect_b64 s[42:43], -1, 0
	s_cbranch_execz .LBB0_652
	s_branch .LBB0_653

; #define LAS __attribute__((address_space(3)))
; #define MFMA32(a, b, c) __builtin_amdgcn_mfma_f32_32x32x16_bf16((a), (b), (c), 0, 0, 0)
; DI s16x4 vtr(LAS const char* p) { return __builtin_bit_cast(s16x4, __builtin_amdgcn_ds_read_tr16_b64_v4i16((LAS v4i16_t*)p)); }
; DI void pv_rows(f32x16 (&o)[2], LAS const char* Vl, int row0, const bf16x8 (&pf)[2], int lane) {
;     const int h = lane >> 5, i = lane & 15, grp = (lane >> 4) & 1;
;     LAS const char* base = Vl + (row0 + 4 * h + (i >> 2)) * KP + grp * 32 + (i & 3) * 8;
;     bf16x8 vf[2][2];
; #pragma unroll
;     for (int dt = 0; dt < 2; ++dt)
; #pragma unroll
;         for (int s2 = 0; s2 < 2; ++s2) {
;             const s16x4 lo = vtr(base + (16 * s2) * KP + dt * 64), hi = vtr(base + (16 * s2 + 8) * KP + dt * 64);
;             vf[dt][s2] = (bf16x8){lo[0], lo[1], lo[2], lo[3], hi[0], hi[1], hi[2], hi[3]};
;         }
;     __builtin_amdgcn_s_setprio(1);
; #pragma unroll
;     for (int s2 = 0; s2 < 2; ++s2)
; #pragma unroll
;         for (int dt = 0; dt < 2; ++dt) o[dt] = MFMA32(vf[dt][s2], pf[s2], o[dt]);
;     __builtin_amdgcn_s_setprio(0);
; }
; template <int MODE, bool PRE = false> ...
;     ...
;         for (int sub = 0; sub < 2; ++sub) {
;             const int kbase = 64 * kt + 32 * sub;
;             if (kbase > q0w + 31) continue;
;             if (MODE == MODE_NWIN && kbase + 31 <= q0w - 512) continue;
;             bool full = (kbase + 31 <= q0w);
;             if (MODE == MODE_NWIN) full = full && (kbase > q0w + 31 - 512);
;             bool lsel = true;
;             if (MODE == MODE_MOBA) lsel = ((sel >> (kbase >> 8)) & 1ull) != 0ull;
;             if (MODE == MODE_NSEL) lsel = ((sel >> kt) & 1ull) != 0ull;
;             const unsigned long long selb = __builtin_amdgcn_ballot_w64(lsel);
;             if (selb == 0ull) continue;
;             int mm; unsigned vm;
;             if (full) { mm = (selb == ~0ull) ? 0 : 1; vm = lsel ? 1u : 0u; }
;             else { mm = 2; vm = 0;
; #pragma unroll
;                 for (int i = 0; i < 16; ++i) { const int kidx = kbase + (i & 3) + 8 * (i >> 2) + 4 * h; bool ok = kidx <= qpos; if (MODE == MODE_NWIN) ok = ok && (kidx > qpos - 512); vm |= ok ? (1u << i) : 0u; }
;                 if (!lsel) vm = 0;
;                 if (__builtin_amdgcn_ballot_w64(vm != 0) == 0ull) continue; }
.LBB0_657:
	s_nop 3
	v_cndmask_b32_e64 v32, v68, v69, s[36:37]
	v_add_f32_e32 v32, v67, v32
	v_add_u32_e32 v49, v64, v191
	v_add_f32_e32 v213, v213, v32
	v_cvt_pk_bf16_f32 v32, v50, v51
	v_cvt_pk_bf16_f32 v33, v52, v53
	v_cvt_pk_bf16_f32 v34, v54, v55
	v_cvt_pk_bf16_f32 v35, v56, v57
	ds_read_b64_tr_b16 v[40:41], v49 offset:9216
	ds_read_b64_tr_b16 v[42:43], v49 offset:10368
	ds_read_b64_tr_b16 v[44:45], v49 offset:11520
	ds_read_b64_tr_b16 v[46:47], v49 offset:12672
	ds_read_b64_tr_b16 v[50:51], v49 offset:9280
	ds_read_b64_tr_b16 v[52:53], v49 offset:10432
	ds_read_b64_tr_b16 v[54:55], v49 offset:11584
	ds_read_b64_tr_b16 v[56:57], v49 offset:12736
	v_cvt_pk_bf16_f32 v36, v58, v59
	v_cvt_pk_bf16_f32 v37, v60, v61
	v_cvt_pk_bf16_f32 v38, v62, v63
	v_cvt_pk_bf16_f32 v39, v65, v66
	s_nop 0
	s_waitcnt lgkmcnt(6)
	v_mfma_f32_32x32x16_bf16 v[0:15], v[40:43], v[32:35], v[0:15]
	s_waitcnt lgkmcnt(2)
	v_mfma_f32_32x32x16_bf16 v[16:31], v[50:53], v[32:35], v[16:31]
	v_mfma_f32_32x32x16_bf16 v[0:15], v[44:47], v[36:39], v[0:15]
	s_waitcnt lgkmcnt(0)
	v_mfma_f32_32x32x16_bf16 v[16:31], v[54:57], v[36:39], v[16:31]
	s_nop 0
.LBB0_658:
	s_or_b32 s10, s10, 32
	s_cmp_gt_i32 s10, s25
	s_cbranch_scc1 .LBB0_663
	v_cmp_ne_u32_e32 vcc, 0, v81
	s_cbranch_vccz .LBB0_663
	v_or_b32_e32 v32, s10, v167
	v_cmp_le_i32_e32 vcc, v32, v160
	v_or_b32_e32 v35, 3, v32
	s_nop 0
	v_cndmask_b32_e64 v33, 0, 1, vcc
	v_cmp_lt_i32_e32 vcc, v32, v160
	s_nop 1
	v_cndmask_b32_e64 v34, 0, 2, vcc
	v_or_b32_e32 v33, v34, v33
	v_or_b32_e32 v34, 2, v32
	v_cmp_gt_i32_e32 vcc, v34, v160
	s_nop 1
	v_cndmask_b32_e64 v34, 4, 0, vcc
	v_cmp_gt_i32_e32 vcc, v35, v160
	s_nop 1
	v_cndmask_b32_e64 v35, 8, 0, vcc
	v_or3_b32 v33, v33, v34, v35
	v_or_b32_e32 v34, 8, v32
	v_cmp_gt_i32_e32 vcc, v34, v160
	v_or_b32_e32 v35, 9, v32
	s_nop 0
	v_cndmask_b32_e64 v34, 16, 0, vcc
	v_cmp_gt_i32_e32 vcc, v35, v160
	s_nop 1
	v_cndmask_b32_e64 v35, 32, 0, vcc
	v_or3_b32 v33, v33, v34, v35
	v_or_b32_e32 v34, 10, v32
	v_cmp_gt_i32_e32 vcc, v34, v160
	v_or_b32_e32 v35, 11, v32
	s_nop 0
	v_cndmask_b32_e64 v34, 64, 0, vcc
	v_cmp_gt_i32_e32 vcc, v35, v160
	s_nop 1
	v_cndmask_b32_e64 v35, v196, 0, vcc
	v_or3_b32 v33, v33, v34, v35
	v_or_b32_e32 v34, 16, v32
	v_cmp_gt_i32_e32 vcc, v34, v160
	v_or_b32_e32 v35, 17, v32
	s_nop 0
	v_cndmask_b32_e64 v34, v197, 0, vcc
	v_cmp_gt_i32_e32 vcc, v35, v160
	s_nop 1
	v_cndmask_b32_e64 v35, v198, 0, vcc
	v_or3_b32 v33, v33, v34, v35
	v_or_b32_e32 v34, 18, v32
	v_cmp_gt_i32_e32 vcc, v34, v160
	v_or_b32_e32 v35, 19, v32
	s_nop 0
	v_cndmask_b32_e64 v34, v199, 0, vcc
	v_cmp_gt_i32_e32 vcc, v35, v160
	s_nop 1
	v_cndmask_b32_e64 v35, v200, 0, vcc
	v_or3_b32 v33, v33, v34, v35
	v_or_b32_e32 v34, 24, v32
	v_cmp_gt_i32_e32 vcc, v34, v160
	v_or_b32_e32 v35, 25, v32
	s_nop 0
	v_cndmask_b32_e64 v34, v201, 0, vcc
	v_cmp_gt_i32_e32 vcc, v35, v160
	s_nop 1
	v_cndmask_b32_e64 v35, v202, 0, vcc
	v_or3_b32 v33, v33, v34, v35
	v_or_b32_e32 v34, 26, v32
	v_cmp_gt_i32_e32 vcc, v34, v160
	v_or_b32_e32 v32, 27, v32
	s_nop 0
	v_cndmask_b32_e64 v34, v203, 0, vcc
	v_cmp_gt_i32_e32 vcc, v32, v160
	s_nop 1
	v_cndmask_b32_e64 v32, v204, 0, vcc
	v_or3_b32 v32, v33, v34, v32
	v_cndmask_b32_e64 v49, 0, v32, s[0:1]
	v_cmp_ne_u32_e32 vcc, 0, v49
	s_cbranch_vccz .LBB0_663
; DI float ex2(float x) { return __builtin_amdgcn_exp2f(x); }
; template <int MM> DI void smax_step(const f32x16& s, unsigned vm, float& m, float& l, f32x16 (&o)[2], bf16x8 (&pf)[2], int lane) {
;     float t[16], mx = -1e30f;
; #pragma unroll
;     for (int i = 0; i < 16; ++i) { t[i] = (MM == 0) ? s[i] : (MM == 1 ? (vm ? s[i] : -1e30f) : (((vm >> i) & 1u) ? s[i] : -1e30f)); mx = fmaxf(mx, t[i]); }
;     mx = fmaxf(mx, shx32(mx, lane));
;     const float mn = (mx > m + 8.0f) ? mx : m;
;     const float mref = fmaxf(mn, -1e29f);
;     float p[16], rs = 0.f;
; #pragma unroll
;     for (int i = 0; i < 16; ++i) { p[i] = ex2(t[i] - mref); rs += p[i]; }
;     rs += shx32(rs, lane);
;     if (__builtin_amdgcn_ballot_w64(mn != m) != 0ull) {
;         const float alpha = ex2(m - mn);
;         l *= alpha;
; #pragma unroll
;         for (int i = 0; i < 16; ++i) { o[0][i] *= alpha; o[1][i] *= alpha; }
;         m = mn;
;     }
;     l += rs;
;     pack_p(p, pf);
; }
; template <int MODE, bool PRE = false> ...
;     ...
;                 const f32x16 s = qk_rows<0, 4>(Kl, 32 * sub, qf, r, h);
;                 if (mm == 0) smax_step<0>(s, vm, m1, l1, o1, pf, lane); else if (mm == 1) smax_step<1>(s, vm, m1, l1, o1, pf, lane); else smax_step<2>(s, vm, m1, l1, o1, pf, lane);
	v_add_u32_e32 v36, v48, v192
	ds_read_b128 v[32:35], v36
	ds_read_b128 v[50:53], v36 offset:32
	ds_read_b128 v[54:57], v36 offset:64
	ds_read_b128 v[58:61], v36 offset:96
	s_nop 0
	s_waitcnt lgkmcnt(3)
	v_mfma_f32_32x32x16_bf16 v[32:47], v[32:35], v[96:99], 0
	s_waitcnt lgkmcnt(2)
	v_mfma_f32_32x32x16_bf16 v[32:47], v[50:53], v[100:103], v[32:47]
	s_waitcnt lgkmcnt(1)
	v_mfma_f32_32x32x16_bf16 v[32:47], v[54:57], v[104:107], v[32:47]
	s_waitcnt lgkmcnt(0)
	v_mfma_f32_32x32x16_bf16 v[32:47], v[58:61], v[108:111], v[32:47]
	s_nop 0
	v_and_b32_e32 v48, 1, v49
	v_cmp_eq_u32_e32 vcc, 1, v48
	v_and_b32_e32 v48, 2, v49
	v_and_b32_e32 v50, 4, v49
	s_nop 6
	v_cndmask_b32_e32 v32, v208, v32, vcc
	v_cmp_ne_u32_e32 vcc, 0, v48
	s_nop 1
	v_cndmask_b32_e32 v33, v208, v33, vcc
	v_cmp_ne_u32_e32 vcc, 0, v50
	v_and_b32_e32 v50, 8, v49
	v_max3_f32 v48, v32, s15, v33
	v_cndmask_b32_e32 v34, v208, v34, vcc
	v_cmp_ne_u32_e32 vcc, 0, v50
	v_and_b32_e32 v50, 16, v49
	s_nop 0
	v_cndmask_b32_e32 v35, v208, v35, vcc
	v_cmp_ne_u32_e32 vcc, 0, v50
	v_and_b32_e32 v50, 32, v49
	v_max3_f32 v48, v48, v34, v35
	v_cndmask_b32_e32 v36, v208, v36, vcc
	v_cmp_ne_u32_e32 vcc, 0, v50
	v_and_b32_e32 v50, 64, v49
	s_nop 0
	v_cndmask_b32_e32 v37, v208, v37, vcc
	v_cmp_ne_u32_e32 vcc, 0, v50
	v_and_b32_e32 v50, 0x80, v49
	v_max3_f32 v48, v48, v36, v37
	v_cndmask_b32_e32 v38, v208, v38, vcc
	v_cmp_ne_u32_e32 vcc, 0, v50
	v_and_b32_e32 v50, 0x100, v49
	s_nop 0
	v_cndmask_b32_e32 v39, v208, v39, vcc
	v_cmp_ne_u32_e32 vcc, 0, v50
	v_and_b32_e32 v50, 0x200, v49
	v_max3_f32 v48, v48, v38, v39
	v_cndmask_b32_e32 v40, v208, v40, vcc
	v_cmp_ne_u32_e32 vcc, 0, v50
	v_and_b32_e32 v50, 0x400, v49
	s_nop 0
	v_cndmask_b32_e32 v41, v208, v41, vcc
	v_cmp_ne_u32_e32 vcc, 0, v50
	v_and_b32_e32 v50, 0x800, v49
	v_max3_f32 v48, v48, v40, v41
	v_cndmask_b32_e32 v42, v208, v42, vcc
	v_cmp_ne_u32_e32 vcc, 0, v50
	v_and_b32_e32 v50, 0x1000, v49
	s_nop 0
	v_cndmask_b32_e32 v43, v208, v43, vcc
	v_cmp_ne_u32_e32 vcc, 0, v50
	v_and_b32_e32 v50, 0x2000, v49
	v_max3_f32 v48, v48, v42, v43
	v_cndmask_b32_e32 v44, v208, v44, vcc
	v_cmp_ne_u32_e32 vcc, 0, v50
	v_and_b32_e32 v50, 0x4000, v49
	v_and_b32_e32 v49, 0x8000, v49
	v_cndmask_b32_e32 v45, v208, v45, vcc
	v_cmp_ne_u32_e32 vcc, 0, v50
	v_max3_f32 v48, v48, v44, v45
	s_nop 0
	v_cndmask_b32_e32 v46, v208, v46, vcc
	v_cmp_ne_u32_e32 vcc, 0, v49
	s_nop 1
	v_cndmask_b32_e32 v47, v208, v47, vcc
	v_max3_f32 v48, v48, v46, v47
	v_mov_b32_e32 v49, v48
	v_mov_b32_e32 v50, v48
	s_nop 1
	v_permlane32_swap_b32_e32 v49, v50
	v_max_f32_e32 v48, v49, v50
	v_add_f32_e32 v49, 0x41000000, v214
	v_cmp_gt_f32_e32 vcc, v48, v49
	s_nop 1
	v_cndmask_b32_e32 v69, v214, v48, vcc
	v_max_f32_e32 v48, 0xefa18f08, v69
	v_sub_f32_e32 v32, v32, v48
	v_exp_f32_e32 v65, v32
	v_sub_f32_e32 v32, v33, v48
	v_exp_f32_e32 v66, v32
	v_sub_f32_e32 v32, v34, v48
	v_exp_f32_e32 v67, v32
	v_sub_f32_e32 v32, v35, v48
	v_exp_f32_e32 v68, v32
	v_sub_f32_e32 v33, v36, v48
	v_exp_f32_e32 v70, v33
	v_sub_f32_e32 v33, v37, v48
	v_add_f32_e32 v32, v66, v65
	v_exp_f32_e32 v71, v33
	v_sub_f32_e32 v33, v38, v48
	v_add_f32_e32 v32, v67, v32
	v_exp_f32_e32 v72, v33
	v_sub_f32_e32 v33, v39, v48
	v_add_f32_e32 v32, v68, v32
	v_exp_f32_e32 v73, v33
	v_sub_f32_e32 v33, v40, v48
	v_add_f32_e32 v32, v70, v32
	v_exp_f32_e32 v74, v33
	v_sub_f32_e32 v33, v41, v48
	v_add_f32_e32 v32, v71, v32
	v_exp_f32_e32 v75, v33
	v_sub_f32_e32 v33, v42, v48
	v_add_f32_e32 v32, v72, v32
	v_exp_f32_e32 v76, v33
	v_sub_f32_e32 v33, v43, v48
	v_add_f32_e32 v32, v73, v32
	v_exp_f32_e32 v77, v33
	v_sub_f32_e32 v33, v44, v48
	v_add_f32_e32 v32, v74, v32
	v_exp_f32_e32 v78, v33
	v_sub_f32_e32 v33, v45, v48
	v_add_f32_e32 v32, v75, v32
	v_exp_f32_e32 v79, v33
	v_sub_f32_e32 v33, v46, v48
	v_add_f32_e32 v32, v76, v32
	v_exp_f32_e32 v80, v33
	v_sub_f32_e32 v33, v47, v48
	v_add_f32_e32 v32, v77, v32
	v_exp_f32_e32 v81, v33
	v_add_f32_e32 v32, v78, v32
	v_add_f32_e32 v32, v79, v32
	v_add_f32_e32 v32, v80, v32
	v_add_f32_e32 v82, v81, v32
	v_mov_b32_e32 v83, v82
	v_mov_b32_e32 v84, v82
	s_nop 1
	v_permlane32_swap_b32_e32 v83, v84
	v_cmp_neq_f32_e32 vcc, v69, v214
	s_cbranch_vccz .LBB0_664
	v_sub_f32_e32 v32, v214, v69
	v_exp_f32_e32 v32, v32
	v_mov_b32_e32 v214, v69
	v_mul_f32_e32 v213, v213, v32
	v_pk_mul_f32 v[62:63], v[30:31], v[32:33] op_sel_hi:[1,0]
	v_pk_mul_f32 v[60:61], v[28:29], v[32:33] op_sel_hi:[1,0]
	v_pk_mul_f32 v[58:59], v[26:27], v[32:33] op_sel_hi:[1,0]
	v_pk_mul_f32 v[56:57], v[24:25], v[32:33] op_sel_hi:[1,0]
	v_pk_mul_f32 v[54:55], v[22:23], v[32:33] op_sel_hi:[1,0]
	v_pk_mul_f32 v[52:53], v[20:21], v[32:33] op_sel_hi:[1,0]
	v_pk_mul_f32 v[50:51], v[18:19], v[32:33] op_sel_hi:[1,0]
	v_pk_mul_f32 v[48:49], v[16:17], v[32:33] op_sel_hi:[1,0]
	v_pk_mul_f32 v[46:47], v[14:15], v[32:33] op_sel_hi:[1,0]
	v_pk_mul_f32 v[44:45], v[12:13], v[32:33] op_sel_hi:[1,0]
	v_pk_mul_f32 v[42:43], v[10:11], v[32:33] op_sel_hi:[1,0]
	v_pk_mul_f32 v[40:41], v[8:9], v[32:33] op_sel_hi:[1,0]
	v_pk_mul_f32 v[38:39], v[6:7], v[32:33] op_sel_hi:[1,0]
	v_pk_mul_f32 v[36:37], v[4:5], v[32:33] op_sel_hi:[1,0]
	v_pk_mul_f32 v[34:35], v[2:3], v[32:33] op_sel_hi:[1,0]
	v_pk_mul_f32 v[32:33], v[0:1], v[32:33] op_sel_hi:[1,0]
	s_branch .LBB0_665

; #define LAS __attribute__((address_space(3)))
; #define MFMA32(a, b, c) __builtin_amdgcn_mfma_f32_32x32x16_bf16((a), (b), (c), 0, 0, 0)
; DI s16x4 vtr(LAS const char* p) { return __builtin_bit_cast(s16x4, __builtin_amdgcn_ds_read_tr16_b64_v4i16((LAS v4i16_t*)p)); }
; DI void pv_rows(f32x16 (&o)[2], LAS const char* Vl, int row0, const bf16x8 (&pf)[2], int lane) {
;     const int h = lane >> 5, i = lane & 15, grp = (lane >> 4) & 1;
;     LAS const char* base = Vl + (row0 + 4 * h + (i >> 2)) * KP + grp * 32 + (i & 3) * 8;
;     bf16x8 vf[2][2];
; #pragma unroll
;     for (int dt = 0; dt < 2; ++dt)
; #pragma unroll
;         for (int s2 = 0; s2 < 2; ++s2) {
;             const s16x4 lo = vtr(base + (16 * s2) * KP + dt * 64), hi = vtr(base + (16 * s2 + 8) * KP + dt * 64);
;             vf[dt][s2] = (bf16x8){lo[0], lo[1], lo[2], lo[3], hi[0], hi[1], hi[2], hi[3]};
;         }
;     __builtin_amdgcn_s_setprio(1);
; #pragma unroll
;     for (int s2 = 0; s2 < 2; ++s2)
; #pragma unroll
;         for (int dt = 0; dt < 2; ++dt) o[dt] = MFMA32(vf[dt][s2], pf[s2], o[dt]);
;     __builtin_amdgcn_s_setprio(0);
; }
; template <int MM> DI void smax_step(const f32x16& s, unsigned vm, float& m, float& l, f32x16 (&o)[2], bf16x8 (&pf)[2], int lane) {
;     ...
;     l += rs;
;     pack_p(p, pf);
.LBB0_665:
	v_cndmask_b32_e64 v69, v83, v84, s[36:37]
	v_add_f32_e32 v69, v82, v69
	v_add_u32_e32 v64, v64, v191
	v_add_f32_e32 v213, v69, v213
	v_cvt_pk_bf16_f32 v67, v67, v68
	v_cvt_pk_bf16_f32 v68, v70, v71
	v_cvt_pk_bf16_f32 v69, v72, v73
	v_cvt_pk_bf16_f32 v70, v74, v75
	v_cvt_pk_bf16_f32 v71, v76, v77
	v_cvt_pk_bf16_f32 v72, v78, v79
	v_cvt_pk_bf16_f32 v73, v80, v81
	ds_read_b64_tr_b16 v[74:75], v64 offset:13824
	ds_read_b64_tr_b16 v[76:77], v64 offset:14976
	ds_read_b64_tr_b16 v[78:79], v64 offset:16128
	ds_read_b64_tr_b16 v[80:81], v64 offset:17280
	ds_read_b64_tr_b16 v[82:83], v64 offset:13888
	ds_read_b64_tr_b16 v[84:85], v64 offset:15040
	ds_read_b64_tr_b16 v[86:87], v64 offset:16192
	ds_read_b64_tr_b16 v[88:89], v64 offset:17344
	v_cvt_pk_bf16_f32 v66, v65, v66
	s_nop 0
	s_waitcnt lgkmcnt(6)
	v_mfma_f32_32x32x16_bf16 v[32:47], v[74:77], v[66:69], v[32:47]
	s_waitcnt lgkmcnt(2)
	v_mfma_f32_32x32x16_bf16 v[48:63], v[82:85], v[66:69], v[48:63]
	v_mfma_f32_32x32x16_bf16 v[32:47], v[78:81], v[70:73], v[32:47]
	s_waitcnt lgkmcnt(0)
	v_mfma_f32_32x32x16_bf16 v[48:63], v[86:89], v[70:73], v[48:63]
	s_cbranch_execz .LBB0_638
	s_branch .LBB0_637

; #define LAS __attribute__((address_space(3)))
; template <int MM> DI void tile128_pipe(LAS const char* K0, LAS const char* V0, LAS const char* K1, LAS const char* V1, const bf16x8 (&qf)[4], unsigned vm0, unsigned vm1,
;                                        float& m, float& l, f32x16 (&o)[2], int r, int h, int lane) {
;     f32x16 sa = qk_rows<0, 4>(K0, 0, qf, r, h), sb = qk_rows<0, 4>(K0, 32, qf, r, h);
;     bf16x8 pfa[2], pfb[2];
;     smax_step_nb<MM>(sa, vm0, m, l, o, pfa, lane);
;     sa = qk_rows<0, 4>(K1, 0, qf, r, h);
;     pv_rows(o, V0, 0, pfa, lane);
;     smax_step_nb<MM>(sb, vm0, m, l, o, pfb, lane);
;     sb = qk_rows<0, 4>(K1, 32, qf, r, h);
;     pv_rows(o, V0, 32, pfb, lane);
; template <int MODE, bool PRE = false> ...
;     ...
;             const int kt0 = kt_lo + 2 * sti;
;             bool both = (kt0 + 1 <= kt_hi) && (64 * kt0 + 127 <= q0w);
;             if (MODE == MODE_NWIN) both = both && (64 * kt0 > q0w + 31 - 512);
;             if (both) {
;                 bool ls0 = true, ls1 = true;
;                 if (MODE == MODE_MOBA) { ls0 = ((sel >> (kt0 >> 2)) & 1ull) != 0ull; ls1 = ((sel >> ((kt0 + 1) >> 2)) & 1ull) != 0ull; }
;                 if (MODE == MODE_NSEL) { ls0 = ((sel >> kt0) & 1ull) != 0ull; ls1 = ((sel >> (kt0 + 1)) & 1ull) != 0ull; }
;                 const unsigned long long b0 = __builtin_amdgcn_ballot_w64(ls0), b1 = __builtin_amdgcn_ballot_w64(ls1);
;                 if (b0 != 0ull && b1 != 0ull) {
;                     LAS char* K0 = lds + (sti & 1) * 4 * TILE_B;
;                     if ((b0 & b1) == ~0ull) tile128_pipe<0>(K0, K0 + TILE_B, K0 + 2 * TILE_B, K0 + 3 * TILE_B, qf, 1u, 1u, m1, l1, o1, r, h, lane);
.LBB0_675:
	s_lshl_b32 s62, s44, 1
	s_add_i32 s62, s62, s27
	s_cmp_lt_u32 s62, s58
	s_cselect_b64 s[0:1], -1, 0
	s_lshl_b32 s24, s62, 6
	s_add_i32 s10, s24, 0x7f
	s_cmp_le_i32 s10, s59
	s_cselect_b64 s[10:11], -1, 0
	s_and_b64 s[0:1], s[0:1], s[10:11]
	s_cmp_gt_i32 s24, s57
	s_cselect_b64 s[10:11], -1, 0
	s_and_b64 s[0:1], s[0:1], s[10:11]
	s_andn2_b64 vcc, exec, s[0:1]
	s_mov_b32 s0, 0
	s_cbranch_vccnz .LBB0_698
	s_cmp_eq_u64 exec, 0
	s_cbranch_scc1 .LBB0_698
	s_lshl_b32 s0, s44, 2
	s_and_b32 s0, s0, 4
	s_mulk_i32 s0, 0x2400
	s_add_i32 s10, s0, 0
	v_add_u32_e32 v32, s10, v190
	v_add_u32_e32 v212, v32, v168
	s_waitcnt lgkmcnt(7)
	ds_read_b128 v[140:143], v212
	s_waitcnt lgkmcnt(7)
	ds_read_b128 v[136:139], v212 offset:32
	s_waitcnt lgkmcnt(7)
	ds_read_b128 v[132:135], v212 offset:64
	s_waitcnt lgkmcnt(7)
	ds_read_b128 v[128:131], v212 offset:96
	s_cmp_lg_u64 exec, -1
	s_nop 0
	s_nop 0
	s_waitcnt lgkmcnt(7)
	ds_read_b128 v[144:147], v212 offset:4608
	s_waitcnt lgkmcnt(7)
	ds_read_b128 v[148:151], v212 offset:4640
	s_waitcnt lgkmcnt(7)
	ds_read_b128 v[152:155], v212 offset:4672
	s_waitcnt lgkmcnt(7)
	ds_read_b128 v[156:159], v212 offset:4704
	s_nop 0
	s_nop 0
	v_add_f32_e32 v213, 0x41000000, v193
	s_cbranch_scc0 .LBB0_687
	s_waitcnt lgkmcnt(7)
	v_mfma_f32_32x32x16_bf16 v[32:47], v[140:143], v[96:99], 0
	s_waitcnt lgkmcnt(6)
	v_mfma_f32_32x32x16_bf16 v[32:47], v[136:139], v[100:103], v[32:47]
	s_waitcnt lgkmcnt(5)
	v_mfma_f32_32x32x16_bf16 v[32:47], v[132:135], v[104:107], v[32:47]
	s_waitcnt lgkmcnt(4)
	v_mfma_f32_32x32x16_bf16 v[32:47], v[128:131], v[108:111], v[32:47]
	s_waitcnt lgkmcnt(3)
	v_mfma_f32_32x32x16_bf16 v[64:79], v[144:147], v[96:99], 0
	s_nop 9
	v_max3_f32 v48, v32, s15, v33
	v_max3_f32 v48, v48, v34, v35
	v_max3_f32 v48, v48, v36, v37
	v_max3_f32 v48, v48, v38, v39
	v_max3_f32 v48, v48, v40, v41
	v_max3_f32 v48, v48, v42, v43
	v_max3_f32 v48, v48, v44, v45
	v_max3_f32 v48, v48, v46, v47
	v_mov_b32_e32 v49, v48
	v_mov_b32_e32 v50, v48
	s_nop 1
	v_permlane32_swap_b32_e32 v49, v50
	v_max_f32_e32 v48, v49, v50
	v_cmp_gt_f32_e32 vcc, v48, v213
	s_waitcnt lgkmcnt(2)
	v_mfma_f32_32x32x16_bf16 v[64:79], v[148:151], v[100:103], v[64:79]
	v_cndmask_b32_e32 v221, v193, v48, vcc
	v_max_f32_e32 v48, 0xefa18f08, v221
	v_sub_f32_e32 v32, v32, v48
	v_sub_f32_e32 v33, v33, v48
	v_exp_f32_e32 v80, v32
	v_sub_f32_e32 v34, v34, v48
	v_exp_f32_e32 v81, v33
	v_sub_f32_e32 v35, v35, v48
	v_exp_f32_e32 v82, v34
	v_sub_f32_e32 v36, v36, v48
	v_exp_f32_e32 v83, v35
	v_sub_f32_e32 v37, v37, v48
	v_exp_f32_e32 v84, v36
	v_sub_f32_e32 v38, v38, v48
	v_exp_f32_e32 v85, v37
	v_add_f32_e32 v32, v81, v80
	v_sub_f32_e32 v39, v39, v48
	v_exp_f32_e32 v86, v38
	s_waitcnt lgkmcnt(1)
	v_mfma_f32_32x32x16_bf16 v[64:79], v[152:155], v[104:107], v[64:79]
	v_add_f32_e32 v32, v82, v32
	v_sub_f32_e32 v40, v40, v48
	v_exp_f32_e32 v87, v39
	v_add_f32_e32 v32, v83, v32
	v_sub_f32_e32 v41, v41, v48
	v_exp_f32_e32 v88, v40
	v_add_f32_e32 v32, v84, v32
	v_sub_f32_e32 v42, v42, v48
	v_exp_f32_e32 v89, v41
	v_add_f32_e32 v32, v85, v32
	v_sub_f32_e32 v43, v43, v48
	v_exp_f32_e32 v90, v42
	v_add_f32_e32 v32, v86, v32
	v_sub_f32_e32 v44, v44, v48
	v_exp_f32_e32 v91, v43
	v_add_f32_e32 v32, v87, v32
	v_add_f32_e32 v32, v88, v32
	v_exp_f32_e32 v92, v44
	v_sub_f32_e32 v33, v45, v48
	v_add_f32_e32 v32, v89, v32
	v_exp_f32_e32 v93, v33
	v_sub_f32_e32 v33, v46, v48
	s_waitcnt lgkmcnt(0)
	v_mfma_f32_32x32x16_bf16 v[64:79], v[156:159], v[108:111], v[64:79]
	v_add_f32_e32 v32, v90, v32
	v_exp_f32_e32 v94, v33
	v_sub_f32_e32 v33, v47, v48
	v_add_f32_e32 v32, v91, v32
	v_exp_f32_e32 v95, v33
	v_add_f32_e32 v32, v92, v32
	v_sub_f32_e32 v49, v193, v221
	v_add_f32_e32 v32, v93, v32
	v_add_f32_e32 v32, v94, v32
	v_exp_f32_e32 v164, v49
	v_add_f32_e32 v214, v95, v32
	v_mov_b32_e32 v215, v214
	v_mov_b32_e32 v216, v214
	s_nop 0
	s_nop 0
	v_permlane32_swap_b32_e32 v215, v216
	v_cmp_neq_f32_e32 vcc, v221, v193
	s_cbranch_vccz .LBB0_680
	v_pk_mul_f32 v[30:31], v[30:31], v[164:165] op_sel_hi:[1,0]
	v_pk_mul_f32 v[28:29], v[28:29], v[164:165] op_sel_hi:[1,0]
	v_pk_mul_f32 v[26:27], v[26:27], v[164:165] op_sel_hi:[1,0]
	v_pk_mul_f32 v[24:25], v[24:25], v[164:165] op_sel_hi:[1,0]
	v_pk_mul_f32 v[22:23], v[22:23], v[164:165] op_sel_hi:[1,0]
	v_pk_mul_f32 v[20:21], v[20:21], v[164:165] op_sel_hi:[1,0]
	v_pk_mul_f32 v[18:19], v[18:19], v[164:165] op_sel_hi:[1,0]
	v_pk_mul_f32 v[16:17], v[16:17], v[164:165] op_sel_hi:[1,0]
	v_pk_mul_f32 v[14:15], v[14:15], v[164:165] op_sel_hi:[1,0]
	v_pk_mul_f32 v[12:13], v[12:13], v[164:165] op_sel_hi:[1,0]
	v_pk_mul_f32 v[10:11], v[10:11], v[164:165] op_sel_hi:[1,0]
	v_pk_mul_f32 v[8:9], v[8:9], v[164:165] op_sel_hi:[1,0]
	v_pk_mul_f32 v[6:7], v[6:7], v[164:165] op_sel_hi:[1,0]
	v_pk_mul_f32 v[4:5], v[4:5], v[164:165] op_sel_hi:[1,0]
	v_pk_mul_f32 v[2:3], v[2:3], v[164:165] op_sel_hi:[1,0]
	v_pk_mul_f32 v[0:1], v[0:1], v[164:165] op_sel_hi:[1,0]
; #define LAS __attribute__((address_space(3)))
; #define MFMA32(a, b, c) __builtin_amdgcn_mfma_f32_32x32x16_bf16((a), (b), (c), 0, 0, 0)
; template <int KS0, int KS1> DI f32x16 qk_rows(LAS const char* Kl, int row0, const bf16x8 (&qf)[4], int r, int h) {
;     f32x16 s;
; #pragma unroll
;     for (int i = 0; i < 16; ++i) s[i] = 0.f;
;     LAS const char* p = Kl + (row0 + r) * KP + 16 * h;
;     bf16x8 kf[4];
; #pragma unroll
;     for (int ks = KS0; ks < KS1; ++ks) kf[ks] = *(LAS const bf16x8*)(p + 32 * ks);
;     __builtin_amdgcn_s_setprio(1);
; #pragma unroll
;     for (int ks = KS0; ks < KS1; ++ks) s = MFMA32(kf[ks], qf[ks], s);
;     __builtin_amdgcn_s_setprio(0);
;     return s;
; }
; DI void pv_rows(f32x16 (&o)[2], LAS const char* Vl, int row0, const bf16x8 (&pf)[2], int lane) {
;     const int h = lane >> 5, i = lane & 15, grp = (lane >> 4) & 1;
;     LAS const char* base = Vl + (row0 + 4 * h + (i >> 2)) * KP + grp * 32 + (i & 3) * 8;
;     bf16x8 vf[2][2];
; #pragma unroll
;     for (int dt = 0; dt < 2; ++dt)
; #pragma unroll
;         for (int s2 = 0; s2 < 2; ++s2) {
;             const s16x4 lo = vtr(base + (16 * s2) * KP + dt * 64), hi = vtr(base + (16 * s2 + 8) * KP + dt * 64);
;             vf[dt][s2] = (bf16x8){lo[0], lo[1], lo[2], lo[3], hi[0], hi[1], hi[2], hi[3]};
;         }
;     __builtin_amdgcn_s_setprio(1);
; #pragma unroll
;     for (int s2 = 0; s2 < 2; ++s2)
; #pragma unroll
;         for (int dt = 0; dt < 2; ++dt) o[dt] = MFMA32(vf[dt][s2], pf[s2], o[dt]);
;     __builtin_amdgcn_s_setprio(0);
; }
; template <int MM> DI void tile128_pipe(LAS const char* K0, LAS const char* V0, LAS const char* K1, LAS const char* V1, const bf16x8 (&qf)[4], unsigned vm0, unsigned vm1,
;                                        float& m, float& l, f32x16 (&o)[2], int r, int h, int lane) {
;     f32x16 sa = qk_rows<0, 4>(K0, 0, qf, r, h), sb = qk_rows<0, 4>(K0, 32, qf, r, h);
;     bf16x8 pfa[2], pfb[2];
;     smax_step_nb<MM>(sa, vm0, m, l, o, pfa, lane);
;     sa = qk_rows<0, 4>(K1, 0, qf, r, h);
;     pv_rows(o, V0, 0, pfa, lane);
;     smax_step_nb<MM>(sb, vm0, m, l, o, pfb, lane);
;     sb = qk_rows<0, 4>(K1, 32, qf, r, h);
;     pv_rows(o, V0, 32, pfb, lane);
;     smax_step_nb<MM>(sa, vm1, m, l, o, pfa, lane);
;     pv_rows(o, V1, 0, pfa, lane);
;     smax_step_nb<MM>(sb, vm1, m, l, o, pfb, lane);
;     pv_rows(o, V1, 32, pfb, lane);
; }
.LBB0_680:
	v_cvt_pk_bf16_f32 v222, v80, v81
	v_cvt_pk_bf16_f32 v223, v82, v83
	ds_read_b128 v[80:83], v212 offset:18432
	ds_read_b128 v[230:233], v212 offset:18464
	ds_read_b128 v[234:237], v212 offset:18496
	ds_read_b128 v[238:241], v212 offset:18528
	v_cvt_pk_bf16_f32 v224, v84, v85
	v_cvt_pk_bf16_f32 v225, v86, v87
	v_cvt_pk_bf16_f32 v226, v88, v89
	v_cvt_pk_bf16_f32 v227, v90, v91
	v_cvt_pk_bf16_f32 v228, v92, v93
	v_cvt_pk_bf16_f32 v229, v94, v95
	s_nop 0
	s_waitcnt lgkmcnt(3)
	v_mfma_f32_32x32x16_bf16 v[80:95], v[80:83], v[96:99], 0
	s_waitcnt lgkmcnt(2)
	v_mfma_f32_32x32x16_bf16 v[80:95], v[230:233], v[100:103], v[80:95]
	s_waitcnt lgkmcnt(1)
	v_mfma_f32_32x32x16_bf16 v[80:95], v[234:237], v[104:107], v[80:95]
	s_waitcnt lgkmcnt(0)
	v_mfma_f32_32x32x16_bf16 v[80:95], v[238:241], v[108:111], v[80:95]
	s_nop 0
	v_add3_u32 v166, s10, v191, v171
	v_add_u32_e32 v217, v166, v186
	ds_read_b64_tr_b16 v[230:231], v217 offset:9216
	ds_read_b64_tr_b16 v[232:233], v217 offset:10368
	ds_read_b64_tr_b16 v[236:237], v217 offset:10432
	ds_read_b64_tr_b16 v[234:235], v217 offset:9280
	ds_read_b64_tr_b16 v[238:239], v217 offset:11520
	ds_read_b64_tr_b16 v[240:241], v217 offset:12672
	ds_read_b64_tr_b16 v[244:245], v217 offset:12736
	ds_read_b64_tr_b16 v[242:243], v217 offset:11584
	s_nop 0
	s_waitcnt lgkmcnt(6)
	v_mfma_f32_32x32x16_bf16 v[0:15], v[230:233], v[222:225], v[0:15]
	s_waitcnt lgkmcnt(4)
	v_mfma_f32_32x32x16_bf16 v[16:31], v[234:237], v[222:225], v[16:31]
	s_waitcnt lgkmcnt(2)
	v_mfma_f32_32x32x16_bf16 v[0:15], v[238:241], v[226:229], v[0:15]
	s_waitcnt lgkmcnt(0)
	v_mfma_f32_32x32x16_bf16 v[16:31], v[242:245], v[226:229], v[16:31]
	s_nop 0
	v_max3_f32 v166, v64, s15, v65
	v_max3_f32 v166, v166, v66, v67
	v_max3_f32 v166, v166, v68, v69
	v_max3_f32 v166, v166, v70, v71
	v_max3_f32 v166, v166, v72, v73
	v_max3_f32 v166, v166, v74, v75
	v_max3_f32 v166, v166, v76, v77
	v_max3_f32 v166, v166, v78, v79
	v_mov_b32_e32 v172, v166
	v_mov_b32_e32 v173, v166
	s_nop 1
	v_permlane32_swap_b32_e32 v172, v173
	v_max_f32_e32 v166, v172, v173
	v_add_f32_e32 v172, 0x41000000, v221
	v_cmp_gt_f32_e32 vcc, v166, v172
	s_nop 1
	v_cndmask_b32_e32 v222, v221, v166, vcc
	v_max_f32_e32 v166, 0xefa18f08, v222
	v_sub_f32_e32 v64, v64, v166
	v_exp_f32_e32 v64, v64
	v_sub_f32_e32 v65, v65, v166
	v_exp_f32_e32 v65, v65
	v_sub_f32_e32 v66, v66, v166
	v_exp_f32_e32 v66, v66
	v_sub_f32_e32 v67, v67, v166
	v_exp_f32_e32 v67, v67
	v_sub_f32_e32 v68, v68, v166
	v_exp_f32_e32 v68, v68
	v_sub_f32_e32 v69, v69, v166
	v_add_f32_e32 v173, v65, v64
	v_exp_f32_e32 v69, v69
	v_sub_f32_e32 v70, v70, v166
	v_add_f32_e32 v173, v66, v173
	v_exp_f32_e32 v70, v70
	v_sub_f32_e32 v71, v71, v166
	v_add_f32_e32 v173, v67, v173
	v_exp_f32_e32 v71, v71
	v_sub_f32_e32 v72, v72, v166
	v_add_f32_e32 v173, v68, v173
	v_exp_f32_e32 v72, v72
	v_sub_f32_e32 v73, v73, v166
	v_add_f32_e32 v173, v69, v173
	v_exp_f32_e32 v73, v73
	v_sub_f32_e32 v74, v74, v166
	v_add_f32_e32 v173, v70, v173
	v_exp_f32_e32 v74, v74
	v_sub_f32_e32 v75, v75, v166
	v_add_f32_e32 v173, v71, v173
	v_exp_f32_e32 v75, v75
	v_sub_f32_e32 v76, v76, v166
	v_add_f32_e32 v173, v72, v173
	v_exp_f32_e32 v76, v76
	v_sub_f32_e32 v77, v77, v166
	v_add_f32_e32 v173, v73, v173
	v_exp_f32_e32 v77, v77
	v_sub_f32_e32 v78, v78, v166
	v_add_f32_e32 v173, v74, v173
	v_exp_f32_e32 v78, v78
	v_sub_f32_e32 v79, v79, v166
	v_add_f32_e32 v173, v75, v173
	v_exp_f32_e32 v79, v79
	v_add_f32_e32 v166, v76, v173
	v_add_f32_e32 v166, v77, v166
	v_sub_f32_e32 v172, v221, v222
	v_add_f32_e32 v166, v78, v166
	v_add_f32_e32 v218, v79, v166
	v_exp_f32_e32 v166, v172
	v_mov_b32_e32 v219, v218
	v_mov_b32_e32 v220, v218
	s_nop 1
	v_permlane32_swap_b32_e32 v219, v220
	v_cmp_neq_f32_e32 vcc, v222, v221
	s_cbranch_vccz .LBB0_682
	v_pk_mul_f32 v[30:31], v[30:31], v[166:167] op_sel_hi:[1,0]
	v_pk_mul_f32 v[28:29], v[28:29], v[166:167] op_sel_hi:[1,0]
	v_pk_mul_f32 v[26:27], v[26:27], v[166:167] op_sel_hi:[1,0]
	v_pk_mul_f32 v[24:25], v[24:25], v[166:167] op_sel_hi:[1,0]
	v_pk_mul_f32 v[22:23], v[22:23], v[166:167] op_sel_hi:[1,0]
	v_pk_mul_f32 v[20:21], v[20:21], v[166:167] op_sel_hi:[1,0]
	v_pk_mul_f32 v[18:19], v[18:19], v[166:167] op_sel_hi:[1,0]
	v_pk_mul_f32 v[16:17], v[16:17], v[166:167] op_sel_hi:[1,0]
	v_pk_mul_f32 v[14:15], v[14:15], v[166:167] op_sel_hi:[1,0]
	v_pk_mul_f32 v[12:13], v[12:13], v[166:167] op_sel_hi:[1,0]
	v_pk_mul_f32 v[10:11], v[10:11], v[166:167] op_sel_hi:[1,0]
	v_pk_mul_f32 v[8:9], v[8:9], v[166:167] op_sel_hi:[1,0]
	v_pk_mul_f32 v[6:7], v[6:7], v[166:167] op_sel_hi:[1,0]
	v_pk_mul_f32 v[4:5], v[4:5], v[166:167] op_sel_hi:[1,0]
	v_pk_mul_f32 v[2:3], v[2:3], v[166:167] op_sel_hi:[1,0]
	v_pk_mul_f32 v[0:1], v[0:1], v[166:167] op_sel_hi:[1,0]
; #define LAS __attribute__((address_space(3)))
; #define MFMA32(a, b, c) __builtin_amdgcn_mfma_f32_32x32x16_bf16((a), (b), (c), 0, 0, 0)
; template <int KS0, int KS1> DI f32x16 qk_rows(LAS const char* Kl, int row0, const bf16x8 (&qf)[4], int r, int h) {
;     f32x16 s;
; #pragma unroll
;     for (int i = 0; i < 16; ++i) s[i] = 0.f;
;     LAS const char* p = Kl + (row0 + r) * KP + 16 * h;
;     bf16x8 kf[4];
; #pragma unroll
;     for (int ks = KS0; ks < KS1; ++ks) kf[ks] = *(LAS const bf16x8*)(p + 32 * ks);
;     __builtin_amdgcn_s_setprio(1);
; #pragma unroll
;     for (int ks = KS0; ks < KS1; ++ks) s = MFMA32(kf[ks], qf[ks], s);
;     __builtin_amdgcn_s_setprio(0);
;     return s;
; }
; DI void pv_rows(f32x16 (&o)[2], LAS const char* Vl, int row0, const bf16x8 (&pf)[2], int lane) {
;     const int h = lane >> 5, i = lane & 15, grp = (lane >> 4) & 1;
;     LAS const char* base = Vl + (row0 + 4 * h + (i >> 2)) * KP + grp * 32 + (i & 3) * 8;
;     bf16x8 vf[2][2];
; #pragma unroll
;     for (int dt = 0; dt < 2; ++dt)
; #pragma unroll
;         for (int s2 = 0; s2 < 2; ++s2) {
;             const s16x4 lo = vtr(base + (16 * s2) * KP + dt * 64), hi = vtr(base + (16 * s2 + 8) * KP + dt * 64);
;             vf[dt][s2] = (bf16x8){lo[0], lo[1], lo[2], lo[3], hi[0], hi[1], hi[2], hi[3]};
;         }
;     __builtin_amdgcn_s_setprio(1);
; #pragma unroll
;     for (int s2 = 0; s2 < 2; ++s2)
; #pragma unroll
;         for (int dt = 0; dt < 2; ++dt) o[dt] = MFMA32(vf[dt][s2], pf[s2], o[dt]);
;     __builtin_amdgcn_s_setprio(0);
; }
; template <int MM> DI void tile128_pipe(LAS const char* K0, LAS const char* V0, LAS const char* K1, LAS const char* V1, const bf16x8 (&qf)[4], unsigned vm0, unsigned vm1,
;                                        float& m, float& l, f32x16 (&o)[2], int r, int h, int lane) {
;     f32x16 sa = qk_rows<0, 4>(K0, 0, qf, r, h), sb = qk_rows<0, 4>(K0, 32, qf, r, h);
;     bf16x8 pfa[2], pfb[2];
;     smax_step_nb<MM>(sa, vm0, m, l, o, pfa, lane);
;     sa = qk_rows<0, 4>(K1, 0, qf, r, h);
;     pv_rows(o, V0, 0, pfa, lane);
;     smax_step_nb<MM>(sb, vm0, m, l, o, pfb, lane);
;     sb = qk_rows<0, 4>(K1, 32, qf, r, h);
;     pv_rows(o, V0, 32, pfb, lane);
;     smax_step_nb<MM>(sa, vm1, m, l, o, pfa, lane);
;     pv_rows(o, V1, 0, pfa, lane);
;     smax_step_nb<MM>(sb, vm1, m, l, o, pfb, lane);
;     pv_rows(o, V1, 32, pfb, lane);
; }
.LBB0_682:
	v_cvt_pk_bf16_f32 v224, v64, v65
	v_cvt_pk_bf16_f32 v225, v66, v67
	ds_read_b128 v[64:67], v212 offset:23040
	ds_read_b128 v[232:235], v212 offset:23072
	ds_read_b128 v[236:239], v212 offset:23104
	ds_read_b128 v[240:243], v212 offset:23136
	v_cvt_pk_bf16_f32 v226, v68, v69
	v_cvt_pk_bf16_f32 v227, v70, v71
	v_cvt_pk_bf16_f32 v228, v72, v73
	v_cvt_pk_bf16_f32 v229, v74, v75
	v_cvt_pk_bf16_f32 v230, v76, v77
	v_cvt_pk_bf16_f32 v231, v78, v79
	s_nop 0
	s_waitcnt lgkmcnt(3)
	v_mfma_f32_32x32x16_bf16 v[64:79], v[64:67], v[96:99], 0
	s_waitcnt lgkmcnt(2)
	v_mfma_f32_32x32x16_bf16 v[64:79], v[232:235], v[100:103], v[64:79]
	s_waitcnt lgkmcnt(1)
	v_mfma_f32_32x32x16_bf16 v[64:79], v[236:239], v[104:107], v[64:79]
	s_waitcnt lgkmcnt(0)
	v_mfma_f32_32x32x16_bf16 v[64:79], v[240:243], v[108:111], v[64:79]
	s_nop 0
	ds_read_b64_tr_b16 v[232:233], v217 offset:13824
	ds_read_b64_tr_b16 v[234:235], v217 offset:14976
	ds_read_b64_tr_b16 v[238:239], v217 offset:15040
	ds_read_b64_tr_b16 v[236:237], v217 offset:13888
	ds_read_b64_tr_b16 v[240:241], v217 offset:16128
	ds_read_b64_tr_b16 v[242:243], v217 offset:17280
	ds_read_b64_tr_b16 v[246:247], v217 offset:17344
	ds_read_b64_tr_b16 v[244:245], v217 offset:16192
	s_nop 0
	s_waitcnt lgkmcnt(6)
	v_mfma_f32_32x32x16_bf16 v[0:15], v[232:235], v[224:227], v[0:15]
	s_waitcnt lgkmcnt(4)
	v_mfma_f32_32x32x16_bf16 v[16:31], v[236:239], v[224:227], v[16:31]
	s_waitcnt lgkmcnt(2)
	v_mfma_f32_32x32x16_bf16 v[0:15], v[240:243], v[228:231], v[0:15]
	s_waitcnt lgkmcnt(0)
	v_mfma_f32_32x32x16_bf16 v[16:31], v[244:247], v[228:231], v[16:31]
	s_nop 0
	v_max3_f32 v172, v80, s15, v81
	v_max3_f32 v172, v172, v82, v83
	v_max3_f32 v172, v172, v84, v85
	v_max3_f32 v172, v172, v86, v87
	v_max3_f32 v172, v172, v88, v89
	v_max3_f32 v172, v172, v90, v91
	v_max3_f32 v172, v172, v92, v93
	v_max3_f32 v172, v172, v94, v95
	v_mov_b32_e32 v173, v172
	v_mov_b32_e32 v206, v172
	s_nop 1
	v_permlane32_swap_b32_e32 v173, v206
	v_cndmask_b32_e64 v173, v173, v206, s[36:37]
	v_max_f32_e32 v173, v173, v173
	v_max_f32_e32 v172, v172, v173
	v_add_f32_e32 v173, 0x41000000, v222
	v_cmp_gt_f32_e32 vcc, v172, v173
	s_nop 1
	v_cndmask_b32_e32 v221, v222, v172, vcc
	v_max_f32_e32 v172, 0xefa18f08, v221
	v_sub_f32_e32 v80, v80, v172
	v_exp_f32_e32 v223, v80
	v_sub_f32_e32 v80, v81, v172
	v_exp_f32_e32 v81, v80
	v_sub_f32_e32 v80, v82, v172
	v_exp_f32_e32 v224, v80
	v_sub_f32_e32 v80, v83, v172
	v_exp_f32_e32 v225, v80
	v_sub_f32_e32 v82, v84, v172
	v_exp_f32_e32 v226, v82
	v_sub_f32_e32 v82, v85, v172
	v_add_f32_e32 v80, v81, v223
	v_exp_f32_e32 v85, v82
	v_sub_f32_e32 v82, v86, v172
	v_add_f32_e32 v80, v224, v80
	v_exp_f32_e32 v86, v82
	v_sub_f32_e32 v82, v87, v172
	v_add_f32_e32 v80, v225, v80
	v_exp_f32_e32 v87, v82
	v_sub_f32_e32 v82, v88, v172
	v_add_f32_e32 v80, v226, v80
	v_exp_f32_e32 v88, v82
	v_sub_f32_e32 v82, v89, v172
	v_add_f32_e32 v80, v85, v80
	v_exp_f32_e32 v89, v82
	v_sub_f32_e32 v82, v90, v172
	v_add_f32_e32 v80, v86, v80
	v_exp_f32_e32 v90, v82
	v_sub_f32_e32 v82, v91, v172
	v_add_f32_e32 v80, v87, v80
	v_exp_f32_e32 v91, v82
	v_sub_f32_e32 v82, v92, v172
	v_add_f32_e32 v80, v88, v80
	v_exp_f32_e32 v92, v82
	v_sub_f32_e32 v82, v93, v172
	v_add_f32_e32 v80, v89, v80
	v_exp_f32_e32 v93, v82
	v_sub_f32_e32 v82, v94, v172
	v_add_f32_e32 v80, v90, v80
	v_exp_f32_e32 v94, v82
	v_sub_f32_e32 v82, v95, v172
	v_add_f32_e32 v80, v91, v80
	v_exp_f32_e32 v95, v82
	v_add_f32_e32 v80, v92, v80
	v_add_f32_e32 v80, v93, v80
	v_sub_f32_e32 v173, v222, v221
	v_add_f32_e32 v80, v94, v80
	v_add_f32_e32 v82, v95, v80
	v_exp_f32_e32 v80, v173
	v_mov_b32_e32 v83, v82
	v_mov_b32_e32 v84, v82
	s_nop 1
	v_permlane32_swap_b32_e32 v83, v84
	v_cmp_neq_f32_e32 vcc, v221, v222
	s_cbranch_vccz .LBB0_684
	v_pk_mul_f32 v[30:31], v[30:31], v[80:81] op_sel_hi:[1,0]
	v_pk_mul_f32 v[28:29], v[28:29], v[80:81] op_sel_hi:[1,0]
	v_pk_mul_f32 v[26:27], v[26:27], v[80:81] op_sel_hi:[1,0]
	v_pk_mul_f32 v[24:25], v[24:25], v[80:81] op_sel_hi:[1,0]
	v_pk_mul_f32 v[22:23], v[22:23], v[80:81] op_sel_hi:[1,0]
	v_pk_mul_f32 v[20:21], v[20:21], v[80:81] op_sel_hi:[1,0]
	v_pk_mul_f32 v[18:19], v[18:19], v[80:81] op_sel_hi:[1,0]
	v_pk_mul_f32 v[16:17], v[16:17], v[80:81] op_sel_hi:[1,0]
	v_pk_mul_f32 v[14:15], v[14:15], v[80:81] op_sel_hi:[1,0]
	v_pk_mul_f32 v[12:13], v[12:13], v[80:81] op_sel_hi:[1,0]
	v_pk_mul_f32 v[10:11], v[10:11], v[80:81] op_sel_hi:[1,0]
	v_pk_mul_f32 v[8:9], v[8:9], v[80:81] op_sel_hi:[1,0]
	v_pk_mul_f32 v[6:7], v[6:7], v[80:81] op_sel_hi:[1,0]
	v_pk_mul_f32 v[4:5], v[4:5], v[80:81] op_sel_hi:[1,0]
	v_pk_mul_f32 v[2:3], v[2:3], v[80:81] op_sel_hi:[1,0]
	v_pk_mul_f32 v[0:1], v[0:1], v[80:81] op_sel_hi:[1,0]
; #define LAS __attribute__((address_space(3)))
; #define MFMA32(a, b, c) __builtin_amdgcn_mfma_f32_32x32x16_bf16((a), (b), (c), 0, 0, 0)
; DI s16x4 vtr(LAS const char* p) { return __builtin_bit_cast(s16x4, __builtin_amdgcn_ds_read_tr16_b64_v4i16((LAS v4i16_t*)p)); }
; DI void pv_rows(f32x16 (&o)[2], LAS const char* Vl, int row0, const bf16x8 (&pf)[2], int lane) {
;     const int h = lane >> 5, i = lane & 15, grp = (lane >> 4) & 1;
;     LAS const char* base = Vl + (row0 + 4 * h + (i >> 2)) * KP + grp * 32 + (i & 3) * 8;
;     bf16x8 vf[2][2];
; #pragma unroll
;     for (int dt = 0; dt < 2; ++dt)
; #pragma unroll
;         for (int s2 = 0; s2 < 2; ++s2) {
;             const s16x4 lo = vtr(base + (16 * s2) * KP + dt * 64), hi = vtr(base + (16 * s2 + 8) * KP + dt * 64);
;             vf[dt][s2] = (bf16x8){lo[0], lo[1], lo[2], lo[3], hi[0], hi[1], hi[2], hi[3]};
;         }
;     __builtin_amdgcn_s_setprio(1);
; #pragma unroll
;     for (int s2 = 0; s2 < 2; ++s2)
; #pragma unroll
;         for (int dt = 0; dt < 2; ++dt) o[dt] = MFMA32(vf[dt][s2], pf[s2], o[dt]);
;     __builtin_amdgcn_s_setprio(0);
; }
; template <int MM> DI void tile128_pipe(LAS const char* K0, LAS const char* V0, LAS const char* K1, LAS const char* V1, const bf16x8 (&qf)[4], unsigned vm0, unsigned vm1,
;                                        float& m, float& l, f32x16 (&o)[2], int r, int h, int lane) {
;     f32x16 sa = qk_rows<0, 4>(K0, 0, qf, r, h), sb = qk_rows<0, 4>(K0, 32, qf, r, h);
;     bf16x8 pfa[2], pfb[2];
;     smax_step_nb<MM>(sa, vm0, m, l, o, pfa, lane);
;     sa = qk_rows<0, 4>(K1, 0, qf, r, h);
;     pv_rows(o, V0, 0, pfa, lane);
;     smax_step_nb<MM>(sb, vm0, m, l, o, pfb, lane);
;     sb = qk_rows<0, 4>(K1, 32, qf, r, h);
;     pv_rows(o, V0, 32, pfb, lane);
;     smax_step_nb<MM>(sa, vm1, m, l, o, pfa, lane);
;     pv_rows(o, V1, 0, pfa, lane);
;     smax_step_nb<MM>(sb, vm1, m, l, o, pfb, lane);
;     pv_rows(o, V1, 32, pfb, lane);
; }
.LBB0_684:
	v_cvt_pk_bf16_f32 v222, v223, v81
	v_cvt_pk_bf16_f32 v223, v224, v225
	v_cvt_pk_bf16_f32 v224, v226, v85
	v_cvt_pk_bf16_f32 v225, v86, v87
	v_cvt_pk_bf16_f32 v86, v88, v89
	v_cvt_pk_bf16_f32 v87, v90, v91
	v_cvt_pk_bf16_f32 v88, v92, v93
	ds_read_b64_tr_b16 v[90:91], v217 offset:27648
	ds_read_b64_tr_b16 v[92:93], v217 offset:28800
	ds_read_b64_tr_b16 v[226:227], v217 offset:29952
	ds_read_b64_tr_b16 v[228:229], v217 offset:31104
	ds_read_b64_tr_b16 v[230:231], v217 offset:27712
	ds_read_b64_tr_b16 v[232:233], v217 offset:28864
	ds_read_b64_tr_b16 v[234:235], v217 offset:30016
	ds_read_b64_tr_b16 v[236:237], v217 offset:31168
	v_cvt_pk_bf16_f32 v89, v94, v95
	s_nop 0
	s_waitcnt lgkmcnt(6)
	v_mfma_f32_32x32x16_bf16 v[0:15], v[90:93], v[222:225], v[0:15]
	s_waitcnt lgkmcnt(2)
	v_mfma_f32_32x32x16_bf16 v[16:31], v[230:233], v[222:225], v[16:31]
	v_mfma_f32_32x32x16_bf16 v[0:15], v[226:229], v[86:89], v[0:15]
	s_waitcnt lgkmcnt(0)
	v_mfma_f32_32x32x16_bf16 v[16:31], v[234:237], v[86:89], v[16:31]
	s_nop 0
	v_max3_f32 v81, v64, s15, v65
	v_max3_f32 v81, v81, v66, v67
	v_max3_f32 v81, v81, v68, v69
	v_max3_f32 v81, v81, v70, v71
	v_max3_f32 v81, v81, v72, v73
	v_max3_f32 v81, v81, v74, v75
	v_max3_f32 v81, v81, v76, v77
	v_max3_f32 v81, v81, v78, v79
	v_mov_b32_e32 v85, v81
	v_mov_b32_e32 v86, v81
	s_nop 1
	v_permlane32_swap_b32_e32 v85, v86
	v_max_f32_e32 v81, v85, v86
	v_add_f32_e32 v85, 0x41000000, v221
	v_cmp_gt_f32_e32 vcc, v81, v85
	s_nop 1
	v_cndmask_b32_e32 v81, v221, v81, vcc
	v_max_f32_e32 v93, 0xefa18f08, v81
	v_sub_f32_e32 v64, v64, v93
	v_exp_f32_e32 v85, v64
	v_sub_f32_e32 v64, v65, v93
	v_exp_f32_e32 v86, v64
	v_sub_f32_e32 v64, v66, v93
	v_exp_f32_e32 v87, v64
	v_sub_f32_e32 v64, v67, v93
	v_exp_f32_e32 v88, v64
	v_sub_f32_e32 v65, v68, v93
	v_exp_f32_e32 v89, v65
	v_sub_f32_e32 v65, v69, v93
	v_add_f32_e32 v64, v86, v85
	v_exp_f32_e32 v90, v65
	v_sub_f32_e32 v65, v70, v93
	v_add_f32_e32 v64, v87, v64
	v_exp_f32_e32 v91, v65
	v_sub_f32_e32 v65, v71, v93
	v_add_f32_e32 v64, v88, v64
	v_exp_f32_e32 v92, v65
	v_sub_f32_e32 v65, v72, v93
	v_add_f32_e32 v64, v89, v64
	v_exp_f32_e32 v66, v65
	v_sub_f32_e32 v65, v73, v93
	v_add_f32_e32 v64, v90, v64
	v_exp_f32_e32 v67, v65
	v_sub_f32_e32 v65, v74, v93
	v_add_f32_e32 v64, v91, v64
	v_exp_f32_e32 v68, v65
	v_sub_f32_e32 v65, v75, v93
	v_add_f32_e32 v64, v92, v64
	v_exp_f32_e32 v69, v65
	v_sub_f32_e32 v65, v76, v93
	v_add_f32_e32 v64, v66, v64
	v_exp_f32_e32 v70, v65
	v_sub_f32_e32 v65, v77, v93
	v_add_f32_e32 v64, v67, v64
	v_exp_f32_e32 v71, v65
	v_sub_f32_e32 v65, v78, v93
	v_add_f32_e32 v64, v68, v64
	v_exp_f32_e32 v72, v65
	v_sub_f32_e32 v65, v79, v93
	v_add_f32_e32 v64, v69, v64
	v_exp_f32_e32 v73, v65
	v_add_f32_e32 v64, v70, v64
	v_add_f32_e32 v64, v71, v64
	v_sub_f32_e32 v94, v221, v81
	v_add_f32_e32 v64, v72, v64
	v_add_f32_e32 v65, v73, v64
	v_exp_f32_e32 v64, v94
	v_mov_b32_e32 v74, v65
	v_mov_b32_e32 v75, v65
	s_nop 1
	v_permlane32_swap_b32_e32 v74, v75
	v_cmp_neq_f32_e32 vcc, v81, v221
	s_cbranch_vccz .LBB0_686
	v_pk_mul_f32 v[30:31], v[30:31], v[64:65] op_sel_hi:[1,0]
	v_pk_mul_f32 v[28:29], v[28:29], v[64:65] op_sel_hi:[1,0]
	v_pk_mul_f32 v[26:27], v[26:27], v[64:65] op_sel_hi:[1,0]
	v_pk_mul_f32 v[24:25], v[24:25], v[64:65] op_sel_hi:[1,0]
	v_pk_mul_f32 v[22:23], v[22:23], v[64:65] op_sel_hi:[1,0]
	v_pk_mul_f32 v[20:21], v[20:21], v[64:65] op_sel_hi:[1,0]
	v_pk_mul_f32 v[18:19], v[18:19], v[64:65] op_sel_hi:[1,0]
	v_pk_mul_f32 v[16:17], v[16:17], v[64:65] op_sel_hi:[1,0]
	v_pk_mul_f32 v[14:15], v[14:15], v[64:65] op_sel_hi:[1,0]
	v_pk_mul_f32 v[12:13], v[12:13], v[64:65] op_sel_hi:[1,0]
	v_pk_mul_f32 v[10:11], v[10:11], v[64:65] op_sel_hi:[1,0]
	v_pk_mul_f32 v[8:9], v[8:9], v[64:65] op_sel_hi:[1,0]
	v_pk_mul_f32 v[6:7], v[6:7], v[64:65] op_sel_hi:[1,0]
	v_pk_mul_f32 v[4:5], v[4:5], v[64:65] op_sel_hi:[1,0]
	v_pk_mul_f32 v[2:3], v[2:3], v[64:65] op_sel_hi:[1,0]
	v_pk_mul_f32 v[0:1], v[0:1], v[64:65] op_sel_hi:[1,0]
.LBB0_686:
	v_cndmask_b32_e64 v76, v215, v216, s[36:37]
	v_add_f32_e32 v76, v214, v76
	v_cndmask_b32_e64 v77, v219, v220, s[36:37]
	v_fmac_f32_e32 v76, v184, v164
	v_add_f32_e32 v77, v218, v77
	v_fmac_f32_e32 v77, v76, v166
	v_cndmask_b32_e64 v76, v83, v84, s[36:37]
	v_add_f32_e32 v76, v82, v76
	v_cndmask_b32_e64 v74, v74, v75, s[36:37]
	v_fmac_f32_e32 v76, v77, v80
	v_add_f32_e32 v65, v65, v74
	v_fmac_f32_e32 v65, v76, v64
	v_cvt_pk_bf16_f32 v74, v85, v86
	v_cvt_pk_bf16_f32 v75, v87, v88
	v_cvt_pk_bf16_f32 v76, v89, v90
	v_cvt_pk_bf16_f32 v77, v91, v92
	ds_read_b64_tr_b16 v[84:85], v217 offset:33408
	ds_read_b64_tr_b16 v[86:87], v217 offset:34560
	ds_read_b64_tr_b16 v[90:91], v217 offset:34624
	ds_read_b64_tr_b16 v[220:221], v217 offset:33472
	ds_read_b64_tr_b16 v[82:83], v217 offset:32256
	ds_read_b64_tr_b16 v[88:89], v217 offset:35712
	ds_read_b64_tr_b16 v[218:219], v217 offset:32320
	ds_read_b64_tr_b16 v[92:93], v217 offset:35776
	v_cvt_pk_bf16_f32 v66, v66, v67
	v_cvt_pk_bf16_f32 v67, v68, v69
	v_cvt_pk_bf16_f32 v68, v70, v71
	v_cvt_pk_bf16_f32 v69, v72, v73
	s_nop 0
	s_waitcnt lgkmcnt(3)
	v_mfma_f32_32x32x16_bf16 v[0:15], v[82:85], v[74:77], v[0:15]
	s_waitcnt lgkmcnt(1)
	v_mfma_f32_32x32x16_bf16 v[16:31], v[218:221], v[74:77], v[16:31]
	v_mfma_f32_32x32x16_bf16 v[0:15], v[86:89], v[66:69], v[0:15]
	s_waitcnt lgkmcnt(0)
	v_mfma_f32_32x32x16_bf16 v[16:31], v[90:93], v[66:69], v[16:31]
	s_branch .LBB0_697

; #define LAS __attribute__((address_space(3)))
; #define MFMA32(a, b, c) __builtin_amdgcn_mfma_f32_32x32x16_bf16((a), (b), (c), 0, 0, 0)
; template <int KS0, int KS1> DI f32x16 qk_rows(LAS const char* Kl, int row0, const bf16x8 (&qf)[4], int r, int h) {
;     f32x16 s;
; #pragma unroll
;     for (int i = 0; i < 16; ++i) s[i] = 0.f;
;     LAS const char* p = Kl + (row0 + r) * KP + 16 * h;
;     bf16x8 kf[4];
; #pragma unroll
;     for (int ks = KS0; ks < KS1; ++ks) kf[ks] = *(LAS const bf16x8*)(p + 32 * ks);
;     __builtin_amdgcn_s_setprio(1);
; #pragma unroll
;     for (int ks = KS0; ks < KS1; ++ks) s = MFMA32(kf[ks], qf[ks], s);
;     __builtin_amdgcn_s_setprio(0);
;     return s;
; }
; DI void pv_rows(f32x16 (&o)[2], LAS const char* Vl, int row0, const bf16x8 (&pf)[2], int lane) {
;     const int h = lane >> 5, i = lane & 15, grp = (lane >> 4) & 1;
;     LAS const char* base = Vl + (row0 + 4 * h + (i >> 2)) * KP + grp * 32 + (i & 3) * 8;
;     bf16x8 vf[2][2];
; #pragma unroll
;     for (int dt = 0; dt < 2; ++dt)
; #pragma unroll
;         for (int s2 = 0; s2 < 2; ++s2) {
;             const s16x4 lo = vtr(base + (16 * s2) * KP + dt * 64), hi = vtr(base + (16 * s2 + 8) * KP + dt * 64);
;             vf[dt][s2] = (bf16x8){lo[0], lo[1], lo[2], lo[3], hi[0], hi[1], hi[2], hi[3]};
;         }
;     __builtin_amdgcn_s_setprio(1);
; #pragma unroll
;     for (int s2 = 0; s2 < 2; ++s2)
; #pragma unroll
;         for (int dt = 0; dt < 2; ++dt) o[dt] = MFMA32(vf[dt][s2], pf[s2], o[dt]);
;     __builtin_amdgcn_s_setprio(0);
; }
; template <int MM> DI void tile128_pipe(LAS const char* K0, LAS const char* V0, LAS const char* K1, LAS const char* V1, const bf16x8 (&qf)[4], unsigned vm0, unsigned vm1,
;                                        float& m, float& l, f32x16 (&o)[2], int r, int h, int lane) {
;     f32x16 sa = qk_rows<0, 4>(K0, 0, qf, r, h), sb = qk_rows<0, 4>(K0, 32, qf, r, h);
;     bf16x8 pfa[2], pfb[2];
;     smax_step_nb<MM>(sa, vm0, m, l, o, pfa, lane);
;     sa = qk_rows<0, 4>(K1, 0, qf, r, h);
;     pv_rows(o, V0, 0, pfa, lane);
;     smax_step_nb<MM>(sb, vm0, m, l, o, pfb, lane);
;     sb = qk_rows<0, 4>(K1, 32, qf, r, h);
;     pv_rows(o, V0, 32, pfb, lane);
;     smax_step_nb<MM>(sa, vm1, m, l, o, pfa, lane);
;     pv_rows(o, V1, 0, pfa, lane);
;     smax_step_nb<MM>(sb, vm1, m, l, o, pfb, lane);
;     pv_rows(o, V1, 32, pfb, lane);
; }
.LBB0_690:
	v_cvt_pk_bf16_f32 v74, v48, v49
	v_cvt_pk_bf16_f32 v75, v50, v51
	ds_read_b128 v[48:51], v212 offset:18432
	ds_read_b128 v[82:85], v212 offset:18464
	ds_read_b128 v[86:89], v212 offset:18496
	ds_read_b128 v[90:93], v212 offset:18528
	v_cvt_pk_bf16_f32 v76, v52, v53
	v_cvt_pk_bf16_f32 v77, v54, v55
	v_cvt_pk_bf16_f32 v78, v56, v57
	v_cvt_pk_bf16_f32 v79, v58, v59
	v_cvt_pk_bf16_f32 v80, v60, v61
	v_cvt_pk_bf16_f32 v81, v62, v63
	s_nop 0
	s_waitcnt lgkmcnt(3)
	v_mfma_f32_32x32x16_bf16 v[48:63], v[48:51], v[96:99], 0
	s_waitcnt lgkmcnt(2)
	v_mfma_f32_32x32x16_bf16 v[48:63], v[82:85], v[100:103], v[48:63]
	s_waitcnt lgkmcnt(1)
	v_mfma_f32_32x32x16_bf16 v[48:63], v[86:89], v[104:107], v[48:63]
	s_waitcnt lgkmcnt(0)
	v_mfma_f32_32x32x16_bf16 v[48:63], v[90:93], v[108:111], v[48:63]
	s_nop 0
	v_add3_u32 v66, s10, v191, v171
	v_add_u32_e32 v69, v66, v186
	ds_read_b64_tr_b16 v[82:83], v69 offset:9216
	ds_read_b64_tr_b16 v[84:85], v69 offset:10368
	ds_read_b64_tr_b16 v[88:89], v69 offset:10432
	ds_read_b64_tr_b16 v[86:87], v69 offset:9280
	ds_read_b64_tr_b16 v[90:91], v69 offset:11520
	ds_read_b64_tr_b16 v[92:93], v69 offset:12672
	ds_read_b64_tr_b16 v[130:131], v69 offset:12736
	ds_read_b64_tr_b16 v[128:129], v69 offset:11584
	s_nop 0
	s_waitcnt lgkmcnt(6)
	v_mfma_f32_32x32x16_bf16 v[0:15], v[82:85], v[74:77], v[0:15]
	s_waitcnt lgkmcnt(4)
	v_mfma_f32_32x32x16_bf16 v[16:31], v[86:89], v[74:77], v[16:31]
	s_waitcnt lgkmcnt(2)
	v_mfma_f32_32x32x16_bf16 v[0:15], v[90:93], v[78:81], v[0:15]
	s_waitcnt lgkmcnt(0)
	v_mfma_f32_32x32x16_bf16 v[16:31], v[128:131], v[78:81], v[16:31]
	s_nop 0
	v_max3_f32 v66, v32, s15, v33
	v_max3_f32 v66, v66, v34, v35
	v_max3_f32 v66, v66, v36, v37
	v_max3_f32 v66, v66, v38, v39
	v_max3_f32 v66, v66, v40, v41
	v_max3_f32 v66, v66, v42, v43
	v_max3_f32 v66, v66, v44, v45
	v_max3_f32 v66, v66, v46, v47
	v_mov_b32_e32 v70, v66
	v_mov_b32_e32 v71, v66
	s_nop 1
	v_permlane32_swap_b32_e32 v70, v71
	v_max_f32_e32 v66, v70, v71
	v_add_f32_e32 v70, 0x41000000, v73
	v_cmp_gt_f32_e32 vcc, v66, v70
	s_nop 1
	v_cndmask_b32_e32 v74, v73, v66, vcc
	v_max_f32_e32 v66, 0xefa18f08, v74
	v_sub_f32_e32 v32, v32, v66
	v_exp_f32_e32 v32, v32
	v_sub_f32_e32 v33, v33, v66
	v_exp_f32_e32 v33, v33
	v_sub_f32_e32 v34, v34, v66
	v_exp_f32_e32 v34, v34
	v_sub_f32_e32 v35, v35, v66
	v_exp_f32_e32 v35, v35
	v_sub_f32_e32 v36, v36, v66
	v_exp_f32_e32 v36, v36
	v_sub_f32_e32 v37, v37, v66
	v_add_f32_e32 v70, v33, v32
	v_exp_f32_e32 v37, v37
	v_sub_f32_e32 v38, v38, v66
	v_add_f32_e32 v70, v34, v70
	v_exp_f32_e32 v38, v38
	v_sub_f32_e32 v39, v39, v66
	v_add_f32_e32 v70, v35, v70
	v_exp_f32_e32 v39, v39
	v_sub_f32_e32 v40, v40, v66
	v_add_f32_e32 v70, v36, v70
	v_exp_f32_e32 v40, v40
	v_sub_f32_e32 v41, v41, v66
	v_add_f32_e32 v70, v37, v70
	v_exp_f32_e32 v41, v41
	v_sub_f32_e32 v42, v42, v66
	v_add_f32_e32 v70, v38, v70
	v_exp_f32_e32 v42, v42
	v_sub_f32_e32 v43, v43, v66
	v_add_f32_e32 v70, v39, v70
	v_exp_f32_e32 v43, v43
	v_sub_f32_e32 v44, v44, v66
	v_add_f32_e32 v70, v40, v70
	v_exp_f32_e32 v44, v44
	v_sub_f32_e32 v45, v45, v66
	v_add_f32_e32 v70, v41, v70
	v_exp_f32_e32 v45, v45
	v_sub_f32_e32 v46, v46, v66
	v_add_f32_e32 v70, v42, v70
	v_exp_f32_e32 v46, v46
	v_sub_f32_e32 v47, v47, v66
	v_add_f32_e32 v70, v43, v70
	v_exp_f32_e32 v47, v47
	v_add_f32_e32 v66, v44, v70
	v_add_f32_e32 v66, v45, v66
	v_sub_f32_e32 v71, v73, v74
	v_add_f32_e32 v66, v46, v66
	v_add_f32_e32 v70, v47, v66
	v_exp_f32_e32 v66, v71
	v_mov_b32_e32 v71, v70
	v_mov_b32_e32 v72, v70
	s_nop 1
	v_permlane32_swap_b32_e32 v71, v72
	v_cmp_neq_f32_e32 vcc, v74, v73
	s_cbranch_vccz .LBB0_692
	v_pk_mul_f32 v[30:31], v[30:31], v[66:67] op_sel_hi:[1,0]
	v_pk_mul_f32 v[28:29], v[28:29], v[66:67] op_sel_hi:[1,0]
	v_pk_mul_f32 v[26:27], v[26:27], v[66:67] op_sel_hi:[1,0]
	v_pk_mul_f32 v[24:25], v[24:25], v[66:67] op_sel_hi:[1,0]
	v_pk_mul_f32 v[22:23], v[22:23], v[66:67] op_sel_hi:[1,0]
	v_pk_mul_f32 v[20:21], v[20:21], v[66:67] op_sel_hi:[1,0]
	v_pk_mul_f32 v[18:19], v[18:19], v[66:67] op_sel_hi:[1,0]
	v_pk_mul_f32 v[16:17], v[16:17], v[66:67] op_sel_hi:[1,0]
	v_pk_mul_f32 v[14:15], v[14:15], v[66:67] op_sel_hi:[1,0]
	v_pk_mul_f32 v[12:13], v[12:13], v[66:67] op_sel_hi:[1,0]
	v_pk_mul_f32 v[10:11], v[10:11], v[66:67] op_sel_hi:[1,0]
	v_pk_mul_f32 v[8:9], v[8:9], v[66:67] op_sel_hi:[1,0]
	v_pk_mul_f32 v[6:7], v[6:7], v[66:67] op_sel_hi:[1,0]
	v_pk_mul_f32 v[4:5], v[4:5], v[66:67] op_sel_hi:[1,0]
	v_pk_mul_f32 v[2:3], v[2:3], v[66:67] op_sel_hi:[1,0]
	v_pk_mul_f32 v[0:1], v[0:1], v[66:67] op_sel_hi:[1,0]
; #define LAS __attribute__((address_space(3)))
; #define MFMA32(a, b, c) __builtin_amdgcn_mfma_f32_32x32x16_bf16((a), (b), (c), 0, 0, 0)
; template <int KS0, int KS1> DI f32x16 qk_rows(LAS const char* Kl, int row0, const bf16x8 (&qf)[4], int r, int h) {
;     f32x16 s;
; #pragma unroll
;     for (int i = 0; i < 16; ++i) s[i] = 0.f;
;     LAS const char* p = Kl + (row0 + r) * KP + 16 * h;
;     bf16x8 kf[4];
; #pragma unroll
;     for (int ks = KS0; ks < KS1; ++ks) kf[ks] = *(LAS const bf16x8*)(p + 32 * ks);
;     __builtin_amdgcn_s_setprio(1);
; #pragma unroll
;     for (int ks = KS0; ks < KS1; ++ks) s = MFMA32(kf[ks], qf[ks], s);
;     __builtin_amdgcn_s_setprio(0);
;     return s;
; }
; DI void pv_rows(f32x16 (&o)[2], LAS const char* Vl, int row0, const bf16x8 (&pf)[2], int lane) {
;     const int h = lane >> 5, i = lane & 15, grp = (lane >> 4) & 1;
;     LAS const char* base = Vl + (row0 + 4 * h + (i >> 2)) * KP + grp * 32 + (i & 3) * 8;
;     bf16x8 vf[2][2];
; #pragma unroll
;     for (int dt = 0; dt < 2; ++dt)
; #pragma unroll
;         for (int s2 = 0; s2 < 2; ++s2) {
;             const s16x4 lo = vtr(base + (16 * s2) * KP + dt * 64), hi = vtr(base + (16 * s2 + 8) * KP + dt * 64);
;             vf[dt][s2] = (bf16x8){lo[0], lo[1], lo[2], lo[3], hi[0], hi[1], hi[2], hi[3]};
;         }
;     __builtin_amdgcn_s_setprio(1);
; #pragma unroll
;     for (int s2 = 0; s2 < 2; ++s2)
; #pragma unroll
;         for (int dt = 0; dt < 2; ++dt) o[dt] = MFMA32(vf[dt][s2], pf[s2], o[dt]);
;     __builtin_amdgcn_s_setprio(0);
; }
; template <int MM> DI void tile128_pipe(LAS const char* K0, LAS const char* V0, LAS const char* K1, LAS const char* V1, const bf16x8 (&qf)[4], unsigned vm0, unsigned vm1,
;                                        float& m, float& l, f32x16 (&o)[2], int r, int h, int lane) {
;     f32x16 sa = qk_rows<0, 4>(K0, 0, qf, r, h), sb = qk_rows<0, 4>(K0, 32, qf, r, h);
;     bf16x8 pfa[2], pfb[2];
;     smax_step_nb<MM>(sa, vm0, m, l, o, pfa, lane);
;     sa = qk_rows<0, 4>(K1, 0, qf, r, h);
;     pv_rows(o, V0, 0, pfa, lane);
;     smax_step_nb<MM>(sb, vm0, m, l, o, pfb, lane);
;     sb = qk_rows<0, 4>(K1, 32, qf, r, h);
;     pv_rows(o, V0, 32, pfb, lane);
;     smax_step_nb<MM>(sa, vm1, m, l, o, pfa, lane);
;     pv_rows(o, V1, 0, pfa, lane);
;     smax_step_nb<MM>(sb, vm1, m, l, o, pfb, lane);
;     pv_rows(o, V1, 32, pfb, lane);
; }
.LBB0_692:
	v_cvt_pk_bf16_f32 v76, v32, v33
	v_cvt_pk_bf16_f32 v77, v34, v35
	ds_read_b128 v[32:35], v212 offset:23040
	ds_read_b128 v[84:87], v212 offset:23072
	ds_read_b128 v[88:91], v212 offset:23104
	ds_read_b128 v[92:95], v212 offset:23136
	v_cvt_pk_bf16_f32 v78, v36, v37
	v_cvt_pk_bf16_f32 v79, v38, v39
	v_cvt_pk_bf16_f32 v80, v40, v41
	v_cvt_pk_bf16_f32 v81, v42, v43
	v_cvt_pk_bf16_f32 v82, v44, v45
	v_cvt_pk_bf16_f32 v83, v46, v47
	s_nop 0
	s_waitcnt lgkmcnt(3)
	v_mfma_f32_32x32x16_bf16 v[32:47], v[32:35], v[96:99], 0
	s_waitcnt lgkmcnt(2)
	v_mfma_f32_32x32x16_bf16 v[32:47], v[84:87], v[100:103], v[32:47]
	s_waitcnt lgkmcnt(1)
	v_mfma_f32_32x32x16_bf16 v[32:47], v[88:91], v[104:107], v[32:47]
	s_waitcnt lgkmcnt(0)
	v_mfma_f32_32x32x16_bf16 v[32:47], v[92:95], v[108:111], v[32:47]
	s_nop 0
	ds_read_b64_tr_b16 v[84:85], v69 offset:13824
	ds_read_b64_tr_b16 v[86:87], v69 offset:14976
	ds_read_b64_tr_b16 v[90:91], v69 offset:15040
	ds_read_b64_tr_b16 v[88:89], v69 offset:13888
	ds_read_b64_tr_b16 v[92:93], v69 offset:16128
	ds_read_b64_tr_b16 v[94:95], v69 offset:17280
	ds_read_b64_tr_b16 v[130:131], v69 offset:17344
	ds_read_b64_tr_b16 v[128:129], v69 offset:16192
	s_nop 0
	s_waitcnt lgkmcnt(6)
	v_mfma_f32_32x32x16_bf16 v[0:15], v[84:87], v[76:79], v[0:15]
	s_waitcnt lgkmcnt(4)
	v_mfma_f32_32x32x16_bf16 v[16:31], v[88:91], v[76:79], v[16:31]
	s_waitcnt lgkmcnt(2)
	v_mfma_f32_32x32x16_bf16 v[0:15], v[92:95], v[80:83], v[0:15]
	s_waitcnt lgkmcnt(0)
	v_mfma_f32_32x32x16_bf16 v[16:31], v[128:131], v[80:83], v[16:31]
	s_nop 0
	v_max3_f32 v73, v48, s15, v49
	v_max3_f32 v73, v73, v50, v51
	v_max3_f32 v73, v73, v52, v53
	v_max3_f32 v73, v73, v54, v55
	v_max3_f32 v73, v73, v56, v57
	v_max3_f32 v73, v73, v58, v59
	v_max3_f32 v73, v73, v60, v61
	v_max3_f32 v73, v73, v62, v63
	v_mov_b32_e32 v75, v73
	v_mov_b32_e32 v76, v73
	s_nop 1
	v_permlane32_swap_b32_e32 v75, v76
	v_max_f32_e32 v73, v75, v76
	v_add_f32_e32 v75, 0x41000000, v74
	v_cmp_gt_f32_e32 vcc, v73, v75
	s_nop 1
	v_cndmask_b32_e32 v73, v74, v73, vcc
	v_max_f32_e32 v79, 0xefa18f08, v73
	v_sub_f32_e32 v48, v48, v79
	v_exp_f32_e32 v75, v48
	v_sub_f32_e32 v48, v49, v79
	v_exp_f32_e32 v76, v48
	v_sub_f32_e32 v48, v50, v79
	v_exp_f32_e32 v77, v48
	v_sub_f32_e32 v48, v51, v79
	v_exp_f32_e32 v78, v48
	v_sub_f32_e32 v49, v52, v79
	v_exp_f32_e32 v52, v49
	v_sub_f32_e32 v49, v53, v79
	v_add_f32_e32 v48, v76, v75
	v_exp_f32_e32 v53, v49
	v_sub_f32_e32 v49, v54, v79
	v_add_f32_e32 v48, v77, v48
	v_exp_f32_e32 v54, v49
	v_sub_f32_e32 v49, v55, v79
	v_add_f32_e32 v48, v78, v48
	v_exp_f32_e32 v55, v49
	v_sub_f32_e32 v49, v56, v79
	v_add_f32_e32 v48, v52, v48
	v_exp_f32_e32 v56, v49
	v_sub_f32_e32 v49, v57, v79
	v_add_f32_e32 v48, v53, v48
	v_exp_f32_e32 v57, v49
	v_sub_f32_e32 v49, v58, v79
	v_add_f32_e32 v48, v54, v48
	v_exp_f32_e32 v58, v49
	v_sub_f32_e32 v49, v59, v79
	v_add_f32_e32 v48, v55, v48
	v_exp_f32_e32 v59, v49
	v_sub_f32_e32 v49, v60, v79
	v_add_f32_e32 v48, v56, v48
	v_exp_f32_e32 v60, v49
	v_sub_f32_e32 v49, v61, v79
	v_add_f32_e32 v48, v57, v48
	v_exp_f32_e32 v61, v49
	v_sub_f32_e32 v49, v62, v79
	v_add_f32_e32 v48, v58, v48
	v_exp_f32_e32 v62, v49
	v_sub_f32_e32 v49, v63, v79
	v_add_f32_e32 v48, v59, v48
	v_exp_f32_e32 v63, v49
	v_add_f32_e32 v48, v60, v48
	v_add_f32_e32 v48, v61, v48
	v_sub_f32_e32 v80, v74, v73
	v_add_f32_e32 v48, v62, v48
	v_add_f32_e32 v49, v63, v48
	v_exp_f32_e32 v48, v80
	v_mov_b32_e32 v50, v49
	v_mov_b32_e32 v51, v49
	s_nop 1
	v_permlane32_swap_b32_e32 v50, v51
	v_cmp_neq_f32_e32 vcc, v73, v74
	s_cbranch_vccz .LBB0_694
	v_pk_mul_f32 v[30:31], v[30:31], v[48:49] op_sel_hi:[1,0]
	v_pk_mul_f32 v[28:29], v[28:29], v[48:49] op_sel_hi:[1,0]
	v_pk_mul_f32 v[26:27], v[26:27], v[48:49] op_sel_hi:[1,0]
	v_pk_mul_f32 v[24:25], v[24:25], v[48:49] op_sel_hi:[1,0]
	v_pk_mul_f32 v[22:23], v[22:23], v[48:49] op_sel_hi:[1,0]
	v_pk_mul_f32 v[20:21], v[20:21], v[48:49] op_sel_hi:[1,0]
	v_pk_mul_f32 v[18:19], v[18:19], v[48:49] op_sel_hi:[1,0]
	v_pk_mul_f32 v[16:17], v[16:17], v[48:49] op_sel_hi:[1,0]
	v_pk_mul_f32 v[14:15], v[14:15], v[48:49] op_sel_hi:[1,0]
	v_pk_mul_f32 v[12:13], v[12:13], v[48:49] op_sel_hi:[1,0]
	v_pk_mul_f32 v[10:11], v[10:11], v[48:49] op_sel_hi:[1,0]
	v_pk_mul_f32 v[8:9], v[8:9], v[48:49] op_sel_hi:[1,0]
	v_pk_mul_f32 v[6:7], v[6:7], v[48:49] op_sel_hi:[1,0]
	v_pk_mul_f32 v[4:5], v[4:5], v[48:49] op_sel_hi:[1,0]
	v_pk_mul_f32 v[2:3], v[2:3], v[48:49] op_sel_hi:[1,0]
	v_pk_mul_f32 v[0:1], v[0:1], v[48:49] op_sel_hi:[1,0]

; #define LAS __attribute__((address_space(3)))
; template <int MM> DI void tile128_pipe(LAS const char* K0, LAS const char* V0, LAS const char* K1, LAS const char* V1, const bf16x8 (&qf)[4], unsigned vm0, unsigned vm1,
;                                        float& m, float& l, f32x16 (&o)[2], int r, int h, int lane) {
;     f32x16 sa = qk_rows<0, 4>(K0, 0, qf, r, h), sb = qk_rows<0, 4>(K0, 32, qf, r, h);
;     bf16x8 pfa[2], pfb[2];
;     smax_step_nb<MM>(sa, vm0, m, l, o, pfa, lane);
;     sa = qk_rows<0, 4>(K1, 0, qf, r, h);
;     pv_rows(o, V0, 0, pfa, lane);
;     smax_step_nb<MM>(sb, vm0, m, l, o, pfb, lane);
;     sb = qk_rows<0, 4>(K1, 32, qf, r, h);
;     pv_rows(o, V0, 32, pfb, lane);
;     smax_step_nb<MM>(sa, vm1, m, l, o, pfa, lane);
;     pv_rows(o, V1, 0, pfa, lane);
;     smax_step_nb<MM>(sb, vm1, m, l, o, pfb, lane);
;     pv_rows(o, V1, 32, pfb, lane);
; }
; template <int MODE, bool PRE = false> ...
;     ...
;                     goto step_done;
.LBB0_696:
	v_cndmask_b32_e64 v44, v67, v68, s[36:37]
	v_add_f32_e32 v44, v65, v44
	v_cndmask_b32_e64 v45, v71, v72, s[36:37]
	v_fmac_f32_e32 v44, v184, v64
	v_add_f32_e32 v45, v70, v45
	v_fmac_f32_e32 v45, v44, v66
	v_cndmask_b32_e64 v44, v50, v51, s[36:37]
	v_add_f32_e32 v44, v49, v44
	v_cndmask_b32_e64 v42, v42, v43, s[36:37]
	v_fmac_f32_e32 v44, v45, v48
	v_add_f32_e32 v65, v41, v42
	v_fmac_f32_e32 v65, v44, v32
	v_cvt_pk_bf16_f32 v42, v52, v53
	v_cvt_pk_bf16_f32 v43, v54, v55
	v_cvt_pk_bf16_f32 v44, v56, v57
	v_cvt_pk_bf16_f32 v45, v58, v59
	ds_read_b64_tr_b16 v[48:49], v69 offset:33408
	ds_read_b64_tr_b16 v[50:51], v69 offset:34560
	ds_read_b64_tr_b16 v[54:55], v69 offset:34624
	ds_read_b64_tr_b16 v[60:61], v69 offset:33472
	ds_read_b64_tr_b16 v[46:47], v69 offset:32256
	ds_read_b64_tr_b16 v[52:53], v69 offset:35712
	ds_read_b64_tr_b16 v[58:59], v69 offset:32320
	ds_read_b64_tr_b16 v[56:57], v69 offset:35776
	v_cvt_pk_bf16_f32 v32, v33, v34
	v_cvt_pk_bf16_f32 v33, v35, v36
	v_cvt_pk_bf16_f32 v34, v37, v38
	v_cvt_pk_bf16_f32 v35, v39, v40
	s_nop 0
	s_waitcnt lgkmcnt(1)
	v_mfma_f32_32x32x16_bf16 v[16:31], v[58:61], v[42:45], v[16:31]
	v_mfma_f32_32x32x16_bf16 v[0:15], v[46:49], v[42:45], v[0:15]
	s_waitcnt lgkmcnt(0)
	v_mfma_f32_32x32x16_bf16 v[16:31], v[54:57], v[32:35], v[16:31]
	v_mfma_f32_32x32x16_bf16 v[0:15], v[50:53], v[32:35], v[0:15]
.LBB0_697:
	s_nop 0
	s_mov_b32 s0, 9
	v_mov_b32_e32 v184, v65
	v_mov_b32_e32 v193, v81

; #define LAS __attribute__((address_space(3)))
; template <int MM> DI void tile64_pipe(LAS const char* Kl, LAS const char* Vl, const bf16x8 (&qf)[4], unsigned vm, float& m, float& l, f32x16 (&o)[2], int r, int h, int lane) {
;     const f32x16 sa = qk_rows<0, 4>(Kl, 0, qf, r, h), sb = qk_rows<0, 4>(Kl, 32, qf, r, h);
;     bf16x8 pfa[2], pfb[2];
;     smax_step_nb<MM>(sa, vm, m, l, o, pfa, lane);
;     pv_rows(o, Vl, 0, pfa, lane);
;     smax_step_nb<MM>(sb, vm, m, l, o, pfb, lane);
;     pv_rows(o, Vl, 32, pfb, lane);
; }
; template <int MODE, bool PRE = false> ...
;     ...
;         for (int half = 0; half < 2; ++half) {
;         const int kt = kt_lo + 2 * sti + half;
;         if (kt > kt_hi) break;
;         LAS char* Kl = lds + (sti & 1) * 4 * TILE_B + half * 2 * TILE_B; LAS char* Vl = Kl + TILE_B;
;         bool full2 = (64 * kt + 63 <= q0w);
;         if (MODE == MODE_NWIN) full2 = full2 && (64 * kt > q0w + 31 - 512);
;         if (full2 && (MODE != MODE_DIFF || DIFF_MERGED)) {
;             bool lsel = true;
;             if (MODE == MODE_MOBA) lsel = ((sel >> (kt >> 2)) & 1ull) != 0ull;
;             if (MODE == MODE_NSEL) lsel = ((sel >> kt) & 1ull) != 0ull;
;             const unsigned long long selb = __builtin_amdgcn_ballot_w64(lsel);
;             if (selb != 0ull) {
;                 const unsigned vm = lsel ? 1u : 0u; bf16x8 pf[4];
;                 if (MODE == MODE_DIFF) {
;                     { const f32x16 sa = qk_rows<0, 2>(Kl, 0, qf, r, h), sb = qk_rows<0, 2>(Kl, 32, qf, r, h);
;                       smax_step64<0>(sa, sb, vm, m1, l1, o1, pf, lane); __builtin_amdgcn_sched_barrier(0); pv_rows64(o1, Vl, pf, lane); }
;                     __builtin_amdgcn_sched_barrier(0);
;                     { const f32x16 sa = qk_rows<2, 4>(Kl, 0, qf, r, h), sb = qk_rows<2, 4>(Kl, 32, qf, r, h);
;                       smax_step64<0>(sa, sb, vm, m2, l2, o2, pf, lane); __builtin_amdgcn_sched_barrier(0); pv_rows64(o2, Vl, pf, lane); }
;                 } else {
;     ...
;                     if (selb == ~0ull) tile64_pipe<0>(Kl, Vl, qf, vm, m1, l1, o1, r, h, lane); else tile64_pipe<1>(Kl, Vl, qf, vm, m1, l1, o1, r, h, lane);
.LBB0_715:
	s_andn2_b64 vcc, exec, s[52:53]
	v_add3_u32 v83, s64, v190, v168
	v_add_f32_e32 v82, 0x41000000, v193
	v_mov_b32_e32 v65, v184
	v_mov_b32_e32 v81, v193
	s_cbranch_vccnz .LBB0_721
	ds_read_b128 v[32:35], v83
	ds_read_b128 v[48:51], v83 offset:32
	ds_read_b128 v[52:55], v83 offset:64
	ds_read_b128 v[56:59], v83 offset:96
	s_nop 0
	s_waitcnt lgkmcnt(3)
	v_mfma_f32_32x32x16_bf16 v[32:47], v[32:35], v[96:99], 0
	s_waitcnt lgkmcnt(2)
	v_mfma_f32_32x32x16_bf16 v[32:47], v[48:51], v[100:103], v[32:47]
	s_waitcnt lgkmcnt(1)
	v_mfma_f32_32x32x16_bf16 v[32:47], v[52:55], v[104:107], v[32:47]
	s_waitcnt lgkmcnt(0)
	v_mfma_f32_32x32x16_bf16 v[32:47], v[56:59], v[108:111], v[32:47]
	s_nop 0
	ds_read_b128 v[48:51], v83 offset:4608
	ds_read_b128 v[52:55], v83 offset:4640
	ds_read_b128 v[56:59], v83 offset:4672
	ds_read_b128 v[60:63], v83 offset:4704
	s_nop 0
	s_waitcnt lgkmcnt(3)
	v_mfma_f32_32x32x16_bf16 v[64:79], v[48:51], v[96:99], 0
	s_waitcnt lgkmcnt(2)
	v_mfma_f32_32x32x16_bf16 v[64:79], v[52:55], v[100:103], v[64:79]
	s_waitcnt lgkmcnt(1)
	v_mfma_f32_32x32x16_bf16 v[64:79], v[56:59], v[104:107], v[64:79]
	s_waitcnt lgkmcnt(0)
	v_mfma_f32_32x32x16_bf16 v[64:79], v[60:63], v[108:111], v[64:79]
	s_nop 0
	v_max3_f32 v48, v32, s15, v33
	v_max3_f32 v48, v48, v34, v35
	v_max3_f32 v48, v48, v36, v37
	v_max3_f32 v48, v48, v38, v39
	v_max3_f32 v48, v48, v40, v41
	v_max3_f32 v48, v48, v42, v43
	v_max3_f32 v48, v48, v44, v45
	v_max3_f32 v48, v48, v46, v47
	v_mov_b32_e32 v49, v48
	v_mov_b32_e32 v50, v48
	s_nop 1
	v_permlane32_swap_b32_e32 v49, v50
	v_max_f32_e32 v48, v49, v50
	v_cmp_gt_f32_e32 vcc, v48, v82
	s_nop 1
	v_cndmask_b32_e32 v88, v193, v48, vcc
	v_max_f32_e32 v48, 0xefa18f08, v88
	v_sub_f32_e32 v32, v32, v48
	v_exp_f32_e32 v81, v32
	v_sub_f32_e32 v32, v33, v48
	v_exp_f32_e32 v87, v32
	v_sub_f32_e32 v32, v34, v48
	v_exp_f32_e32 v89, v32
	v_sub_f32_e32 v32, v35, v48
	v_exp_f32_e32 v90, v32
	v_sub_f32_e32 v33, v36, v48
	v_exp_f32_e32 v91, v33
	v_sub_f32_e32 v33, v37, v48
	v_add_f32_e32 v32, v87, v81
	v_exp_f32_e32 v92, v33
	v_sub_f32_e32 v33, v38, v48
	v_add_f32_e32 v32, v89, v32
	v_exp_f32_e32 v93, v33
	v_sub_f32_e32 v33, v39, v48
	v_add_f32_e32 v32, v90, v32
	v_exp_f32_e32 v94, v33
	v_sub_f32_e32 v33, v40, v48
	v_add_f32_e32 v32, v91, v32
	v_exp_f32_e32 v95, v33
	v_sub_f32_e32 v33, v41, v48
	v_add_f32_e32 v32, v92, v32
	v_exp_f32_e32 v128, v33
	v_sub_f32_e32 v33, v42, v48
	v_add_f32_e32 v32, v93, v32
	v_exp_f32_e32 v129, v33
	v_sub_f32_e32 v33, v43, v48
	v_add_f32_e32 v32, v94, v32
	v_exp_f32_e32 v130, v33
	v_sub_f32_e32 v33, v44, v48
	v_add_f32_e32 v32, v95, v32
	v_exp_f32_e32 v131, v33
	v_sub_f32_e32 v33, v45, v48
	v_add_f32_e32 v32, v128, v32
	v_exp_f32_e32 v132, v33
	v_sub_f32_e32 v33, v46, v48
	v_add_f32_e32 v32, v129, v32
	v_exp_f32_e32 v133, v33
	v_sub_f32_e32 v33, v47, v48
	v_add_f32_e32 v32, v130, v32
	v_exp_f32_e32 v134, v33
	v_add_f32_e32 v32, v131, v32
	v_sub_f32_e32 v49, v193, v88
	v_add_f32_e32 v32, v132, v32
	v_add_f32_e32 v32, v133, v32
	v_exp_f32_e32 v80, v49
	v_add_f32_e32 v84, v134, v32
	v_mov_b32_e32 v85, v84
	v_mov_b32_e32 v86, v84
	v_mov_b64_e32 v[62:63], v[30:31]
	s_nop 0
	v_permlane32_swap_b32_e32 v85, v86
	v_cmp_neq_f32_e32 vcc, v88, v193
	v_mov_b64_e32 v[60:61], v[28:29]
	v_mov_b64_e32 v[58:59], v[26:27]
	v_mov_b64_e32 v[56:57], v[24:25]
	v_mov_b64_e32 v[54:55], v[22:23]
	v_mov_b64_e32 v[52:53], v[20:21]
	v_mov_b64_e32 v[50:51], v[18:19]
	v_mov_b64_e32 v[48:49], v[16:17]
	v_mov_b64_e32 v[46:47], v[14:15]
	v_mov_b64_e32 v[44:45], v[12:13]
	v_mov_b64_e32 v[42:43], v[10:11]
	v_mov_b64_e32 v[40:41], v[8:9]
	v_mov_b64_e32 v[38:39], v[6:7]
	v_mov_b64_e32 v[36:37], v[4:5]
	v_mov_b64_e32 v[34:35], v[2:3]
	v_mov_b64_e32 v[32:33], v[0:1]
	s_cbranch_vccz .LBB0_718
	v_pk_mul_f32 v[62:63], v[30:31], v[80:81] op_sel_hi:[1,0]
	v_pk_mul_f32 v[60:61], v[28:29], v[80:81] op_sel_hi:[1,0]
	v_pk_mul_f32 v[58:59], v[26:27], v[80:81] op_sel_hi:[1,0]
	v_pk_mul_f32 v[56:57], v[24:25], v[80:81] op_sel_hi:[1,0]
	v_pk_mul_f32 v[54:55], v[22:23], v[80:81] op_sel_hi:[1,0]
	v_pk_mul_f32 v[52:53], v[20:21], v[80:81] op_sel_hi:[1,0]
	v_pk_mul_f32 v[50:51], v[18:19], v[80:81] op_sel_hi:[1,0]
	v_pk_mul_f32 v[48:49], v[16:17], v[80:81] op_sel_hi:[1,0]
	v_pk_mul_f32 v[46:47], v[14:15], v[80:81] op_sel_hi:[1,0]
	v_pk_mul_f32 v[44:45], v[12:13], v[80:81] op_sel_hi:[1,0]
	v_pk_mul_f32 v[42:43], v[10:11], v[80:81] op_sel_hi:[1,0]
	v_pk_mul_f32 v[40:41], v[8:9], v[80:81] op_sel_hi:[1,0]
	v_pk_mul_f32 v[38:39], v[6:7], v[80:81] op_sel_hi:[1,0]
	v_pk_mul_f32 v[36:37], v[4:5], v[80:81] op_sel_hi:[1,0]
	v_pk_mul_f32 v[34:35], v[2:3], v[80:81] op_sel_hi:[1,0]
	v_pk_mul_f32 v[32:33], v[0:1], v[80:81] op_sel_hi:[1,0]
; #define LAS __attribute__((address_space(3)))
; #define MFMA32(a, b, c) __builtin_amdgcn_mfma_f32_32x32x16_bf16((a), (b), (c), 0, 0, 0)
; DI s16x4 vtr(LAS const char* p) { return __builtin_bit_cast(s16x4, __builtin_amdgcn_ds_read_tr16_b64_v4i16((LAS v4i16_t*)p)); }
; DI void pv_rows(f32x16 (&o)[2], LAS const char* Vl, int row0, const bf16x8 (&pf)[2], int lane) {
;     const int h = lane >> 5, i = lane & 15, grp = (lane >> 4) & 1;
;     LAS const char* base = Vl + (row0 + 4 * h + (i >> 2)) * KP + grp * 32 + (i & 3) * 8;
;     bf16x8 vf[2][2];
; #pragma unroll
;     for (int dt = 0; dt < 2; ++dt)
; #pragma unroll
;         for (int s2 = 0; s2 < 2; ++s2) {
;             const s16x4 lo = vtr(base + (16 * s2) * KP + dt * 64), hi = vtr(base + (16 * s2 + 8) * KP + dt * 64);
;             vf[dt][s2] = (bf16x8){lo[0], lo[1], lo[2], lo[3], hi[0], hi[1], hi[2], hi[3]};
;         }
;     __builtin_amdgcn_s_setprio(1);
; #pragma unroll
;     for (int s2 = 0; s2 < 2; ++s2)
; #pragma unroll
;         for (int dt = 0; dt < 2; ++dt) o[dt] = MFMA32(vf[dt][s2], pf[s2], o[dt]);
;     __builtin_amdgcn_s_setprio(0);
; }
; template <int MM> DI void tile64_pipe(LAS const char* Kl, LAS const char* Vl, const bf16x8 (&qf)[4], unsigned vm, float& m, float& l, f32x16 (&o)[2], int r, int h, int lane) {
;     const f32x16 sa = qk_rows<0, 4>(Kl, 0, qf, r, h), sb = qk_rows<0, 4>(Kl, 32, qf, r, h);
;     bf16x8 pfa[2], pfb[2];
;     smax_step_nb<MM>(sa, vm, m, l, o, pfa, lane);
;     pv_rows(o, Vl, 0, pfa, lane);
;     smax_step_nb<MM>(sb, vm, m, l, o, pfb, lane);
;     pv_rows(o, Vl, 32, pfb, lane);
; }
.LBB0_718:
	v_cvt_pk_bf16_f32 v136, v81, v87
	v_add3_u32 v81, s64, v191, v171
	v_add_u32_e32 v87, v81, v186
	v_cvt_pk_bf16_f32 v137, v89, v90
	v_cvt_pk_bf16_f32 v138, v91, v92
	v_cvt_pk_bf16_f32 v139, v93, v94
	v_cvt_pk_bf16_f32 v90, v95, v128
	v_cvt_pk_bf16_f32 v91, v129, v130
	v_cvt_pk_bf16_f32 v92, v131, v132
	v_cvt_pk_bf16_f32 v93, v133, v134
	ds_read_b64_tr_b16 v[128:129], v87 offset:9216
	ds_read_b64_tr_b16 v[130:131], v87 offset:10368
	ds_read_b64_tr_b16 v[132:133], v87 offset:11520
	ds_read_b64_tr_b16 v[134:135], v87 offset:12672
	ds_read_b64_tr_b16 v[140:141], v87 offset:9280
	ds_read_b64_tr_b16 v[142:143], v87 offset:10432
	ds_read_b64_tr_b16 v[144:145], v87 offset:11584
	ds_read_b64_tr_b16 v[146:147], v87 offset:12736
	s_nop 0
	s_waitcnt lgkmcnt(6)
	v_mfma_f32_32x32x16_bf16 v[32:47], v[128:131], v[136:139], v[32:47]
	s_waitcnt lgkmcnt(2)
	v_mfma_f32_32x32x16_bf16 v[48:63], v[140:143], v[136:139], v[48:63]
	v_mfma_f32_32x32x16_bf16 v[32:47], v[132:135], v[90:93], v[32:47]
	s_waitcnt lgkmcnt(0)
	v_mfma_f32_32x32x16_bf16 v[48:63], v[144:147], v[90:93], v[48:63]
	s_nop 0
	v_max3_f32 v81, v64, s15, v65
	v_max3_f32 v81, v81, v66, v67
	v_max3_f32 v81, v81, v68, v69
	v_max3_f32 v81, v81, v70, v71
	v_max3_f32 v81, v81, v72, v73
	v_max3_f32 v81, v81, v74, v75
	v_max3_f32 v81, v81, v76, v77
	v_max3_f32 v81, v81, v78, v79
	v_mov_b32_e32 v89, v81
	v_mov_b32_e32 v90, v81
	s_nop 1
	v_permlane32_swap_b32_e32 v89, v90
	v_max_f32_e32 v81, v89, v90
	v_add_f32_e32 v89, 0x41000000, v88
	v_cmp_gt_f32_e32 vcc, v81, v89
	s_nop 1
	v_cndmask_b32_e32 v81, v88, v81, vcc
	v_max_f32_e32 v91, 0xefa18f08, v81
	v_sub_f32_e32 v64, v64, v91
	v_exp_f32_e32 v89, v64
	v_sub_f32_e32 v64, v65, v91
	v_exp_f32_e32 v90, v64
	v_sub_f32_e32 v64, v66, v91
	v_exp_f32_e32 v66, v64
	v_sub_f32_e32 v64, v67, v91
	v_exp_f32_e32 v67, v64
	v_sub_f32_e32 v65, v68, v91
	v_exp_f32_e32 v68, v65
	v_sub_f32_e32 v65, v69, v91
	v_add_f32_e32 v64, v90, v89
	v_exp_f32_e32 v69, v65
	v_sub_f32_e32 v65, v70, v91
	v_add_f32_e32 v64, v66, v64
	v_exp_f32_e32 v70, v65
	v_sub_f32_e32 v65, v71, v91
	v_add_f32_e32 v64, v67, v64
	v_exp_f32_e32 v71, v65
	v_sub_f32_e32 v65, v72, v91
	v_add_f32_e32 v64, v68, v64
	v_exp_f32_e32 v72, v65
	v_sub_f32_e32 v65, v73, v91
	v_add_f32_e32 v64, v69, v64
	v_exp_f32_e32 v73, v65
	v_sub_f32_e32 v65, v74, v91
	v_add_f32_e32 v64, v70, v64
	v_exp_f32_e32 v74, v65
	v_sub_f32_e32 v65, v75, v91
	v_add_f32_e32 v64, v71, v64
	v_exp_f32_e32 v75, v65
	v_sub_f32_e32 v65, v76, v91
	v_add_f32_e32 v64, v72, v64
	v_exp_f32_e32 v76, v65
	v_sub_f32_e32 v65, v77, v91
	v_add_f32_e32 v64, v73, v64
	v_exp_f32_e32 v77, v65
	v_sub_f32_e32 v65, v78, v91
	v_add_f32_e32 v64, v74, v64
	v_exp_f32_e32 v78, v65
	v_sub_f32_e32 v65, v79, v91
	v_add_f32_e32 v64, v75, v64
	v_exp_f32_e32 v79, v65
	v_add_f32_e32 v64, v76, v64
	v_add_f32_e32 v64, v77, v64
	v_sub_f32_e32 v92, v88, v81
	v_add_f32_e32 v64, v78, v64
	v_add_f32_e32 v65, v79, v64
	v_exp_f32_e32 v64, v92
	v_mov_b32_e32 v91, v65
	v_mov_b32_e32 v92, v65
	s_nop 1
	v_permlane32_swap_b32_e32 v91, v92
	v_cmp_neq_f32_e32 vcc, v81, v88
	s_cbranch_vccz .LBB0_720
	v_pk_mul_f32 v[62:63], v[62:63], v[64:65] op_sel_hi:[1,0]
	v_pk_mul_f32 v[60:61], v[60:61], v[64:65] op_sel_hi:[1,0]
	v_pk_mul_f32 v[58:59], v[58:59], v[64:65] op_sel_hi:[1,0]
	v_pk_mul_f32 v[56:57], v[56:57], v[64:65] op_sel_hi:[1,0]
	v_pk_mul_f32 v[54:55], v[54:55], v[64:65] op_sel_hi:[1,0]
	v_pk_mul_f32 v[52:53], v[52:53], v[64:65] op_sel_hi:[1,0]
	v_pk_mul_f32 v[50:51], v[50:51], v[64:65] op_sel_hi:[1,0]
	v_pk_mul_f32 v[48:49], v[48:49], v[64:65] op_sel_hi:[1,0]
	v_pk_mul_f32 v[46:47], v[46:47], v[64:65] op_sel_hi:[1,0]
	v_pk_mul_f32 v[44:45], v[44:45], v[64:65] op_sel_hi:[1,0]
	v_pk_mul_f32 v[42:43], v[42:43], v[64:65] op_sel_hi:[1,0]
	v_pk_mul_f32 v[40:41], v[40:41], v[64:65] op_sel_hi:[1,0]
	v_pk_mul_f32 v[38:39], v[38:39], v[64:65] op_sel_hi:[1,0]
	v_pk_mul_f32 v[36:37], v[36:37], v[64:65] op_sel_hi:[1,0]
	v_pk_mul_f32 v[34:35], v[34:35], v[64:65] op_sel_hi:[1,0]
	v_pk_mul_f32 v[32:33], v[32:33], v[64:65] op_sel_hi:[1,0]
.LBB0_720:
	v_cndmask_b32_e64 v85, v85, v86, s[36:37]
	v_add_f32_e32 v84, v84, v85
	v_fmac_f32_e32 v84, v184, v80
	v_cndmask_b32_e64 v80, v91, v92, s[36:37]
	v_add_f32_e32 v65, v65, v80
	v_fmac_f32_e32 v65, v84, v64
	v_cvt_pk_bf16_f32 v88, v89, v90
	v_cvt_pk_bf16_f32 v89, v66, v67
	v_cvt_pk_bf16_f32 v90, v68, v69
	v_cvt_pk_bf16_f32 v91, v70, v71
	v_cvt_pk_bf16_f32 v66, v72, v73
	v_cvt_pk_bf16_f32 v67, v74, v75
	v_cvt_pk_bf16_f32 v68, v76, v77
	ds_read_b64_tr_b16 v[70:71], v87 offset:13824
	ds_read_b64_tr_b16 v[72:73], v87 offset:14976
	ds_read_b64_tr_b16 v[74:75], v87 offset:16128
	ds_read_b64_tr_b16 v[76:77], v87 offset:17280
	ds_read_b64_tr_b16 v[92:93], v87 offset:13888
	ds_read_b64_tr_b16 v[94:95], v87 offset:15040
	ds_read_b64_tr_b16 v[84:85], v87 offset:16192
	ds_read_b64_tr_b16 v[86:87], v87 offset:17344
	v_cvt_pk_bf16_f32 v69, v78, v79
	s_nop 0
	s_waitcnt lgkmcnt(6)
	v_mfma_f32_32x32x16_bf16 v[32:47], v[70:73], v[88:91], v[32:47]
	s_mov_b64 s[48:49], 0
	s_mov_b64 s[0:1], -1
	s_waitcnt lgkmcnt(2)
	v_mfma_f32_32x32x16_bf16 v[48:63], v[92:95], v[88:91], v[48:63]
	v_mfma_f32_32x32x16_bf16 v[32:47], v[74:77], v[66:69], v[32:47]
	s_waitcnt lgkmcnt(0)
	v_mfma_f32_32x32x16_bf16 v[48:63], v[84:87], v[66:69], v[48:63]
; #define LAS __attribute__((address_space(3)))
; #define MFMA32(a, b, c) __builtin_amdgcn_mfma_f32_32x32x16_bf16((a), (b), (c), 0, 0, 0)
; template <int KS0, int KS1> DI f32x16 qk_rows(LAS const char* Kl, int row0, const bf16x8 (&qf)[4], int r, int h) {
;     f32x16 s;
; #pragma unroll
;     for (int i = 0; i < 16; ++i) s[i] = 0.f;
;     LAS const char* p = Kl + (row0 + r) * KP + 16 * h;
;     bf16x8 kf[4];
; #pragma unroll
;     for (int ks = KS0; ks < KS1; ++ks) kf[ks] = *(LAS const bf16x8*)(p + 32 * ks);
;     __builtin_amdgcn_s_setprio(1);
; #pragma unroll
;     for (int ks = KS0; ks < KS1; ++ks) s = MFMA32(kf[ks], qf[ks], s);
;     __builtin_amdgcn_s_setprio(0);
;     return s;
; }
; template <int MM> DI void tile64_pipe(LAS const char* Kl, LAS const char* Vl, const bf16x8 (&qf)[4], unsigned vm, float& m, float& l, f32x16 (&o)[2], int r, int h, int lane) {
;     const f32x16 sa = qk_rows<0, 4>(Kl, 0, qf, r, h), sb = qk_rows<0, 4>(Kl, 32, qf, r, h);
;     bf16x8 pfa[2], pfb[2];
;     smax_step_nb<MM>(sa, vm, m, l, o, pfa, lane);
;     pv_rows(o, Vl, 0, pfa, lane);
;     smax_step_nb<MM>(sb, vm, m, l, o, pfb, lane);
;     pv_rows(o, Vl, 32, pfb, lane);
; }
.LBB0_721:
	s_and_b64 vcc, exec, s[48:49]
	s_cbranch_vccz .LBB0_727
	s_nop 7
	ds_read_b128 v[32:35], v83
	s_nop 0
	ds_read_b128 v[48:51], v83 offset:32
	ds_read_b128 v[52:55], v83 offset:64
	ds_read_b128 v[56:59], v83 offset:96
	s_nop 0
	s_waitcnt lgkmcnt(3)
	v_mfma_f32_32x32x16_bf16 v[32:47], v[32:35], v[96:99], 0
	s_waitcnt lgkmcnt(2)
	v_mfma_f32_32x32x16_bf16 v[32:47], v[48:51], v[100:103], v[32:47]
	s_waitcnt lgkmcnt(1)
	v_mfma_f32_32x32x16_bf16 v[32:47], v[52:55], v[104:107], v[32:47]
	s_waitcnt lgkmcnt(0)
	v_mfma_f32_32x32x16_bf16 v[32:47], v[56:59], v[108:111], v[32:47]
	s_nop 0
	ds_read_b128 v[48:51], v83 offset:4608
	ds_read_b128 v[52:55], v83 offset:4640
	ds_read_b128 v[56:59], v83 offset:4672
	ds_read_b128 v[60:63], v83 offset:4704
	s_nop 0
	s_waitcnt lgkmcnt(3)
	v_mfma_f32_32x32x16_bf16 v[64:79], v[48:51], v[96:99], 0
	s_waitcnt lgkmcnt(2)
	v_mfma_f32_32x32x16_bf16 v[64:79], v[52:55], v[100:103], v[64:79]
	s_waitcnt lgkmcnt(1)
	v_mfma_f32_32x32x16_bf16 v[64:79], v[56:59], v[104:107], v[64:79]
	s_waitcnt lgkmcnt(0)
	v_mfma_f32_32x32x16_bf16 v[64:79], v[60:63], v[108:111], v[64:79]
	s_nop 0
	v_max3_f32 v48, v32, s15, v33
	v_max3_f32 v48, v48, v34, v35
	v_max3_f32 v48, v48, v36, v37
	v_max3_f32 v48, v48, v38, v39
	v_max3_f32 v48, v48, v40, v41
	v_max3_f32 v48, v48, v42, v43
	v_max3_f32 v48, v48, v44, v45
	v_max3_f32 v48, v48, v46, v47
	v_mov_b32_e32 v49, v48
	v_mov_b32_e32 v50, v48
	s_nop 1
	v_permlane32_swap_b32_e32 v49, v50
	v_max_f32_e32 v48, v49, v50
	v_cmp_gt_f32_e32 vcc, v48, v82
	s_nop 1
	v_cndmask_b32_e32 v86, v193, v48, vcc
	v_max_f32_e32 v48, 0xefa18f08, v86
	v_sub_f32_e32 v32, v32, v48
	v_exp_f32_e32 v81, v32
	v_sub_f32_e32 v32, v33, v48
	v_exp_f32_e32 v85, v32
	v_sub_f32_e32 v32, v34, v48
	v_exp_f32_e32 v87, v32
	v_sub_f32_e32 v32, v35, v48
	v_exp_f32_e32 v88, v32
	v_sub_f32_e32 v33, v36, v48
	v_exp_f32_e32 v89, v33
	v_sub_f32_e32 v33, v37, v48
	v_add_f32_e32 v32, v85, v81
	v_exp_f32_e32 v90, v33
	v_sub_f32_e32 v33, v38, v48
	v_add_f32_e32 v32, v87, v32
	v_exp_f32_e32 v91, v33
	v_sub_f32_e32 v33, v39, v48
	v_add_f32_e32 v32, v88, v32
	v_exp_f32_e32 v92, v33
	v_sub_f32_e32 v33, v40, v48
	v_add_f32_e32 v32, v89, v32
	v_exp_f32_e32 v93, v33
	v_sub_f32_e32 v33, v41, v48
	v_add_f32_e32 v32, v90, v32
	v_exp_f32_e32 v94, v33
	v_sub_f32_e32 v33, v42, v48
	v_add_f32_e32 v32, v91, v32
	v_exp_f32_e32 v95, v33
	v_sub_f32_e32 v33, v43, v48
	v_add_f32_e32 v32, v92, v32
	v_exp_f32_e32 v128, v33
	v_sub_f32_e32 v33, v44, v48
	v_add_f32_e32 v32, v93, v32
	v_exp_f32_e32 v129, v33
	v_sub_f32_e32 v33, v45, v48
	v_add_f32_e32 v32, v94, v32
	v_exp_f32_e32 v130, v33
	v_sub_f32_e32 v33, v46, v48
	v_add_f32_e32 v32, v95, v32
	v_exp_f32_e32 v131, v33
	v_sub_f32_e32 v33, v47, v48
	v_add_f32_e32 v32, v128, v32
	v_exp_f32_e32 v132, v33
	v_add_f32_e32 v32, v129, v32
	v_sub_f32_e32 v49, v193, v86
	v_add_f32_e32 v32, v130, v32
	v_add_f32_e32 v32, v131, v32
	v_exp_f32_e32 v80, v49
	v_add_f32_e32 v82, v132, v32
	v_mov_b32_e32 v83, v82
	v_mov_b32_e32 v84, v82
	v_mov_b64_e32 v[62:63], v[30:31]
	s_nop 0
	v_permlane32_swap_b32_e32 v83, v84
	v_cmp_neq_f32_e32 vcc, v86, v193
	v_mov_b64_e32 v[60:61], v[28:29]
	v_mov_b64_e32 v[58:59], v[26:27]
	v_mov_b64_e32 v[56:57], v[24:25]
	v_mov_b64_e32 v[54:55], v[22:23]
	v_mov_b64_e32 v[52:53], v[20:21]
	v_mov_b64_e32 v[50:51], v[18:19]
	v_mov_b64_e32 v[48:49], v[16:17]
	v_mov_b64_e32 v[46:47], v[14:15]
	v_mov_b64_e32 v[44:45], v[12:13]
	v_mov_b64_e32 v[42:43], v[10:11]
	v_mov_b64_e32 v[40:41], v[8:9]
	v_mov_b64_e32 v[38:39], v[6:7]
	v_mov_b64_e32 v[36:37], v[4:5]
	v_mov_b64_e32 v[34:35], v[2:3]
	v_mov_b64_e32 v[32:33], v[0:1]
	s_cbranch_vccz .LBB0_724
	v_pk_mul_f32 v[62:63], v[30:31], v[80:81] op_sel_hi:[1,0]
	v_pk_mul_f32 v[60:61], v[28:29], v[80:81] op_sel_hi:[1,0]
	v_pk_mul_f32 v[58:59], v[26:27], v[80:81] op_sel_hi:[1,0]
	v_pk_mul_f32 v[56:57], v[24:25], v[80:81] op_sel_hi:[1,0]
	v_pk_mul_f32 v[54:55], v[22:23], v[80:81] op_sel_hi:[1,0]
	v_pk_mul_f32 v[52:53], v[20:21], v[80:81] op_sel_hi:[1,0]
	v_pk_mul_f32 v[50:51], v[18:19], v[80:81] op_sel_hi:[1,0]
	v_pk_mul_f32 v[48:49], v[16:17], v[80:81] op_sel_hi:[1,0]
	v_pk_mul_f32 v[46:47], v[14:15], v[80:81] op_sel_hi:[1,0]
	v_pk_mul_f32 v[44:45], v[12:13], v[80:81] op_sel_hi:[1,0]
	v_pk_mul_f32 v[42:43], v[10:11], v[80:81] op_sel_hi:[1,0]
	v_pk_mul_f32 v[40:41], v[8:9], v[80:81] op_sel_hi:[1,0]
	v_pk_mul_f32 v[38:39], v[6:7], v[80:81] op_sel_hi:[1,0]
	v_pk_mul_f32 v[36:37], v[4:5], v[80:81] op_sel_hi:[1,0]
	v_pk_mul_f32 v[34:35], v[2:3], v[80:81] op_sel_hi:[1,0]
	v_pk_mul_f32 v[32:33], v[0:1], v[80:81] op_sel_hi:[1,0]
; #define LAS __attribute__((address_space(3)))
; #define MFMA32(a, b, c) __builtin_amdgcn_mfma_f32_32x32x16_bf16((a), (b), (c), 0, 0, 0)
; DI s16x4 vtr(LAS const char* p) { return __builtin_bit_cast(s16x4, __builtin_amdgcn_ds_read_tr16_b64_v4i16((LAS v4i16_t*)p)); }
; DI void pv_rows(f32x16 (&o)[2], LAS const char* Vl, int row0, const bf16x8 (&pf)[2], int lane) {
;     const int h = lane >> 5, i = lane & 15, grp = (lane >> 4) & 1;
;     LAS const char* base = Vl + (row0 + 4 * h + (i >> 2)) * KP + grp * 32 + (i & 3) * 8;
;     bf16x8 vf[2][2];
; #pragma unroll
;     for (int dt = 0; dt < 2; ++dt)
; #pragma unroll
;         for (int s2 = 0; s2 < 2; ++s2) {
;             const s16x4 lo = vtr(base + (16 * s2) * KP + dt * 64), hi = vtr(base + (16 * s2 + 8) * KP + dt * 64);
;             vf[dt][s2] = (bf16x8){lo[0], lo[1], lo[2], lo[3], hi[0], hi[1], hi[2], hi[3]};
;         }
;     __builtin_amdgcn_s_setprio(1);
; #pragma unroll
;     for (int s2 = 0; s2 < 2; ++s2)
; #pragma unroll
;         for (int dt = 0; dt < 2; ++dt) o[dt] = MFMA32(vf[dt][s2], pf[s2], o[dt]);
;     __builtin_amdgcn_s_setprio(0);
; }
; template <int MM> DI void tile64_pipe(LAS const char* Kl, LAS const char* Vl, const bf16x8 (&qf)[4], unsigned vm, float& m, float& l, f32x16 (&o)[2], int r, int h, int lane) {
;     const f32x16 sa = qk_rows<0, 4>(Kl, 0, qf, r, h), sb = qk_rows<0, 4>(Kl, 32, qf, r, h);
;     bf16x8 pfa[2], pfb[2];
;     smax_step_nb<MM>(sa, vm, m, l, o, pfa, lane);
;     pv_rows(o, Vl, 0, pfa, lane);
;     smax_step_nb<MM>(sb, vm, m, l, o, pfb, lane);
;     pv_rows(o, Vl, 32, pfb, lane);
; }
.LBB0_724:
	v_cvt_pk_bf16_f32 v134, v81, v85
	v_add3_u32 v81, s64, v191, v171
	v_add_u32_e32 v85, v81, v186
	v_cvt_pk_bf16_f32 v135, v87, v88
	v_cvt_pk_bf16_f32 v136, v89, v90
	v_cvt_pk_bf16_f32 v137, v91, v92
	v_cvt_pk_bf16_f32 v88, v93, v94
	v_cvt_pk_bf16_f32 v89, v95, v128
	v_cvt_pk_bf16_f32 v90, v129, v130
	v_cvt_pk_bf16_f32 v91, v131, v132
	ds_read_b64_tr_b16 v[92:93], v85 offset:9216
	ds_read_b64_tr_b16 v[94:95], v85 offset:10368
	ds_read_b64_tr_b16 v[128:129], v85 offset:11520
	ds_read_b64_tr_b16 v[130:131], v85 offset:12672
	ds_read_b64_tr_b16 v[138:139], v85 offset:9280
	ds_read_b64_tr_b16 v[140:141], v85 offset:10432
	ds_read_b64_tr_b16 v[142:143], v85 offset:11584
	ds_read_b64_tr_b16 v[144:145], v85 offset:12736
	s_nop 0
	s_waitcnt lgkmcnt(6)
	v_mfma_f32_32x32x16_bf16 v[32:47], v[92:95], v[134:137], v[32:47]
	s_waitcnt lgkmcnt(2)
	v_mfma_f32_32x32x16_bf16 v[48:63], v[138:141], v[134:137], v[48:63]
	v_mfma_f32_32x32x16_bf16 v[32:47], v[128:131], v[88:91], v[32:47]
	s_waitcnt lgkmcnt(0)
	v_mfma_f32_32x32x16_bf16 v[48:63], v[142:145], v[88:91], v[48:63]
	s_nop 0
	v_max3_f32 v81, v64, s15, v65
	v_max3_f32 v81, v81, v66, v67
	v_max3_f32 v81, v81, v68, v69
	v_max3_f32 v81, v81, v70, v71
	v_max3_f32 v81, v81, v72, v73
	v_max3_f32 v81, v81, v74, v75
	v_max3_f32 v81, v81, v76, v77
	v_max3_f32 v81, v81, v78, v79
	v_mov_b32_e32 v87, v81
	v_mov_b32_e32 v88, v81
	s_nop 1
	v_permlane32_swap_b32_e32 v87, v88
	v_max_f32_e32 v81, v87, v88
	v_add_f32_e32 v87, 0x41000000, v86
	v_cmp_gt_f32_e32 vcc, v81, v87
	s_nop 1
	v_cndmask_b32_e32 v81, v86, v81, vcc
	v_max_f32_e32 v89, 0xefa18f08, v81
	v_sub_f32_e32 v64, v64, v89
	v_exp_f32_e32 v87, v64
	v_sub_f32_e32 v64, v65, v89
	v_exp_f32_e32 v88, v64
	v_sub_f32_e32 v64, v66, v89
	v_exp_f32_e32 v66, v64
	v_sub_f32_e32 v64, v67, v89
	v_exp_f32_e32 v67, v64
	v_sub_f32_e32 v65, v68, v89
	v_exp_f32_e32 v68, v65
	v_sub_f32_e32 v65, v69, v89
	v_add_f32_e32 v64, v88, v87
	v_exp_f32_e32 v69, v65
	v_sub_f32_e32 v65, v70, v89
	v_add_f32_e32 v64, v66, v64
	v_exp_f32_e32 v70, v65
	v_sub_f32_e32 v65, v71, v89
	v_add_f32_e32 v64, v67, v64
	v_exp_f32_e32 v71, v65
	v_sub_f32_e32 v65, v72, v89
	v_add_f32_e32 v64, v68, v64
	v_exp_f32_e32 v72, v65
	v_sub_f32_e32 v65, v73, v89
	v_add_f32_e32 v64, v69, v64
	v_exp_f32_e32 v73, v65
	v_sub_f32_e32 v65, v74, v89
	v_add_f32_e32 v64, v70, v64
	v_exp_f32_e32 v74, v65
	v_sub_f32_e32 v65, v75, v89
	v_add_f32_e32 v64, v71, v64
	v_exp_f32_e32 v75, v65
	v_sub_f32_e32 v65, v76, v89
	v_add_f32_e32 v64, v72, v64
	v_exp_f32_e32 v76, v65
	v_sub_f32_e32 v65, v77, v89
	v_add_f32_e32 v64, v73, v64
	v_exp_f32_e32 v77, v65
	v_sub_f32_e32 v65, v78, v89
	v_add_f32_e32 v64, v74, v64
	v_exp_f32_e32 v78, v65
	v_sub_f32_e32 v65, v79, v89
	v_add_f32_e32 v64, v75, v64
	v_exp_f32_e32 v79, v65
	v_add_f32_e32 v64, v76, v64
	v_add_f32_e32 v64, v77, v64
	v_sub_f32_e32 v90, v86, v81
	v_add_f32_e32 v64, v78, v64
	v_add_f32_e32 v65, v79, v64
	v_exp_f32_e32 v64, v90
	v_mov_b32_e32 v89, v65
	v_mov_b32_e32 v90, v65
	s_nop 1
	v_permlane32_swap_b32_e32 v89, v90
	v_cmp_neq_f32_e32 vcc, v81, v86
	s_cbranch_vccz .LBB0_726
	v_pk_mul_f32 v[62:63], v[62:63], v[64:65] op_sel_hi:[1,0]
	v_pk_mul_f32 v[60:61], v[60:61], v[64:65] op_sel_hi:[1,0]
	v_pk_mul_f32 v[58:59], v[58:59], v[64:65] op_sel_hi:[1,0]
	v_pk_mul_f32 v[56:57], v[56:57], v[64:65] op_sel_hi:[1,0]
	v_pk_mul_f32 v[54:55], v[54:55], v[64:65] op_sel_hi:[1,0]
	v_pk_mul_f32 v[52:53], v[52:53], v[64:65] op_sel_hi:[1,0]
	v_pk_mul_f32 v[50:51], v[50:51], v[64:65] op_sel_hi:[1,0]
	v_pk_mul_f32 v[48:49], v[48:49], v[64:65] op_sel_hi:[1,0]
	v_pk_mul_f32 v[46:47], v[46:47], v[64:65] op_sel_hi:[1,0]
	v_pk_mul_f32 v[44:45], v[44:45], v[64:65] op_sel_hi:[1,0]
	v_pk_mul_f32 v[42:43], v[42:43], v[64:65] op_sel_hi:[1,0]
	v_pk_mul_f32 v[40:41], v[40:41], v[64:65] op_sel_hi:[1,0]
	v_pk_mul_f32 v[38:39], v[38:39], v[64:65] op_sel_hi:[1,0]
	v_pk_mul_f32 v[36:37], v[36:37], v[64:65] op_sel_hi:[1,0]
	v_pk_mul_f32 v[34:35], v[34:35], v[64:65] op_sel_hi:[1,0]
	v_pk_mul_f32 v[32:33], v[32:33], v[64:65] op_sel_hi:[1,0]
.LBB0_726:
	v_cndmask_b32_e64 v83, v83, v84, s[36:37]
	v_add_f32_e32 v82, v82, v83
	v_fmac_f32_e32 v82, v184, v80
	v_cndmask_b32_e64 v80, v89, v90, s[36:37]
	v_add_f32_e32 v65, v65, v80
	v_fmac_f32_e32 v65, v82, v64
	v_cvt_pk_bf16_f32 v86, v87, v88
	v_cvt_pk_bf16_f32 v87, v66, v67
	v_cvt_pk_bf16_f32 v88, v68, v69
	v_cvt_pk_bf16_f32 v89, v70, v71
	v_cvt_pk_bf16_f32 v66, v72, v73
	v_cvt_pk_bf16_f32 v67, v74, v75
	v_cvt_pk_bf16_f32 v68, v76, v77
	ds_read_b64_tr_b16 v[70:71], v85 offset:13824
	ds_read_b64_tr_b16 v[72:73], v85 offset:14976
	ds_read_b64_tr_b16 v[74:75], v85 offset:16128
	ds_read_b64_tr_b16 v[76:77], v85 offset:17280
	ds_read_b64_tr_b16 v[90:91], v85 offset:13888
	ds_read_b64_tr_b16 v[92:93], v85 offset:15040
	ds_read_b64_tr_b16 v[82:83], v85 offset:16192
	ds_read_b64_tr_b16 v[84:85], v85 offset:17344
	v_cvt_pk_bf16_f32 v69, v78, v79
	s_nop 0
	s_waitcnt lgkmcnt(6)
	v_mfma_f32_32x32x16_bf16 v[32:47], v[70:73], v[86:89], v[32:47]
	s_mov_b64 s[0:1], -1
	s_waitcnt lgkmcnt(2)
	v_mfma_f32_32x32x16_bf16 v[48:63], v[90:93], v[86:89], v[48:63]
	v_mfma_f32_32x32x16_bf16 v[32:47], v[74:77], v[66:69], v[32:47]
	s_waitcnt lgkmcnt(0)
	v_mfma_f32_32x32x16_bf16 v[48:63], v[82:85], v[66:69], v[48:63]

; #define MFMA32(a, b, c) __builtin_amdgcn_mfma_f32_32x32x16_bf16((a), (b), (c), 0, 0, 0)
; DI void pv_rows(f32x16 (&o)[2], LAS const char* Vl, int row0, const bf16x8 (&pf)[2], int lane) {
;     ...
;     __builtin_amdgcn_s_setprio(1);
; #pragma unroll
;     for (int s2 = 0; s2 < 2; ++s2)
; #pragma unroll
;         for (int dt = 0; dt < 2; ++dt) o[dt] = MFMA32(vf[dt][s2], pf[s2], o[dt]);
;     __builtin_amdgcn_s_setprio(0);
; template <int MODE, bool PRE = false> ...
;     ...
;                     if (selb == ~0ull) tile64_pipe<0>(Kl, Vl, qf, vm, m1, l1, o1, r, h, lane); else tile64_pipe<1>(Kl, Vl, qf, vm, m1, l1, o1, r, h, lane);
.LBB0_728:
	s_nop 0
	s_nop 4
	v_mov_b64_e32 v[0:1], v[32:33]
	v_mov_b64_e32 v[2:3], v[34:35]
	v_mov_b64_e32 v[4:5], v[36:37]
	v_mov_b64_e32 v[6:7], v[38:39]
	v_mov_b64_e32 v[8:9], v[40:41]
	v_mov_b64_e32 v[10:11], v[42:43]
	v_mov_b64_e32 v[12:13], v[44:45]
	v_mov_b64_e32 v[14:15], v[46:47]
	v_mov_b64_e32 v[16:17], v[48:49]
	v_mov_b64_e32 v[18:19], v[50:51]
	v_mov_b64_e32 v[20:21], v[52:53]
	v_mov_b64_e32 v[22:23], v[54:55]
	v_mov_b64_e32 v[24:25], v[56:57]
	v_mov_b64_e32 v[26:27], v[58:59]
	v_mov_b64_e32 v[28:29], v[60:61]
	v_mov_b64_e32 v[30:31], v[62:63]

; template <int MM> DI void smax_step(const f32x16& s, unsigned vm, float& m, float& l, f32x16 (&o)[2], bf16x8 (&pf)[2], int lane) {
;     float t[16], mx = -1e30f;
; #pragma unroll
;     for (int i = 0; i < 16; ++i) { t[i] = (MM == 0) ? s[i] : (MM == 1 ? (vm ? s[i] : -1e30f) : (((vm >> i) & 1u) ? s[i] : -1e30f)); mx = fmaxf(mx, t[i]); }
; template <int MODE, bool PRE = false> ...
;     ...
;         for (int sub = 0; sub < 2; ++sub) {
;             const int kbase = 64 * kt + 32 * sub;
;             if (kbase > q0w + 31) continue;
;             if (MODE == MODE_NWIN && kbase + 31 <= q0w - 512) continue;
;             bool full = (kbase + 31 <= q0w);
;             if (MODE == MODE_NWIN) full = full && (kbase > q0w + 31 - 512);
;             bool lsel = true;
;             if (MODE == MODE_MOBA) lsel = ((sel >> (kbase >> 8)) & 1ull) != 0ull;
;             if (MODE == MODE_NSEL) lsel = ((sel >> kt) & 1ull) != 0ull;
;             const unsigned long long selb = __builtin_amdgcn_ballot_w64(lsel);
;             if (selb == 0ull) continue;
;             int mm; unsigned vm;
;             if (full) { mm = (selb == ~0ull) ? 0 : 1; vm = lsel ? 1u : 0u; }
;             else { mm = 2; vm = 0;
; #pragma unroll
;                 for (int i = 0; i < 16; ++i) { const int kidx = kbase + (i & 3) + 8 * (i >> 2) + 4 * h; bool ok = kidx <= qpos; if (MODE == MODE_NWIN) ok = ok && (kidx > qpos - 512); vm |= ok ? (1u << i) : 0u; }
;                 if (!lsel) vm = 0;
;                 if (__builtin_amdgcn_ballot_w64(vm != 0) == 0ull) continue; }
;             bf16x8 pf[2];
;             if (MODE == MODE_DIFF) {
;                 const f32x16 s1 = qk_rows<0, 2>(Kl, 32 * sub, qf, r, h), s2 = qk_rows<2, 4>(Kl, 32 * sub, qf, r, h);
;                 bf16x8 pf2[2];
;                 if (mm == 0) { smax_step<0>(s1, vm, m1, l1, o1, pf, lane); smax_step<0>(s2, vm, m2, l2, o2, pf2, lane); }
;                 else { smax_step<2>(s1, vm, m1, l1, o1, pf, lane); smax_step<2>(s2, vm, m2, l2, o2, pf2, lane); }
;                 pv_rows(o1, Vl, 32 * sub, pf, lane);
;                 pv_rows(o2, Vl, 32 * sub, pf2, lane);
;             } else {
;                 const f32x16 s = qk_rows<0, 4>(Kl, 32 * sub, qf, r, h);
;                 if (mm == 0) smax_step<0>(s, vm, m1, l1, o1, pf, lane); else if (mm == 1) smax_step<1>(s, vm, m1, l1, o1, pf, lane); else smax_step<2>(s, vm, m1, l1, o1, pf, lane);
.LBB0_732:
	v_mov_b64_e32 v[94:95], v[30:31]
	s_andn2_b64 vcc, exec, s[0:1]
	v_mov_b64_e32 v[92:93], v[28:29]
	v_mov_b64_e32 v[90:91], v[26:27]
	v_mov_b64_e32 v[88:89], v[24:25]
	v_mov_b64_e32 v[86:87], v[22:23]
	v_mov_b64_e32 v[84:85], v[20:21]
	v_mov_b64_e32 v[82:83], v[18:19]
	v_mov_b64_e32 v[80:81], v[16:17]
	v_mov_b64_e32 v[78:79], v[14:15]
	v_mov_b64_e32 v[76:77], v[12:13]
	v_mov_b64_e32 v[74:75], v[10:11]
	v_mov_b64_e32 v[72:73], v[8:9]
	v_mov_b64_e32 v[70:71], v[6:7]
	v_mov_b64_e32 v[68:69], v[4:5]
	v_mov_b64_e32 v[66:67], v[2:3]
	v_mov_b64_e32 v[64:65], v[0:1]
	v_mov_b32_e32 v129, v184
	v_mov_b32_e32 v130, v193
	s_cbranch_vccnz .LBB0_744
	v_add_u32_e32 v36, v48, v190
	ds_read_b128 v[32:35], v36
	ds_read_b128 v[50:53], v36 offset:32
	ds_read_b128 v[54:57], v36 offset:64
	ds_read_b128 v[58:61], v36 offset:96
	s_nop 0
	s_waitcnt lgkmcnt(3)
	v_mfma_f32_32x32x16_bf16 v[32:47], v[32:35], v[96:99], 0
	s_waitcnt lgkmcnt(2)
	v_mfma_f32_32x32x16_bf16 v[32:47], v[50:53], v[100:103], v[32:47]
	s_waitcnt lgkmcnt(1)
	v_mfma_f32_32x32x16_bf16 v[32:47], v[54:57], v[104:107], v[32:47]
	s_waitcnt lgkmcnt(0)
	v_mfma_f32_32x32x16_bf16 v[32:47], v[58:61], v[108:111], v[32:47]
	s_nop 0
	s_cmp_lt_i32 s24, 1
	s_cbranch_scc1 .LBB0_736
	s_cmp_lg_u32 s24, 1
	s_cbranch_scc0 .LBB0_737
	v_and_b32_e32 v49, 1, v135
	v_cmp_eq_u32_e32 vcc, 1, v49
	v_and_b32_e32 v49, 2, v135
	v_and_b32_e32 v52, 4, v135
	s_nop 2
	v_cndmask_b32_e32 v50, v208, v32, vcc
	v_cmp_ne_u32_e32 vcc, 0, v49
	v_and_b32_e32 v53, 8, v135
	v_and_b32_e32 v54, 16, v135
	v_cndmask_b32_e32 v51, v208, v33, vcc
	v_cmp_ne_u32_e32 vcc, 0, v52
	v_and_b32_e32 v55, 32, v135
	v_and_b32_e32 v56, 64, v135
	v_cndmask_b32_e32 v52, v208, v34, vcc
	v_cmp_ne_u32_e32 vcc, 0, v53
	v_and_b32_e32 v57, 0x80, v135
	v_and_b32_e32 v58, 0x100, v135
	v_cndmask_b32_e32 v53, v208, v35, vcc
	v_cmp_ne_u32_e32 vcc, 0, v54
	v_and_b32_e32 v59, 0x200, v135
	v_and_b32_e32 v60, 0x400, v135
	v_cndmask_b32_e32 v54, v208, v36, vcc
	v_cmp_ne_u32_e32 vcc, 0, v55
	v_max3_f32 v49, v50, s15, v51
	v_and_b32_e32 v61, 0x800, v135
	v_cndmask_b32_e32 v55, v208, v37, vcc
	v_cmp_ne_u32_e32 vcc, 0, v56
	v_max3_f32 v49, v49, v52, v53
	v_and_b32_e32 v62, 0x1000, v135
	v_cndmask_b32_e32 v56, v208, v38, vcc
	v_cmp_ne_u32_e32 vcc, 0, v57
	v_max3_f32 v49, v49, v54, v55
	v_and_b32_e32 v63, 0x2000, v135
	v_cndmask_b32_e32 v57, v208, v39, vcc
	v_cmp_ne_u32_e32 vcc, 0, v58
	v_max3_f32 v49, v49, v56, v57
	v_and_b32_e32 v64, 0x4000, v135
	v_cndmask_b32_e32 v58, v208, v40, vcc
	v_cmp_ne_u32_e32 vcc, 0, v59
	v_and_b32_e32 v65, 0x8000, v135
	s_nop 0
	v_cndmask_b32_e32 v59, v208, v41, vcc
	v_cmp_ne_u32_e32 vcc, 0, v60
	v_max3_f32 v49, v49, v58, v59
	s_nop 0
	v_cndmask_b32_e32 v60, v208, v42, vcc
	v_cmp_ne_u32_e32 vcc, 0, v61
	s_nop 1
	v_cndmask_b32_e32 v61, v208, v43, vcc
	v_cmp_ne_u32_e32 vcc, 0, v62
	v_max3_f32 v49, v49, v60, v61
	s_nop 0
	v_cndmask_b32_e32 v62, v208, v44, vcc
	v_cmp_ne_u32_e32 vcc, 0, v63
	s_nop 1
	v_cndmask_b32_e32 v63, v208, v45, vcc
	v_cmp_ne_u32_e32 vcc, 0, v64
	v_max3_f32 v49, v49, v62, v63
	s_nop 0
	v_cndmask_b32_e32 v64, v208, v46, vcc
	v_cmp_ne_u32_e32 vcc, 0, v65
	s_nop 1
	v_cndmask_b32_e32 v65, v208, v47, vcc
	v_max3_f32 v49, v49, v64, v65
	v_mov_b32_e32 v66, v49
	v_mov_b32_e32 v67, v49
	s_nop 1
	v_permlane32_swap_b32_e32 v66, v67
	v_max_f32_e32 v49, v66, v67
	v_add_f32_e32 v66, 0x41000000, v193
	v_cmp_gt_f32_e32 vcc, v49, v66
	s_nop 1
	v_cndmask_b32_e32 v49, v193, v49, vcc
	v_max_f32_e32 v66, 0xefa18f08, v49
	v_sub_f32_e32 v50, v50, v66
	v_exp_f32_e32 v50, v50
	v_sub_f32_e32 v51, v51, v66
	v_exp_f32_e32 v51, v51
	v_sub_f32_e32 v52, v52, v66
	v_exp_f32_e32 v52, v52
	v_sub_f32_e32 v53, v53, v66
	v_exp_f32_e32 v53, v53
	v_sub_f32_e32 v54, v54, v66
	v_exp_f32_e32 v54, v54
	v_sub_f32_e32 v55, v55, v66
	v_add_f32_e32 v67, v51, v50
	v_exp_f32_e32 v55, v55
	v_sub_f32_e32 v56, v56, v66
	v_add_f32_e32 v67, v52, v67
	v_exp_f32_e32 v56, v56
	v_sub_f32_e32 v57, v57, v66
	v_add_f32_e32 v67, v53, v67
	v_exp_f32_e32 v57, v57
	v_sub_f32_e32 v58, v58, v66
	v_add_f32_e32 v67, v54, v67
	v_exp_f32_e32 v58, v58
	v_sub_f32_e32 v59, v59, v66
	v_add_f32_e32 v67, v55, v67
	v_exp_f32_e32 v59, v59
	v_sub_f32_e32 v60, v60, v66
	v_add_f32_e32 v67, v56, v67
	v_exp_f32_e32 v60, v60
	v_sub_f32_e32 v61, v61, v66
	v_add_f32_e32 v67, v57, v67
	v_exp_f32_e32 v61, v61
	v_sub_f32_e32 v62, v62, v66
	v_add_f32_e32 v67, v58, v67
	v_exp_f32_e32 v62, v62
	v_sub_f32_e32 v63, v63, v66
	v_add_f32_e32 v67, v59, v67
	v_exp_f32_e32 v63, v63
	v_sub_f32_e32 v64, v64, v66
	v_add_f32_e32 v67, v60, v67
	v_exp_f32_e32 v131, v64
	v_sub_f32_e32 v64, v65, v66
	v_add_f32_e32 v67, v61, v67
	v_exp_f32_e32 v132, v64
	v_add_f32_e32 v64, v62, v67
	v_add_f32_e32 v64, v63, v64
	v_add_f32_e32 v64, v131, v64
	v_add_f32_e32 v129, v132, v64
	v_cmp_neq_f32_e32 vcc, v49, v193
	v_mov_b32_e32 v133, v129
	v_mov_b32_e32 v134, v129
	s_cmp_lg_u64 vcc, 0
	s_nop 0
	v_permlane32_swap_b32_e32 v133, v134
	s_cselect_b64 s[0:1], -1, 0
	s_cbranch_execz .LBB0_738
	s_branch .LBB0_739

; #define LAS __attribute__((address_space(3)))
; #define MFMA32(a, b, c) __builtin_amdgcn_mfma_f32_32x32x16_bf16((a), (b), (c), 0, 0, 0)
; DI s16x4 vtr(LAS const char* p) { return __builtin_bit_cast(s16x4, __builtin_amdgcn_ds_read_tr16_b64_v4i16((LAS v4i16_t*)p)); }
; DI void pv_rows(f32x16 (&o)[2], LAS const char* Vl, int row0, const bf16x8 (&pf)[2], int lane) {
;     const int h = lane >> 5, i = lane & 15, grp = (lane >> 4) & 1;
;     LAS const char* base = Vl + (row0 + 4 * h + (i >> 2)) * KP + grp * 32 + (i & 3) * 8;
;     bf16x8 vf[2][2];
; #pragma unroll
;     for (int dt = 0; dt < 2; ++dt)
; #pragma unroll
;         for (int s2 = 0; s2 < 2; ++s2) {
;             const s16x4 lo = vtr(base + (16 * s2) * KP + dt * 64), hi = vtr(base + (16 * s2 + 8) * KP + dt * 64);
;             vf[dt][s2] = (bf16x8){lo[0], lo[1], lo[2], lo[3], hi[0], hi[1], hi[2], hi[3]};
;         }
;     __builtin_amdgcn_s_setprio(1);
; #pragma unroll
;     for (int s2 = 0; s2 < 2; ++s2)
; #pragma unroll
;         for (int dt = 0; dt < 2; ++dt) o[dt] = MFMA32(vf[dt][s2], pf[s2], o[dt]);
;     __builtin_amdgcn_s_setprio(0);
; }
; template <int MM> DI void smax_step(const f32x16& s, unsigned vm, float& m, float& l, f32x16 (&o)[2], bf16x8 (&pf)[2], int lane) {
;     ...
;     l += rs;
;     pack_p(p, pf);
.LBB0_743:
	v_cndmask_b32_e64 v33, v133, v134, s[36:37]
	v_add_f32_e32 v33, v129, v33
	v_add_u32_e32 v49, v128, v191
	v_add_f32_e32 v129, v32, v33
	v_cvt_pk_bf16_f32 v32, v50, v51
	v_cvt_pk_bf16_f32 v33, v52, v53
	v_cvt_pk_bf16_f32 v34, v54, v55
	v_cvt_pk_bf16_f32 v35, v56, v57
	ds_read_b64_tr_b16 v[40:41], v49 offset:9216
	ds_read_b64_tr_b16 v[42:43], v49 offset:10368
	ds_read_b64_tr_b16 v[44:45], v49 offset:11520
	ds_read_b64_tr_b16 v[46:47], v49 offset:12672
	ds_read_b64_tr_b16 v[50:51], v49 offset:9280
	ds_read_b64_tr_b16 v[52:53], v49 offset:10432
	ds_read_b64_tr_b16 v[54:55], v49 offset:11584
	ds_read_b64_tr_b16 v[56:57], v49 offset:12736
	v_cvt_pk_bf16_f32 v36, v58, v59
	v_cvt_pk_bf16_f32 v37, v60, v61
	v_cvt_pk_bf16_f32 v38, v62, v63
	v_cvt_pk_bf16_f32 v39, v131, v132
	s_nop 0
	s_waitcnt lgkmcnt(6)
	v_mfma_f32_32x32x16_bf16 v[64:79], v[40:43], v[32:35], v[64:79]
	s_waitcnt lgkmcnt(2)
	v_mfma_f32_32x32x16_bf16 v[80:95], v[50:53], v[32:35], v[80:95]
	v_mfma_f32_32x32x16_bf16 v[64:79], v[44:47], v[36:39], v[64:79]
	s_waitcnt lgkmcnt(0)
	v_mfma_f32_32x32x16_bf16 v[80:95], v[54:57], v[36:39], v[80:95]
	s_nop 0

; template <int MM> DI void smax_step(const f32x16& s, unsigned vm, float& m, float& l, f32x16 (&o)[2], bf16x8 (&pf)[2], int lane) {
;     float t[16], mx = -1e30f;
; #pragma unroll
;     for (int i = 0; i < 16; ++i) { t[i] = (MM == 0) ? s[i] : (MM == 1 ? (vm ? s[i] : -1e30f) : (((vm >> i) & 1u) ? s[i] : -1e30f)); mx = fmaxf(mx, t[i]); }
; template <int MODE, bool PRE = false> ...
;     ...
;         for (int sub = 0; sub < 2; ++sub) {
;             const int kbase = 64 * kt + 32 * sub;
;             if (kbase > q0w + 31) continue;
;             if (MODE == MODE_NWIN && kbase + 31 <= q0w - 512) continue;
;             bool full = (kbase + 31 <= q0w);
;             if (MODE == MODE_NWIN) full = full && (kbase > q0w + 31 - 512);
;             bool lsel = true;
;             if (MODE == MODE_MOBA) lsel = ((sel >> (kbase >> 8)) & 1ull) != 0ull;
;             if (MODE == MODE_NSEL) lsel = ((sel >> kt) & 1ull) != 0ull;
;             const unsigned long long selb = __builtin_amdgcn_ballot_w64(lsel);
;             if (selb == 0ull) continue;
;             int mm; unsigned vm;
;             if (full) { mm = (selb == ~0ull) ? 0 : 1; vm = lsel ? 1u : 0u; }
;             else { mm = 2; vm = 0;
; #pragma unroll
;                 for (int i = 0; i < 16; ++i) { const int kidx = kbase + (i & 3) + 8 * (i >> 2) + 4 * h; bool ok = kidx <= qpos; if (MODE == MODE_NWIN) ok = ok && (kidx > qpos - 512); vm |= ok ? (1u << i) : 0u; }
;                 if (!lsel) vm = 0;
;                 if (__builtin_amdgcn_ballot_w64(vm != 0) == 0ull) continue; }
;             bf16x8 pf[2];
;             if (MODE == MODE_DIFF) {
;                 const f32x16 s1 = qk_rows<0, 2>(Kl, 32 * sub, qf, r, h), s2 = qk_rows<2, 4>(Kl, 32 * sub, qf, r, h);
;                 bf16x8 pf2[2];
;                 if (mm == 0) { smax_step<0>(s1, vm, m1, l1, o1, pf, lane); smax_step<0>(s2, vm, m2, l2, o2, pf2, lane); }
;                 else { smax_step<2>(s1, vm, m1, l1, o1, pf, lane); smax_step<2>(s2, vm, m2, l2, o2, pf2, lane); }
;                 pv_rows(o1, Vl, 32 * sub, pf, lane);
;                 pv_rows(o2, Vl, 32 * sub, pf2, lane);
;             } else {
;                 const f32x16 s = qk_rows<0, 4>(Kl, 32 * sub, qf, r, h);
;                 if (mm == 0) smax_step<0>(s, vm, m1, l1, o1, pf, lane); else if (mm == 1) smax_step<1>(s, vm, m1, l1, o1, pf, lane); else smax_step<2>(s, vm, m1, l1, o1, pf, lane);
.LBB0_753:
	s_andn2_b64 vcc, exec, s[0:1]
	s_mov_b64 s[0:1], 0
	s_cbranch_vccnz .LBB0_757
	v_add_u32_e32 v36, v48, v192
	ds_read_b128 v[32:35], v36
	ds_read_b128 v[50:53], v36 offset:32
	ds_read_b128 v[54:57], v36 offset:64
	ds_read_b128 v[58:61], v36 offset:96
	s_nop 0
	s_waitcnt lgkmcnt(3)
	v_mfma_f32_32x32x16_bf16 v[32:47], v[32:35], v[96:99], 0
	s_waitcnt lgkmcnt(2)
	v_mfma_f32_32x32x16_bf16 v[32:47], v[50:53], v[100:103], v[32:47]
	s_waitcnt lgkmcnt(1)
	v_mfma_f32_32x32x16_bf16 v[32:47], v[54:57], v[104:107], v[32:47]
	s_waitcnt lgkmcnt(0)
	v_mfma_f32_32x32x16_bf16 v[32:47], v[58:61], v[108:111], v[32:47]
	s_nop 0
	s_cmp_lt_i32 s10, 1
	s_cbranch_scc1 .LBB0_758
	s_cmp_lg_u32 s10, 1
	s_cbranch_scc0 .LBB0_759
	v_and_b32_e32 v48, 1, v49
	v_cmp_eq_u32_e32 vcc, 1, v48
	v_and_b32_e32 v50, 2, v49
	v_and_b32_e32 v52, 4, v49
	s_nop 2
	v_cndmask_b32_e32 v48, v208, v32, vcc
	v_cmp_ne_u32_e32 vcc, 0, v50
	v_and_b32_e32 v53, 8, v49
	v_and_b32_e32 v54, 16, v49
	v_cndmask_b32_e32 v50, v208, v33, vcc
	v_cmp_ne_u32_e32 vcc, 0, v52
	v_and_b32_e32 v55, 32, v49
	v_and_b32_e32 v56, 64, v49
	v_cndmask_b32_e32 v52, v208, v34, vcc
	v_cmp_ne_u32_e32 vcc, 0, v53
	v_and_b32_e32 v57, 0x80, v49
	v_and_b32_e32 v58, 0x100, v49
	v_cndmask_b32_e32 v53, v208, v35, vcc
	v_cmp_ne_u32_e32 vcc, 0, v54
	v_and_b32_e32 v59, 0x200, v49
	v_and_b32_e32 v60, 0x400, v49
	v_cndmask_b32_e32 v54, v208, v36, vcc
	v_cmp_ne_u32_e32 vcc, 0, v55
	v_max3_f32 v51, v48, s15, v50
	v_and_b32_e32 v61, 0x800, v49
	v_cndmask_b32_e32 v55, v208, v37, vcc
	v_cmp_ne_u32_e32 vcc, 0, v56
	v_max3_f32 v51, v51, v52, v53
	v_and_b32_e32 v62, 0x1000, v49
	v_cndmask_b32_e32 v56, v208, v38, vcc
	v_cmp_ne_u32_e32 vcc, 0, v57
	v_max3_f32 v51, v51, v54, v55
	v_and_b32_e32 v63, 0x2000, v49
	v_cndmask_b32_e32 v57, v208, v39, vcc
	v_cmp_ne_u32_e32 vcc, 0, v58
	v_max3_f32 v51, v51, v56, v57
	v_and_b32_e32 v131, 0x4000, v49
	v_cndmask_b32_e32 v58, v208, v40, vcc
	v_cmp_ne_u32_e32 vcc, 0, v59
	s_nop 1
	v_cndmask_b32_e32 v59, v208, v41, vcc
	v_cmp_ne_u32_e32 vcc, 0, v60
	v_max3_f32 v51, v51, v58, v59
	s_nop 0
	v_cndmask_b32_e32 v60, v208, v42, vcc
	v_cmp_ne_u32_e32 vcc, 0, v61
	s_nop 1
	v_cndmask_b32_e32 v61, v208, v43, vcc
	v_cmp_ne_u32_e32 vcc, 0, v62
	v_max3_f32 v51, v51, v60, v61
	s_nop 0
	v_cndmask_b32_e32 v62, v208, v44, vcc
	v_cmp_ne_u32_e32 vcc, 0, v63
	s_nop 1
	v_cndmask_b32_e32 v63, v208, v45, vcc
	v_cmp_ne_u32_e32 vcc, 0, v131
	v_and_b32_e32 v131, 0x8000, v49
	v_max3_f32 v51, v51, v62, v63
	v_cndmask_b32_e32 v146, v208, v46, vcc
	v_cmp_ne_u32_e32 vcc, 0, v131
	s_nop 1
	v_cndmask_b32_e32 v147, v208, v47, vcc
	v_max3_f32 v51, v51, v146, v147
	v_mov_b32_e32 v131, v51
	v_mov_b32_e32 v132, v51
	s_nop 1
	v_permlane32_swap_b32_e32 v131, v132
	v_max_f32_e32 v51, v131, v132
	v_add_f32_e32 v131, 0x41000000, v130
	v_cmp_gt_f32_e32 vcc, v51, v131
	s_nop 1
	v_cndmask_b32_e32 v131, v130, v51, vcc
	v_max_f32_e32 v51, 0xefa18f08, v131
	v_sub_f32_e32 v48, v48, v51
	v_exp_f32_e32 v132, v48
	v_sub_f32_e32 v48, v50, v51
	v_exp_f32_e32 v133, v48
	v_sub_f32_e32 v48, v52, v51
	v_exp_f32_e32 v134, v48
	v_sub_f32_e32 v48, v53, v51
	v_exp_f32_e32 v135, v48
	v_sub_f32_e32 v50, v54, v51
	v_exp_f32_e32 v136, v50
	v_sub_f32_e32 v50, v55, v51
	v_add_f32_e32 v48, v133, v132
	v_exp_f32_e32 v137, v50
	v_sub_f32_e32 v50, v56, v51
	v_add_f32_e32 v48, v134, v48
	v_exp_f32_e32 v138, v50
	v_sub_f32_e32 v50, v57, v51
	v_add_f32_e32 v48, v135, v48
	v_exp_f32_e32 v139, v50
	v_sub_f32_e32 v50, v58, v51
	v_add_f32_e32 v48, v136, v48
	v_exp_f32_e32 v140, v50
	v_sub_f32_e32 v50, v59, v51
	v_add_f32_e32 v48, v137, v48
	v_exp_f32_e32 v141, v50
	v_sub_f32_e32 v50, v60, v51
	v_add_f32_e32 v48, v138, v48
	v_exp_f32_e32 v142, v50
	v_sub_f32_e32 v50, v61, v51
	v_add_f32_e32 v48, v139, v48
	v_exp_f32_e32 v143, v50
	v_sub_f32_e32 v50, v62, v51
	v_add_f32_e32 v48, v140, v48
	v_exp_f32_e32 v144, v50
	v_sub_f32_e32 v50, v63, v51
	v_add_f32_e32 v48, v141, v48
	v_exp_f32_e32 v145, v50
	v_sub_f32_e32 v50, v146, v51
	v_add_f32_e32 v48, v142, v48
	v_exp_f32_e32 v146, v50
	v_sub_f32_e32 v50, v147, v51
	v_add_f32_e32 v48, v143, v48
	v_exp_f32_e32 v147, v50
	v_add_f32_e32 v48, v144, v48
	v_add_f32_e32 v48, v145, v48
	v_add_f32_e32 v48, v146, v48
	v_add_f32_e32 v148, v147, v48
	v_cmp_neq_f32_e32 vcc, v131, v130
	v_mov_b32_e32 v149, v148
	v_mov_b32_e32 v150, v148
	s_cmp_lg_u64 vcc, 0
	s_nop 0
	v_permlane32_swap_b32_e32 v149, v150
	s_cselect_b64 s[0:1], -1, 0
	s_cbranch_execz .LBB0_760
	s_branch .LBB0_761

; #define LAS __attribute__((address_space(3)))
; #define MFMA32(a, b, c) __builtin_amdgcn_mfma_f32_32x32x16_bf16((a), (b), (c), 0, 0, 0)
; DI s16x4 vtr(LAS const char* p) { return __builtin_bit_cast(s16x4, __builtin_amdgcn_ds_read_tr16_b64_v4i16((LAS v4i16_t*)p)); }
; DI void pv_rows(f32x16 (&o)[2], LAS const char* Vl, int row0, const bf16x8 (&pf)[2], int lane) {
;     const int h = lane >> 5, i = lane & 15, grp = (lane >> 4) & 1;
;     LAS const char* base = Vl + (row0 + 4 * h + (i >> 2)) * KP + grp * 32 + (i & 3) * 8;
;     bf16x8 vf[2][2];
; #pragma unroll
;     for (int dt = 0; dt < 2; ++dt)
; #pragma unroll
;         for (int s2 = 0; s2 < 2; ++s2) {
;             const s16x4 lo = vtr(base + (16 * s2) * KP + dt * 64), hi = vtr(base + (16 * s2 + 8) * KP + dt * 64);
;             vf[dt][s2] = (bf16x8){lo[0], lo[1], lo[2], lo[3], hi[0], hi[1], hi[2], hi[3]};
;         }
;     __builtin_amdgcn_s_setprio(1);
; #pragma unroll
;     for (int s2 = 0; s2 < 2; ++s2)
; #pragma unroll
;         for (int dt = 0; dt < 2; ++dt) o[dt] = MFMA32(vf[dt][s2], pf[s2], o[dt]);
;     __builtin_amdgcn_s_setprio(0);
; }
; template <int MM> DI void smax_step(const f32x16& s, unsigned vm, float& m, float& l, f32x16 (&o)[2], bf16x8 (&pf)[2], int lane) {
;     ...
;     l += rs;
;     pack_p(p, pf);
.LBB0_766:
	v_cndmask_b32_e64 v131, v149, v150, s[36:37]
	v_add_u32_e32 v128, v128, v191
	v_add_f32_e32 v131, v148, v131
	v_cvt_pk_bf16_f32 v132, v132, v133
	v_cvt_pk_bf16_f32 v133, v134, v135
	v_cvt_pk_bf16_f32 v134, v136, v137
	v_cvt_pk_bf16_f32 v135, v138, v139
	v_cvt_pk_bf16_f32 v136, v140, v141
	v_cvt_pk_bf16_f32 v137, v142, v143
	v_cvt_pk_bf16_f32 v138, v144, v145
	v_cvt_pk_bf16_f32 v139, v146, v147
	ds_read_b64_tr_b16 v[140:141], v128 offset:13824
	ds_read_b64_tr_b16 v[142:143], v128 offset:14976
	ds_read_b64_tr_b16 v[144:145], v128 offset:16128
	ds_read_b64_tr_b16 v[146:147], v128 offset:17280
	ds_read_b64_tr_b16 v[148:149], v128 offset:13888
	ds_read_b64_tr_b16 v[150:151], v128 offset:15040
	ds_read_b64_tr_b16 v[152:153], v128 offset:16192
	ds_read_b64_tr_b16 v[154:155], v128 offset:17344
	v_add_f32_e32 v129, v129, v131
	s_nop 0
	s_waitcnt lgkmcnt(6)
	v_mfma_f32_32x32x16_bf16 v[32:47], v[140:143], v[132:135], v[32:47]
	s_mov_b64 s[0:1], -1
	s_waitcnt lgkmcnt(2)
	v_mfma_f32_32x32x16_bf16 v[48:63], v[148:151], v[132:135], v[48:63]
	v_mfma_f32_32x32x16_bf16 v[32:47], v[144:147], v[136:139], v[32:47]
	s_waitcnt lgkmcnt(0)
	v_mfma_f32_32x32x16_bf16 v[48:63], v[152:155], v[136:139], v[48:63]
	s_and_b64 vcc, exec, s[48:49]
	s_cbranch_vccz .LBB0_749
	s_branch .LBB0_711

; DI float ex2(float x) { return __builtin_amdgcn_exp2f(x); }
; template <int MM> DI void smax_step(const f32x16& s, unsigned vm, float& m, float& l, f32x16 (&o)[2], bf16x8 (&pf)[2], int lane) {
;     float t[16], mx = -1e30f;
; #pragma unroll
;     for (int i = 0; i < 16; ++i) { t[i] = (MM == 0) ? s[i] : (MM == 1 ? (vm ? s[i] : -1e30f) : (((vm >> i) & 1u) ? s[i] : -1e30f)); mx = fmaxf(mx, t[i]); }
;     mx = fmaxf(mx, shx32(mx, lane));
;     const float mn = (mx > m + 8.0f) ? mx : m;
;     const float mref = fmaxf(mn, -1e29f);
;     float p[16], rs = 0.f;
; #pragma unroll
;     for (int i = 0; i < 16; ++i) { p[i] = ex2(t[i] - mref); rs += p[i]; }
;     rs += shx32(rs, lane);
;     if (__builtin_amdgcn_ballot_w64(mn != m) != 0ull) {
;         const float alpha = ex2(m - mn);
;         l *= alpha;
; #pragma unroll
;         for (int i = 0; i < 16; ++i) { o[0][i] *= alpha; o[1][i] *= alpha; }
;         m = mn;
;     }
;     l += rs;
;     pack_p(p, pf);
; }
; template <int MODE, bool PRE = false> ...
;     ...
;                 for (int i = 0; i < 16; ++i) { const int kidx = kbase + (i & 3) + 8 * (i >> 2) + 4 * h; bool ok = kidx <= qpos; if (MODE == MODE_NWIN) ok = ok && (kidx > qpos - 512); vm |= ok ? (1u << i) : 0u; }
;                 if (!lsel) vm = 0;
;                 if (__builtin_amdgcn_ballot_w64(vm != 0) == 0ull) continue; }
;             bf16x8 pf[2];
;             if (MODE == MODE_DIFF) {
;                 const f32x16 s1 = qk_rows<0, 2>(Kl, 32 * sub, qf, r, h), s2 = qk_rows<2, 4>(Kl, 32 * sub, qf, r, h);
;                 bf16x8 pf2[2];
;                 if (mm == 0) { smax_step<0>(s1, vm, m1, l1, o1, pf, lane); smax_step<0>(s2, vm, m2, l2, o2, pf2, lane); }
;                 else { smax_step<2>(s1, vm, m1, l1, o1, pf, lane); smax_step<2>(s2, vm, m2, l2, o2, pf2, lane); }
;                 pv_rows(o1, Vl, 32 * sub, pf, lane);
;                 pv_rows(o2, Vl, 32 * sub, pf2, lane);
.LBB0_791:
	s_andn2_b64 vcc, exec, s[38:39]
	s_cbranch_vccnz .LBB0_804
	v_add_u32_e32 v33, v227, v221
	ds_read_b128 v[34:37], v33
	ds_read_b128 v[38:41], v33 offset:32
	ds_read_b128 v[52:55], v33 offset:64
	ds_read_b128 v[56:59], v33 offset:96
	s_nop 0
	s_waitcnt lgkmcnt(3)
	v_mfma_f32_32x32x16_bf16 v[112:127], v[34:37], v[152:155], 0
	s_waitcnt lgkmcnt(2)
	v_mfma_f32_32x32x16_bf16 v[112:127], v[38:41], v[156:159], v[112:127]
	s_waitcnt lgkmcnt(1)
	v_mfma_f32_32x32x16_bf16 v[96:111], v[52:55], v[160:163], 0
	s_waitcnt lgkmcnt(0)
	v_mfma_f32_32x32x16_bf16 v[96:111], v[56:59], v[164:167], v[96:111]
	s_nop 0
	v_add_u32_e32 v51, v225, v222
	ds_read_b64_tr_b16 v[52:53], v51 offset:9216
	ds_read_b64_tr_b16 v[54:55], v51 offset:10368
	ds_read_b64_tr_b16 v[56:57], v51 offset:9280
	ds_read_b64_tr_b16 v[58:59], v51 offset:10432
	ds_read_b64_tr_b16 v[60:61], v51 offset:11520
	ds_read_b64_tr_b16 v[62:63], v51 offset:12672
	s_andn2_b64 vcc, exec, s[0:1]
	v_add_f32_e32 v229, 0x41000000, v226
	s_cbranch_vccz .LBB0_796
	v_and_b32_e32 v33, 1, v32
	v_and_b32_e32 v34, 2, v32
	v_cmp_eq_u32_e64 s[0:1], 0, v33
	v_cmp_eq_u32_e64 s[38:39], 0, v34
	v_and_b32_e32 v36, 4, v32
	v_and_b32_e32 v37, 8, v32
	v_cndmask_b32_e64 v33, v112, v208, s[0:1]
	v_cndmask_b32_e64 v34, v113, v208, s[38:39]
	v_cmp_eq_u32_e64 s[40:41], 0, v36
	v_cmp_eq_u32_e64 s[42:43], 0, v37
	v_and_b32_e32 v38, 16, v32
	v_and_b32_e32 v39, 32, v32
	v_max3_f32 v35, v33, s15, v34
	v_cndmask_b32_e64 v36, v114, v208, s[40:41]
	v_cndmask_b32_e64 v37, v115, v208, s[42:43]
	v_cmp_eq_u32_e64 s[44:45], 0, v38
	v_cmp_eq_u32_e64 s[48:49], 0, v39
	v_and_b32_e32 v40, 64, v32
	v_and_b32_e32 v41, 0x80, v32
	v_max3_f32 v35, v35, v36, v37
	v_cndmask_b32_e64 v38, v116, v208, s[44:45]
	v_cndmask_b32_e64 v39, v117, v208, s[48:49]
	v_cmp_eq_u32_e64 s[50:51], 0, v40
	v_cmp_eq_u32_e64 s[52:53], 0, v41
	v_and_b32_e32 v42, 0x100, v32
	v_and_b32_e32 v43, 0x200, v32
	v_max3_f32 v35, v35, v38, v39
	v_cndmask_b32_e64 v40, v118, v208, s[50:51]
	v_cndmask_b32_e64 v41, v119, v208, s[52:53]
	v_cmp_eq_u32_e64 s[54:55], 0, v42
	v_cmp_eq_u32_e64 s[56:57], 0, v43
	v_and_b32_e32 v44, 0x400, v32
	v_and_b32_e32 v45, 0x800, v32
	v_max3_f32 v35, v35, v40, v41
	v_cndmask_b32_e64 v42, v120, v208, s[54:55]
	v_cndmask_b32_e64 v43, v121, v208, s[56:57]
	v_cmp_eq_u32_e64 s[58:59], 0, v44
	v_cmp_eq_u32_e64 s[60:61], 0, v45
	v_and_b32_e32 v46, 0x1000, v32
	v_and_b32_e32 v47, 0x2000, v32
	v_max3_f32 v35, v35, v42, v43
	v_cndmask_b32_e64 v44, v122, v208, s[58:59]
	v_cndmask_b32_e64 v45, v123, v208, s[60:61]
	v_cmp_eq_u32_e64 s[62:63], 0, v46
	v_cmp_eq_u32_e64 s[64:65], 0, v47
	v_and_b32_e32 v48, 0x4000, v32
	v_and_b32_e32 v32, 0x8000, v32
	v_max3_f32 v35, v35, v44, v45
	v_cndmask_b32_e64 v46, v124, v208, s[62:63]
	v_cndmask_b32_e64 v47, v125, v208, s[64:65]
	v_cmp_eq_u32_e64 s[66:67], 0, v48
	v_cmp_eq_u32_e64 s[68:69], 0, v32
	v_max3_f32 v35, v35, v46, v47
	v_cndmask_b32_e64 v48, v126, v208, s[66:67]
	v_cndmask_b32_e64 v32, v127, v208, s[68:69]
	v_max3_f32 v35, v35, v48, v32
	v_mov_b32_e32 v49, v35
	v_mov_b32_e32 v50, v35
	s_nop 1
	v_permlane32_swap_b32_e32 v49, v50
	v_max_f32_e32 v35, v49, v50
	v_cmp_gt_f32_e32 vcc, v35, v229
	v_mov_b32_e32 v228, v226
	v_mov_b32_e32 v192, v186
	v_cndmask_b32_e32 v130, v226, v35, vcc
	v_max_f32_e32 v35, 0xefa18f08, v130
	v_sub_f32_e32 v33, v33, v35
	v_exp_f32_e32 v128, v33
	v_sub_f32_e32 v33, v34, v35
	v_exp_f32_e32 v129, v33
	v_sub_f32_e32 v33, v36, v35
	v_exp_f32_e32 v131, v33
	v_sub_f32_e32 v33, v37, v35
	v_exp_f32_e32 v132, v33
	v_sub_f32_e32 v34, v38, v35
	v_exp_f32_e32 v133, v34
	v_sub_f32_e32 v34, v39, v35
	v_add_f32_e32 v33, v129, v128
	v_exp_f32_e32 v134, v34
	v_sub_f32_e32 v34, v40, v35
	v_add_f32_e32 v33, v131, v33
	v_exp_f32_e32 v135, v34
	v_sub_f32_e32 v34, v41, v35
	v_add_f32_e32 v33, v132, v33
	v_exp_f32_e32 v187, v34
	v_sub_f32_e32 v34, v42, v35
	v_add_f32_e32 v33, v133, v33
	v_exp_f32_e32 v189, v34
	v_sub_f32_e32 v34, v43, v35
	v_add_f32_e32 v33, v134, v33
	v_exp_f32_e32 v190, v34
	v_sub_f32_e32 v34, v44, v35
	v_add_f32_e32 v33, v135, v33
	v_exp_f32_e32 v191, v34
	v_sub_f32_e32 v34, v45, v35
	v_add_f32_e32 v33, v187, v33
	v_exp_f32_e32 v193, v34
	v_sub_f32_e32 v34, v46, v35
	v_add_f32_e32 v33, v189, v33
	v_exp_f32_e32 v230, v34
	v_sub_f32_e32 v34, v47, v35
	v_add_f32_e32 v33, v190, v33
	v_exp_f32_e32 v231, v34
	v_sub_f32_e32 v34, v48, v35
	v_add_f32_e32 v33, v191, v33
	v_exp_f32_e32 v232, v34
	v_sub_f32_e32 v32, v32, v35
	v_add_f32_e32 v33, v193, v33
	v_exp_f32_e32 v233, v32
	v_add_f32_e32 v32, v230, v33
	v_add_f32_e32 v32, v231, v32
	v_add_f32_e32 v32, v232, v32
	v_add_f32_e32 v188, v233, v32
	v_mov_b32_e32 v234, v188
	v_mov_b32_e32 v235, v188
	s_nop 0
	s_nop 0
	v_permlane32_swap_b32_e32 v234, v235
	v_cmp_neq_f32_e32 vcc, v130, v226
	s_cbranch_vccz .LBB0_795
	v_sub_f32_e32 v32, v226, v130
	v_exp_f32_e32 v32, v32
	v_mov_b32_e32 v228, v130
	v_mul_f32_e32 v192, v186, v32
	v_pk_mul_f32 v[30:31], v[30:31], v[32:33] op_sel_hi:[1,0]
	v_pk_mul_f32 v[28:29], v[28:29], v[32:33] op_sel_hi:[1,0]
	v_pk_mul_f32 v[26:27], v[26:27], v[32:33] op_sel_hi:[1,0]
	v_pk_mul_f32 v[24:25], v[24:25], v[32:33] op_sel_hi:[1,0]
	v_pk_mul_f32 v[22:23], v[22:23], v[32:33] op_sel_hi:[1,0]
	v_pk_mul_f32 v[20:21], v[20:21], v[32:33] op_sel_hi:[1,0]
	v_pk_mul_f32 v[18:19], v[18:19], v[32:33] op_sel_hi:[1,0]
	v_pk_mul_f32 v[16:17], v[16:17], v[32:33] op_sel_hi:[1,0]
	v_pk_mul_f32 v[14:15], v[14:15], v[32:33] op_sel_hi:[1,0]
	v_pk_mul_f32 v[12:13], v[12:13], v[32:33] op_sel_hi:[1,0]
	v_pk_mul_f32 v[10:11], v[10:11], v[32:33] op_sel_hi:[1,0]
	v_pk_mul_f32 v[8:9], v[8:9], v[32:33] op_sel_hi:[1,0]
	v_pk_mul_f32 v[6:7], v[6:7], v[32:33] op_sel_hi:[1,0]
	v_pk_mul_f32 v[4:5], v[4:5], v[32:33] op_sel_hi:[1,0]
	v_pk_mul_f32 v[2:3], v[2:3], v[32:33] op_sel_hi:[1,0]
	v_pk_mul_f32 v[0:1], v[0:1], v[32:33] op_sel_hi:[1,0]

; #define LAS __attribute__((address_space(3)))
; #define MFMA32(a, b, c) __builtin_amdgcn_mfma_f32_32x32x16_bf16((a), (b), (c), 0, 0, 0)
; DI s16x4 vtr(LAS const char* p) { return __builtin_bit_cast(s16x4, __builtin_amdgcn_ds_read_tr16_b64_v4i16((LAS v4i16_t*)p)); }
; DI void pv_rows(f32x16 (&o)[2], LAS const char* Vl, int row0, const bf16x8 (&pf)[2], int lane) {
;     const int h = lane >> 5, i = lane & 15, grp = (lane >> 4) & 1;
;     LAS const char* base = Vl + (row0 + 4 * h + (i >> 2)) * KP + grp * 32 + (i & 3) * 8;
;     bf16x8 vf[2][2];
; #pragma unroll
;     for (int dt = 0; dt < 2; ++dt)
; #pragma unroll
;         for (int s2 = 0; s2 < 2; ++s2) {
;             const s16x4 lo = vtr(base + (16 * s2) * KP + dt * 64), hi = vtr(base + (16 * s2 + 8) * KP + dt * 64);
;             vf[dt][s2] = (bf16x8){lo[0], lo[1], lo[2], lo[3], hi[0], hi[1], hi[2], hi[3]};
;         }
;     __builtin_amdgcn_s_setprio(1);
; #pragma unroll
;     for (int s2 = 0; s2 < 2; ++s2)
; #pragma unroll
;         for (int dt = 0; dt < 2; ++dt) o[dt] = MFMA32(vf[dt][s2], pf[s2], o[dt]);
;     __builtin_amdgcn_s_setprio(0);
; }
; template <int MODE, bool PRE = false> ...
;     ...
;             if (MODE == MODE_DIFF) {
;                 const f32x16 s1 = qk_rows<0, 2>(Kl, 32 * sub, qf, r, h), s2 = qk_rows<2, 4>(Kl, 32 * sub, qf, r, h);
;                 bf16x8 pf2[2];
;                 if (mm == 0) { smax_step<0>(s1, vm, m1, l1, o1, pf, lane); smax_step<0>(s2, vm, m2, l2, o2, pf2, lane); }
;                 else { smax_step<2>(s1, vm, m1, l1, o1, pf, lane); smax_step<2>(s2, vm, m2, l2, o2, pf2, lane); }
;                 pv_rows(o1, Vl, 32 * sub, pf, lane);
;                 pv_rows(o2, Vl, 32 * sub, pf2, lane);
.LBB0_803:
	ds_read_b64_tr_b16 v[44:45], v51 offset:11584
	ds_read_b64_tr_b16 v[46:47], v51 offset:12736
	v_cndmask_b32_e64 v32, v188, v192, s[36:37]
	v_add_f32_e32 v32, v191, v32
	v_add_f32_e32 v217, v217, v32
	v_cvt_pk_bf16_f32 v32, v231, v232
	v_cvt_pk_bf16_f32 v33, v233, v234
	v_cvt_pk_bf16_f32 v34, v235, v236
	v_cvt_pk_bf16_f32 v35, v237, v238
	v_cvt_pk_bf16_f32 v36, v239, v240
	v_cvt_pk_bf16_f32 v37, v241, v242
	v_cvt_pk_bf16_f32 v38, v243, v244
	v_cvt_pk_bf16_f32 v39, v189, v187
	s_nop 0
	s_waitcnt lgkmcnt(2)
	v_mfma_f32_32x32x16_bf16 v[0:15], v[52:55], v[128:131], v[0:15]
	v_mfma_f32_32x32x16_bf16 v[16:31], v[56:59], v[128:131], v[16:31]
	v_mfma_f32_32x32x16_bf16 v[0:15], v[60:63], v[132:135], v[0:15]
	s_waitcnt lgkmcnt(0)
	v_mfma_f32_32x32x16_bf16 v[16:31], v[44:47], v[132:135], v[16:31]
	v_mfma_f32_32x32x16_bf16 v[64:79], v[52:55], v[32:35], v[64:79]
	v_mfma_f32_32x32x16_bf16 v[80:95], v[56:59], v[32:35], v[80:95]
	v_mfma_f32_32x32x16_bf16 v[64:79], v[60:63], v[36:39], v[64:79]
	v_mfma_f32_32x32x16_bf16 v[80:95], v[44:47], v[36:39], v[80:95]
	s_nop 0
	v_mov_b32_e32 v186, v190
	v_mov_b32_e32 v226, v228

; DI float ex2(float x) { return __builtin_amdgcn_exp2f(x); }
; template <int MM> DI void smax_step(const f32x16& s, unsigned vm, float& m, float& l, f32x16 (&o)[2], bf16x8 (&pf)[2], int lane) {
;     float t[16], mx = -1e30f;
; #pragma unroll
;     for (int i = 0; i < 16; ++i) { t[i] = (MM == 0) ? s[i] : (MM == 1 ? (vm ? s[i] : -1e30f) : (((vm >> i) & 1u) ? s[i] : -1e30f)); mx = fmaxf(mx, t[i]); }
;     mx = fmaxf(mx, shx32(mx, lane));
;     const float mn = (mx > m + 8.0f) ? mx : m;
;     const float mref = fmaxf(mn, -1e29f);
;     float p[16], rs = 0.f;
; #pragma unroll
;     for (int i = 0; i < 16; ++i) { p[i] = ex2(t[i] - mref); rs += p[i]; }
;     rs += shx32(rs, lane);
;     if (__builtin_amdgcn_ballot_w64(mn != m) != 0ull) {
;         const float alpha = ex2(m - mn);
;         l *= alpha;
; #pragma unroll
;         for (int i = 0; i < 16; ++i) { o[0][i] *= alpha; o[1][i] *= alpha; }
;         m = mn;
;     }
;     l += rs;
;     pack_p(p, pf);
; }
; template <int MODE, bool PRE = false> ...
;     ...
;                 for (int i = 0; i < 16; ++i) { const int kidx = kbase + (i & 3) + 8 * (i >> 2) + 4 * h; bool ok = kidx <= qpos; if (MODE == MODE_NWIN) ok = ok && (kidx > qpos - 512); vm |= ok ? (1u << i) : 0u; }
;                 if (!lsel) vm = 0;
;                 if (__builtin_amdgcn_ballot_w64(vm != 0) == 0ull) continue; }
;             bf16x8 pf[2];
;             if (MODE == MODE_DIFF) {
;                 const f32x16 s1 = qk_rows<0, 2>(Kl, 32 * sub, qf, r, h), s2 = qk_rows<2, 4>(Kl, 32 * sub, qf, r, h);
;                 bf16x8 pf2[2];
;                 if (mm == 0) { smax_step<0>(s1, vm, m1, l1, o1, pf, lane); smax_step<0>(s2, vm, m2, l2, o2, pf2, lane); }
;                 else { smax_step<2>(s1, vm, m1, l1, o1, pf, lane); smax_step<2>(s2, vm, m2, l2, o2, pf2, lane); }
;                 pv_rows(o1, Vl, 32 * sub, pf, lane);
;                 pv_rows(o2, Vl, 32 * sub, pf2, lane);
.LBB0_810:
	s_andn2_b64 vcc, exec, s[38:39]
	s_cbranch_vccnz .LBB0_823
	v_add_u32_e32 v33, v227, v223
	ds_read_b128 v[34:37], v33
	ds_read_b128 v[38:41], v33 offset:32
	ds_read_b128 v[52:55], v33 offset:64
	ds_read_b128 v[56:59], v33 offset:96
	s_nop 0
	s_waitcnt lgkmcnt(3)
	v_mfma_f32_32x32x16_bf16 v[112:127], v[34:37], v[152:155], 0
	s_waitcnt lgkmcnt(2)
	v_mfma_f32_32x32x16_bf16 v[112:127], v[38:41], v[156:159], v[112:127]
	s_waitcnt lgkmcnt(1)
	v_mfma_f32_32x32x16_bf16 v[96:111], v[52:55], v[160:163], 0
	s_waitcnt lgkmcnt(0)
	v_mfma_f32_32x32x16_bf16 v[96:111], v[56:59], v[164:167], v[96:111]
	s_nop 0
	v_add_u32_e32 v51, v225, v222
	ds_read_b64_tr_b16 v[52:53], v51 offset:13824
	ds_read_b64_tr_b16 v[54:55], v51 offset:14976
	ds_read_b64_tr_b16 v[56:57], v51 offset:13888
	ds_read_b64_tr_b16 v[58:59], v51 offset:15040
	ds_read_b64_tr_b16 v[60:61], v51 offset:16128
	ds_read_b64_tr_b16 v[62:63], v51 offset:17280
	s_and_b64 vcc, exec, s[0:1]
	v_add_f32_e32 v187, 0x41000000, v226
	s_cbranch_vccnz .LBB0_815
	v_and_b32_e32 v33, 1, v32
	v_and_b32_e32 v34, 2, v32
	v_cmp_eq_u32_e64 s[0:1], 0, v33
	v_cmp_eq_u32_e64 s[38:39], 0, v34
	v_and_b32_e32 v36, 4, v32
	v_and_b32_e32 v37, 8, v32
	v_cndmask_b32_e64 v33, v112, v208, s[0:1]
	v_cndmask_b32_e64 v34, v113, v208, s[38:39]
	v_cmp_eq_u32_e64 s[40:41], 0, v36
	v_cmp_eq_u32_e64 s[42:43], 0, v37
	v_and_b32_e32 v38, 16, v32
	v_and_b32_e32 v39, 32, v32
	v_max3_f32 v35, v33, s15, v34
	v_cndmask_b32_e64 v36, v114, v208, s[40:41]
	v_cndmask_b32_e64 v37, v115, v208, s[42:43]
	v_cmp_eq_u32_e64 s[44:45], 0, v38
	v_cmp_eq_u32_e64 s[48:49], 0, v39
	v_and_b32_e32 v40, 64, v32
	v_and_b32_e32 v41, 0x80, v32
	v_max3_f32 v35, v35, v36, v37
	v_cndmask_b32_e64 v38, v116, v208, s[44:45]
	v_cndmask_b32_e64 v39, v117, v208, s[48:49]
	v_cmp_eq_u32_e64 s[50:51], 0, v40
	v_cmp_eq_u32_e64 s[52:53], 0, v41
	v_and_b32_e32 v42, 0x100, v32
	v_and_b32_e32 v43, 0x200, v32
	v_max3_f32 v35, v35, v38, v39
	v_cndmask_b32_e64 v40, v118, v208, s[50:51]
	v_cndmask_b32_e64 v41, v119, v208, s[52:53]
	v_cmp_eq_u32_e64 s[54:55], 0, v42
	v_cmp_eq_u32_e64 s[56:57], 0, v43
	v_and_b32_e32 v44, 0x400, v32
	v_and_b32_e32 v45, 0x800, v32
	v_max3_f32 v35, v35, v40, v41
	v_cndmask_b32_e64 v42, v120, v208, s[54:55]
	v_cndmask_b32_e64 v43, v121, v208, s[56:57]
	v_cmp_eq_u32_e64 s[58:59], 0, v44
	v_cmp_eq_u32_e64 s[60:61], 0, v45
	v_and_b32_e32 v46, 0x1000, v32
	v_and_b32_e32 v47, 0x2000, v32
	v_max3_f32 v35, v35, v42, v43
	v_cndmask_b32_e64 v44, v122, v208, s[58:59]
	v_cndmask_b32_e64 v45, v123, v208, s[60:61]
	v_cmp_eq_u32_e64 s[62:63], 0, v46
	v_cmp_eq_u32_e64 s[64:65], 0, v47
	v_and_b32_e32 v48, 0x4000, v32
	v_and_b32_e32 v32, 0x8000, v32
	v_max3_f32 v35, v35, v44, v45
	v_cndmask_b32_e64 v46, v124, v208, s[62:63]
	v_cndmask_b32_e64 v47, v125, v208, s[64:65]
	v_cmp_eq_u32_e64 s[66:67], 0, v48
	v_cmp_eq_u32_e64 s[68:69], 0, v32
	v_max3_f32 v35, v35, v46, v47
	v_cndmask_b32_e64 v48, v126, v208, s[66:67]
	v_cndmask_b32_e64 v32, v127, v208, s[68:69]
	v_max3_f32 v35, v35, v48, v32
	v_mov_b32_e32 v49, v35
	v_mov_b32_e32 v50, v35
	s_nop 1
	v_permlane32_swap_b32_e32 v49, v50
	v_max_f32_e32 v35, v49, v50
	v_cmp_gt_f32_e32 vcc, v35, v187
	v_mov_b32_e32 v227, v226
	v_mov_b32_e32 v192, v186
	v_cndmask_b32_e32 v130, v226, v35, vcc
	v_max_f32_e32 v35, 0xefa18f08, v130
	v_sub_f32_e32 v33, v33, v35
	v_exp_f32_e32 v128, v33
	v_sub_f32_e32 v33, v34, v35
	v_exp_f32_e32 v129, v33
	v_sub_f32_e32 v33, v36, v35
	v_exp_f32_e32 v131, v33
	v_sub_f32_e32 v33, v37, v35
	v_exp_f32_e32 v132, v33
	v_sub_f32_e32 v34, v38, v35
	v_exp_f32_e32 v133, v34
	v_sub_f32_e32 v34, v39, v35
	v_add_f32_e32 v33, v129, v128
	v_exp_f32_e32 v134, v34
	v_sub_f32_e32 v34, v40, v35
	v_add_f32_e32 v33, v131, v33
	v_exp_f32_e32 v135, v34
	v_sub_f32_e32 v34, v41, v35
	v_add_f32_e32 v33, v132, v33
	v_exp_f32_e32 v189, v34
	v_sub_f32_e32 v34, v42, v35
	v_add_f32_e32 v33, v133, v33
	v_exp_f32_e32 v190, v34
	v_sub_f32_e32 v34, v43, v35
	v_add_f32_e32 v33, v134, v33
	v_exp_f32_e32 v191, v34
	v_sub_f32_e32 v34, v44, v35
	v_add_f32_e32 v33, v135, v33
	v_exp_f32_e32 v193, v34
	v_sub_f32_e32 v34, v45, v35
	v_add_f32_e32 v33, v189, v33
	v_exp_f32_e32 v228, v34
	v_sub_f32_e32 v34, v46, v35
	v_add_f32_e32 v33, v190, v33
	v_exp_f32_e32 v229, v34
	v_sub_f32_e32 v34, v47, v35
	v_add_f32_e32 v33, v191, v33
	v_exp_f32_e32 v230, v34
	v_sub_f32_e32 v34, v48, v35
	v_add_f32_e32 v33, v193, v33
	v_exp_f32_e32 v231, v34
	v_sub_f32_e32 v32, v32, v35
	v_add_f32_e32 v33, v228, v33
	v_exp_f32_e32 v232, v32
	v_add_f32_e32 v32, v229, v33
	v_add_f32_e32 v32, v230, v32
	v_add_f32_e32 v32, v231, v32
	v_add_f32_e32 v188, v232, v32
	v_mov_b32_e32 v233, v188
	v_mov_b32_e32 v234, v188
	s_nop 0
	s_nop 0
	v_permlane32_swap_b32_e32 v233, v234
	v_cmp_neq_f32_e32 vcc, v130, v226
	s_cbranch_vccz .LBB0_814
	v_sub_f32_e32 v32, v226, v130
	v_exp_f32_e32 v32, v32
	v_mov_b32_e32 v227, v130
	v_mul_f32_e32 v192, v186, v32
	v_pk_mul_f32 v[30:31], v[30:31], v[32:33] op_sel_hi:[1,0]
	v_pk_mul_f32 v[28:29], v[28:29], v[32:33] op_sel_hi:[1,0]
	v_pk_mul_f32 v[26:27], v[26:27], v[32:33] op_sel_hi:[1,0]
	v_pk_mul_f32 v[24:25], v[24:25], v[32:33] op_sel_hi:[1,0]
	v_pk_mul_f32 v[22:23], v[22:23], v[32:33] op_sel_hi:[1,0]
	v_pk_mul_f32 v[20:21], v[20:21], v[32:33] op_sel_hi:[1,0]
	v_pk_mul_f32 v[18:19], v[18:19], v[32:33] op_sel_hi:[1,0]
	v_pk_mul_f32 v[16:17], v[16:17], v[32:33] op_sel_hi:[1,0]
	v_pk_mul_f32 v[14:15], v[14:15], v[32:33] op_sel_hi:[1,0]
	v_pk_mul_f32 v[12:13], v[12:13], v[32:33] op_sel_hi:[1,0]
	v_pk_mul_f32 v[10:11], v[10:11], v[32:33] op_sel_hi:[1,0]
	v_pk_mul_f32 v[8:9], v[8:9], v[32:33] op_sel_hi:[1,0]
	v_pk_mul_f32 v[6:7], v[6:7], v[32:33] op_sel_hi:[1,0]
	v_pk_mul_f32 v[4:5], v[4:5], v[32:33] op_sel_hi:[1,0]
	v_pk_mul_f32 v[2:3], v[2:3], v[32:33] op_sel_hi:[1,0]
	v_pk_mul_f32 v[0:1], v[0:1], v[32:33] op_sel_hi:[1,0]

; #define LAS __attribute__((address_space(3)))
; #define MFMA32(a, b, c) __builtin_amdgcn_mfma_f32_32x32x16_bf16((a), (b), (c), 0, 0, 0)
; DI s16x4 vtr(LAS const char* p) { return __builtin_bit_cast(s16x4, __builtin_amdgcn_ds_read_tr16_b64_v4i16((LAS v4i16_t*)p)); }
; DI void pv_rows(f32x16 (&o)[2], LAS const char* Vl, int row0, const bf16x8 (&pf)[2], int lane) {
;     const int h = lane >> 5, i = lane & 15, grp = (lane >> 4) & 1;
;     LAS const char* base = Vl + (row0 + 4 * h + (i >> 2)) * KP + grp * 32 + (i & 3) * 8;
;     bf16x8 vf[2][2];
; #pragma unroll
;     for (int dt = 0; dt < 2; ++dt)
; #pragma unroll
;         for (int s2 = 0; s2 < 2; ++s2) {
;             const s16x4 lo = vtr(base + (16 * s2) * KP + dt * 64), hi = vtr(base + (16 * s2 + 8) * KP + dt * 64);
;             vf[dt][s2] = (bf16x8){lo[0], lo[1], lo[2], lo[3], hi[0], hi[1], hi[2], hi[3]};
;         }
;     __builtin_amdgcn_s_setprio(1);
; #pragma unroll
;     for (int s2 = 0; s2 < 2; ++s2)
; #pragma unroll
;         for (int dt = 0; dt < 2; ++dt) o[dt] = MFMA32(vf[dt][s2], pf[s2], o[dt]);
;     __builtin_amdgcn_s_setprio(0);
; }
; template <int MODE, bool PRE = false> ...
;     ...
;             if (MODE == MODE_DIFF) {
;                 const f32x16 s1 = qk_rows<0, 2>(Kl, 32 * sub, qf, r, h), s2 = qk_rows<2, 4>(Kl, 32 * sub, qf, r, h);
;                 bf16x8 pf2[2];
;                 if (mm == 0) { smax_step<0>(s1, vm, m1, l1, o1, pf, lane); smax_step<0>(s2, vm, m2, l2, o2, pf2, lane); }
;                 else { smax_step<2>(s1, vm, m1, l1, o1, pf, lane); smax_step<2>(s2, vm, m2, l2, o2, pf2, lane); }
;                 pv_rows(o1, Vl, 32 * sub, pf, lane);
;                 pv_rows(o2, Vl, 32 * sub, pf2, lane);
.LBB0_822:
	ds_read_b64_tr_b16 v[44:45], v51 offset:16192
	ds_read_b64_tr_b16 v[46:47], v51 offset:17344
	v_cndmask_b32_e64 v32, v188, v192, s[36:37]
	v_add_f32_e32 v32, v191, v32
	v_add_f32_e32 v217, v217, v32
	v_cvt_pk_bf16_f32 v32, v229, v230
	v_cvt_pk_bf16_f32 v33, v231, v232
	v_cvt_pk_bf16_f32 v34, v233, v234
	v_cvt_pk_bf16_f32 v35, v235, v236
	v_cvt_pk_bf16_f32 v36, v237, v238
	v_cvt_pk_bf16_f32 v37, v239, v240
	v_cvt_pk_bf16_f32 v38, v241, v242
	v_cvt_pk_bf16_f32 v39, v189, v193
	s_nop 0
	s_waitcnt lgkmcnt(2)
	v_mfma_f32_32x32x16_bf16 v[0:15], v[52:55], v[128:131], v[0:15]
	v_mfma_f32_32x32x16_bf16 v[16:31], v[56:59], v[128:131], v[16:31]
	v_mfma_f32_32x32x16_bf16 v[0:15], v[60:63], v[132:135], v[0:15]
	s_waitcnt lgkmcnt(0)
	v_mfma_f32_32x32x16_bf16 v[16:31], v[44:47], v[132:135], v[16:31]
	v_mfma_f32_32x32x16_bf16 v[64:79], v[52:55], v[32:35], v[64:79]
	v_mfma_f32_32x32x16_bf16 v[80:95], v[56:59], v[32:35], v[80:95]
	v_mfma_f32_32x32x16_bf16 v[64:79], v[60:63], v[36:39], v[64:79]
	v_mfma_f32_32x32x16_bf16 v[80:95], v[44:47], v[36:39], v[80:95]
	s_nop 0
	v_mov_b32_e32 v186, v190
	v_mov_b32_e32 v226, v227

; #define LAS __attribute__((address_space(3)))
; template <int MM> DI void tile128_pipe(LAS const char* K0, LAS const char* V0, LAS const char* K1, LAS const char* V1, const bf16x8 (&qf)[4], unsigned vm0, unsigned vm1,
;                                        float& m, float& l, f32x16 (&o)[2], int r, int h, int lane) {
;     f32x16 sa = qk_rows<0, 4>(K0, 0, qf, r, h), sb = qk_rows<0, 4>(K0, 32, qf, r, h);
;     bf16x8 pfa[2], pfb[2];
;     smax_step_nb<MM>(sa, vm0, m, l, o, pfa, lane);
;     sa = qk_rows<0, 4>(K1, 0, qf, r, h);
;     pv_rows(o, V0, 0, pfa, lane);
;     smax_step_nb<MM>(sb, vm0, m, l, o, pfb, lane);
;     sb = qk_rows<0, 4>(K1, 32, qf, r, h);
;     pv_rows(o, V0, 32, pfb, lane);
; template <int MODE, bool PRE = false> ...
;     ...
;             const int kt0 = kt_lo + 2 * sti;
;             bool both = (kt0 + 1 <= kt_hi) && (64 * kt0 + 127 <= q0w);
;             if (MODE == MODE_NWIN) both = both && (64 * kt0 > q0w + 31 - 512);
;             if (both) {
;                 bool ls0 = true, ls1 = true;
;                 if (MODE == MODE_MOBA) { ls0 = ((sel >> (kt0 >> 2)) & 1ull) != 0ull; ls1 = ((sel >> ((kt0 + 1) >> 2)) & 1ull) != 0ull; }
;                 if (MODE == MODE_NSEL) { ls0 = ((sel >> kt0) & 1ull) != 0ull; ls1 = ((sel >> (kt0 + 1)) & 1ull) != 0ull; }
;                 const unsigned long long b0 = __builtin_amdgcn_ballot_w64(ls0), b1 = __builtin_amdgcn_ballot_w64(ls1);
;                 if (b0 != 0ull && b1 != 0ull) {
;                     LAS char* K0 = lds + (sti & 1) * 4 * TILE_B;
;                     if ((b0 & b1) == ~0ull) tile128_pipe<0>(K0, K0 + TILE_B, K0 + 2 * TILE_B, K0 + 3 * TILE_B, qf, 1u, 1u, m1, l1, o1, r, h, lane);
;                     else tile128_pipe<1>(K0, K0 + TILE_B, K0 + 2 * TILE_B, K0 + 3 * TILE_B, qf, ls0 ? 1u : 0u, ls1 ? 1u : 0u, m1, l1, o1, r, h, lane);
.LBB0_849:
	s_lshl_b32 s62, s38, 1
	s_cmp_lt_u32 s62, s58
	s_cselect_b64 s[0:1], -1, 0
	s_lshl_b32 s10, s38, 7
	s_or_b32 s10, s10, 0x7f
	s_cmp_le_i32 s10, s27
	s_cselect_b64 s[10:11], -1, 0
	s_and_b64 s[0:1], s[0:1], s[10:11]
	s_andn2_b64 vcc, exec, s[0:1]
	s_mov_b32 s10, 0
	s_cbranch_vccnz .LBB0_872
	s_lshr_b32 s0, s38, 1
	v_lshrrev_b64 v[32:33], s0, v[168:169]
	v_and_b32_e32 v32, 1, v32
	v_cmp_eq_u32_e64 s[0:1], 1, v32
	v_cmp_ne_u32_e32 vcc, 0, v32
	s_cbranch_vccz .LBB0_872
	s_lshl_b32 s10, s38, 2
	s_and_b32 s10, s10, 4
	s_mulk_i32 s10, 0x2400
	s_add_i32 s10, s10, 0
	v_add_u32_e32 v32, s10, v184
	v_add_u32_e32 v192, v32, v160
	s_waitcnt lgkmcnt(7)
	ds_read_b128 v[140:143], v192
	s_waitcnt lgkmcnt(7)
	ds_read_b128 v[136:139], v192 offset:32
	s_waitcnt lgkmcnt(7)
	ds_read_b128 v[132:135], v192 offset:64
	s_waitcnt lgkmcnt(7)
	ds_read_b128 v[128:131], v192 offset:96
	s_cmp_lg_u64 vcc, -1
	s_nop 0
	s_nop 0
	s_waitcnt lgkmcnt(7)
	ds_read_b128 v[144:147], v192 offset:4608
	s_waitcnt lgkmcnt(7)
	ds_read_b128 v[148:151], v192 offset:4640
	s_waitcnt lgkmcnt(7)
	ds_read_b128 v[152:155], v192 offset:4672
	s_waitcnt lgkmcnt(7)
	ds_read_b128 v[156:159], v192 offset:4704
	s_nop 0
	s_nop 0
	v_add_f32_e32 v193, 0x41000000, v191
	s_cbranch_scc0 .LBB0_861
	s_waitcnt lgkmcnt(7)
	v_mfma_f32_32x32x16_bf16 v[32:47], v[140:143], v[112:115], 0
	s_waitcnt lgkmcnt(6)
	v_mfma_f32_32x32x16_bf16 v[32:47], v[136:139], v[116:119], v[32:47]
	s_waitcnt lgkmcnt(5)
	v_mfma_f32_32x32x16_bf16 v[32:47], v[132:135], v[120:123], v[32:47]
	s_waitcnt lgkmcnt(4)
	v_mfma_f32_32x32x16_bf16 v[32:47], v[128:131], v[124:127], v[32:47]
	s_waitcnt lgkmcnt(3)
	v_mfma_f32_32x32x16_bf16 v[64:79], v[144:147], v[112:115], 0
	s_nop 9
	v_max3_f32 v48, v32, s15, v33
	v_max3_f32 v48, v48, v34, v35
	v_max3_f32 v48, v48, v36, v37
	v_max3_f32 v48, v48, v38, v39
	v_max3_f32 v48, v48, v40, v41
	v_max3_f32 v48, v48, v42, v43
	v_max3_f32 v48, v48, v44, v45
	v_max3_f32 v48, v48, v46, v47
	v_cndmask_b32_e64 v48, v208, v48, s[0:1]
	v_mov_b32_e32 v49, v48
	v_mov_b32_e32 v50, v48
	s_nop 1
	v_permlane32_swap_b32_e32 v49, v50
	v_max_f32_e32 v48, v49, v50
	v_cmp_gt_f32_e32 vcc, v48, v193
	s_waitcnt lgkmcnt(2)
	v_mfma_f32_32x32x16_bf16 v[64:79], v[148:151], v[116:119], v[64:79]
	v_cndmask_b32_e32 v219, v191, v48, vcc
	v_max_f32_e32 v48, 0xefa18f08, v219
	v_cndmask_b32_e64 v48, v209, v48, s[0:1]
	v_sub_f32_e32 v32, v32, v48
	v_sub_f32_e32 v33, v33, v48
	v_exp_f32_e32 v80, v32
	v_sub_f32_e32 v34, v34, v48
	v_exp_f32_e32 v81, v33
	v_sub_f32_e32 v35, v35, v48
	v_exp_f32_e32 v82, v34
	v_sub_f32_e32 v36, v36, v48
	v_exp_f32_e32 v83, v35
	v_sub_f32_e32 v37, v37, v48
	v_exp_f32_e32 v84, v36
	v_sub_f32_e32 v38, v38, v48
	v_exp_f32_e32 v85, v37
	v_add_f32_e32 v32, v81, v80
	v_sub_f32_e32 v39, v39, v48
	v_exp_f32_e32 v86, v38
	s_waitcnt lgkmcnt(1)
	v_mfma_f32_32x32x16_bf16 v[64:79], v[152:155], v[120:123], v[64:79]
	v_add_f32_e32 v32, v82, v32
	v_sub_f32_e32 v40, v40, v48
	v_exp_f32_e32 v87, v39
	v_add_f32_e32 v32, v83, v32
	v_sub_f32_e32 v41, v41, v48
	v_exp_f32_e32 v88, v40
	v_add_f32_e32 v32, v84, v32
	v_sub_f32_e32 v42, v42, v48
	v_exp_f32_e32 v89, v41
	v_add_f32_e32 v32, v85, v32
	v_sub_f32_e32 v43, v43, v48
	v_exp_f32_e32 v90, v42
	v_add_f32_e32 v32, v86, v32
	v_sub_f32_e32 v44, v44, v48
	v_exp_f32_e32 v91, v43
	v_add_f32_e32 v32, v87, v32
	v_add_f32_e32 v32, v88, v32
	v_exp_f32_e32 v92, v44
	v_sub_f32_e32 v33, v45, v48
	v_add_f32_e32 v32, v89, v32
	v_exp_f32_e32 v93, v33
	v_sub_f32_e32 v33, v46, v48
	s_waitcnt lgkmcnt(0)
	v_mfma_f32_32x32x16_bf16 v[64:79], v[156:159], v[124:127], v[64:79]
	v_add_f32_e32 v32, v90, v32
	v_exp_f32_e32 v94, v33
	v_sub_f32_e32 v33, v47, v48
	v_add_f32_e32 v32, v91, v32
	v_exp_f32_e32 v95, v33
	v_add_f32_e32 v32, v92, v32
	v_sub_f32_e32 v49, v191, v219
	v_add_f32_e32 v32, v93, v32
	v_add_f32_e32 v32, v94, v32
	v_exp_f32_e32 v164, v49
	v_add_f32_e32 v212, v95, v32
	v_mov_b32_e32 v213, v212
	v_mov_b32_e32 v214, v212
	s_nop 0
	s_nop 0
	v_permlane32_swap_b32_e32 v213, v214
	v_cmp_neq_f32_e32 vcc, v219, v191
	s_cbranch_vccz .LBB0_854
	v_pk_mul_f32 v[30:31], v[30:31], v[164:165] op_sel_hi:[1,0]
	v_pk_mul_f32 v[28:29], v[28:29], v[164:165] op_sel_hi:[1,0]
	v_pk_mul_f32 v[26:27], v[26:27], v[164:165] op_sel_hi:[1,0]
	v_pk_mul_f32 v[24:25], v[24:25], v[164:165] op_sel_hi:[1,0]
	v_pk_mul_f32 v[22:23], v[22:23], v[164:165] op_sel_hi:[1,0]
	v_pk_mul_f32 v[20:21], v[20:21], v[164:165] op_sel_hi:[1,0]
	v_pk_mul_f32 v[18:19], v[18:19], v[164:165] op_sel_hi:[1,0]
	v_pk_mul_f32 v[16:17], v[16:17], v[164:165] op_sel_hi:[1,0]
	v_pk_mul_f32 v[14:15], v[14:15], v[164:165] op_sel_hi:[1,0]
	v_pk_mul_f32 v[12:13], v[12:13], v[164:165] op_sel_hi:[1,0]
	v_pk_mul_f32 v[10:11], v[10:11], v[164:165] op_sel_hi:[1,0]
	v_pk_mul_f32 v[8:9], v[8:9], v[164:165] op_sel_hi:[1,0]
	v_pk_mul_f32 v[6:7], v[6:7], v[164:165] op_sel_hi:[1,0]
	v_pk_mul_f32 v[4:5], v[4:5], v[164:165] op_sel_hi:[1,0]
	v_pk_mul_f32 v[2:3], v[2:3], v[164:165] op_sel_hi:[1,0]
	v_pk_mul_f32 v[0:1], v[0:1], v[164:165] op_sel_hi:[1,0]
; #define LAS __attribute__((address_space(3)))
; #define MFMA32(a, b, c) __builtin_amdgcn_mfma_f32_32x32x16_bf16((a), (b), (c), 0, 0, 0)
; template <int KS0, int KS1> DI f32x16 qk_rows(LAS const char* Kl, int row0, const bf16x8 (&qf)[4], int r, int h) {
;     f32x16 s;
; #pragma unroll
;     for (int i = 0; i < 16; ++i) s[i] = 0.f;
;     LAS const char* p = Kl + (row0 + r) * KP + 16 * h;
;     bf16x8 kf[4];
; #pragma unroll
;     for (int ks = KS0; ks < KS1; ++ks) kf[ks] = *(LAS const bf16x8*)(p + 32 * ks);
;     __builtin_amdgcn_s_setprio(1);
; #pragma unroll
;     for (int ks = KS0; ks < KS1; ++ks) s = MFMA32(kf[ks], qf[ks], s);
;     __builtin_amdgcn_s_setprio(0);
;     return s;
; }
; DI void pv_rows(f32x16 (&o)[2], LAS const char* Vl, int row0, const bf16x8 (&pf)[2], int lane) {
;     const int h = lane >> 5, i = lane & 15, grp = (lane >> 4) & 1;
;     LAS const char* base = Vl + (row0 + 4 * h + (i >> 2)) * KP + grp * 32 + (i & 3) * 8;
;     bf16x8 vf[2][2];
; #pragma unroll
;     for (int dt = 0; dt < 2; ++dt)
; #pragma unroll
;         for (int s2 = 0; s2 < 2; ++s2) {
;             const s16x4 lo = vtr(base + (16 * s2) * KP + dt * 64), hi = vtr(base + (16 * s2 + 8) * KP + dt * 64);
;             vf[dt][s2] = (bf16x8){lo[0], lo[1], lo[2], lo[3], hi[0], hi[1], hi[2], hi[3]};
;         }
;     __builtin_amdgcn_s_setprio(1);
; #pragma unroll
;     for (int s2 = 0; s2 < 2; ++s2)
; #pragma unroll
;         for (int dt = 0; dt < 2; ++dt) o[dt] = MFMA32(vf[dt][s2], pf[s2], o[dt]);
;     __builtin_amdgcn_s_setprio(0);
; }
; template <int MM> DI void tile128_pipe(LAS const char* K0, LAS const char* V0, LAS const char* K1, LAS const char* V1, const bf16x8 (&qf)[4], unsigned vm0, unsigned vm1,
;                                        float& m, float& l, f32x16 (&o)[2], int r, int h, int lane) {
;     f32x16 sa = qk_rows<0, 4>(K0, 0, qf, r, h), sb = qk_rows<0, 4>(K0, 32, qf, r, h);
;     bf16x8 pfa[2], pfb[2];
;     smax_step_nb<MM>(sa, vm0, m, l, o, pfa, lane);
;     sa = qk_rows<0, 4>(K1, 0, qf, r, h);
;     pv_rows(o, V0, 0, pfa, lane);
;     smax_step_nb<MM>(sb, vm0, m, l, o, pfb, lane);
;     sb = qk_rows<0, 4>(K1, 32, qf, r, h);
;     pv_rows(o, V0, 32, pfb, lane);
;     smax_step_nb<MM>(sa, vm1, m, l, o, pfa, lane);
;     pv_rows(o, V1, 0, pfa, lane);
;     smax_step_nb<MM>(sb, vm1, m, l, o, pfb, lane);
;     pv_rows(o, V1, 32, pfb, lane);
; }
.LBB0_854:
	v_cvt_pk_bf16_f32 v220, v80, v81
	v_cvt_pk_bf16_f32 v221, v82, v83
	ds_read_b128 v[80:83], v192 offset:18432
	ds_read_b128 v[228:231], v192 offset:18464
	ds_read_b128 v[232:235], v192 offset:18496
	ds_read_b128 v[236:239], v192 offset:18528
	v_cvt_pk_bf16_f32 v222, v84, v85
	v_cvt_pk_bf16_f32 v223, v86, v87
	v_cvt_pk_bf16_f32 v224, v88, v89
	v_cvt_pk_bf16_f32 v225, v90, v91
	v_cvt_pk_bf16_f32 v226, v92, v93
	v_cvt_pk_bf16_f32 v227, v94, v95
	s_nop 0
	s_waitcnt lgkmcnt(3)
	v_mfma_f32_32x32x16_bf16 v[80:95], v[80:83], v[112:115], 0
	s_waitcnt lgkmcnt(2)
	v_mfma_f32_32x32x16_bf16 v[80:95], v[228:231], v[116:119], v[80:95]
	s_waitcnt lgkmcnt(1)
	v_mfma_f32_32x32x16_bf16 v[80:95], v[232:235], v[120:123], v[80:95]
	s_waitcnt lgkmcnt(0)
	v_mfma_f32_32x32x16_bf16 v[80:95], v[236:239], v[124:127], v[80:95]
	s_nop 0
	v_add3_u32 v166, s10, v186, v187
	v_add_u32_e32 v215, v166, v188
	ds_read_b64_tr_b16 v[228:229], v215 offset:9216
	ds_read_b64_tr_b16 v[230:231], v215 offset:10368
	ds_read_b64_tr_b16 v[234:235], v215 offset:10432
	ds_read_b64_tr_b16 v[232:233], v215 offset:9280
	ds_read_b64_tr_b16 v[236:237], v215 offset:11520
	ds_read_b64_tr_b16 v[238:239], v215 offset:12672
	ds_read_b64_tr_b16 v[242:243], v215 offset:12736
	ds_read_b64_tr_b16 v[240:241], v215 offset:11584
	s_nop 0
	s_waitcnt lgkmcnt(6)
	v_mfma_f32_32x32x16_bf16 v[0:15], v[228:231], v[220:223], v[0:15]
	s_waitcnt lgkmcnt(4)
	v_mfma_f32_32x32x16_bf16 v[16:31], v[232:235], v[220:223], v[16:31]
	s_waitcnt lgkmcnt(2)
	v_mfma_f32_32x32x16_bf16 v[0:15], v[236:239], v[224:227], v[0:15]
	s_waitcnt lgkmcnt(0)
	v_mfma_f32_32x32x16_bf16 v[16:31], v[240:243], v[224:227], v[16:31]
	s_nop 0
	v_max3_f32 v166, v64, s15, v65
	v_max3_f32 v166, v166, v66, v67
	v_max3_f32 v166, v166, v68, v69
	v_max3_f32 v166, v166, v70, v71
	v_max3_f32 v166, v166, v72, v73
	v_max3_f32 v166, v166, v74, v75
	v_max3_f32 v166, v166, v76, v77
	v_max3_f32 v166, v166, v78, v79
	v_cndmask_b32_e64 v166, v208, v166, s[0:1]
	v_mov_b32_e32 v172, v166
	v_mov_b32_e32 v173, v166
	s_nop 1
	v_permlane32_swap_b32_e32 v172, v173
	v_max_f32_e32 v166, v172, v173
	v_add_f32_e32 v172, 0x41000000, v219
	v_cmp_gt_f32_e32 vcc, v166, v172
	s_nop 1
	v_cndmask_b32_e32 v220, v219, v166, vcc
	v_max_f32_e32 v166, 0xefa18f08, v220
	v_cndmask_b32_e64 v166, v209, v166, s[0:1]
	v_sub_f32_e32 v64, v64, v166
	v_exp_f32_e32 v64, v64
	v_sub_f32_e32 v65, v65, v166
	v_exp_f32_e32 v65, v65
	v_sub_f32_e32 v66, v66, v166
	v_exp_f32_e32 v66, v66
	v_sub_f32_e32 v67, v67, v166
	v_exp_f32_e32 v67, v67
	v_sub_f32_e32 v68, v68, v166
	v_exp_f32_e32 v68, v68
	v_sub_f32_e32 v69, v69, v166
	v_add_f32_e32 v173, v65, v64
	v_exp_f32_e32 v69, v69
	v_sub_f32_e32 v70, v70, v166
	v_add_f32_e32 v173, v66, v173
	v_exp_f32_e32 v70, v70
	v_sub_f32_e32 v71, v71, v166
	v_add_f32_e32 v173, v67, v173
	v_exp_f32_e32 v71, v71
	v_sub_f32_e32 v72, v72, v166
	v_add_f32_e32 v173, v68, v173
	v_exp_f32_e32 v72, v72
	v_sub_f32_e32 v73, v73, v166
	v_add_f32_e32 v173, v69, v173
	v_exp_f32_e32 v73, v73
	v_sub_f32_e32 v74, v74, v166
	v_add_f32_e32 v173, v70, v173
	v_exp_f32_e32 v74, v74
	v_sub_f32_e32 v75, v75, v166
	v_add_f32_e32 v173, v71, v173
	v_exp_f32_e32 v75, v75
	v_sub_f32_e32 v76, v76, v166
	v_add_f32_e32 v173, v72, v173
	v_exp_f32_e32 v76, v76
	v_sub_f32_e32 v77, v77, v166
	v_add_f32_e32 v173, v73, v173
	v_exp_f32_e32 v77, v77
	v_sub_f32_e32 v78, v78, v166
	v_add_f32_e32 v173, v74, v173
	v_exp_f32_e32 v78, v78
	v_sub_f32_e32 v79, v79, v166
	v_add_f32_e32 v173, v75, v173
	v_exp_f32_e32 v79, v79
	v_add_f32_e32 v166, v76, v173
	v_add_f32_e32 v166, v77, v166
	v_sub_f32_e32 v172, v219, v220
	v_add_f32_e32 v166, v78, v166
	v_add_f32_e32 v216, v79, v166
	v_exp_f32_e32 v166, v172
	v_mov_b32_e32 v217, v216
	v_mov_b32_e32 v218, v216
	s_nop 1
	v_permlane32_swap_b32_e32 v217, v218
	v_cmp_neq_f32_e32 vcc, v220, v219
	s_cbranch_vccz .LBB0_856
	v_pk_mul_f32 v[30:31], v[30:31], v[166:167] op_sel_hi:[1,0]
	v_pk_mul_f32 v[28:29], v[28:29], v[166:167] op_sel_hi:[1,0]
	v_pk_mul_f32 v[26:27], v[26:27], v[166:167] op_sel_hi:[1,0]
	v_pk_mul_f32 v[24:25], v[24:25], v[166:167] op_sel_hi:[1,0]
	v_pk_mul_f32 v[22:23], v[22:23], v[166:167] op_sel_hi:[1,0]
	v_pk_mul_f32 v[20:21], v[20:21], v[166:167] op_sel_hi:[1,0]
	v_pk_mul_f32 v[18:19], v[18:19], v[166:167] op_sel_hi:[1,0]
	v_pk_mul_f32 v[16:17], v[16:17], v[166:167] op_sel_hi:[1,0]
	v_pk_mul_f32 v[14:15], v[14:15], v[166:167] op_sel_hi:[1,0]
	v_pk_mul_f32 v[12:13], v[12:13], v[166:167] op_sel_hi:[1,0]
	v_pk_mul_f32 v[10:11], v[10:11], v[166:167] op_sel_hi:[1,0]
	v_pk_mul_f32 v[8:9], v[8:9], v[166:167] op_sel_hi:[1,0]
	v_pk_mul_f32 v[6:7], v[6:7], v[166:167] op_sel_hi:[1,0]
	v_pk_mul_f32 v[4:5], v[4:5], v[166:167] op_sel_hi:[1,0]
	v_pk_mul_f32 v[2:3], v[2:3], v[166:167] op_sel_hi:[1,0]
	v_pk_mul_f32 v[0:1], v[0:1], v[166:167] op_sel_hi:[1,0]
; #define LAS __attribute__((address_space(3)))
; #define MFMA32(a, b, c) __builtin_amdgcn_mfma_f32_32x32x16_bf16((a), (b), (c), 0, 0, 0)
; template <int KS0, int KS1> DI f32x16 qk_rows(LAS const char* Kl, int row0, const bf16x8 (&qf)[4], int r, int h) {
;     f32x16 s;
; #pragma unroll
;     for (int i = 0; i < 16; ++i) s[i] = 0.f;
;     LAS const char* p = Kl + (row0 + r) * KP + 16 * h;
;     bf16x8 kf[4];
; #pragma unroll
;     for (int ks = KS0; ks < KS1; ++ks) kf[ks] = *(LAS const bf16x8*)(p + 32 * ks);
;     __builtin_amdgcn_s_setprio(1);
; #pragma unroll
;     for (int ks = KS0; ks < KS1; ++ks) s = MFMA32(kf[ks], qf[ks], s);
;     __builtin_amdgcn_s_setprio(0);
;     return s;
; }
; DI void pv_rows(f32x16 (&o)[2], LAS const char* Vl, int row0, const bf16x8 (&pf)[2], int lane) {
;     const int h = lane >> 5, i = lane & 15, grp = (lane >> 4) & 1;
;     LAS const char* base = Vl + (row0 + 4 * h + (i >> 2)) * KP + grp * 32 + (i & 3) * 8;
;     bf16x8 vf[2][2];
; #pragma unroll
;     for (int dt = 0; dt < 2; ++dt)
; #pragma unroll
;         for (int s2 = 0; s2 < 2; ++s2) {
;             const s16x4 lo = vtr(base + (16 * s2) * KP + dt * 64), hi = vtr(base + (16 * s2 + 8) * KP + dt * 64);
;             vf[dt][s2] = (bf16x8){lo[0], lo[1], lo[2], lo[3], hi[0], hi[1], hi[2], hi[3]};
;         }
;     __builtin_amdgcn_s_setprio(1);
; #pragma unroll
;     for (int s2 = 0; s2 < 2; ++s2)
; #pragma unroll
;         for (int dt = 0; dt < 2; ++dt) o[dt] = MFMA32(vf[dt][s2], pf[s2], o[dt]);
;     __builtin_amdgcn_s_setprio(0);
; }
; template <int MM> DI void tile128_pipe(LAS const char* K0, LAS const char* V0, LAS const char* K1, LAS const char* V1, const bf16x8 (&qf)[4], unsigned vm0, unsigned vm1,
;                                        float& m, float& l, f32x16 (&o)[2], int r, int h, int lane) {
;     f32x16 sa = qk_rows<0, 4>(K0, 0, qf, r, h), sb = qk_rows<0, 4>(K0, 32, qf, r, h);
;     bf16x8 pfa[2], pfb[2];
;     smax_step_nb<MM>(sa, vm0, m, l, o, pfa, lane);
;     sa = qk_rows<0, 4>(K1, 0, qf, r, h);
;     pv_rows(o, V0, 0, pfa, lane);
;     smax_step_nb<MM>(sb, vm0, m, l, o, pfb, lane);
;     sb = qk_rows<0, 4>(K1, 32, qf, r, h);
;     pv_rows(o, V0, 32, pfb, lane);
;     smax_step_nb<MM>(sa, vm1, m, l, o, pfa, lane);
;     pv_rows(o, V1, 0, pfa, lane);
;     smax_step_nb<MM>(sb, vm1, m, l, o, pfb, lane);
;     pv_rows(o, V1, 32, pfb, lane);
; }
.LBB0_856:
	v_cvt_pk_bf16_f32 v222, v64, v65
	v_cvt_pk_bf16_f32 v223, v66, v67
	ds_read_b128 v[64:67], v192 offset:23040
	ds_read_b128 v[230:233], v192 offset:23072
	ds_read_b128 v[234:237], v192 offset:23104
	ds_read_b128 v[238:241], v192 offset:23136
	v_cvt_pk_bf16_f32 v224, v68, v69
	v_cvt_pk_bf16_f32 v225, v70, v71
	v_cvt_pk_bf16_f32 v226, v72, v73
	v_cvt_pk_bf16_f32 v227, v74, v75
	v_cvt_pk_bf16_f32 v228, v76, v77
	v_cvt_pk_bf16_f32 v229, v78, v79
	s_nop 0
	s_waitcnt lgkmcnt(3)
	v_mfma_f32_32x32x16_bf16 v[64:79], v[64:67], v[112:115], 0
	s_waitcnt lgkmcnt(2)
	v_mfma_f32_32x32x16_bf16 v[64:79], v[230:233], v[116:119], v[64:79]
	s_waitcnt lgkmcnt(1)
	v_mfma_f32_32x32x16_bf16 v[64:79], v[234:237], v[120:123], v[64:79]
	s_waitcnt lgkmcnt(0)
	v_mfma_f32_32x32x16_bf16 v[64:79], v[238:241], v[124:127], v[64:79]
	s_nop 0
	ds_read_b64_tr_b16 v[230:231], v215 offset:13824
	ds_read_b64_tr_b16 v[232:233], v215 offset:14976
	ds_read_b64_tr_b16 v[236:237], v215 offset:15040
	ds_read_b64_tr_b16 v[234:235], v215 offset:13888
	ds_read_b64_tr_b16 v[238:239], v215 offset:16128
	ds_read_b64_tr_b16 v[240:241], v215 offset:17280
	ds_read_b64_tr_b16 v[244:245], v215 offset:17344
	ds_read_b64_tr_b16 v[242:243], v215 offset:16192
	s_nop 0
	s_waitcnt lgkmcnt(6)
	v_mfma_f32_32x32x16_bf16 v[0:15], v[230:233], v[222:225], v[0:15]
	s_waitcnt lgkmcnt(4)
	v_mfma_f32_32x32x16_bf16 v[16:31], v[234:237], v[222:225], v[16:31]
	s_waitcnt lgkmcnt(2)
	v_mfma_f32_32x32x16_bf16 v[0:15], v[238:241], v[226:229], v[0:15]
	s_waitcnt lgkmcnt(0)
	v_mfma_f32_32x32x16_bf16 v[16:31], v[242:245], v[226:229], v[16:31]
	s_nop 0
	v_max3_f32 v172, v80, s15, v81
	v_max3_f32 v172, v172, v82, v83
	v_max3_f32 v172, v172, v84, v85
	v_max3_f32 v172, v172, v86, v87
	v_max3_f32 v172, v172, v88, v89
	v_max3_f32 v172, v172, v90, v91
	v_max3_f32 v172, v172, v92, v93
	v_max3_f32 v172, v172, v94, v95
	v_cndmask_b32_e64 v172, v208, v172, s[0:1]
	v_mov_b32_e32 v173, v172
	v_mov_b32_e32 v206, v172
	s_nop 1
	v_permlane32_swap_b32_e32 v173, v206
	v_cndmask_b32_e64 v173, v173, v206, s[36:37]
	v_max_f32_e32 v173, v173, v173
	v_max_f32_e32 v172, v172, v173
	v_add_f32_e32 v173, 0x41000000, v220
	v_cmp_gt_f32_e32 vcc, v172, v173
	s_nop 1
	v_cndmask_b32_e32 v219, v220, v172, vcc
	v_max_f32_e32 v172, 0xefa18f08, v219
	v_cndmask_b32_e64 v172, v209, v172, s[0:1]
	v_sub_f32_e32 v80, v80, v172
	v_exp_f32_e32 v221, v80
	v_sub_f32_e32 v80, v81, v172
	v_exp_f32_e32 v81, v80
	v_sub_f32_e32 v80, v82, v172
	v_exp_f32_e32 v222, v80
	v_sub_f32_e32 v80, v83, v172
	v_exp_f32_e32 v223, v80
	v_sub_f32_e32 v82, v84, v172
	v_exp_f32_e32 v224, v82
	v_sub_f32_e32 v82, v85, v172
	v_add_f32_e32 v80, v81, v221
	v_exp_f32_e32 v85, v82
	v_sub_f32_e32 v82, v86, v172
	v_add_f32_e32 v80, v222, v80
	v_exp_f32_e32 v86, v82
	v_sub_f32_e32 v82, v87, v172
	v_add_f32_e32 v80, v223, v80
	v_exp_f32_e32 v87, v82
	v_sub_f32_e32 v82, v88, v172
	v_add_f32_e32 v80, v224, v80
	v_exp_f32_e32 v88, v82
	v_sub_f32_e32 v82, v89, v172
	v_add_f32_e32 v80, v85, v80
	v_exp_f32_e32 v89, v82
	v_sub_f32_e32 v82, v90, v172
	v_add_f32_e32 v80, v86, v80
	v_exp_f32_e32 v90, v82
	v_sub_f32_e32 v82, v91, v172
	v_add_f32_e32 v80, v87, v80
	v_exp_f32_e32 v91, v82
	v_sub_f32_e32 v82, v92, v172
	v_add_f32_e32 v80, v88, v80
	v_exp_f32_e32 v92, v82
	v_sub_f32_e32 v82, v93, v172
	v_add_f32_e32 v80, v89, v80
	v_exp_f32_e32 v93, v82
	v_sub_f32_e32 v82, v94, v172
	v_add_f32_e32 v80, v90, v80
	v_exp_f32_e32 v94, v82
	v_sub_f32_e32 v82, v95, v172
	v_add_f32_e32 v80, v91, v80
	v_exp_f32_e32 v95, v82
	v_add_f32_e32 v80, v92, v80
	v_add_f32_e32 v80, v93, v80
	v_sub_f32_e32 v173, v220, v219
	v_add_f32_e32 v80, v94, v80
	v_add_f32_e32 v82, v95, v80
	v_exp_f32_e32 v80, v173
	v_mov_b32_e32 v83, v82
	v_mov_b32_e32 v84, v82
	s_nop 1
	v_permlane32_swap_b32_e32 v83, v84
	v_cmp_neq_f32_e32 vcc, v219, v220
	s_cbranch_vccz .LBB0_858
	v_pk_mul_f32 v[30:31], v[30:31], v[80:81] op_sel_hi:[1,0]
	v_pk_mul_f32 v[28:29], v[28:29], v[80:81] op_sel_hi:[1,0]
	v_pk_mul_f32 v[26:27], v[26:27], v[80:81] op_sel_hi:[1,0]
	v_pk_mul_f32 v[24:25], v[24:25], v[80:81] op_sel_hi:[1,0]
	v_pk_mul_f32 v[22:23], v[22:23], v[80:81] op_sel_hi:[1,0]
	v_pk_mul_f32 v[20:21], v[20:21], v[80:81] op_sel_hi:[1,0]
	v_pk_mul_f32 v[18:19], v[18:19], v[80:81] op_sel_hi:[1,0]
	v_pk_mul_f32 v[16:17], v[16:17], v[80:81] op_sel_hi:[1,0]
	v_pk_mul_f32 v[14:15], v[14:15], v[80:81] op_sel_hi:[1,0]
	v_pk_mul_f32 v[12:13], v[12:13], v[80:81] op_sel_hi:[1,0]
	v_pk_mul_f32 v[10:11], v[10:11], v[80:81] op_sel_hi:[1,0]
	v_pk_mul_f32 v[8:9], v[8:9], v[80:81] op_sel_hi:[1,0]
	v_pk_mul_f32 v[6:7], v[6:7], v[80:81] op_sel_hi:[1,0]
	v_pk_mul_f32 v[4:5], v[4:5], v[80:81] op_sel_hi:[1,0]
	v_pk_mul_f32 v[2:3], v[2:3], v[80:81] op_sel_hi:[1,0]
	v_pk_mul_f32 v[0:1], v[0:1], v[80:81] op_sel_hi:[1,0]
; #define LAS __attribute__((address_space(3)))
; #define MFMA32(a, b, c) __builtin_amdgcn_mfma_f32_32x32x16_bf16((a), (b), (c), 0, 0, 0)
; DI s16x4 vtr(LAS const char* p) { return __builtin_bit_cast(s16x4, __builtin_amdgcn_ds_read_tr16_b64_v4i16((LAS v4i16_t*)p)); }
; DI float ex2(float x) { return __builtin_amdgcn_exp2f(x); }
; DI void pv_rows(f32x16 (&o)[2], LAS const char* Vl, int row0, const bf16x8 (&pf)[2], int lane) {
;     const int h = lane >> 5, i = lane & 15, grp = (lane >> 4) & 1;
;     LAS const char* base = Vl + (row0 + 4 * h + (i >> 2)) * KP + grp * 32 + (i & 3) * 8;
;     bf16x8 vf[2][2];
; #pragma unroll
;     for (int dt = 0; dt < 2; ++dt)
; #pragma unroll
;         for (int s2 = 0; s2 < 2; ++s2) {
;             const s16x4 lo = vtr(base + (16 * s2) * KP + dt * 64), hi = vtr(base + (16 * s2 + 8) * KP + dt * 64);
;             vf[dt][s2] = (bf16x8){lo[0], lo[1], lo[2], lo[3], hi[0], hi[1], hi[2], hi[3]};
;         }
;     __builtin_amdgcn_s_setprio(1);
; #pragma unroll
;     for (int s2 = 0; s2 < 2; ++s2)
; #pragma unroll
;         for (int dt = 0; dt < 2; ++dt) o[dt] = MFMA32(vf[dt][s2], pf[s2], o[dt]);
;     __builtin_amdgcn_s_setprio(0);
; }
; template <int MM> DI void smax_step_nb(const f32x16& s, unsigned vm, float& m, float& l, f32x16 (&o)[2], bf16x8 (&pf)[2], int lane) {
;     float mx = -1e30f;
; #pragma unroll
;     for (int i = 0; i < 16; ++i) mx = fmaxf(mx, s[i]);
;     if (MM == 1) mx = vm ? mx : -1e30f;
;     mx = fmaxf(mx, shx32(mx, lane));
;     const float mn = (mx > m + 8.0f) ? mx : m;
;     float mref = fmaxf(mn, -1e29f);
;     if (MM == 1) mref = vm ? mref : 3e38f;
;     const float alpha = ex2(m - mn);
;     float p[16], rs = 0.f;
; #pragma unroll
;     for (int i = 0; i < 16; ++i) { p[i] = ex2(s[i] - mref); rs += p[i]; }
;     rs += shx32(rs, lane);
;     l = l * alpha + rs;
;     if (__builtin_amdgcn_ballot_w64(mn != m) != 0ull) {
; #pragma unroll
;         for (int i = 0; i < 16; ++i) { o[0][i] *= alpha; o[1][i] *= alpha; }
;     }
;     m = mn;
;     pack_p(p, pf);
; }
.LBB0_858:
	v_cvt_pk_bf16_f32 v220, v221, v81
	v_cvt_pk_bf16_f32 v221, v222, v223
	v_cvt_pk_bf16_f32 v222, v224, v85
	v_cvt_pk_bf16_f32 v223, v86, v87
	v_cvt_pk_bf16_f32 v86, v88, v89
	v_cvt_pk_bf16_f32 v87, v90, v91
	v_cvt_pk_bf16_f32 v88, v92, v93
	ds_read_b64_tr_b16 v[90:91], v215 offset:27648
	ds_read_b64_tr_b16 v[92:93], v215 offset:28800
	ds_read_b64_tr_b16 v[224:225], v215 offset:29952
	ds_read_b64_tr_b16 v[226:227], v215 offset:31104
	ds_read_b64_tr_b16 v[228:229], v215 offset:27712
	ds_read_b64_tr_b16 v[230:231], v215 offset:28864
	ds_read_b64_tr_b16 v[232:233], v215 offset:30016
	ds_read_b64_tr_b16 v[234:235], v215 offset:31168
	v_cvt_pk_bf16_f32 v89, v94, v95
	s_nop 0
	s_waitcnt lgkmcnt(6)
	v_mfma_f32_32x32x16_bf16 v[0:15], v[90:93], v[220:223], v[0:15]
	s_waitcnt lgkmcnt(2)
	v_mfma_f32_32x32x16_bf16 v[16:31], v[228:231], v[220:223], v[16:31]
	v_mfma_f32_32x32x16_bf16 v[0:15], v[224:227], v[86:89], v[0:15]
	s_waitcnt lgkmcnt(0)
	v_mfma_f32_32x32x16_bf16 v[16:31], v[232:235], v[86:89], v[16:31]
	s_nop 0
	v_max3_f32 v81, v64, s15, v65
	v_max3_f32 v81, v81, v66, v67
	v_max3_f32 v81, v81, v68, v69
	v_max3_f32 v81, v81, v70, v71
	v_max3_f32 v81, v81, v72, v73
	v_max3_f32 v81, v81, v74, v75
	v_max3_f32 v81, v81, v76, v77
	v_max3_f32 v81, v81, v78, v79
	v_cndmask_b32_e64 v81, v208, v81, s[0:1]
	v_mov_b32_e32 v85, v81
	v_mov_b32_e32 v86, v81
	s_nop 1
	v_permlane32_swap_b32_e32 v85, v86
	v_max_f32_e32 v81, v85, v86
	v_add_f32_e32 v85, 0x41000000, v219
	v_cmp_gt_f32_e32 vcc, v81, v85
	s_nop 1
	v_cndmask_b32_e32 v81, v219, v81, vcc
	v_max_f32_e32 v85, 0xefa18f08, v81
	v_cndmask_b32_e64 v93, v209, v85, s[0:1]
	v_sub_f32_e32 v64, v64, v93
	v_exp_f32_e32 v85, v64
	v_sub_f32_e32 v64, v65, v93
	v_exp_f32_e32 v86, v64
	v_sub_f32_e32 v64, v66, v93
	v_exp_f32_e32 v87, v64
	v_sub_f32_e32 v64, v67, v93
	v_exp_f32_e32 v88, v64
	v_sub_f32_e32 v65, v68, v93
	v_exp_f32_e32 v89, v65
	v_sub_f32_e32 v65, v69, v93
	v_add_f32_e32 v64, v86, v85
	v_exp_f32_e32 v90, v65
	v_sub_f32_e32 v65, v70, v93
	v_add_f32_e32 v64, v87, v64
	v_exp_f32_e32 v91, v65
	v_sub_f32_e32 v65, v71, v93
	v_add_f32_e32 v64, v88, v64
	v_exp_f32_e32 v92, v65
	v_sub_f32_e32 v65, v72, v93
	v_add_f32_e32 v64, v89, v64
	v_exp_f32_e32 v66, v65
	v_sub_f32_e32 v65, v73, v93
	v_add_f32_e32 v64, v90, v64
	v_exp_f32_e32 v67, v65
	v_sub_f32_e32 v65, v74, v93
	v_add_f32_e32 v64, v91, v64
	v_exp_f32_e32 v68, v65
	v_sub_f32_e32 v65, v75, v93
	v_add_f32_e32 v64, v92, v64
	v_exp_f32_e32 v69, v65
	v_sub_f32_e32 v65, v76, v93
	v_add_f32_e32 v64, v66, v64
	v_exp_f32_e32 v70, v65
	v_sub_f32_e32 v65, v77, v93
	v_add_f32_e32 v64, v67, v64
	v_exp_f32_e32 v71, v65
	v_sub_f32_e32 v65, v78, v93
	v_add_f32_e32 v64, v68, v64
	v_exp_f32_e32 v72, v65
	v_sub_f32_e32 v65, v79, v93
	v_add_f32_e32 v64, v69, v64
	v_exp_f32_e32 v73, v65
	v_add_f32_e32 v64, v70, v64
	v_add_f32_e32 v64, v71, v64
	v_sub_f32_e32 v94, v219, v81
	v_add_f32_e32 v64, v72, v64
	v_add_f32_e32 v65, v73, v64
	v_exp_f32_e32 v64, v94
	v_mov_b32_e32 v74, v65
	v_mov_b32_e32 v75, v65
	s_nop 1
	v_permlane32_swap_b32_e32 v74, v75
	v_cmp_neq_f32_e32 vcc, v81, v219
	s_cbranch_vccz .LBB0_860
	v_pk_mul_f32 v[30:31], v[30:31], v[64:65] op_sel_hi:[1,0]
	v_pk_mul_f32 v[28:29], v[28:29], v[64:65] op_sel_hi:[1,0]
	v_pk_mul_f32 v[26:27], v[26:27], v[64:65] op_sel_hi:[1,0]
	v_pk_mul_f32 v[24:25], v[24:25], v[64:65] op_sel_hi:[1,0]
	v_pk_mul_f32 v[22:23], v[22:23], v[64:65] op_sel_hi:[1,0]
	v_pk_mul_f32 v[20:21], v[20:21], v[64:65] op_sel_hi:[1,0]
	v_pk_mul_f32 v[18:19], v[18:19], v[64:65] op_sel_hi:[1,0]
	v_pk_mul_f32 v[16:17], v[16:17], v[64:65] op_sel_hi:[1,0]
	v_pk_mul_f32 v[14:15], v[14:15], v[64:65] op_sel_hi:[1,0]
	v_pk_mul_f32 v[12:13], v[12:13], v[64:65] op_sel_hi:[1,0]
	v_pk_mul_f32 v[10:11], v[10:11], v[64:65] op_sel_hi:[1,0]
	v_pk_mul_f32 v[8:9], v[8:9], v[64:65] op_sel_hi:[1,0]
	v_pk_mul_f32 v[6:7], v[6:7], v[64:65] op_sel_hi:[1,0]
	v_pk_mul_f32 v[4:5], v[4:5], v[64:65] op_sel_hi:[1,0]
	v_pk_mul_f32 v[2:3], v[2:3], v[64:65] op_sel_hi:[1,0]
	v_pk_mul_f32 v[0:1], v[0:1], v[64:65] op_sel_hi:[1,0]
.LBB0_860:
	v_cndmask_b32_e64 v76, v213, v214, s[36:37]
	v_add_f32_e32 v76, v212, v76
	v_cndmask_b32_e64 v77, v217, v218, s[36:37]
	v_fmac_f32_e32 v76, v190, v164
	v_add_f32_e32 v77, v216, v77
	v_fmac_f32_e32 v77, v76, v166
	v_cndmask_b32_e64 v76, v83, v84, s[36:37]
	v_add_f32_e32 v76, v82, v76
	v_cndmask_b32_e64 v74, v74, v75, s[36:37]
	v_fmac_f32_e32 v76, v77, v80
	v_add_f32_e32 v65, v65, v74
	v_fmac_f32_e32 v65, v76, v64
	v_cvt_pk_bf16_f32 v74, v85, v86
	v_cvt_pk_bf16_f32 v75, v87, v88
	v_cvt_pk_bf16_f32 v76, v89, v90
	v_cvt_pk_bf16_f32 v77, v91, v92
	ds_read_b64_tr_b16 v[84:85], v215 offset:33408
	ds_read_b64_tr_b16 v[86:87], v215 offset:34560
	ds_read_b64_tr_b16 v[90:91], v215 offset:34624
	ds_read_b64_tr_b16 v[218:219], v215 offset:33472
	ds_read_b64_tr_b16 v[82:83], v215 offset:32256
	ds_read_b64_tr_b16 v[88:89], v215 offset:35712
	ds_read_b64_tr_b16 v[216:217], v215 offset:32320
	ds_read_b64_tr_b16 v[92:93], v215 offset:35776
	v_cvt_pk_bf16_f32 v66, v66, v67
	v_cvt_pk_bf16_f32 v67, v68, v69
	v_cvt_pk_bf16_f32 v68, v70, v71
	v_cvt_pk_bf16_f32 v69, v72, v73
	s_nop 0
	s_waitcnt lgkmcnt(3)
	v_mfma_f32_32x32x16_bf16 v[0:15], v[82:85], v[74:77], v[0:15]
	s_waitcnt lgkmcnt(1)
	v_mfma_f32_32x32x16_bf16 v[16:31], v[216:219], v[74:77], v[16:31]
	v_mfma_f32_32x32x16_bf16 v[0:15], v[86:89], v[66:69], v[0:15]
	s_waitcnt lgkmcnt(0)
	v_mfma_f32_32x32x16_bf16 v[16:31], v[90:93], v[66:69], v[16:31]
	s_branch .LBB0_871

; #define LAS __attribute__((address_space(3)))
; DI float ex2(float x) { return __builtin_amdgcn_exp2f(x); }
; template <int KS0, int KS1> DI f32x16 qk_rows(LAS const char* Kl, int row0, const bf16x8 (&qf)[4], int r, int h) {
;     f32x16 s;
; #pragma unroll
;     for (int i = 0; i < 16; ++i) s[i] = 0.f;
;     LAS const char* p = Kl + (row0 + r) * KP + 16 * h;
;     bf16x8 kf[4];
; #pragma unroll
;     for (int ks = KS0; ks < KS1; ++ks) kf[ks] = *(LAS const bf16x8*)(p + 32 * ks);
;     __builtin_amdgcn_s_setprio(1);
; #pragma unroll
;     for (int ks = KS0; ks < KS1; ++ks) s = MFMA32(kf[ks], qf[ks], s);
;     __builtin_amdgcn_s_setprio(0);
;     return s;
; }
; DI void pv_rows(f32x16 (&o)[2], LAS const char* Vl, int row0, const bf16x8 (&pf)[2], int lane) {
;     const int h = lane >> 5, i = lane & 15, grp = (lane >> 4) & 1;
;     LAS const char* base = Vl + (row0 + 4 * h + (i >> 2)) * KP + grp * 32 + (i & 3) * 8;
;     bf16x8 vf[2][2];
; #pragma unroll
;     for (int dt = 0; dt < 2; ++dt)
; #pragma unroll
;         for (int s2 = 0; s2 < 2; ++s2) {
;             const s16x4 lo = vtr(base + (16 * s2) * KP + dt * 64), hi = vtr(base + (16 * s2 + 8) * KP + dt * 64);
;             vf[dt][s2] = (bf16x8){lo[0], lo[1], lo[2], lo[3], hi[0], hi[1], hi[2], hi[3]};
;         }
;     __builtin_amdgcn_s_setprio(1);
; #pragma unroll
;     for (int s2 = 0; s2 < 2; ++s2)
; #pragma unroll
;         for (int dt = 0; dt < 2; ++dt) o[dt] = MFMA32(vf[dt][s2], pf[s2], o[dt]);
;     __builtin_amdgcn_s_setprio(0);
; }
; template <int MM> DI void smax_step_nb(const f32x16& s, unsigned vm, float& m, float& l, f32x16 (&o)[2], bf16x8 (&pf)[2], int lane) {
;     float mx = -1e30f;
; #pragma unroll
;     for (int i = 0; i < 16; ++i) mx = fmaxf(mx, s[i]);
;     if (MM == 1) mx = vm ? mx : -1e30f;
;     mx = fmaxf(mx, shx32(mx, lane));
;     const float mn = (mx > m + 8.0f) ? mx : m;
;     float mref = fmaxf(mn, -1e29f);
;     if (MM == 1) mref = vm ? mref : 3e38f;
;     const float alpha = ex2(m - mn);
;     float p[16], rs = 0.f;
; #pragma unroll
;     for (int i = 0; i < 16; ++i) { p[i] = ex2(s[i] - mref); rs += p[i]; }
;     rs += shx32(rs, lane);
;     l = l * alpha + rs;
;     if (__builtin_amdgcn_ballot_w64(mn != m) != 0ull) {
; #pragma unroll
;         for (int i = 0; i < 16; ++i) { o[0][i] *= alpha; o[1][i] *= alpha; }
;     }
;     m = mn;
;     pack_p(p, pf);
; }
.LBB0_864:
	v_cvt_pk_bf16_f32 v74, v48, v49
	v_cvt_pk_bf16_f32 v75, v50, v51
	ds_read_b128 v[48:51], v192 offset:18432
	ds_read_b128 v[82:85], v192 offset:18464
	ds_read_b128 v[86:89], v192 offset:18496
	ds_read_b128 v[90:93], v192 offset:18528
	v_cvt_pk_bf16_f32 v76, v52, v53
	v_cvt_pk_bf16_f32 v77, v54, v55
	v_cvt_pk_bf16_f32 v78, v56, v57
	v_cvt_pk_bf16_f32 v79, v58, v59
	v_cvt_pk_bf16_f32 v80, v60, v61
	v_cvt_pk_bf16_f32 v81, v62, v63
	s_nop 0
	s_waitcnt lgkmcnt(3)
	v_mfma_f32_32x32x16_bf16 v[48:63], v[48:51], v[112:115], 0
	s_waitcnt lgkmcnt(2)
	v_mfma_f32_32x32x16_bf16 v[48:63], v[82:85], v[116:119], v[48:63]
	s_waitcnt lgkmcnt(1)
	v_mfma_f32_32x32x16_bf16 v[48:63], v[86:89], v[120:123], v[48:63]
	s_waitcnt lgkmcnt(0)
	v_mfma_f32_32x32x16_bf16 v[48:63], v[90:93], v[124:127], v[48:63]
	s_nop 0
	v_add3_u32 v66, s10, v186, v187
	v_add_u32_e32 v69, v66, v188
	ds_read_b64_tr_b16 v[82:83], v69 offset:9216
	ds_read_b64_tr_b16 v[84:85], v69 offset:10368
	ds_read_b64_tr_b16 v[88:89], v69 offset:10432
	ds_read_b64_tr_b16 v[86:87], v69 offset:9280
	ds_read_b64_tr_b16 v[90:91], v69 offset:11520
	ds_read_b64_tr_b16 v[92:93], v69 offset:12672
	ds_read_b64_tr_b16 v[130:131], v69 offset:12736
	ds_read_b64_tr_b16 v[128:129], v69 offset:11584
	s_nop 0
	s_waitcnt lgkmcnt(6)
	v_mfma_f32_32x32x16_bf16 v[0:15], v[82:85], v[74:77], v[0:15]
	s_waitcnt lgkmcnt(4)
	v_mfma_f32_32x32x16_bf16 v[16:31], v[86:89], v[74:77], v[16:31]
	s_waitcnt lgkmcnt(2)
	v_mfma_f32_32x32x16_bf16 v[0:15], v[90:93], v[78:81], v[0:15]
	s_waitcnt lgkmcnt(0)
	v_mfma_f32_32x32x16_bf16 v[16:31], v[128:131], v[78:81], v[16:31]
	s_nop 0
	v_max3_f32 v66, v32, s15, v33
	v_max3_f32 v66, v66, v34, v35
	v_max3_f32 v66, v66, v36, v37
	v_max3_f32 v66, v66, v38, v39
	v_max3_f32 v66, v66, v40, v41
	v_max3_f32 v66, v66, v42, v43
	v_max3_f32 v66, v66, v44, v45
	v_max3_f32 v66, v66, v46, v47
	v_mov_b32_e32 v70, v66
	v_mov_b32_e32 v71, v66
	s_nop 1
	v_permlane32_swap_b32_e32 v70, v71
	v_max_f32_e32 v66, v70, v71
	v_add_f32_e32 v70, 0x41000000, v73
	v_cmp_gt_f32_e32 vcc, v66, v70
	s_nop 1
	v_cndmask_b32_e32 v74, v73, v66, vcc
	v_max_f32_e32 v66, 0xefa18f08, v74
	v_sub_f32_e32 v32, v32, v66
	v_exp_f32_e32 v32, v32
	v_sub_f32_e32 v33, v33, v66
	v_exp_f32_e32 v33, v33
	v_sub_f32_e32 v34, v34, v66
	v_exp_f32_e32 v34, v34
	v_sub_f32_e32 v35, v35, v66
	v_exp_f32_e32 v35, v35
	v_sub_f32_e32 v36, v36, v66
	v_exp_f32_e32 v36, v36
	v_sub_f32_e32 v37, v37, v66
	v_add_f32_e32 v70, v33, v32
	v_exp_f32_e32 v37, v37
	v_sub_f32_e32 v38, v38, v66
	v_add_f32_e32 v70, v34, v70
	v_exp_f32_e32 v38, v38
	v_sub_f32_e32 v39, v39, v66
	v_add_f32_e32 v70, v35, v70
	v_exp_f32_e32 v39, v39
	v_sub_f32_e32 v40, v40, v66
	v_add_f32_e32 v70, v36, v70
	v_exp_f32_e32 v40, v40
	v_sub_f32_e32 v41, v41, v66
	v_add_f32_e32 v70, v37, v70
	v_exp_f32_e32 v41, v41
	v_sub_f32_e32 v42, v42, v66
	v_add_f32_e32 v70, v38, v70
	v_exp_f32_e32 v42, v42
	v_sub_f32_e32 v43, v43, v66
	v_add_f32_e32 v70, v39, v70
	v_exp_f32_e32 v43, v43
	v_sub_f32_e32 v44, v44, v66
	v_add_f32_e32 v70, v40, v70
	v_exp_f32_e32 v44, v44
	v_sub_f32_e32 v45, v45, v66
	v_add_f32_e32 v70, v41, v70
	v_exp_f32_e32 v45, v45
	v_sub_f32_e32 v46, v46, v66
	v_add_f32_e32 v70, v42, v70
	v_exp_f32_e32 v46, v46
	v_sub_f32_e32 v47, v47, v66
	v_add_f32_e32 v70, v43, v70
	v_exp_f32_e32 v47, v47
	v_add_f32_e32 v66, v44, v70
	v_add_f32_e32 v66, v45, v66
	v_sub_f32_e32 v71, v73, v74
	v_add_f32_e32 v66, v46, v66
	v_add_f32_e32 v70, v47, v66
	v_exp_f32_e32 v66, v71
	v_mov_b32_e32 v71, v70
	v_mov_b32_e32 v72, v70
	s_nop 1
	v_permlane32_swap_b32_e32 v71, v72
	v_cmp_neq_f32_e32 vcc, v74, v73
	s_cbranch_vccz .LBB0_866
	v_pk_mul_f32 v[30:31], v[30:31], v[66:67] op_sel_hi:[1,0]
	v_pk_mul_f32 v[28:29], v[28:29], v[66:67] op_sel_hi:[1,0]
	v_pk_mul_f32 v[26:27], v[26:27], v[66:67] op_sel_hi:[1,0]
	v_pk_mul_f32 v[24:25], v[24:25], v[66:67] op_sel_hi:[1,0]
	v_pk_mul_f32 v[22:23], v[22:23], v[66:67] op_sel_hi:[1,0]
	v_pk_mul_f32 v[20:21], v[20:21], v[66:67] op_sel_hi:[1,0]
	v_pk_mul_f32 v[18:19], v[18:19], v[66:67] op_sel_hi:[1,0]
	v_pk_mul_f32 v[16:17], v[16:17], v[66:67] op_sel_hi:[1,0]
	v_pk_mul_f32 v[14:15], v[14:15], v[66:67] op_sel_hi:[1,0]
	v_pk_mul_f32 v[12:13], v[12:13], v[66:67] op_sel_hi:[1,0]
	v_pk_mul_f32 v[10:11], v[10:11], v[66:67] op_sel_hi:[1,0]
	v_pk_mul_f32 v[8:9], v[8:9], v[66:67] op_sel_hi:[1,0]
	v_pk_mul_f32 v[6:7], v[6:7], v[66:67] op_sel_hi:[1,0]
	v_pk_mul_f32 v[4:5], v[4:5], v[66:67] op_sel_hi:[1,0]
	v_pk_mul_f32 v[2:3], v[2:3], v[66:67] op_sel_hi:[1,0]
	v_pk_mul_f32 v[0:1], v[0:1], v[66:67] op_sel_hi:[1,0]
; #define LAS __attribute__((address_space(3)))
; DI float ex2(float x) { return __builtin_amdgcn_exp2f(x); }
; template <int KS0, int KS1> DI f32x16 qk_rows(LAS const char* Kl, int row0, const bf16x8 (&qf)[4], int r, int h) {
;     f32x16 s;
; #pragma unroll
;     for (int i = 0; i < 16; ++i) s[i] = 0.f;
;     LAS const char* p = Kl + (row0 + r) * KP + 16 * h;
;     bf16x8 kf[4];
; #pragma unroll
;     for (int ks = KS0; ks < KS1; ++ks) kf[ks] = *(LAS const bf16x8*)(p + 32 * ks);
;     __builtin_amdgcn_s_setprio(1);
; #pragma unroll
;     for (int ks = KS0; ks < KS1; ++ks) s = MFMA32(kf[ks], qf[ks], s);
;     __builtin_amdgcn_s_setprio(0);
;     return s;
; }
; DI void pv_rows(f32x16 (&o)[2], LAS const char* Vl, int row0, const bf16x8 (&pf)[2], int lane) {
;     const int h = lane >> 5, i = lane & 15, grp = (lane >> 4) & 1;
;     LAS const char* base = Vl + (row0 + 4 * h + (i >> 2)) * KP + grp * 32 + (i & 3) * 8;
;     bf16x8 vf[2][2];
; #pragma unroll
;     for (int dt = 0; dt < 2; ++dt)
; #pragma unroll
;         for (int s2 = 0; s2 < 2; ++s2) {
;             const s16x4 lo = vtr(base + (16 * s2) * KP + dt * 64), hi = vtr(base + (16 * s2 + 8) * KP + dt * 64);
;             vf[dt][s2] = (bf16x8){lo[0], lo[1], lo[2], lo[3], hi[0], hi[1], hi[2], hi[3]};
;         }
;     __builtin_amdgcn_s_setprio(1);
; #pragma unroll
;     for (int s2 = 0; s2 < 2; ++s2)
; #pragma unroll
;         for (int dt = 0; dt < 2; ++dt) o[dt] = MFMA32(vf[dt][s2], pf[s2], o[dt]);
;     __builtin_amdgcn_s_setprio(0);
; }
; template <int MM> DI void smax_step_nb(const f32x16& s, unsigned vm, float& m, float& l, f32x16 (&o)[2], bf16x8 (&pf)[2], int lane) {
;     float mx = -1e30f;
; #pragma unroll
;     for (int i = 0; i < 16; ++i) mx = fmaxf(mx, s[i]);
;     if (MM == 1) mx = vm ? mx : -1e30f;
;     mx = fmaxf(mx, shx32(mx, lane));
;     const float mn = (mx > m + 8.0f) ? mx : m;
;     float mref = fmaxf(mn, -1e29f);
;     if (MM == 1) mref = vm ? mref : 3e38f;
;     const float alpha = ex2(m - mn);
;     float p[16], rs = 0.f;
; #pragma unroll
;     for (int i = 0; i < 16; ++i) { p[i] = ex2(s[i] - mref); rs += p[i]; }
;     rs += shx32(rs, lane);
;     l = l * alpha + rs;
;     if (__builtin_amdgcn_ballot_w64(mn != m) != 0ull) {
; #pragma unroll
;         for (int i = 0; i < 16; ++i) { o[0][i] *= alpha; o[1][i] *= alpha; }
;     }
;     m = mn;
;     pack_p(p, pf);
; }
.LBB0_866:
	v_cvt_pk_bf16_f32 v76, v32, v33
	v_cvt_pk_bf16_f32 v77, v34, v35
	ds_read_b128 v[32:35], v192 offset:23040
	ds_read_b128 v[84:87], v192 offset:23072
	ds_read_b128 v[88:91], v192 offset:23104
	ds_read_b128 v[92:95], v192 offset:23136
	v_cvt_pk_bf16_f32 v78, v36, v37
	v_cvt_pk_bf16_f32 v79, v38, v39
	v_cvt_pk_bf16_f32 v80, v40, v41
	v_cvt_pk_bf16_f32 v81, v42, v43
	v_cvt_pk_bf16_f32 v82, v44, v45
	v_cvt_pk_bf16_f32 v83, v46, v47
	s_nop 0
	s_waitcnt lgkmcnt(3)
	v_mfma_f32_32x32x16_bf16 v[32:47], v[32:35], v[112:115], 0
	s_waitcnt lgkmcnt(2)
	v_mfma_f32_32x32x16_bf16 v[32:47], v[84:87], v[116:119], v[32:47]
	s_waitcnt lgkmcnt(1)
	v_mfma_f32_32x32x16_bf16 v[32:47], v[88:91], v[120:123], v[32:47]
	s_waitcnt lgkmcnt(0)
	v_mfma_f32_32x32x16_bf16 v[32:47], v[92:95], v[124:127], v[32:47]
	s_nop 0
	ds_read_b64_tr_b16 v[84:85], v69 offset:13824
	ds_read_b64_tr_b16 v[86:87], v69 offset:14976
	ds_read_b64_tr_b16 v[90:91], v69 offset:15040
	ds_read_b64_tr_b16 v[88:89], v69 offset:13888
	ds_read_b64_tr_b16 v[92:93], v69 offset:16128
	ds_read_b64_tr_b16 v[94:95], v69 offset:17280
	ds_read_b64_tr_b16 v[130:131], v69 offset:17344
	ds_read_b64_tr_b16 v[128:129], v69 offset:16192
	s_nop 0
	s_waitcnt lgkmcnt(6)
	v_mfma_f32_32x32x16_bf16 v[0:15], v[84:87], v[76:79], v[0:15]
	s_waitcnt lgkmcnt(4)
	v_mfma_f32_32x32x16_bf16 v[16:31], v[88:91], v[76:79], v[16:31]
	s_waitcnt lgkmcnt(2)
	v_mfma_f32_32x32x16_bf16 v[0:15], v[92:95], v[80:83], v[0:15]
	s_waitcnt lgkmcnt(0)
	v_mfma_f32_32x32x16_bf16 v[16:31], v[128:131], v[80:83], v[16:31]
	s_nop 0
	v_max3_f32 v73, v48, s15, v49
	v_max3_f32 v73, v73, v50, v51
	v_max3_f32 v73, v73, v52, v53
	v_max3_f32 v73, v73, v54, v55
	v_max3_f32 v73, v73, v56, v57
	v_max3_f32 v73, v73, v58, v59
	v_max3_f32 v73, v73, v60, v61
	v_max3_f32 v73, v73, v62, v63
	v_mov_b32_e32 v75, v73
	v_mov_b32_e32 v76, v73
	s_nop 1
	v_permlane32_swap_b32_e32 v75, v76
	v_max_f32_e32 v73, v75, v76
	v_add_f32_e32 v75, 0x41000000, v74
	v_cmp_gt_f32_e32 vcc, v73, v75
	s_nop 1
	v_cndmask_b32_e32 v73, v74, v73, vcc
	v_max_f32_e32 v79, 0xefa18f08, v73
	v_sub_f32_e32 v48, v48, v79
	v_exp_f32_e32 v75, v48
	v_sub_f32_e32 v48, v49, v79
	v_exp_f32_e32 v76, v48
	v_sub_f32_e32 v48, v50, v79
	v_exp_f32_e32 v77, v48
	v_sub_f32_e32 v48, v51, v79
	v_exp_f32_e32 v78, v48
	v_sub_f32_e32 v49, v52, v79
	v_exp_f32_e32 v52, v49
	v_sub_f32_e32 v49, v53, v79
	v_add_f32_e32 v48, v76, v75
	v_exp_f32_e32 v53, v49
	v_sub_f32_e32 v49, v54, v79
	v_add_f32_e32 v48, v77, v48
	v_exp_f32_e32 v54, v49
	v_sub_f32_e32 v49, v55, v79
	v_add_f32_e32 v48, v78, v48
	v_exp_f32_e32 v55, v49
	v_sub_f32_e32 v49, v56, v79
	v_add_f32_e32 v48, v52, v48
	v_exp_f32_e32 v56, v49
	v_sub_f32_e32 v49, v57, v79
	v_add_f32_e32 v48, v53, v48
	v_exp_f32_e32 v57, v49
	v_sub_f32_e32 v49, v58, v79
	v_add_f32_e32 v48, v54, v48
	v_exp_f32_e32 v58, v49
	v_sub_f32_e32 v49, v59, v79
	v_add_f32_e32 v48, v55, v48
	v_exp_f32_e32 v59, v49
	v_sub_f32_e32 v49, v60, v79
	v_add_f32_e32 v48, v56, v48
	v_exp_f32_e32 v60, v49
	v_sub_f32_e32 v49, v61, v79
	v_add_f32_e32 v48, v57, v48
	v_exp_f32_e32 v61, v49
	v_sub_f32_e32 v49, v62, v79
	v_add_f32_e32 v48, v58, v48
	v_exp_f32_e32 v62, v49
	v_sub_f32_e32 v49, v63, v79
	v_add_f32_e32 v48, v59, v48
	v_exp_f32_e32 v63, v49
	v_add_f32_e32 v48, v60, v48
	v_add_f32_e32 v48, v61, v48
	v_sub_f32_e32 v80, v74, v73
	v_add_f32_e32 v48, v62, v48
	v_add_f32_e32 v49, v63, v48
	v_exp_f32_e32 v48, v80
	v_mov_b32_e32 v50, v49
	v_mov_b32_e32 v51, v49
	s_nop 1
	v_permlane32_swap_b32_e32 v50, v51
	v_cmp_neq_f32_e32 vcc, v73, v74
	s_cbranch_vccz .LBB0_868
	v_pk_mul_f32 v[30:31], v[30:31], v[48:49] op_sel_hi:[1,0]
	v_pk_mul_f32 v[28:29], v[28:29], v[48:49] op_sel_hi:[1,0]
	v_pk_mul_f32 v[26:27], v[26:27], v[48:49] op_sel_hi:[1,0]
	v_pk_mul_f32 v[24:25], v[24:25], v[48:49] op_sel_hi:[1,0]
	v_pk_mul_f32 v[22:23], v[22:23], v[48:49] op_sel_hi:[1,0]
	v_pk_mul_f32 v[20:21], v[20:21], v[48:49] op_sel_hi:[1,0]
	v_pk_mul_f32 v[18:19], v[18:19], v[48:49] op_sel_hi:[1,0]
	v_pk_mul_f32 v[16:17], v[16:17], v[48:49] op_sel_hi:[1,0]
	v_pk_mul_f32 v[14:15], v[14:15], v[48:49] op_sel_hi:[1,0]
	v_pk_mul_f32 v[12:13], v[12:13], v[48:49] op_sel_hi:[1,0]
	v_pk_mul_f32 v[10:11], v[10:11], v[48:49] op_sel_hi:[1,0]
	v_pk_mul_f32 v[8:9], v[8:9], v[48:49] op_sel_hi:[1,0]
	v_pk_mul_f32 v[6:7], v[6:7], v[48:49] op_sel_hi:[1,0]
	v_pk_mul_f32 v[4:5], v[4:5], v[48:49] op_sel_hi:[1,0]
	v_pk_mul_f32 v[2:3], v[2:3], v[48:49] op_sel_hi:[1,0]
	v_pk_mul_f32 v[0:1], v[0:1], v[48:49] op_sel_hi:[1,0]

; #define LAS __attribute__((address_space(3)))
; #define MFMA32(a, b, c) __builtin_amdgcn_mfma_f32_32x32x16_bf16((a), (b), (c), 0, 0, 0)
; DI s16x4 vtr(LAS const char* p) { return __builtin_bit_cast(s16x4, __builtin_amdgcn_ds_read_tr16_b64_v4i16((LAS v4i16_t*)p)); }
; DI void pv_rows(f32x16 (&o)[2], LAS const char* Vl, int row0, const bf16x8 (&pf)[2], int lane) {
;     const int h = lane >> 5, i = lane & 15, grp = (lane >> 4) & 1;
;     LAS const char* base = Vl + (row0 + 4 * h + (i >> 2)) * KP + grp * 32 + (i & 3) * 8;
;     bf16x8 vf[2][2];
; #pragma unroll
;     for (int dt = 0; dt < 2; ++dt)
; #pragma unroll
;         for (int s2 = 0; s2 < 2; ++s2) {
;             const s16x4 lo = vtr(base + (16 * s2) * KP + dt * 64), hi = vtr(base + (16 * s2 + 8) * KP + dt * 64);
;             vf[dt][s2] = (bf16x8){lo[0], lo[1], lo[2], lo[3], hi[0], hi[1], hi[2], hi[3]};
;         }
;     __builtin_amdgcn_s_setprio(1);
; #pragma unroll
;     for (int s2 = 0; s2 < 2; ++s2)
; #pragma unroll
;         for (int dt = 0; dt < 2; ++dt) o[dt] = MFMA32(vf[dt][s2], pf[s2], o[dt]);
;     __builtin_amdgcn_s_setprio(0);
; }
; template <int MM> DI void smax_step_nb(const f32x16& s, unsigned vm, float& m, float& l, f32x16 (&o)[2], bf16x8 (&pf)[2], int lane) {
;     ...
;     l = l * alpha + rs;
;     if (__builtin_amdgcn_ballot_w64(mn != m) != 0ull) {
; #pragma unroll
;         for (int i = 0; i < 16; ++i) { o[0][i] *= alpha; o[1][i] *= alpha; }
;     }
;     m = mn;
;     pack_p(p, pf);
.LBB0_870:
	v_cndmask_b32_e64 v44, v67, v68, s[36:37]
	v_add_f32_e32 v44, v65, v44
	v_cndmask_b32_e64 v45, v71, v72, s[36:37]
	v_fmac_f32_e32 v44, v190, v64
	v_add_f32_e32 v45, v70, v45
	v_fmac_f32_e32 v45, v44, v66
	v_cndmask_b32_e64 v44, v50, v51, s[36:37]
	v_add_f32_e32 v44, v49, v44
	v_cndmask_b32_e64 v42, v42, v43, s[36:37]
	v_fmac_f32_e32 v44, v45, v48
	v_add_f32_e32 v65, v41, v42
	v_fmac_f32_e32 v65, v44, v32
	v_cvt_pk_bf16_f32 v42, v52, v53
	v_cvt_pk_bf16_f32 v43, v54, v55
	v_cvt_pk_bf16_f32 v44, v56, v57
	v_cvt_pk_bf16_f32 v45, v58, v59
	ds_read_b64_tr_b16 v[48:49], v69 offset:33408
	ds_read_b64_tr_b16 v[50:51], v69 offset:34560
	ds_read_b64_tr_b16 v[54:55], v69 offset:34624
	ds_read_b64_tr_b16 v[60:61], v69 offset:33472
	ds_read_b64_tr_b16 v[46:47], v69 offset:32256
	ds_read_b64_tr_b16 v[52:53], v69 offset:35712
	ds_read_b64_tr_b16 v[58:59], v69 offset:32320
	ds_read_b64_tr_b16 v[56:57], v69 offset:35776
	v_cvt_pk_bf16_f32 v32, v33, v34
	v_cvt_pk_bf16_f32 v33, v35, v36
	v_cvt_pk_bf16_f32 v34, v37, v38
	v_cvt_pk_bf16_f32 v35, v39, v40
	s_nop 0
	s_waitcnt lgkmcnt(1)
	v_mfma_f32_32x32x16_bf16 v[16:31], v[58:61], v[42:45], v[16:31]
	v_mfma_f32_32x32x16_bf16 v[0:15], v[46:49], v[42:45], v[0:15]
	s_waitcnt lgkmcnt(0)
	v_mfma_f32_32x32x16_bf16 v[16:31], v[54:57], v[32:35], v[16:31]
	v_mfma_f32_32x32x16_bf16 v[0:15], v[50:53], v[32:35], v[0:15]
.LBB0_871:
	s_nop 0
	s_mov_b32 s10, 9
	v_mov_b32_e32 v191, v81
	v_mov_b32_e32 v190, v65

; #define LAS __attribute__((address_space(3)))
; #define MFMA32(a, b, c) __builtin_amdgcn_mfma_f32_32x32x16_bf16((a), (b), (c), 0, 0, 0)
; DI float ex2(float x) { return __builtin_amdgcn_exp2f(x); }
; template <int KS0, int KS1> DI f32x16 qk_rows(LAS const char* Kl, int row0, const bf16x8 (&qf)[4], int r, int h) {
;     f32x16 s;
; #pragma unroll
;     for (int i = 0; i < 16; ++i) s[i] = 0.f;
;     LAS const char* p = Kl + (row0 + r) * KP + 16 * h;
;     bf16x8 kf[4];
; #pragma unroll
;     for (int ks = KS0; ks < KS1; ++ks) kf[ks] = *(LAS const bf16x8*)(p + 32 * ks);
;     __builtin_amdgcn_s_setprio(1);
; #pragma unroll
;     for (int ks = KS0; ks < KS1; ++ks) s = MFMA32(kf[ks], qf[ks], s);
;     __builtin_amdgcn_s_setprio(0);
;     return s;
; }
; template <int MM> DI void smax_step_nb(const f32x16& s, unsigned vm, float& m, float& l, f32x16 (&o)[2], bf16x8 (&pf)[2], int lane) {
;     float mx = -1e30f;
; #pragma unroll
;     for (int i = 0; i < 16; ++i) mx = fmaxf(mx, s[i]);
;     if (MM == 1) mx = vm ? mx : -1e30f;
;     mx = fmaxf(mx, shx32(mx, lane));
;     const float mn = (mx > m + 8.0f) ? mx : m;
;     float mref = fmaxf(mn, -1e29f);
;     if (MM == 1) mref = vm ? mref : 3e38f;
;     const float alpha = ex2(m - mn);
;     float p[16], rs = 0.f;
; #pragma unroll
;     for (int i = 0; i < 16; ++i) { p[i] = ex2(s[i] - mref); rs += p[i]; }
;     rs += shx32(rs, lane);
;     l = l * alpha + rs;
;     if (__builtin_amdgcn_ballot_w64(mn != m) != 0ull) {
; #pragma unroll
;         for (int i = 0; i < 16; ++i) { o[0][i] *= alpha; o[1][i] *= alpha; }
;     }
;     m = mn;
;     pack_p(p, pf);
; }
.LBB0_883:
	s_mov_b64 s[52:53], 0
	s_andn2_b64 vcc, exec, s[56:57]
	v_add3_u32 v82, s11, v184, v160
	v_mov_b32_e32 v65, v190
	v_mov_b32_e32 v81, v191
	s_cbranch_vccnz .LBB0_889
	ds_read_b128 v[32:35], v82
	ds_read_b128 v[48:51], v82 offset:32
	ds_read_b128 v[52:55], v82 offset:64
	ds_read_b128 v[56:59], v82 offset:96
	s_nop 0
	s_waitcnt lgkmcnt(3)
	v_mfma_f32_32x32x16_bf16 v[32:47], v[32:35], v[112:115], 0
	s_waitcnt lgkmcnt(2)
	v_mfma_f32_32x32x16_bf16 v[32:47], v[48:51], v[116:119], v[32:47]
	s_waitcnt lgkmcnt(1)
	v_mfma_f32_32x32x16_bf16 v[32:47], v[52:55], v[120:123], v[32:47]
	s_waitcnt lgkmcnt(0)
	v_mfma_f32_32x32x16_bf16 v[32:47], v[56:59], v[124:127], v[32:47]
	s_nop 0
	ds_read_b128 v[48:51], v82 offset:4608
	ds_read_b128 v[52:55], v82 offset:4640
	ds_read_b128 v[56:59], v82 offset:4672
	ds_read_b128 v[60:63], v82 offset:4704
	s_nop 0
	s_waitcnt lgkmcnt(3)
	v_mfma_f32_32x32x16_bf16 v[64:79], v[48:51], v[112:115], 0
	s_waitcnt lgkmcnt(2)
	v_mfma_f32_32x32x16_bf16 v[64:79], v[52:55], v[116:119], v[64:79]
	s_waitcnt lgkmcnt(1)
	v_mfma_f32_32x32x16_bf16 v[64:79], v[56:59], v[120:123], v[64:79]
	s_waitcnt lgkmcnt(0)
	v_mfma_f32_32x32x16_bf16 v[64:79], v[60:63], v[124:127], v[64:79]
	s_nop 0
	v_max3_f32 v48, v32, s15, v33
	v_max3_f32 v48, v48, v34, v35
	v_max3_f32 v48, v48, v36, v37
	v_max3_f32 v48, v48, v38, v39
	v_max3_f32 v48, v48, v40, v41
	v_max3_f32 v48, v48, v42, v43
	v_max3_f32 v48, v48, v44, v45
	v_max3_f32 v48, v48, v46, v47
	v_cndmask_b32_e64 v48, v208, v48, s[38:39]
	v_mov_b32_e32 v49, v48
	v_mov_b32_e32 v50, v48
	s_nop 1
	v_permlane32_swap_b32_e32 v49, v50
	v_max_f32_e32 v48, v49, v50
	v_add_f32_e32 v49, 0x41000000, v191
	v_cmp_gt_f32_e32 vcc, v48, v49
	s_nop 1
	v_cndmask_b32_e32 v87, v191, v48, vcc
	v_max_f32_e32 v48, 0xefa18f08, v87
	v_cndmask_b32_e64 v48, v209, v48, s[38:39]
	v_sub_f32_e32 v32, v32, v48
	v_exp_f32_e32 v81, v32
	v_sub_f32_e32 v32, v33, v48
	v_exp_f32_e32 v86, v32
	v_sub_f32_e32 v32, v34, v48
	v_exp_f32_e32 v88, v32
	v_sub_f32_e32 v32, v35, v48
	v_exp_f32_e32 v89, v32
	v_sub_f32_e32 v33, v36, v48
	v_exp_f32_e32 v90, v33
	v_sub_f32_e32 v33, v37, v48
	v_add_f32_e32 v32, v86, v81
	v_exp_f32_e32 v91, v33
	v_sub_f32_e32 v33, v38, v48
	v_add_f32_e32 v32, v88, v32
	v_exp_f32_e32 v92, v33
	v_sub_f32_e32 v33, v39, v48
	v_add_f32_e32 v32, v89, v32
	v_exp_f32_e32 v93, v33
	v_sub_f32_e32 v33, v40, v48
	v_add_f32_e32 v32, v90, v32
	v_exp_f32_e32 v94, v33
	v_sub_f32_e32 v33, v41, v48
	v_add_f32_e32 v32, v91, v32
	v_exp_f32_e32 v95, v33
	v_sub_f32_e32 v33, v42, v48
	v_add_f32_e32 v32, v92, v32
	v_exp_f32_e32 v128, v33
	v_sub_f32_e32 v33, v43, v48
	v_add_f32_e32 v32, v93, v32
	v_exp_f32_e32 v129, v33
	v_sub_f32_e32 v33, v44, v48
	v_add_f32_e32 v32, v94, v32
	v_exp_f32_e32 v130, v33
	v_sub_f32_e32 v33, v45, v48
	v_add_f32_e32 v32, v95, v32
	v_exp_f32_e32 v131, v33
	v_sub_f32_e32 v33, v46, v48
	v_add_f32_e32 v32, v128, v32
	v_exp_f32_e32 v132, v33
	v_sub_f32_e32 v33, v47, v48
	v_add_f32_e32 v32, v129, v32
	v_exp_f32_e32 v133, v33
	v_add_f32_e32 v32, v130, v32
	v_sub_f32_e32 v49, v191, v87
	v_add_f32_e32 v32, v131, v32
	v_add_f32_e32 v32, v132, v32
	v_exp_f32_e32 v80, v49
	v_add_f32_e32 v83, v133, v32
	v_mov_b32_e32 v84, v83
	v_mov_b32_e32 v85, v83
	v_mov_b64_e32 v[62:63], v[30:31]
	s_nop 0
	v_permlane32_swap_b32_e32 v84, v85
	v_cmp_neq_f32_e32 vcc, v87, v191
	v_mov_b64_e32 v[60:61], v[28:29]
	v_mov_b64_e32 v[58:59], v[26:27]
	v_mov_b64_e32 v[56:57], v[24:25]
	v_mov_b64_e32 v[54:55], v[22:23]
	v_mov_b64_e32 v[52:53], v[20:21]
	v_mov_b64_e32 v[50:51], v[18:19]
	v_mov_b64_e32 v[48:49], v[16:17]
	v_mov_b64_e32 v[46:47], v[14:15]
	v_mov_b64_e32 v[44:45], v[12:13]
	v_mov_b64_e32 v[42:43], v[10:11]
	v_mov_b64_e32 v[40:41], v[8:9]
	v_mov_b64_e32 v[38:39], v[6:7]
	v_mov_b64_e32 v[36:37], v[4:5]
	v_mov_b64_e32 v[34:35], v[2:3]
	v_mov_b64_e32 v[32:33], v[0:1]
	s_cbranch_vccz .LBB0_886
	v_pk_mul_f32 v[62:63], v[30:31], v[80:81] op_sel_hi:[1,0]
	v_pk_mul_f32 v[60:61], v[28:29], v[80:81] op_sel_hi:[1,0]
	v_pk_mul_f32 v[58:59], v[26:27], v[80:81] op_sel_hi:[1,0]
	v_pk_mul_f32 v[56:57], v[24:25], v[80:81] op_sel_hi:[1,0]
	v_pk_mul_f32 v[54:55], v[22:23], v[80:81] op_sel_hi:[1,0]
	v_pk_mul_f32 v[52:53], v[20:21], v[80:81] op_sel_hi:[1,0]
	v_pk_mul_f32 v[50:51], v[18:19], v[80:81] op_sel_hi:[1,0]
	v_pk_mul_f32 v[48:49], v[16:17], v[80:81] op_sel_hi:[1,0]
	v_pk_mul_f32 v[46:47], v[14:15], v[80:81] op_sel_hi:[1,0]
	v_pk_mul_f32 v[44:45], v[12:13], v[80:81] op_sel_hi:[1,0]
	v_pk_mul_f32 v[42:43], v[10:11], v[80:81] op_sel_hi:[1,0]
	v_pk_mul_f32 v[40:41], v[8:9], v[80:81] op_sel_hi:[1,0]
	v_pk_mul_f32 v[38:39], v[6:7], v[80:81] op_sel_hi:[1,0]
	v_pk_mul_f32 v[36:37], v[4:5], v[80:81] op_sel_hi:[1,0]
	v_pk_mul_f32 v[34:35], v[2:3], v[80:81] op_sel_hi:[1,0]
	v_pk_mul_f32 v[32:33], v[0:1], v[80:81] op_sel_hi:[1,0]
; #define LAS __attribute__((address_space(3)))
; #define MFMA32(a, b, c) __builtin_amdgcn_mfma_f32_32x32x16_bf16((a), (b), (c), 0, 0, 0)
; DI s16x4 vtr(LAS const char* p) { return __builtin_bit_cast(s16x4, __builtin_amdgcn_ds_read_tr16_b64_v4i16((LAS v4i16_t*)p)); }
; DI float ex2(float x) { return __builtin_amdgcn_exp2f(x); }
; DI void pv_rows(f32x16 (&o)[2], LAS const char* Vl, int row0, const bf16x8 (&pf)[2], int lane) {
;     const int h = lane >> 5, i = lane & 15, grp = (lane >> 4) & 1;
;     LAS const char* base = Vl + (row0 + 4 * h + (i >> 2)) * KP + grp * 32 + (i & 3) * 8;
;     bf16x8 vf[2][2];
; #pragma unroll
;     for (int dt = 0; dt < 2; ++dt)
; #pragma unroll
;         for (int s2 = 0; s2 < 2; ++s2) {
;             const s16x4 lo = vtr(base + (16 * s2) * KP + dt * 64), hi = vtr(base + (16 * s2 + 8) * KP + dt * 64);
;             vf[dt][s2] = (bf16x8){lo[0], lo[1], lo[2], lo[3], hi[0], hi[1], hi[2], hi[3]};
;         }
;     __builtin_amdgcn_s_setprio(1);
; #pragma unroll
;     for (int s2 = 0; s2 < 2; ++s2)
; #pragma unroll
;         for (int dt = 0; dt < 2; ++dt) o[dt] = MFMA32(vf[dt][s2], pf[s2], o[dt]);
;     __builtin_amdgcn_s_setprio(0);
; }
; template <int MM> DI void smax_step_nb(const f32x16& s, unsigned vm, float& m, float& l, f32x16 (&o)[2], bf16x8 (&pf)[2], int lane) {
;     float mx = -1e30f;
; #pragma unroll
;     for (int i = 0; i < 16; ++i) mx = fmaxf(mx, s[i]);
;     if (MM == 1) mx = vm ? mx : -1e30f;
;     mx = fmaxf(mx, shx32(mx, lane));
;     const float mn = (mx > m + 8.0f) ? mx : m;
;     float mref = fmaxf(mn, -1e29f);
;     if (MM == 1) mref = vm ? mref : 3e38f;
;     const float alpha = ex2(m - mn);
;     float p[16], rs = 0.f;
; #pragma unroll
;     for (int i = 0; i < 16; ++i) { p[i] = ex2(s[i] - mref); rs += p[i]; }
;     rs += shx32(rs, lane);
;     l = l * alpha + rs;
;     if (__builtin_amdgcn_ballot_w64(mn != m) != 0ull) {
; #pragma unroll
;         for (int i = 0; i < 16; ++i) { o[0][i] *= alpha; o[1][i] *= alpha; }
;     }
;     m = mn;
;     pack_p(p, pf);
; }
.LBB0_886:
	v_cvt_pk_bf16_f32 v134, v81, v86
	v_add3_u32 v81, s11, v186, v187
	v_add_u32_e32 v86, v81, v188
	v_cvt_pk_bf16_f32 v135, v88, v89
	v_cvt_pk_bf16_f32 v136, v90, v91
	v_cvt_pk_bf16_f32 v137, v92, v93
	v_cvt_pk_bf16_f32 v88, v94, v95
	v_cvt_pk_bf16_f32 v89, v128, v129
	v_cvt_pk_bf16_f32 v90, v130, v131
	ds_read_b64_tr_b16 v[92:93], v86 offset:9216
	ds_read_b64_tr_b16 v[94:95], v86 offset:10368
	ds_read_b64_tr_b16 v[128:129], v86 offset:11520
	ds_read_b64_tr_b16 v[130:131], v86 offset:12672
	ds_read_b64_tr_b16 v[138:139], v86 offset:9280
	ds_read_b64_tr_b16 v[140:141], v86 offset:10432
	ds_read_b64_tr_b16 v[142:143], v86 offset:11584
	ds_read_b64_tr_b16 v[144:145], v86 offset:12736
	v_cvt_pk_bf16_f32 v91, v132, v133
	s_nop 0
	s_waitcnt lgkmcnt(6)
	v_mfma_f32_32x32x16_bf16 v[32:47], v[92:95], v[134:137], v[32:47]
	s_waitcnt lgkmcnt(2)
	v_mfma_f32_32x32x16_bf16 v[48:63], v[138:141], v[134:137], v[48:63]
	v_mfma_f32_32x32x16_bf16 v[32:47], v[128:131], v[88:91], v[32:47]
	s_waitcnt lgkmcnt(0)
	v_mfma_f32_32x32x16_bf16 v[48:63], v[142:145], v[88:91], v[48:63]
	s_nop 0
	v_max3_f32 v81, v64, s15, v65
	v_max3_f32 v81, v81, v66, v67
	v_max3_f32 v81, v81, v68, v69
	v_max3_f32 v81, v81, v70, v71
	v_max3_f32 v81, v81, v72, v73
	v_max3_f32 v81, v81, v74, v75
	v_max3_f32 v81, v81, v76, v77
	v_max3_f32 v81, v81, v78, v79
	v_cndmask_b32_e64 v81, v208, v81, s[38:39]
	v_mov_b32_e32 v88, v81
	v_mov_b32_e32 v89, v81
	s_nop 1
	v_permlane32_swap_b32_e32 v88, v89
	v_max_f32_e32 v81, v88, v89
	v_add_f32_e32 v88, 0x41000000, v87
	v_cmp_gt_f32_e32 vcc, v81, v88
	s_nop 1
	v_cndmask_b32_e32 v81, v87, v81, vcc
	v_max_f32_e32 v88, 0xefa18f08, v81
	v_cndmask_b32_e64 v90, v209, v88, s[38:39]
	v_sub_f32_e32 v64, v64, v90
	v_exp_f32_e32 v88, v64
	v_sub_f32_e32 v64, v65, v90
	v_exp_f32_e32 v89, v64
	v_sub_f32_e32 v64, v66, v90
	v_exp_f32_e32 v66, v64
	v_sub_f32_e32 v64, v67, v90
	v_exp_f32_e32 v67, v64
	v_sub_f32_e32 v65, v68, v90
	v_exp_f32_e32 v68, v65
	v_sub_f32_e32 v65, v69, v90
	v_add_f32_e32 v64, v89, v88
	v_exp_f32_e32 v69, v65
	v_sub_f32_e32 v65, v70, v90
	v_add_f32_e32 v64, v66, v64
	v_exp_f32_e32 v70, v65
	v_sub_f32_e32 v65, v71, v90
	v_add_f32_e32 v64, v67, v64
	v_exp_f32_e32 v71, v65
	v_sub_f32_e32 v65, v72, v90
	v_add_f32_e32 v64, v68, v64
	v_exp_f32_e32 v72, v65
	v_sub_f32_e32 v65, v73, v90
	v_add_f32_e32 v64, v69, v64
	v_exp_f32_e32 v73, v65
	v_sub_f32_e32 v65, v74, v90
	v_add_f32_e32 v64, v70, v64
	v_exp_f32_e32 v74, v65
	v_sub_f32_e32 v65, v75, v90
	v_add_f32_e32 v64, v71, v64
	v_exp_f32_e32 v75, v65
	v_sub_f32_e32 v65, v76, v90
	v_add_f32_e32 v64, v72, v64
	v_exp_f32_e32 v76, v65
	v_sub_f32_e32 v65, v77, v90
	v_add_f32_e32 v64, v73, v64
	v_exp_f32_e32 v77, v65
	v_sub_f32_e32 v65, v78, v90
	v_add_f32_e32 v64, v74, v64
	v_exp_f32_e32 v78, v65
	v_sub_f32_e32 v65, v79, v90
	v_add_f32_e32 v64, v75, v64
	v_exp_f32_e32 v79, v65
	v_add_f32_e32 v64, v76, v64
	v_add_f32_e32 v64, v77, v64
	v_sub_f32_e32 v91, v87, v81
	v_add_f32_e32 v64, v78, v64
	v_add_f32_e32 v65, v79, v64
	v_exp_f32_e32 v64, v91
	v_mov_b32_e32 v90, v65
	v_mov_b32_e32 v91, v65
	s_nop 1
	v_permlane32_swap_b32_e32 v90, v91
	v_cmp_neq_f32_e32 vcc, v81, v87
	s_cbranch_vccz .LBB0_888
	v_pk_mul_f32 v[62:63], v[62:63], v[64:65] op_sel_hi:[1,0]
	v_pk_mul_f32 v[60:61], v[60:61], v[64:65] op_sel_hi:[1,0]
	v_pk_mul_f32 v[58:59], v[58:59], v[64:65] op_sel_hi:[1,0]
	v_pk_mul_f32 v[56:57], v[56:57], v[64:65] op_sel_hi:[1,0]
	v_pk_mul_f32 v[54:55], v[54:55], v[64:65] op_sel_hi:[1,0]
	v_pk_mul_f32 v[52:53], v[52:53], v[64:65] op_sel_hi:[1,0]
	v_pk_mul_f32 v[50:51], v[50:51], v[64:65] op_sel_hi:[1,0]
	v_pk_mul_f32 v[48:49], v[48:49], v[64:65] op_sel_hi:[1,0]
	v_pk_mul_f32 v[46:47], v[46:47], v[64:65] op_sel_hi:[1,0]
	v_pk_mul_f32 v[44:45], v[44:45], v[64:65] op_sel_hi:[1,0]
	v_pk_mul_f32 v[42:43], v[42:43], v[64:65] op_sel_hi:[1,0]
	v_pk_mul_f32 v[40:41], v[40:41], v[64:65] op_sel_hi:[1,0]
	v_pk_mul_f32 v[38:39], v[38:39], v[64:65] op_sel_hi:[1,0]
	v_pk_mul_f32 v[36:37], v[36:37], v[64:65] op_sel_hi:[1,0]
	v_pk_mul_f32 v[34:35], v[34:35], v[64:65] op_sel_hi:[1,0]
	v_pk_mul_f32 v[32:33], v[32:33], v[64:65] op_sel_hi:[1,0]
.LBB0_888:
	v_cndmask_b32_e64 v84, v84, v85, s[36:37]
	v_add_f32_e32 v83, v83, v84
	v_fmac_f32_e32 v83, v190, v80
	v_cndmask_b32_e64 v80, v90, v91, s[36:37]
	v_cvt_pk_bf16_f32 v88, v88, v89
	v_cvt_pk_bf16_f32 v89, v66, v67
	v_cvt_pk_bf16_f32 v90, v68, v69
	v_cvt_pk_bf16_f32 v91, v70, v71
	v_cvt_pk_bf16_f32 v66, v72, v73
	v_cvt_pk_bf16_f32 v67, v74, v75
	v_cvt_pk_bf16_f32 v68, v76, v77
	ds_read_b64_tr_b16 v[70:71], v86 offset:13824
	ds_read_b64_tr_b16 v[72:73], v86 offset:14976
	ds_read_b64_tr_b16 v[74:75], v86 offset:16128
	ds_read_b64_tr_b16 v[76:77], v86 offset:17280
	ds_read_b64_tr_b16 v[92:93], v86 offset:13888
	ds_read_b64_tr_b16 v[94:95], v86 offset:15040
	ds_read_b64_tr_b16 v[84:85], v86 offset:16192
	ds_read_b64_tr_b16 v[86:87], v86 offset:17344
	v_add_f32_e32 v65, v65, v80
	v_fmac_f32_e32 v65, v83, v64
	v_cvt_pk_bf16_f32 v69, v78, v79
	s_nop 0
	s_waitcnt lgkmcnt(6)
	v_mfma_f32_32x32x16_bf16 v[32:47], v[70:73], v[88:91], v[32:47]
	s_mov_b64 s[54:55], 0
	s_mov_b64 s[52:53], -1
	s_waitcnt lgkmcnt(2)
	v_mfma_f32_32x32x16_bf16 v[48:63], v[92:95], v[88:91], v[48:63]
	v_mfma_f32_32x32x16_bf16 v[32:47], v[74:77], v[66:69], v[32:47]
	s_waitcnt lgkmcnt(0)
	v_mfma_f32_32x32x16_bf16 v[48:63], v[84:87], v[66:69], v[48:63]
; #define LAS __attribute__((address_space(3)))
; #define MFMA32(a, b, c) __builtin_amdgcn_mfma_f32_32x32x16_bf16((a), (b), (c), 0, 0, 0)
; DI float ex2(float x) { return __builtin_amdgcn_exp2f(x); }
; template <int KS0, int KS1> DI f32x16 qk_rows(LAS const char* Kl, int row0, const bf16x8 (&qf)[4], int r, int h) {
;     f32x16 s;
; #pragma unroll
;     for (int i = 0; i < 16; ++i) s[i] = 0.f;
;     LAS const char* p = Kl + (row0 + r) * KP + 16 * h;
;     bf16x8 kf[4];
; #pragma unroll
;     for (int ks = KS0; ks < KS1; ++ks) kf[ks] = *(LAS const bf16x8*)(p + 32 * ks);
;     __builtin_amdgcn_s_setprio(1);
; #pragma unroll
;     for (int ks = KS0; ks < KS1; ++ks) s = MFMA32(kf[ks], qf[ks], s);
;     __builtin_amdgcn_s_setprio(0);
;     return s;
; }
; template <int MM> DI void smax_step_nb(const f32x16& s, unsigned vm, float& m, float& l, f32x16 (&o)[2], bf16x8 (&pf)[2], int lane) {
;     float mx = -1e30f;
; #pragma unroll
;     for (int i = 0; i < 16; ++i) mx = fmaxf(mx, s[i]);
;     if (MM == 1) mx = vm ? mx : -1e30f;
;     mx = fmaxf(mx, shx32(mx, lane));
;     const float mn = (mx > m + 8.0f) ? mx : m;
;     float mref = fmaxf(mn, -1e29f);
;     if (MM == 1) mref = vm ? mref : 3e38f;
;     const float alpha = ex2(m - mn);
;     float p[16], rs = 0.f;
; #pragma unroll
;     for (int i = 0; i < 16; ++i) { p[i] = ex2(s[i] - mref); rs += p[i]; }
;     rs += shx32(rs, lane);
;     l = l * alpha + rs;
;     if (__builtin_amdgcn_ballot_w64(mn != m) != 0ull) {
; #pragma unroll
;         for (int i = 0; i < 16; ++i) { o[0][i] *= alpha; o[1][i] *= alpha; }
;     }
;     m = mn;
;     pack_p(p, pf);
; }
.LBB0_889:
	s_and_b64 vcc, exec, s[54:55]
	s_cbranch_vccz .LBB0_895
	s_nop 7
	ds_read_b128 v[32:35], v82
	s_nop 0
	ds_read_b128 v[48:51], v82 offset:32
	ds_read_b128 v[52:55], v82 offset:64
	ds_read_b128 v[56:59], v82 offset:96
	s_nop 0
	s_waitcnt lgkmcnt(3)
	v_mfma_f32_32x32x16_bf16 v[32:47], v[32:35], v[112:115], 0
	s_waitcnt lgkmcnt(2)
	v_mfma_f32_32x32x16_bf16 v[32:47], v[48:51], v[116:119], v[32:47]
	s_waitcnt lgkmcnt(1)
	v_mfma_f32_32x32x16_bf16 v[32:47], v[52:55], v[120:123], v[32:47]
	s_waitcnt lgkmcnt(0)
	v_mfma_f32_32x32x16_bf16 v[32:47], v[56:59], v[124:127], v[32:47]
	s_nop 0
	ds_read_b128 v[48:51], v82 offset:4608
	ds_read_b128 v[52:55], v82 offset:4640
	ds_read_b128 v[56:59], v82 offset:4672
	ds_read_b128 v[60:63], v82 offset:4704
	s_nop 0
	s_waitcnt lgkmcnt(3)
	v_mfma_f32_32x32x16_bf16 v[64:79], v[48:51], v[112:115], 0
	s_waitcnt lgkmcnt(2)
	v_mfma_f32_32x32x16_bf16 v[64:79], v[52:55], v[116:119], v[64:79]
	s_waitcnt lgkmcnt(1)
	v_mfma_f32_32x32x16_bf16 v[64:79], v[56:59], v[120:123], v[64:79]
	s_waitcnt lgkmcnt(0)
	v_mfma_f32_32x32x16_bf16 v[64:79], v[60:63], v[124:127], v[64:79]
	s_nop 0
	v_max3_f32 v48, v32, s15, v33
	v_max3_f32 v48, v48, v34, v35
	v_max3_f32 v48, v48, v36, v37
	v_max3_f32 v48, v48, v38, v39
	v_max3_f32 v48, v48, v40, v41
	v_max3_f32 v48, v48, v42, v43
	v_max3_f32 v48, v48, v44, v45
	v_max3_f32 v48, v48, v46, v47
	v_mov_b32_e32 v49, v48
	v_mov_b32_e32 v50, v48
	s_nop 1
	v_permlane32_swap_b32_e32 v49, v50
	v_max_f32_e32 v48, v49, v50
	v_add_f32_e32 v49, 0x41000000, v191
	v_cmp_gt_f32_e32 vcc, v48, v49
	s_nop 1
	v_cndmask_b32_e32 v86, v191, v48, vcc
	v_max_f32_e32 v48, 0xefa18f08, v86
	v_sub_f32_e32 v32, v32, v48
	v_exp_f32_e32 v81, v32
	v_sub_f32_e32 v32, v33, v48
	v_exp_f32_e32 v85, v32
	v_sub_f32_e32 v32, v34, v48
	v_exp_f32_e32 v87, v32
	v_sub_f32_e32 v32, v35, v48
	v_exp_f32_e32 v88, v32
	v_sub_f32_e32 v33, v36, v48
	v_exp_f32_e32 v89, v33
	v_sub_f32_e32 v33, v37, v48
	v_add_f32_e32 v32, v85, v81
	v_exp_f32_e32 v90, v33
	v_sub_f32_e32 v33, v38, v48
	v_add_f32_e32 v32, v87, v32
	v_exp_f32_e32 v91, v33
	v_sub_f32_e32 v33, v39, v48
	v_add_f32_e32 v32, v88, v32
	v_exp_f32_e32 v92, v33
	v_sub_f32_e32 v33, v40, v48
	v_add_f32_e32 v32, v89, v32
	v_exp_f32_e32 v93, v33
	v_sub_f32_e32 v33, v41, v48
	v_add_f32_e32 v32, v90, v32
	v_exp_f32_e32 v94, v33
	v_sub_f32_e32 v33, v42, v48
	v_add_f32_e32 v32, v91, v32
	v_exp_f32_e32 v95, v33
	v_sub_f32_e32 v33, v43, v48
	v_add_f32_e32 v32, v92, v32
	v_exp_f32_e32 v128, v33
	v_sub_f32_e32 v33, v44, v48
	v_add_f32_e32 v32, v93, v32
	v_exp_f32_e32 v129, v33
	v_sub_f32_e32 v33, v45, v48
	v_add_f32_e32 v32, v94, v32
	v_exp_f32_e32 v130, v33
	v_sub_f32_e32 v33, v46, v48
	v_add_f32_e32 v32, v95, v32
	v_exp_f32_e32 v131, v33
	v_sub_f32_e32 v33, v47, v48
	v_add_f32_e32 v32, v128, v32
	v_exp_f32_e32 v132, v33
	v_add_f32_e32 v32, v129, v32
	v_sub_f32_e32 v49, v191, v86
	v_add_f32_e32 v32, v130, v32
	v_add_f32_e32 v32, v131, v32
	v_exp_f32_e32 v80, v49
	v_add_f32_e32 v82, v132, v32
	v_mov_b32_e32 v83, v82
	v_mov_b32_e32 v84, v82
	v_mov_b64_e32 v[62:63], v[30:31]
	s_nop 0
	v_permlane32_swap_b32_e32 v83, v84
	v_cmp_neq_f32_e32 vcc, v86, v191
	v_mov_b64_e32 v[60:61], v[28:29]
	v_mov_b64_e32 v[58:59], v[26:27]
	v_mov_b64_e32 v[56:57], v[24:25]
	v_mov_b64_e32 v[54:55], v[22:23]
	v_mov_b64_e32 v[52:53], v[20:21]
	v_mov_b64_e32 v[50:51], v[18:19]
	v_mov_b64_e32 v[48:49], v[16:17]
	v_mov_b64_e32 v[46:47], v[14:15]
	v_mov_b64_e32 v[44:45], v[12:13]
	v_mov_b64_e32 v[42:43], v[10:11]
	v_mov_b64_e32 v[40:41], v[8:9]
	v_mov_b64_e32 v[38:39], v[6:7]
	v_mov_b64_e32 v[36:37], v[4:5]
	v_mov_b64_e32 v[34:35], v[2:3]
	v_mov_b64_e32 v[32:33], v[0:1]
	s_cbranch_vccz .LBB0_892
	v_pk_mul_f32 v[62:63], v[30:31], v[80:81] op_sel_hi:[1,0]
	v_pk_mul_f32 v[60:61], v[28:29], v[80:81] op_sel_hi:[1,0]
	v_pk_mul_f32 v[58:59], v[26:27], v[80:81] op_sel_hi:[1,0]
	v_pk_mul_f32 v[56:57], v[24:25], v[80:81] op_sel_hi:[1,0]
	v_pk_mul_f32 v[54:55], v[22:23], v[80:81] op_sel_hi:[1,0]
	v_pk_mul_f32 v[52:53], v[20:21], v[80:81] op_sel_hi:[1,0]
	v_pk_mul_f32 v[50:51], v[18:19], v[80:81] op_sel_hi:[1,0]
	v_pk_mul_f32 v[48:49], v[16:17], v[80:81] op_sel_hi:[1,0]
	v_pk_mul_f32 v[46:47], v[14:15], v[80:81] op_sel_hi:[1,0]
	v_pk_mul_f32 v[44:45], v[12:13], v[80:81] op_sel_hi:[1,0]
	v_pk_mul_f32 v[42:43], v[10:11], v[80:81] op_sel_hi:[1,0]
	v_pk_mul_f32 v[40:41], v[8:9], v[80:81] op_sel_hi:[1,0]
	v_pk_mul_f32 v[38:39], v[6:7], v[80:81] op_sel_hi:[1,0]
	v_pk_mul_f32 v[36:37], v[4:5], v[80:81] op_sel_hi:[1,0]
	v_pk_mul_f32 v[34:35], v[2:3], v[80:81] op_sel_hi:[1,0]
	v_pk_mul_f32 v[32:33], v[0:1], v[80:81] op_sel_hi:[1,0]
; #define LAS __attribute__((address_space(3)))
; #define MFMA32(a, b, c) __builtin_amdgcn_mfma_f32_32x32x16_bf16((a), (b), (c), 0, 0, 0)
; DI s16x4 vtr(LAS const char* p) { return __builtin_bit_cast(s16x4, __builtin_amdgcn_ds_read_tr16_b64_v4i16((LAS v4i16_t*)p)); }
; DI float ex2(float x) { return __builtin_amdgcn_exp2f(x); }
; DI void pv_rows(f32x16 (&o)[2], LAS const char* Vl, int row0, const bf16x8 (&pf)[2], int lane) {
;     const int h = lane >> 5, i = lane & 15, grp = (lane >> 4) & 1;
;     LAS const char* base = Vl + (row0 + 4 * h + (i >> 2)) * KP + grp * 32 + (i & 3) * 8;
;     bf16x8 vf[2][2];
; #pragma unroll
;     for (int dt = 0; dt < 2; ++dt)
; #pragma unroll
;         for (int s2 = 0; s2 < 2; ++s2) {
;             const s16x4 lo = vtr(base + (16 * s2) * KP + dt * 64), hi = vtr(base + (16 * s2 + 8) * KP + dt * 64);
;             vf[dt][s2] = (bf16x8){lo[0], lo[1], lo[2], lo[3], hi[0], hi[1], hi[2], hi[3]};
;         }
;     __builtin_amdgcn_s_setprio(1);
; #pragma unroll
;     for (int s2 = 0; s2 < 2; ++s2)
; #pragma unroll
;         for (int dt = 0; dt < 2; ++dt) o[dt] = MFMA32(vf[dt][s2], pf[s2], o[dt]);
;     __builtin_amdgcn_s_setprio(0);
; }
; template <int MM> DI void smax_step_nb(const f32x16& s, unsigned vm, float& m, float& l, f32x16 (&o)[2], bf16x8 (&pf)[2], int lane) {
;     float mx = -1e30f;
; #pragma unroll
;     for (int i = 0; i < 16; ++i) mx = fmaxf(mx, s[i]);
;     if (MM == 1) mx = vm ? mx : -1e30f;
;     mx = fmaxf(mx, shx32(mx, lane));
;     const float mn = (mx > m + 8.0f) ? mx : m;
;     float mref = fmaxf(mn, -1e29f);
;     if (MM == 1) mref = vm ? mref : 3e38f;
;     const float alpha = ex2(m - mn);
;     float p[16], rs = 0.f;
; #pragma unroll
;     for (int i = 0; i < 16; ++i) { p[i] = ex2(s[i] - mref); rs += p[i]; }
;     rs += shx32(rs, lane);
;     l = l * alpha + rs;
;     if (__builtin_amdgcn_ballot_w64(mn != m) != 0ull) {
; #pragma unroll
;         for (int i = 0; i < 16; ++i) { o[0][i] *= alpha; o[1][i] *= alpha; }
;     }
;     m = mn;
;     pack_p(p, pf);
; }
.LBB0_892:
	v_cvt_pk_bf16_f32 v134, v81, v85
	v_add3_u32 v81, s11, v186, v187
	v_add_u32_e32 v85, v81, v188
	v_cvt_pk_bf16_f32 v135, v87, v88
	v_cvt_pk_bf16_f32 v136, v89, v90
	v_cvt_pk_bf16_f32 v137, v91, v92
	v_cvt_pk_bf16_f32 v88, v93, v94
	v_cvt_pk_bf16_f32 v89, v95, v128
	v_cvt_pk_bf16_f32 v90, v129, v130
	v_cvt_pk_bf16_f32 v91, v131, v132
	ds_read_b64_tr_b16 v[92:93], v85 offset:9216
	ds_read_b64_tr_b16 v[94:95], v85 offset:10368
	ds_read_b64_tr_b16 v[128:129], v85 offset:11520
	ds_read_b64_tr_b16 v[130:131], v85 offset:12672
	ds_read_b64_tr_b16 v[138:139], v85 offset:9280
	ds_read_b64_tr_b16 v[140:141], v85 offset:10432
	ds_read_b64_tr_b16 v[142:143], v85 offset:11584
	ds_read_b64_tr_b16 v[144:145], v85 offset:12736
	s_nop 0
	s_waitcnt lgkmcnt(6)
	v_mfma_f32_32x32x16_bf16 v[32:47], v[92:95], v[134:137], v[32:47]
	s_waitcnt lgkmcnt(2)
	v_mfma_f32_32x32x16_bf16 v[48:63], v[138:141], v[134:137], v[48:63]
	v_mfma_f32_32x32x16_bf16 v[32:47], v[128:131], v[88:91], v[32:47]
	s_waitcnt lgkmcnt(0)
	v_mfma_f32_32x32x16_bf16 v[48:63], v[142:145], v[88:91], v[48:63]
	s_nop 0
	v_max3_f32 v81, v64, s15, v65
	v_max3_f32 v81, v81, v66, v67
	v_max3_f32 v81, v81, v68, v69
	v_max3_f32 v81, v81, v70, v71
	v_max3_f32 v81, v81, v72, v73
	v_max3_f32 v81, v81, v74, v75
	v_max3_f32 v81, v81, v76, v77
	v_max3_f32 v81, v81, v78, v79
	v_mov_b32_e32 v87, v81
	v_mov_b32_e32 v88, v81
	s_nop 1
	v_permlane32_swap_b32_e32 v87, v88
	v_max_f32_e32 v81, v87, v88
	v_add_f32_e32 v87, 0x41000000, v86
	v_cmp_gt_f32_e32 vcc, v81, v87
	s_nop 1
	v_cndmask_b32_e32 v81, v86, v81, vcc
	v_max_f32_e32 v89, 0xefa18f08, v81
	v_sub_f32_e32 v64, v64, v89
	v_exp_f32_e32 v87, v64
	v_sub_f32_e32 v64, v65, v89
	v_exp_f32_e32 v88, v64
	v_sub_f32_e32 v64, v66, v89
	v_exp_f32_e32 v66, v64
	v_sub_f32_e32 v64, v67, v89
	v_exp_f32_e32 v67, v64
	v_sub_f32_e32 v65, v68, v89
	v_exp_f32_e32 v68, v65
	v_sub_f32_e32 v65, v69, v89
	v_add_f32_e32 v64, v88, v87
	v_exp_f32_e32 v69, v65
	v_sub_f32_e32 v65, v70, v89
	v_add_f32_e32 v64, v66, v64
	v_exp_f32_e32 v70, v65
	v_sub_f32_e32 v65, v71, v89
	v_add_f32_e32 v64, v67, v64
	v_exp_f32_e32 v71, v65
	v_sub_f32_e32 v65, v72, v89
	v_add_f32_e32 v64, v68, v64
	v_exp_f32_e32 v72, v65
	v_sub_f32_e32 v65, v73, v89
	v_add_f32_e32 v64, v69, v64
	v_exp_f32_e32 v73, v65
	v_sub_f32_e32 v65, v74, v89
	v_add_f32_e32 v64, v70, v64
	v_exp_f32_e32 v74, v65
	v_sub_f32_e32 v65, v75, v89
	v_add_f32_e32 v64, v71, v64
	v_exp_f32_e32 v75, v65
	v_sub_f32_e32 v65, v76, v89
	v_add_f32_e32 v64, v72, v64
	v_exp_f32_e32 v76, v65
	v_sub_f32_e32 v65, v77, v89
	v_add_f32_e32 v64, v73, v64
	v_exp_f32_e32 v77, v65
	v_sub_f32_e32 v65, v78, v89
	v_add_f32_e32 v64, v74, v64
	v_exp_f32_e32 v78, v65
	v_sub_f32_e32 v65, v79, v89
	v_add_f32_e32 v64, v75, v64
	v_exp_f32_e32 v79, v65
	v_add_f32_e32 v64, v76, v64
	v_add_f32_e32 v64, v77, v64
	v_sub_f32_e32 v90, v86, v81
	v_add_f32_e32 v64, v78, v64
	v_add_f32_e32 v65, v79, v64
	v_exp_f32_e32 v64, v90
	v_mov_b32_e32 v89, v65
	v_mov_b32_e32 v90, v65
	s_nop 1
	v_permlane32_swap_b32_e32 v89, v90
	v_cmp_neq_f32_e32 vcc, v81, v86
	s_cbranch_vccz .LBB0_894
	v_pk_mul_f32 v[62:63], v[62:63], v[64:65] op_sel_hi:[1,0]
	v_pk_mul_f32 v[60:61], v[60:61], v[64:65] op_sel_hi:[1,0]
	v_pk_mul_f32 v[58:59], v[58:59], v[64:65] op_sel_hi:[1,0]
	v_pk_mul_f32 v[56:57], v[56:57], v[64:65] op_sel_hi:[1,0]
	v_pk_mul_f32 v[54:55], v[54:55], v[64:65] op_sel_hi:[1,0]
	v_pk_mul_f32 v[52:53], v[52:53], v[64:65] op_sel_hi:[1,0]
	v_pk_mul_f32 v[50:51], v[50:51], v[64:65] op_sel_hi:[1,0]
	v_pk_mul_f32 v[48:49], v[48:49], v[64:65] op_sel_hi:[1,0]
	v_pk_mul_f32 v[46:47], v[46:47], v[64:65] op_sel_hi:[1,0]
	v_pk_mul_f32 v[44:45], v[44:45], v[64:65] op_sel_hi:[1,0]
	v_pk_mul_f32 v[42:43], v[42:43], v[64:65] op_sel_hi:[1,0]
	v_pk_mul_f32 v[40:41], v[40:41], v[64:65] op_sel_hi:[1,0]
	v_pk_mul_f32 v[38:39], v[38:39], v[64:65] op_sel_hi:[1,0]
	v_pk_mul_f32 v[36:37], v[36:37], v[64:65] op_sel_hi:[1,0]
	v_pk_mul_f32 v[34:35], v[34:35], v[64:65] op_sel_hi:[1,0]
	v_pk_mul_f32 v[32:33], v[32:33], v[64:65] op_sel_hi:[1,0]
.LBB0_894:
	v_cndmask_b32_e64 v83, v83, v84, s[36:37]
	v_add_f32_e32 v82, v82, v83
	v_fmac_f32_e32 v82, v190, v80
	v_cndmask_b32_e64 v80, v89, v90, s[36:37]
	v_add_f32_e32 v65, v65, v80
	v_fmac_f32_e32 v65, v82, v64
	v_cvt_pk_bf16_f32 v86, v87, v88
	v_cvt_pk_bf16_f32 v87, v66, v67
	v_cvt_pk_bf16_f32 v88, v68, v69
	v_cvt_pk_bf16_f32 v89, v70, v71
	v_cvt_pk_bf16_f32 v66, v72, v73
	v_cvt_pk_bf16_f32 v67, v74, v75
	v_cvt_pk_bf16_f32 v68, v76, v77
	ds_read_b64_tr_b16 v[70:71], v85 offset:13824
	ds_read_b64_tr_b16 v[72:73], v85 offset:14976
	ds_read_b64_tr_b16 v[74:75], v85 offset:16128
	ds_read_b64_tr_b16 v[76:77], v85 offset:17280
	ds_read_b64_tr_b16 v[90:91], v85 offset:13888
	ds_read_b64_tr_b16 v[92:93], v85 offset:15040
	ds_read_b64_tr_b16 v[82:83], v85 offset:16192
	ds_read_b64_tr_b16 v[84:85], v85 offset:17344
	v_cvt_pk_bf16_f32 v69, v78, v79
	s_nop 0
	s_waitcnt lgkmcnt(6)
	v_mfma_f32_32x32x16_bf16 v[32:47], v[70:73], v[86:89], v[32:47]
	s_mov_b64 s[52:53], -1
	s_waitcnt lgkmcnt(2)
	v_mfma_f32_32x32x16_bf16 v[48:63], v[90:93], v[86:89], v[48:63]
	v_mfma_f32_32x32x16_bf16 v[32:47], v[74:77], v[66:69], v[32:47]
	s_waitcnt lgkmcnt(0)
	v_mfma_f32_32x32x16_bf16 v[48:63], v[82:85], v[66:69], v[48:63]

; #define LAS __attribute__((address_space(3)))
; #define MFMA32(a, b, c) __builtin_amdgcn_mfma_f32_32x32x16_bf16((a), (b), (c), 0, 0, 0)
; DI float ex2(float x) { return __builtin_amdgcn_exp2f(x); }
; template <int KS0, int KS1> DI f32x16 qk_rows(LAS const char* Kl, int row0, const bf16x8 (&qf)[4], int r, int h) {
;     f32x16 s;
; #pragma unroll
;     for (int i = 0; i < 16; ++i) s[i] = 0.f;
;     LAS const char* p = Kl + (row0 + r) * KP + 16 * h;
;     bf16x8 kf[4];
; #pragma unroll
;     for (int ks = KS0; ks < KS1; ++ks) kf[ks] = *(LAS const bf16x8*)(p + 32 * ks);
;     __builtin_amdgcn_s_setprio(1);
; #pragma unroll
;     for (int ks = KS0; ks < KS1; ++ks) s = MFMA32(kf[ks], qf[ks], s);
;     __builtin_amdgcn_s_setprio(0);
;     return s;
; }
; template <int MM> DI void smax_step(const f32x16& s, unsigned vm, float& m, float& l, f32x16 (&o)[2], bf16x8 (&pf)[2], int lane) {
;     float t[16], mx = -1e30f;
; #pragma unroll
;     for (int i = 0; i < 16; ++i) { t[i] = (MM == 0) ? s[i] : (MM == 1 ? (vm ? s[i] : -1e30f) : (((vm >> i) & 1u) ? s[i] : -1e30f)); mx = fmaxf(mx, t[i]); }
;     mx = fmaxf(mx, shx32(mx, lane));
;     const float mn = (mx > m + 8.0f) ? mx : m;
;     const float mref = fmaxf(mn, -1e29f);
;     float p[16], rs = 0.f;
; #pragma unroll
;     for (int i = 0; i < 16; ++i) { p[i] = ex2(t[i] - mref); rs += p[i]; }
;     rs += shx32(rs, lane);
;     if (__builtin_amdgcn_ballot_w64(mn != m) != 0ull) {
;         const float alpha = ex2(m - mn);
;         l *= alpha;
; #pragma unroll
;         for (int i = 0; i < 16; ++i) { o[0][i] *= alpha; o[1][i] *= alpha; }
;         m = mn;
;     }
;     l += rs;
;     pack_p(p, pf);
; }
.LBB0_906:
	s_andn2_b64 vcc, exec, s[54:55]
	s_cbranch_vccnz .LBB0_918
	v_add_u32_e32 v36, v48, v184
	ds_read_b128 v[32:35], v36
	ds_read_b128 v[52:55], v36 offset:32
	ds_read_b128 v[56:59], v36 offset:64
	ds_read_b128 v[60:63], v36 offset:96
	s_nop 0
	s_waitcnt lgkmcnt(3)
	v_mfma_f32_32x32x16_bf16 v[32:47], v[32:35], v[112:115], 0
	s_waitcnt lgkmcnt(2)
	v_mfma_f32_32x32x16_bf16 v[32:47], v[52:55], v[116:119], v[32:47]
	s_waitcnt lgkmcnt(1)
	v_mfma_f32_32x32x16_bf16 v[32:47], v[56:59], v[120:123], v[32:47]
	s_waitcnt lgkmcnt(0)
	v_mfma_f32_32x32x16_bf16 v[32:47], v[60:63], v[124:127], v[32:47]
	s_nop 0
	v_cmp_gt_i32_e32 vcc, 1, v50
	s_cbranch_vccnz .LBB0_910
	v_cmp_ne_u32_e32 vcc, 1, v50
	s_cbranch_vccz .LBB0_911
	v_and_b32_e32 v50, 1, v71
	v_cmp_eq_u32_e32 vcc, 1, v50
	v_and_b32_e32 v50, 2, v71
	v_and_b32_e32 v53, 4, v71
	s_nop 2
	v_cndmask_b32_e32 v51, v208, v32, vcc
	v_cmp_ne_u32_e32 vcc, 0, v50
	v_and_b32_e32 v54, 8, v71
	v_and_b32_e32 v55, 16, v71
	v_cndmask_b32_e32 v52, v208, v33, vcc
	v_cmp_ne_u32_e32 vcc, 0, v53
	v_and_b32_e32 v56, 32, v71
	v_and_b32_e32 v57, 64, v71
	v_cndmask_b32_e32 v53, v208, v34, vcc
	v_cmp_ne_u32_e32 vcc, 0, v54
	v_and_b32_e32 v58, 0x80, v71
	v_and_b32_e32 v59, 0x100, v71
	v_cndmask_b32_e32 v54, v208, v35, vcc
	v_cmp_ne_u32_e32 vcc, 0, v55
	v_and_b32_e32 v60, 0x200, v71
	v_and_b32_e32 v61, 0x400, v71
	v_cndmask_b32_e32 v55, v208, v36, vcc
	v_cmp_ne_u32_e32 vcc, 0, v56
	v_max3_f32 v50, v51, s15, v52
	v_and_b32_e32 v62, 0x800, v71
	v_cndmask_b32_e32 v56, v208, v37, vcc
	v_cmp_ne_u32_e32 vcc, 0, v57
	v_max3_f32 v50, v50, v53, v54
	v_and_b32_e32 v63, 0x1000, v71
	v_cndmask_b32_e32 v57, v208, v38, vcc
	v_cmp_ne_u32_e32 vcc, 0, v58
	v_max3_f32 v50, v50, v55, v56
	v_and_b32_e32 v65, 0x2000, v71
	v_cndmask_b32_e32 v58, v208, v39, vcc
	v_cmp_ne_u32_e32 vcc, 0, v59
	v_max3_f32 v50, v50, v57, v58
	v_and_b32_e32 v66, 0x4000, v71
	v_cndmask_b32_e32 v59, v208, v40, vcc
	v_cmp_ne_u32_e32 vcc, 0, v60
	v_and_b32_e32 v67, 0x8000, v71
	s_nop 0
	v_cndmask_b32_e32 v60, v208, v41, vcc
	v_cmp_ne_u32_e32 vcc, 0, v61
	v_max3_f32 v50, v50, v59, v60
	s_nop 0
	v_cndmask_b32_e32 v61, v208, v42, vcc
	v_cmp_ne_u32_e32 vcc, 0, v62
	s_nop 1
	v_cndmask_b32_e32 v62, v208, v43, vcc
	v_cmp_ne_u32_e32 vcc, 0, v63
	v_max3_f32 v50, v50, v61, v62
	s_nop 0
	v_cndmask_b32_e32 v63, v208, v44, vcc
	v_cmp_ne_u32_e32 vcc, 0, v65
	s_nop 1
	v_cndmask_b32_e32 v65, v208, v45, vcc
	v_cmp_ne_u32_e32 vcc, 0, v66
	v_max3_f32 v50, v50, v63, v65
	s_nop 0
	v_cndmask_b32_e32 v66, v208, v46, vcc
	v_cmp_ne_u32_e32 vcc, 0, v67
	s_nop 1
	v_cndmask_b32_e32 v67, v208, v47, vcc
	v_max3_f32 v50, v50, v66, v67
	v_mov_b32_e32 v68, v50
	v_mov_b32_e32 v69, v50
	s_nop 1
	v_permlane32_swap_b32_e32 v68, v69
	v_max_f32_e32 v50, v68, v69
	v_add_f32_e32 v68, 0x41000000, v191
	v_cmp_gt_f32_e32 vcc, v50, v68
	s_nop 1
	v_cndmask_b32_e32 v50, v191, v50, vcc
	v_max_f32_e32 v68, 0xefa18f08, v50
	v_sub_f32_e32 v51, v51, v68
	v_exp_f32_e32 v51, v51
	v_sub_f32_e32 v52, v52, v68
	v_exp_f32_e32 v52, v52
	v_sub_f32_e32 v53, v53, v68
	v_exp_f32_e32 v53, v53
	v_sub_f32_e32 v54, v54, v68
	v_exp_f32_e32 v54, v54
	v_sub_f32_e32 v55, v55, v68
	v_exp_f32_e32 v55, v55
	v_sub_f32_e32 v56, v56, v68
	v_add_f32_e32 v69, v52, v51
	v_exp_f32_e32 v56, v56
	v_sub_f32_e32 v57, v57, v68
	v_add_f32_e32 v69, v53, v69
	v_exp_f32_e32 v57, v57
	v_sub_f32_e32 v58, v58, v68
	v_add_f32_e32 v69, v54, v69
	v_exp_f32_e32 v58, v58
	v_sub_f32_e32 v59, v59, v68
	v_add_f32_e32 v69, v55, v69
	v_exp_f32_e32 v59, v59
	v_sub_f32_e32 v60, v60, v68
	v_add_f32_e32 v69, v56, v69
	v_exp_f32_e32 v60, v60
	v_sub_f32_e32 v61, v61, v68
	v_add_f32_e32 v69, v57, v69
	v_exp_f32_e32 v61, v61
	v_sub_f32_e32 v62, v62, v68
	v_add_f32_e32 v69, v58, v69
	v_exp_f32_e32 v62, v62
	v_sub_f32_e32 v63, v63, v68
	v_add_f32_e32 v69, v59, v69
	v_exp_f32_e32 v63, v63
	v_sub_f32_e32 v65, v65, v68
	v_add_f32_e32 v69, v60, v69
	v_exp_f32_e32 v65, v65
	v_sub_f32_e32 v66, v66, v68
	v_add_f32_e32 v69, v61, v69
	v_exp_f32_e32 v66, v66
	v_sub_f32_e32 v67, v67, v68
	v_add_f32_e32 v69, v62, v69
	v_exp_f32_e32 v67, v67
	v_add_f32_e32 v68, v63, v69
	v_add_f32_e32 v68, v65, v68
	v_add_f32_e32 v68, v66, v68
	v_add_f32_e32 v68, v67, v68
	v_cmp_neq_f32_e32 vcc, v50, v191
	v_mov_b32_e32 v69, v68
	v_mov_b32_e32 v70, v68
	s_cmp_lg_u64 vcc, 0
	s_nop 0
	v_permlane32_swap_b32_e32 v69, v70
	s_cselect_b64 s[54:55], -1, 0
	s_cbranch_execz .LBB0_912
	s_branch .LBB0_913

; #define LAS __attribute__((address_space(3)))
; #define MFMA32(a, b, c) __builtin_amdgcn_mfma_f32_32x32x16_bf16((a), (b), (c), 0, 0, 0)
; DI s16x4 vtr(LAS const char* p) { return __builtin_bit_cast(s16x4, __builtin_amdgcn_ds_read_tr16_b64_v4i16((LAS v4i16_t*)p)); }
; DI void pv_rows(f32x16 (&o)[2], LAS const char* Vl, int row0, const bf16x8 (&pf)[2], int lane) {
;     const int h = lane >> 5, i = lane & 15, grp = (lane >> 4) & 1;
;     LAS const char* base = Vl + (row0 + 4 * h + (i >> 2)) * KP + grp * 32 + (i & 3) * 8;
;     bf16x8 vf[2][2];
; #pragma unroll
;     for (int dt = 0; dt < 2; ++dt)
; #pragma unroll
;         for (int s2 = 0; s2 < 2; ++s2) {
;             const s16x4 lo = vtr(base + (16 * s2) * KP + dt * 64), hi = vtr(base + (16 * s2 + 8) * KP + dt * 64);
;             vf[dt][s2] = (bf16x8){lo[0], lo[1], lo[2], lo[3], hi[0], hi[1], hi[2], hi[3]};
;         }
;     __builtin_amdgcn_s_setprio(1);
; #pragma unroll
;     for (int s2 = 0; s2 < 2; ++s2)
; #pragma unroll
;         for (int dt = 0; dt < 2; ++dt) o[dt] = MFMA32(vf[dt][s2], pf[s2], o[dt]);
;     __builtin_amdgcn_s_setprio(0);
; }
; template <int MODE, bool PRE = false> ...
;     ...
;             const int kbase = 64 * kt + 32 * sub;
;             if (kbase > q0w + 31) continue;
;             if (MODE == MODE_NWIN && kbase + 31 <= q0w - 512) continue;
;             bool full = (kbase + 31 <= q0w);
;             if (MODE == MODE_NWIN) full = full && (kbase > q0w + 31 - 512);
;             bool lsel = true;
;             if (MODE == MODE_MOBA) lsel = ((sel >> (kbase >> 8)) & 1ull) != 0ull;
;             if (MODE == MODE_NSEL) lsel = ((sel >> kt) & 1ull) != 0ull;
;             const unsigned long long selb = __builtin_amdgcn_ballot_w64(lsel);
;             if (selb == 0ull) continue;
;             int mm; unsigned vm;
;             if (full) { mm = (selb == ~0ull) ? 0 : 1; vm = lsel ? 1u : 0u; }
;             else { mm = 2; vm = 0;
; #pragma unroll
;                 for (int i = 0; i < 16; ++i) { const int kidx = kbase + (i & 3) + 8 * (i >> 2) + 4 * h; bool ok = kidx <= qpos; if (MODE == MODE_NWIN) ok = ok && (kidx > qpos - 512); vm |= ok ? (1u << i) : 0u; }
;                 if (!lsel) vm = 0;
;                 if (__builtin_amdgcn_ballot_w64(vm != 0) == 0ull) continue; }
.LBB0_917:
	s_nop 3
	v_cndmask_b32_e64 v32, v69, v70, s[36:37]
	v_add_f32_e32 v32, v68, v32
	v_cvt_pk_bf16_f32 v34, v55, v56
	v_add_u32_e32 v56, v64, v186
	v_add_f32_e32 v190, v190, v32
	v_cvt_pk_bf16_f32 v32, v51, v52
	v_cvt_pk_bf16_f32 v33, v53, v54
	v_cvt_pk_bf16_f32 v35, v57, v58
	ds_read_b64_tr_b16 v[40:41], v56 offset:9216
	ds_read_b64_tr_b16 v[42:43], v56 offset:10368
	ds_read_b64_tr_b16 v[44:45], v56 offset:11520
	ds_read_b64_tr_b16 v[46:47], v56 offset:12672
	ds_read_b64_tr_b16 v[50:51], v56 offset:9280
	ds_read_b64_tr_b16 v[52:53], v56 offset:10432
	ds_read_b64_tr_b16 v[54:55], v56 offset:11584
	ds_read_b64_tr_b16 v[56:57], v56 offset:12736
	v_cvt_pk_bf16_f32 v36, v59, v60
	v_cvt_pk_bf16_f32 v37, v61, v62
	v_cvt_pk_bf16_f32 v38, v63, v65
	v_cvt_pk_bf16_f32 v39, v66, v67
	s_nop 0
	s_waitcnt lgkmcnt(6)
	v_mfma_f32_32x32x16_bf16 v[0:15], v[40:43], v[32:35], v[0:15]
	s_waitcnt lgkmcnt(2)
	v_mfma_f32_32x32x16_bf16 v[16:31], v[50:53], v[32:35], v[16:31]
	v_mfma_f32_32x32x16_bf16 v[0:15], v[44:47], v[36:39], v[0:15]
	s_waitcnt lgkmcnt(0)
	v_mfma_f32_32x32x16_bf16 v[16:31], v[54:57], v[36:39], v[16:31]
	s_nop 0
.LBB0_918:
	s_or_b32 s10, s10, 32
	s_cmp_gt_i32 s10, s60
	s_cbranch_scc1 .LBB0_923
	v_cmp_ne_u32_e32 vcc, 0, v49
	s_cbranch_vccz .LBB0_923
	v_or_b32_e32 v32, s10, v161
	v_cmp_le_i32_e32 vcc, v32, v167
	v_or_b32_e32 v35, 3, v32
	s_nop 0
	v_cndmask_b32_e64 v33, 0, 1, vcc
	v_cmp_lt_i32_e32 vcc, v32, v167
	s_nop 1
	v_cndmask_b32_e64 v34, 0, 2, vcc
	v_or_b32_e32 v33, v34, v33
	v_or_b32_e32 v34, 2, v32
	v_cmp_gt_i32_e32 vcc, v34, v167
	s_nop 1
	v_cndmask_b32_e64 v34, 4, 0, vcc
	v_cmp_gt_i32_e32 vcc, v35, v167
	s_nop 1
	v_cndmask_b32_e64 v35, 8, 0, vcc
	v_or3_b32 v33, v33, v34, v35
	v_or_b32_e32 v34, 8, v32
	v_cmp_gt_i32_e32 vcc, v34, v167
	v_or_b32_e32 v35, 9, v32
	s_nop 0
	v_cndmask_b32_e64 v34, 16, 0, vcc
	v_cmp_gt_i32_e32 vcc, v35, v167
	s_nop 1
	v_cndmask_b32_e64 v35, 32, 0, vcc
	v_or3_b32 v33, v33, v34, v35
	v_or_b32_e32 v34, 10, v32
	v_cmp_gt_i32_e32 vcc, v34, v167
	v_or_b32_e32 v35, 11, v32
	s_nop 0
	v_cndmask_b32_e64 v34, 64, 0, vcc
	v_cmp_gt_i32_e32 vcc, v35, v167
	s_nop 1
	v_cndmask_b32_e64 v35, v196, 0, vcc
	v_or3_b32 v33, v33, v34, v35
	v_or_b32_e32 v34, 16, v32
	v_cmp_gt_i32_e32 vcc, v34, v167
	v_or_b32_e32 v35, 17, v32
	s_nop 0
	v_cndmask_b32_e64 v34, v197, 0, vcc
	v_cmp_gt_i32_e32 vcc, v35, v167
	s_nop 1
	v_cndmask_b32_e64 v35, v198, 0, vcc
	v_or3_b32 v33, v33, v34, v35
	v_or_b32_e32 v34, 18, v32
	v_cmp_gt_i32_e32 vcc, v34, v167
	v_or_b32_e32 v35, 19, v32
	s_nop 0
	v_cndmask_b32_e64 v34, v199, 0, vcc
	v_cmp_gt_i32_e32 vcc, v35, v167
	s_nop 1
	v_cndmask_b32_e64 v35, v200, 0, vcc
	v_or3_b32 v33, v33, v34, v35
	v_or_b32_e32 v34, 24, v32
	v_cmp_gt_i32_e32 vcc, v34, v167
	v_or_b32_e32 v35, 25, v32
	s_nop 0
	v_cndmask_b32_e64 v34, v201, 0, vcc
	v_cmp_gt_i32_e32 vcc, v35, v167
	s_nop 1
	v_cndmask_b32_e64 v35, v202, 0, vcc
	v_or3_b32 v33, v33, v34, v35
	v_or_b32_e32 v34, 26, v32
	v_cmp_gt_i32_e32 vcc, v34, v167
	v_or_b32_e32 v32, 27, v32
	s_nop 0
	v_cndmask_b32_e64 v34, v203, 0, vcc
	v_cmp_gt_i32_e32 vcc, v32, v167
	s_nop 1
	v_cndmask_b32_e64 v32, v204, 0, vcc
	v_or3_b32 v32, v33, v34, v32
	v_cndmask_b32_e64 v49, 0, v32, s[0:1]
	v_cmp_ne_u32_e32 vcc, 0, v49
	s_cbranch_vccz .LBB0_923
; #define LAS __attribute__((address_space(3)))
; #define MFMA32(a, b, c) __builtin_amdgcn_mfma_f32_32x32x16_bf16((a), (b), (c), 0, 0, 0)
; DI float ex2(float x) { return __builtin_amdgcn_exp2f(x); }
; template <int KS0, int KS1> DI f32x16 qk_rows(LAS const char* Kl, int row0, const bf16x8 (&qf)[4], int r, int h) {
;     f32x16 s;
; #pragma unroll
;     for (int i = 0; i < 16; ++i) s[i] = 0.f;
;     LAS const char* p = Kl + (row0 + r) * KP + 16 * h;
;     bf16x8 kf[4];
; #pragma unroll
;     for (int ks = KS0; ks < KS1; ++ks) kf[ks] = *(LAS const bf16x8*)(p + 32 * ks);
;     __builtin_amdgcn_s_setprio(1);
; #pragma unroll
;     for (int ks = KS0; ks < KS1; ++ks) s = MFMA32(kf[ks], qf[ks], s);
;     __builtin_amdgcn_s_setprio(0);
;     return s;
; }
; template <int MM> DI void smax_step(const f32x16& s, unsigned vm, float& m, float& l, f32x16 (&o)[2], bf16x8 (&pf)[2], int lane) {
;     float t[16], mx = -1e30f;
; #pragma unroll
;     for (int i = 0; i < 16; ++i) { t[i] = (MM == 0) ? s[i] : (MM == 1 ? (vm ? s[i] : -1e30f) : (((vm >> i) & 1u) ? s[i] : -1e30f)); mx = fmaxf(mx, t[i]); }
;     mx = fmaxf(mx, shx32(mx, lane));
;     const float mn = (mx > m + 8.0f) ? mx : m;
;     const float mref = fmaxf(mn, -1e29f);
;     float p[16], rs = 0.f;
; #pragma unroll
;     for (int i = 0; i < 16; ++i) { p[i] = ex2(t[i] - mref); rs += p[i]; }
;     rs += shx32(rs, lane);
;     if (__builtin_amdgcn_ballot_w64(mn != m) != 0ull) {
;         const float alpha = ex2(m - mn);
;         l *= alpha;
; #pragma unroll
;         for (int i = 0; i < 16; ++i) { o[0][i] *= alpha; o[1][i] *= alpha; }
;         m = mn;
;     }
;     l += rs;
;     pack_p(p, pf);
; }
	v_add_u32_e32 v36, v48, v189
	ds_read_b128 v[32:35], v36
	ds_read_b128 v[50:53], v36 offset:32
	ds_read_b128 v[54:57], v36 offset:64
	ds_read_b128 v[58:61], v36 offset:96
	s_nop 0
	s_waitcnt lgkmcnt(3)
	v_mfma_f32_32x32x16_bf16 v[32:47], v[32:35], v[112:115], 0
	s_waitcnt lgkmcnt(2)
	v_mfma_f32_32x32x16_bf16 v[32:47], v[50:53], v[116:119], v[32:47]
	s_waitcnt lgkmcnt(1)
	v_mfma_f32_32x32x16_bf16 v[32:47], v[54:57], v[120:123], v[32:47]
	s_waitcnt lgkmcnt(0)
	v_mfma_f32_32x32x16_bf16 v[32:47], v[58:61], v[124:127], v[32:47]
	s_nop 0
	v_and_b32_e32 v48, 1, v49
	v_cmp_eq_u32_e32 vcc, 1, v48
	v_and_b32_e32 v48, 2, v49
	v_and_b32_e32 v50, 4, v49
	s_nop 6
	v_cndmask_b32_e32 v32, v208, v32, vcc
	v_cmp_ne_u32_e32 vcc, 0, v48
	s_nop 1
	v_cndmask_b32_e32 v33, v208, v33, vcc
	v_cmp_ne_u32_e32 vcc, 0, v50
	v_and_b32_e32 v50, 8, v49
	v_max3_f32 v48, v32, s15, v33
	v_cndmask_b32_e32 v34, v208, v34, vcc
	v_cmp_ne_u32_e32 vcc, 0, v50
	v_and_b32_e32 v50, 16, v49
	s_nop 0
	v_cndmask_b32_e32 v35, v208, v35, vcc
	v_cmp_ne_u32_e32 vcc, 0, v50
	v_and_b32_e32 v50, 32, v49
	v_max3_f32 v48, v48, v34, v35
	v_cndmask_b32_e32 v36, v208, v36, vcc
	v_cmp_ne_u32_e32 vcc, 0, v50
	v_and_b32_e32 v50, 64, v49
	s_nop 0
	v_cndmask_b32_e32 v37, v208, v37, vcc
	v_cmp_ne_u32_e32 vcc, 0, v50
	v_and_b32_e32 v50, 0x80, v49
	v_max3_f32 v48, v48, v36, v37
	v_cndmask_b32_e32 v38, v208, v38, vcc
	v_cmp_ne_u32_e32 vcc, 0, v50
	v_and_b32_e32 v50, 0x100, v49
	s_nop 0
	v_cndmask_b32_e32 v39, v208, v39, vcc
	v_cmp_ne_u32_e32 vcc, 0, v50
	v_and_b32_e32 v50, 0x200, v49
	v_max3_f32 v48, v48, v38, v39
	v_cndmask_b32_e32 v40, v208, v40, vcc
	v_cmp_ne_u32_e32 vcc, 0, v50
	v_and_b32_e32 v50, 0x400, v49
	s_nop 0
	v_cndmask_b32_e32 v41, v208, v41, vcc
	v_cmp_ne_u32_e32 vcc, 0, v50
	v_and_b32_e32 v50, 0x800, v49
	v_max3_f32 v48, v48, v40, v41
	v_cndmask_b32_e32 v42, v208, v42, vcc
	v_cmp_ne_u32_e32 vcc, 0, v50
	v_and_b32_e32 v50, 0x1000, v49
	s_nop 0
	v_cndmask_b32_e32 v43, v208, v43, vcc
	v_cmp_ne_u32_e32 vcc, 0, v50
	v_and_b32_e32 v50, 0x2000, v49
	v_max3_f32 v48, v48, v42, v43
	v_cndmask_b32_e32 v44, v208, v44, vcc
	v_cmp_ne_u32_e32 vcc, 0, v50
	v_and_b32_e32 v50, 0x4000, v49
	v_and_b32_e32 v49, 0x8000, v49
	v_cndmask_b32_e32 v45, v208, v45, vcc
	v_cmp_ne_u32_e32 vcc, 0, v50
	v_max3_f32 v48, v48, v44, v45
	s_nop 0
	v_cndmask_b32_e32 v46, v208, v46, vcc
	v_cmp_ne_u32_e32 vcc, 0, v49
	s_nop 1
	v_cndmask_b32_e32 v47, v208, v47, vcc
	v_max3_f32 v48, v48, v46, v47
	v_mov_b32_e32 v49, v48
	v_mov_b32_e32 v50, v48
	s_nop 1
	v_permlane32_swap_b32_e32 v49, v50
	v_max_f32_e32 v48, v49, v50
	v_add_f32_e32 v49, 0x41000000, v191
	v_cmp_gt_f32_e32 vcc, v48, v49
	s_nop 1
	v_cndmask_b32_e32 v69, v191, v48, vcc
	v_max_f32_e32 v48, 0xefa18f08, v69
	v_sub_f32_e32 v32, v32, v48
	v_exp_f32_e32 v65, v32
	v_sub_f32_e32 v32, v33, v48
	v_exp_f32_e32 v66, v32
	v_sub_f32_e32 v32, v34, v48
	v_exp_f32_e32 v67, v32
	v_sub_f32_e32 v32, v35, v48
	v_exp_f32_e32 v68, v32
	v_sub_f32_e32 v33, v36, v48
	v_exp_f32_e32 v70, v33
	v_sub_f32_e32 v33, v37, v48
	v_add_f32_e32 v32, v66, v65
	v_exp_f32_e32 v71, v33
	v_sub_f32_e32 v33, v38, v48
	v_add_f32_e32 v32, v67, v32
	v_exp_f32_e32 v72, v33
	v_sub_f32_e32 v33, v39, v48
	v_add_f32_e32 v32, v68, v32
	v_exp_f32_e32 v73, v33
	v_sub_f32_e32 v33, v40, v48
	v_add_f32_e32 v32, v70, v32
	v_exp_f32_e32 v74, v33
	v_sub_f32_e32 v33, v41, v48
	v_add_f32_e32 v32, v71, v32
	v_exp_f32_e32 v75, v33
	v_sub_f32_e32 v33, v42, v48
	v_add_f32_e32 v32, v72, v32
	v_exp_f32_e32 v76, v33
	v_sub_f32_e32 v33, v43, v48
	v_add_f32_e32 v32, v73, v32
	v_exp_f32_e32 v77, v33
	v_sub_f32_e32 v33, v44, v48
	v_add_f32_e32 v32, v74, v32
	v_exp_f32_e32 v78, v33
	v_sub_f32_e32 v33, v45, v48
	v_add_f32_e32 v32, v75, v32
	v_exp_f32_e32 v79, v33
	v_sub_f32_e32 v33, v46, v48
	v_add_f32_e32 v32, v76, v32
	v_exp_f32_e32 v80, v33
	v_sub_f32_e32 v33, v47, v48
	v_add_f32_e32 v32, v77, v32
	v_exp_f32_e32 v81, v33
	v_add_f32_e32 v32, v78, v32
	v_add_f32_e32 v32, v79, v32
	v_add_f32_e32 v32, v80, v32
	v_add_f32_e32 v82, v81, v32
	v_mov_b32_e32 v83, v82
	v_mov_b32_e32 v84, v82
	s_nop 1
	v_permlane32_swap_b32_e32 v83, v84
	v_cmp_neq_f32_e32 vcc, v69, v191
	s_cbranch_vccz .LBB0_924
	v_sub_f32_e32 v32, v191, v69
	v_exp_f32_e32 v32, v32
	v_mov_b32_e32 v191, v69
	v_mul_f32_e32 v190, v190, v32
	v_pk_mul_f32 v[62:63], v[30:31], v[32:33] op_sel_hi:[1,0]
	v_pk_mul_f32 v[60:61], v[28:29], v[32:33] op_sel_hi:[1,0]
	v_pk_mul_f32 v[58:59], v[26:27], v[32:33] op_sel_hi:[1,0]
	v_pk_mul_f32 v[56:57], v[24:25], v[32:33] op_sel_hi:[1,0]
	v_pk_mul_f32 v[54:55], v[22:23], v[32:33] op_sel_hi:[1,0]
	v_pk_mul_f32 v[52:53], v[20:21], v[32:33] op_sel_hi:[1,0]
	v_pk_mul_f32 v[50:51], v[18:19], v[32:33] op_sel_hi:[1,0]
	v_pk_mul_f32 v[48:49], v[16:17], v[32:33] op_sel_hi:[1,0]
	v_pk_mul_f32 v[46:47], v[14:15], v[32:33] op_sel_hi:[1,0]
	v_pk_mul_f32 v[44:45], v[12:13], v[32:33] op_sel_hi:[1,0]
	v_pk_mul_f32 v[42:43], v[10:11], v[32:33] op_sel_hi:[1,0]
	v_pk_mul_f32 v[40:41], v[8:9], v[32:33] op_sel_hi:[1,0]
	v_pk_mul_f32 v[38:39], v[6:7], v[32:33] op_sel_hi:[1,0]
	v_pk_mul_f32 v[36:37], v[4:5], v[32:33] op_sel_hi:[1,0]
	v_pk_mul_f32 v[34:35], v[2:3], v[32:33] op_sel_hi:[1,0]
	v_pk_mul_f32 v[32:33], v[0:1], v[32:33] op_sel_hi:[1,0]
	s_branch .LBB0_925

; #define LAS __attribute__((address_space(3)))
; DI unsigned cvtpk(float lo, float hi) { f32x2_t v = {lo, hi}; bf16x2_t b = __builtin_convertvector(v, bf16x2_t); return __builtin_bit_cast(unsigned, b); }
; #define MFMA32(a, b, c) __builtin_amdgcn_mfma_f32_32x32x16_bf16((a), (b), (c), 0, 0, 0)
; DI s16x4 vtr(LAS const char* p) { return __builtin_bit_cast(s16x4, __builtin_amdgcn_ds_read_tr16_b64_v4i16((LAS v4i16_t*)p)); }
; DI void pv_rows(f32x16 (&o)[2], LAS const char* Vl, int row0, const bf16x8 (&pf)[2], int lane) {
;     const int h = lane >> 5, i = lane & 15, grp = (lane >> 4) & 1;
;     LAS const char* base = Vl + (row0 + 4 * h + (i >> 2)) * KP + grp * 32 + (i & 3) * 8;
;     bf16x8 vf[2][2];
; #pragma unroll
;     for (int dt = 0; dt < 2; ++dt)
; #pragma unroll
;         for (int s2 = 0; s2 < 2; ++s2) {
;             const s16x4 lo = vtr(base + (16 * s2) * KP + dt * 64), hi = vtr(base + (16 * s2 + 8) * KP + dt * 64);
;             vf[dt][s2] = (bf16x8){lo[0], lo[1], lo[2], lo[3], hi[0], hi[1], hi[2], hi[3]};
;         }
;     __builtin_amdgcn_s_setprio(1);
; #pragma unroll
;     for (int s2 = 0; s2 < 2; ++s2)
; #pragma unroll
;         for (int dt = 0; dt < 2; ++dt) o[dt] = MFMA32(vf[dt][s2], pf[s2], o[dt]);
;     __builtin_amdgcn_s_setprio(0);
; }
; DI void pack_p(const float (&p)[16], bf16x8 (&pf)[2]) {
; #pragma unroll
;     for (int s2 = 0; s2 < 2; ++s2) { u32x4 w; w.x = cvtpk(p[8 * s2], p[8 * s2 + 1]); w.y = cvtpk(p[8 * s2 + 2], p[8 * s2 + 3]); w.z = cvtpk(p[8 * s2 + 4], p[8 * s2 + 5]); w.w = cvtpk(p[8 * s2 + 6], p[8 * s2 + 7]);
;         pf[s2] = __builtin_bit_cast(bf16x8, w); }
; }
.LBB0_925:
	v_cndmask_b32_e64 v69, v83, v84, s[36:37]
	v_add_f32_e32 v69, v82, v69
	v_add_u32_e32 v64, v64, v186
	v_add_f32_e32 v190, v69, v190
	v_cvt_pk_bf16_f32 v67, v67, v68
	v_cvt_pk_bf16_f32 v68, v70, v71
	v_cvt_pk_bf16_f32 v69, v72, v73
	v_cvt_pk_bf16_f32 v70, v74, v75
	v_cvt_pk_bf16_f32 v71, v76, v77
	v_cvt_pk_bf16_f32 v72, v78, v79
	v_cvt_pk_bf16_f32 v73, v80, v81
	ds_read_b64_tr_b16 v[74:75], v64 offset:13824
	ds_read_b64_tr_b16 v[76:77], v64 offset:14976
	ds_read_b64_tr_b16 v[78:79], v64 offset:16128
	ds_read_b64_tr_b16 v[80:81], v64 offset:17280
	ds_read_b64_tr_b16 v[82:83], v64 offset:13888
	ds_read_b64_tr_b16 v[84:85], v64 offset:15040
	ds_read_b64_tr_b16 v[86:87], v64 offset:16192
	ds_read_b64_tr_b16 v[88:89], v64 offset:17344
	v_cvt_pk_bf16_f32 v66, v65, v66
	s_nop 0
	s_waitcnt lgkmcnt(6)
	v_mfma_f32_32x32x16_bf16 v[32:47], v[74:77], v[66:69], v[32:47]
	s_waitcnt lgkmcnt(2)
	v_mfma_f32_32x32x16_bf16 v[48:63], v[82:85], v[66:69], v[48:63]
	v_mfma_f32_32x32x16_bf16 v[32:47], v[78:81], v[70:73], v[32:47]
	s_waitcnt lgkmcnt(0)
	v_mfma_f32_32x32x16_bf16 v[48:63], v[86:89], v[70:73], v[48:63]
	s_cbranch_execz .LBB0_898
	s_branch .LBB0_897

; DI void sb_unit(const Params& P, LAS char* lds, int b, int hd, int qb, int wave, int lane) {
;     ...
;         const f32x16 s = qk_rows<0, 4>(Kl, 0, qf, r, h);
;         float l1m[16], ls[16];
;         unsigned vm = 0;
; #pragma unroll
;         for (int i = 0; i < 16; ++i) { const int kidx = kbase + (i & 3) + 8 * (i >> 2) + 4 * h; const bool ok = kidx < qpos; vm |= ok ? (1u << i) : 0u;
;             const float z = s[i] * 0.125f; const float sp = fmaxf(z, 0.f) + __logf(1.0f + __expf(-fabsf(z)));
;             l1m[i] = ok ? -sp : 0.f; ls[i] = z - sp; }
.Lsb_nopf:
	s_waitcnt lgkmcnt(0)
	ds_read_b128 v[32:35], v105
	ds_read_b128 v[64:67], v105 offset:32
	ds_read_b128 v[68:71], v105 offset:64
	ds_read_b128 v[76:79], v105 offset:96
	ds_read_b64_tr_b16 v[116:117], v106 offset:4608
	ds_read_b64_tr_b16 v[118:119], v106 offset:5760
	ds_read_b64_tr_b16 v[120:121], v106 offset:4672
	ds_read_b64_tr_b16 v[122:123], v106 offset:5824
	ds_read_b64_tr_b16 v[124:125], v106 offset:6912
	ds_read_b64_tr_b16 v[126:127], v106 offset:8064
	ds_read_b64_tr_b16 v[160:161], v106 offset:6976
	ds_read_b64_tr_b16 v[162:163], v106 offset:8128
	s_nop 0
	s_waitcnt lgkmcnt(11)
	v_mfma_f32_32x32x16_bf16 v[32:47], v[32:35], v[48:51], 0
	s_waitcnt lgkmcnt(10)
	v_mfma_f32_32x32x16_bf16 v[32:47], v[64:67], v[52:55], v[32:47]
	s_waitcnt lgkmcnt(9)
	v_mfma_f32_32x32x16_bf16 v[32:47], v[68:71], v[56:59], v[32:47]
	s_waitcnt lgkmcnt(8)
	v_mfma_f32_32x32x16_bf16 v[32:47], v[76:79], v[60:63], v[32:47]
	s_nop 0
	s_nop 10
	v_mul_f32_e32 v64, 0x3e000000, v32
	v_max_f32_e32 v65, 0, v64
	v_mul_f32_e64 v64, |v64|, s17
	v_exp_f32_e32 v64, v64
	v_mul_f32_e32 v70, 0x3e000000, v45
	v_mul_f32_e32 v78, 0x3e000000, v46
	v_mul_f32_e32 v82, 0x3e000000, v47
	v_add_f32_e32 v64, 1.0, v64
	v_cmp_gt_f32_e32 vcc, s21, v64
	s_nop 1
	v_cndmask_b32_e64 v66, 0, 32, vcc
	v_ldexp_f32 v64, v64, v66
	v_log_f32_e32 v64, v64
	s_nop 0
	v_mul_f32_e32 v66, 0x3f317217, v64
	v_fma_f32 v66, v64, s30, -v66
	v_fmac_f32_e32 v66, 0x3377d1cf, v64
	v_fmac_f32_e32 v66, 0x3f317217, v64
	v_cmp_lt_f32_e64 s[0:1], |v64|, s19
	s_nop 1
	v_cndmask_b32_e64 v64, v64, v66, s[0:1]
	v_cndmask_b32_e32 v66, 0, v211, vcc
	v_sub_f32_e32 v67, v64, v66
	v_mul_f32_e32 v64, 0x3e000000, v33
	v_max_f32_e32 v69, 0, v64
	v_mul_f32_e64 v64, |v64|, s17
	v_exp_f32_e32 v64, v64
	s_nop 0
	v_add_f32_e32 v64, 1.0, v64
	v_cmp_gt_f32_e32 vcc, s21, v64
	s_nop 1
	v_cndmask_b32_e64 v66, 0, 32, vcc
	v_ldexp_f32 v64, v64, v66
	v_log_f32_e32 v64, v64
	s_nop 0
	v_mul_f32_e32 v66, 0x3f317217, v64
	v_fma_f32 v66, v64, s30, -v66
	v_fmac_f32_e32 v66, 0x3377d1cf, v64
	v_fmac_f32_e32 v66, 0x3f317217, v64
	v_cmp_lt_f32_e64 s[0:1], |v64|, s19
	s_nop 1
	v_cndmask_b32_e64 v64, v64, v66, s[0:1]
	v_cndmask_b32_e32 v66, 0, v211, vcc
	v_sub_f32_e32 v71, v64, v66
	v_mul_f32_e32 v64, 0x3e000000, v34
	v_max_f32_e32 v77, 0, v64
	v_mul_f32_e64 v64, |v64|, s17
	v_exp_f32_e32 v64, v64
	s_nop 0
	v_add_f32_e32 v64, 1.0, v64
	v_cmp_gt_f32_e32 vcc, s21, v64
	s_nop 1
	v_cndmask_b32_e64 v66, 0, 32, vcc
	v_ldexp_f32 v64, v64, v66
	v_log_f32_e32 v64, v64
	s_nop 0
	v_mul_f32_e32 v66, 0x3f317217, v64
	v_fma_f32 v66, v64, s30, -v66
	v_fmac_f32_e32 v66, 0x3377d1cf, v64
	v_fmac_f32_e32 v66, 0x3f317217, v64
	v_cmp_lt_f32_e64 s[0:1], |v64|, s19
	s_nop 1
	v_cndmask_b32_e64 v64, v64, v66, s[0:1]
	v_cndmask_b32_e32 v66, 0, v211, vcc
	v_sub_f32_e32 v79, v64, v66
	v_mul_f32_e32 v64, 0x3e000000, v35
	v_max_f32_e32 v81, 0, v64
	v_mul_f32_e64 v64, |v64|, s17
	v_exp_f32_e32 v64, v64
	s_nop 0
	v_add_f32_e32 v64, 1.0, v64
	v_cmp_gt_f32_e32 vcc, s21, v64
	s_nop 1
	v_cndmask_b32_e64 v66, 0, 32, vcc
	v_ldexp_f32 v64, v64, v66
	v_log_f32_e32 v64, v64
	s_nop 0
	v_mul_f32_e32 v66, 0x3f317217, v64
	v_fma_f32 v66, v64, s30, -v66
	v_fmac_f32_e32 v66, 0x3377d1cf, v64
	v_fmac_f32_e32 v66, 0x3f317217, v64
	v_cmp_lt_f32_e64 s[0:1], |v64|, s19
	s_nop 1
	v_cndmask_b32_e64 v64, v64, v66, s[0:1]
	v_cndmask_b32_e32 v66, 0, v211, vcc
	v_sub_f32_e32 v83, v64, v66
	v_mul_f32_e32 v64, 0x3e000000, v36
	v_max_f32_e32 v85, 0, v64
	v_mul_f32_e64 v64, |v64|, s17
	v_exp_f32_e32 v64, v64
	s_nop 0
	v_add_f32_e32 v64, 1.0, v64
	v_cmp_gt_f32_e32 vcc, s21, v64
	s_nop 1
	v_cndmask_b32_e64 v66, 0, 32, vcc
	v_ldexp_f32 v64, v64, v66
	v_log_f32_e32 v64, v64
	s_nop 0
	v_mul_f32_e32 v66, 0x3f317217, v64
	v_fma_f32 v66, v64, s30, -v66
	v_fmac_f32_e32 v66, 0x3377d1cf, v64
	v_fmac_f32_e32 v66, 0x3f317217, v64
	v_cmp_lt_f32_e64 s[0:1], |v64|, s19
	s_nop 1
	v_cndmask_b32_e64 v64, v64, v66, s[0:1]
	v_cndmask_b32_e32 v66, 0, v211, vcc
	v_sub_f32_e32 v87, v64, v66
	v_mul_f32_e32 v64, 0x3e000000, v37
	v_max_f32_e32 v89, 0, v64
	v_mul_f32_e64 v64, |v64|, s17
	v_exp_f32_e32 v64, v64
	s_nop 0
	v_add_f32_e32 v64, 1.0, v64
	v_cmp_gt_f32_e32 vcc, s21, v64
	s_nop 1
	v_cndmask_b32_e64 v66, 0, 32, vcc
	v_ldexp_f32 v64, v64, v66
	v_log_f32_e32 v64, v64
	s_nop 0
	v_mul_f32_e32 v66, 0x3f317217, v64
	v_fma_f32 v66, v64, s30, -v66
	v_fmac_f32_e32 v66, 0x3377d1cf, v64
	v_fmac_f32_e32 v66, 0x3f317217, v64
	v_cmp_lt_f32_e64 s[0:1], |v64|, s19
	s_nop 1
	v_cndmask_b32_e64 v64, v64, v66, s[0:1]
	v_cndmask_b32_e32 v66, 0, v211, vcc
	v_sub_f32_e32 v91, v64, v66
	v_mul_f32_e32 v64, 0x3e000000, v38
	v_max_f32_e32 v93, 0, v64
	v_mul_f32_e64 v64, |v64|, s17
	v_exp_f32_e32 v64, v64
	s_nop 0
	v_add_f32_e32 v64, 1.0, v64
	v_cmp_gt_f32_e32 vcc, s21, v64
	s_nop 1
	v_cndmask_b32_e64 v66, 0, 32, vcc
	v_ldexp_f32 v64, v64, v66
	v_log_f32_e32 v64, v64
	s_nop 0
	v_mul_f32_e32 v66, 0x3f317217, v64
	v_fma_f32 v66, v64, s30, -v66
	v_fmac_f32_e32 v66, 0x3377d1cf, v64
	v_fmac_f32_e32 v66, 0x3f317217, v64
	v_cmp_lt_f32_e64 s[0:1], |v64|, s19
	s_nop 1
	v_cndmask_b32_e64 v64, v64, v66, s[0:1]
	v_cndmask_b32_e32 v66, 0, v211, vcc
	v_sub_f32_e32 v95, v64, v66
	v_mul_f32_e32 v64, 0x3e000000, v39
	v_max_f32_e32 v97, 0, v64
	v_mul_f32_e64 v64, |v64|, s17
	v_exp_f32_e32 v64, v64
	s_nop 0
	v_add_f32_e32 v64, 1.0, v64
	v_cmp_gt_f32_e32 vcc, s21, v64
	s_nop 1
	v_cndmask_b32_e64 v66, 0, 32, vcc
	v_ldexp_f32 v64, v64, v66
	v_log_f32_e32 v64, v64
	s_nop 0
	v_mul_f32_e32 v66, 0x3f317217, v64
	v_fma_f32 v66, v64, s30, -v66
	v_fmac_f32_e32 v66, 0x3377d1cf, v64
	v_fmac_f32_e32 v66, 0x3f317217, v64
	v_cmp_lt_f32_e64 s[0:1], |v64|, s19
	s_nop 1
; DI void sb_unit(const Params& P, LAS char* lds, int b, int hd, int qb, int wave, int lane) {
;     ...
;         const f32x16 s = qk_rows<0, 4>(Kl, 0, qf, r, h);
;         float l1m[16], ls[16];
;         unsigned vm = 0;
; #pragma unroll
;         for (int i = 0; i < 16; ++i) { const int kidx = kbase + (i & 3) + 8 * (i >> 2) + 4 * h; const bool ok = kidx < qpos; vm |= ok ? (1u << i) : 0u;
;             const float z = s[i] * 0.125f; const float sp = fmaxf(z, 0.f) + __logf(1.0f + __expf(-fabsf(z)));
;             l1m[i] = ok ? -sp : 0.f; ls[i] = z - sp; }
	v_cndmask_b32_e64 v64, v64, v66, s[0:1]
	v_cndmask_b32_e32 v66, 0, v211, vcc
	v_sub_f32_e32 v99, v64, v66
	v_mul_f32_e32 v64, 0x3e000000, v40
	v_max_f32_e32 v84, 0, v64
	v_mul_f32_e64 v64, |v64|, s17
	v_exp_f32_e32 v64, v64
	s_nop 0
	v_add_f32_e32 v64, 1.0, v64
	v_cmp_gt_f32_e32 vcc, s21, v64
	s_nop 1
	v_cndmask_b32_e64 v66, 0, 32, vcc
	v_ldexp_f32 v64, v64, v66
	v_log_f32_e32 v64, v64
	s_nop 0
	v_mul_f32_e32 v66, 0x3f317217, v64
	v_fma_f32 v66, v64, s30, -v66
	v_fmac_f32_e32 v66, 0x3377d1cf, v64
	v_fmac_f32_e32 v66, 0x3f317217, v64
	v_cmp_lt_f32_e64 s[0:1], |v64|, s19
	s_nop 1
	v_cndmask_b32_e64 v64, v64, v66, s[0:1]
	v_cndmask_b32_e32 v66, 0, v211, vcc
	v_sub_f32_e32 v86, v64, v66
	v_mul_f32_e32 v64, 0x3e000000, v41
	v_max_f32_e32 v88, 0, v64
	v_mul_f32_e64 v64, |v64|, s17
	v_exp_f32_e32 v64, v64
	s_nop 0
	v_add_f32_e32 v64, 1.0, v64
	v_cmp_gt_f32_e32 vcc, s21, v64
	s_nop 1
	v_cndmask_b32_e64 v66, 0, 32, vcc
	v_ldexp_f32 v64, v64, v66
	v_log_f32_e32 v64, v64
	s_nop 0
	v_mul_f32_e32 v66, 0x3f317217, v64
	v_fma_f32 v66, v64, s30, -v66
	v_fmac_f32_e32 v66, 0x3377d1cf, v64
	v_fmac_f32_e32 v66, 0x3f317217, v64
	v_cmp_lt_f32_e64 s[0:1], |v64|, s19
	s_nop 1
	v_cndmask_b32_e64 v64, v64, v66, s[0:1]
	v_cndmask_b32_e32 v66, 0, v211, vcc
	v_sub_f32_e32 v90, v64, v66
	v_mul_f32_e32 v64, 0x3e000000, v42
	v_max_f32_e32 v92, 0, v64
	v_mul_f32_e64 v64, |v64|, s17
	v_exp_f32_e32 v64, v64
	s_nop 0
	v_add_f32_e32 v64, 1.0, v64
	v_cmp_gt_f32_e32 vcc, s21, v64
	s_nop 1
	v_cndmask_b32_e64 v66, 0, 32, vcc
	v_ldexp_f32 v64, v64, v66
	v_log_f32_e32 v64, v64
	s_nop 0
	v_mul_f32_e32 v66, 0x3f317217, v64
	v_fma_f32 v66, v64, s30, -v66
	v_fmac_f32_e32 v66, 0x3377d1cf, v64
	v_fmac_f32_e32 v66, 0x3f317217, v64
	v_cmp_lt_f32_e64 s[0:1], |v64|, s19
	s_nop 1
	v_cndmask_b32_e64 v64, v64, v66, s[0:1]
	v_cndmask_b32_e32 v66, 0, v211, vcc
	v_sub_f32_e32 v94, v64, v66
	v_mul_f32_e32 v64, 0x3e000000, v43
	v_max_f32_e32 v96, 0, v64
	v_mul_f32_e64 v64, |v64|, s17
	v_exp_f32_e32 v64, v64
	s_nop 0
	v_add_f32_e32 v64, 1.0, v64
	v_cmp_gt_f32_e32 vcc, s21, v64
	s_nop 1
	v_cndmask_b32_e64 v66, 0, 32, vcc
	v_ldexp_f32 v64, v64, v66
	v_log_f32_e32 v64, v64
	s_nop 0
	v_mul_f32_e32 v66, 0x3f317217, v64
	v_fma_f32 v66, v64, s30, -v66
	v_fmac_f32_e32 v66, 0x3377d1cf, v64
	v_fmac_f32_e32 v66, 0x3f317217, v64
	v_cmp_lt_f32_e64 s[0:1], |v64|, s19
	s_nop 1
	v_cndmask_b32_e64 v64, v64, v66, s[0:1]
	v_cndmask_b32_e32 v66, 0, v211, vcc
	v_sub_f32_e32 v98, v64, v66
	v_mul_f32_e32 v66, 0x3e000000, v44
	v_max_f32_e32 v64, 0, v66
	v_mul_f32_e64 v66, |v66|, s17
	v_exp_f32_e32 v66, v66
	s_nop 0
	v_add_f32_e32 v66, 1.0, v66
	v_cmp_gt_f32_e32 vcc, s21, v66
	s_nop 1
	v_cndmask_b32_e64 v68, 0, 32, vcc
	v_ldexp_f32 v66, v66, v68
	v_log_f32_e32 v66, v66
	s_nop 0
	v_mul_f32_e32 v68, 0x3f317217, v66
	v_fma_f32 v68, v66, s30, -v68
	v_fmac_f32_e32 v68, 0x3377d1cf, v66
	v_fmac_f32_e32 v68, 0x3f317217, v66
	v_cmp_lt_f32_e64 s[0:1], |v66|, s19
	s_nop 1
	v_cndmask_b32_e64 v66, v66, v68, s[0:1]
	v_cndmask_b32_e32 v68, 0, v211, vcc
	v_sub_f32_e32 v66, v66, v68
	v_max_f32_e32 v68, 0, v70
	v_mul_f32_e64 v70, |v70|, s17
	v_exp_f32_e32 v70, v70
	s_nop 0
	v_add_f32_e32 v70, 1.0, v70
	v_cmp_gt_f32_e32 vcc, s21, v70
	s_nop 1
	v_cndmask_b32_e64 v76, 0, 32, vcc
	v_ldexp_f32 v70, v70, v76
	v_log_f32_e32 v70, v70
	s_nop 0
	v_mul_f32_e32 v76, 0x3f317217, v70
	v_fma_f32 v76, v70, s30, -v76
	v_fmac_f32_e32 v76, 0x3377d1cf, v70
	v_fmac_f32_e32 v76, 0x3f317217, v70
	v_cmp_lt_f32_e64 s[0:1], |v70|, s19
	s_nop 1
	v_cndmask_b32_e64 v70, v70, v76, s[0:1]
	v_cndmask_b32_e32 v76, 0, v211, vcc
	v_sub_f32_e32 v70, v70, v76
	v_max_f32_e32 v76, 0, v78
	v_mul_f32_e64 v78, |v78|, s17
	v_exp_f32_e32 v78, v78
	v_pk_add_f32 v[68:69], v[68:69], v[70:71]
	v_add_f32_e32 v78, 1.0, v78
	v_cmp_gt_f32_e32 vcc, s21, v78
	s_nop 1
	v_cndmask_b32_e64 v80, 0, 32, vcc
	v_ldexp_f32 v78, v78, v80
	v_log_f32_e32 v78, v78
	s_nop 0
	v_mul_f32_e32 v80, 0x3f317217, v78
	v_fma_f32 v80, v78, s30, -v80
	v_fmac_f32_e32 v80, 0x3377d1cf, v78
	v_fmac_f32_e32 v80, 0x3f317217, v78
	v_cmp_lt_f32_e64 s[0:1], |v78|, s19
	s_nop 1
	v_cndmask_b32_e64 v78, v78, v80, s[0:1]
	v_cndmask_b32_e32 v80, 0, v211, vcc
	v_sub_f32_e32 v78, v78, v80
	v_max_f32_e32 v80, 0, v82
	v_mul_f32_e64 v82, |v82|, s17
	v_exp_f32_e32 v82, v82
	s_nop 0
	v_add_f32_e32 v82, 1.0, v82
	v_cmp_gt_f32_e32 vcc, s21, v82
	s_nop 1
	v_cndmask_b32_e64 v107, 0, 32, vcc
	v_ldexp_f32 v82, v82, v107
	v_log_f32_e32 v82, v82
	s_nop 0
	v_mul_f32_e32 v107, 0x3f317217, v82
	v_fma_f32 v107, v82, s30, -v107
	v_fmac_f32_e32 v107, 0x3377d1cf, v82
	v_fmac_f32_e32 v107, 0x3f317217, v82
	v_cmp_lt_f32_e64 s[0:1], |v82|, s19
	s_nop 1
	v_cndmask_b32_e64 v82, v82, v107, s[0:1]
	v_cndmask_b32_e32 v107, 0, v211, vcc
	v_sub_f32_e32 v82, v82, v107
	v_add_u32_e32 v107, s34, v100
	v_or_b32_e32 v70, 26, v107
	v_or_b32_e32 v109, 25, v107
	v_cmp_lt_i32_e64 s[60:61], v70, v72
	v_pk_add_f32 v[70:71], v[76:77], v[78:79]
	v_cmp_lt_i32_e64 s[58:59], v109, v72
	v_fma_f32 v109, v33, s20, -v69
	v_or_b32_e32 v33, 2, v107
	v_fma_f32 v111, v34, s20, -v71
	v_or_b32_e32 v34, 27, v107
	v_cmp_lt_i32_e64 s[44:45], v33, v73
	v_or_b32_e32 v33, 3, v107
	v_cmp_lt_i32_e64 s[62:63], v34, v72
	v_pk_add_f32 v[76:77], v[80:81], v[82:83]
	v_or_b32_e32 v34, 16, v107
	v_cmp_lt_i32_e64 s[50:51], v33, v73
	v_fma_f32 v82, v35, s20, -v77
	v_or_b32_e32 v33, 8, v107
	v_cmp_lt_i32_e32 vcc, v34, v72
	v_pk_add_f32 v[34:35], v[84:85], v[86:87]
	v_or_b32_e32 v78, 17, v107
	v_cmp_lt_i32_e64 s[48:49], v33, v73
	v_fma_f32 v33, v36, s20, -v35
	v_or_b32_e32 v36, 9, v107
	v_cmp_lt_i32_e64 s[0:1], v78, v72
	v_pk_add_f32 v[78:79], v[88:89], v[90:91]
	v_cmp_lt_i32_e64 s[52:53], v36, v73
; DI void sb_unit(const Params& P, LAS char* lds, int b, int hd, int qb, int wave, int lane) {
;     ...
;         for (int i = 0; i < 16; ++i) { const int kidx = kbase + (i & 3) + 8 * (i >> 2) + 4 * h; const bool ok = kidx < qpos; vm |= ok ? (1u << i) : 0u;
;             const float z = s[i] * 0.125f; const float sp = fmaxf(z, 0.f) + __logf(1.0f + __expf(-fabsf(z)));
;             l1m[i] = ok ? -sp : 0.f; ls[i] = z - sp; }
;         float G[4], Gp[4], tot[4];
; #pragma unroll
;         for (int g = 0; g < 4; ++g) { G[g] = (l1m[4 * g] + l1m[4 * g + 1]) + (l1m[4 * g + 2] + l1m[4 * g + 3]); Gp[g] = shx32(G[g], lane); tot[g] = G[g] + Gp[g]; }
;         float aft[4];
;         aft[3] = (h == 0) ? Gp[3] : 0.f;
;         aft[2] = tot[3] + ((h == 0) ? Gp[2] : 0.f);
;         aft[1] = tot[3] + tot[2] + ((h == 0) ? Gp[1] : 0.f);
;         aft[0] = tot[3] + tot[2] + tot[1] + ((h == 0) ? Gp[0] : 0.f);
;         float p[16];
; #pragma unroll
;         for (int g = 0; g < 4; ++g) {
;             const float base = carry + aft[g];
;             const float w3 = 0.f, w2 = l1m[4 * g + 3], w1 = w2 + l1m[4 * g + 2], w0 = w1 + l1m[4 * g + 1];
;             p[4 * g + 0] = ((vm >> (4 * g + 0)) & 1u) ? __expf(ls[4 * g + 0] + base + w0) : 0.f;
;             p[4 * g + 1] = ((vm >> (4 * g + 1)) & 1u) ? __expf(ls[4 * g + 1] + base + w1) : 0.f;
;             p[4 * g + 2] = ((vm >> (4 * g + 2)) & 1u) ? __expf(ls[4 * g + 2] + base + w2) : 0.f;
;             p[4 * g + 3] = ((vm >> (4 * g + 3)) & 1u) ? __expf(ls[4 * g + 3] + base + w3) : 0.f;
;         }
	v_fma_f32 v85, v37, s20, -v79
	v_or_b32_e32 v36, 10, v107
	v_or_b32_e32 v37, 18, v107
	v_cmp_lt_i32_e64 s[38:39], v37, v72
	v_cmp_lt_i32_e64 s[54:55], v36, v73
	v_pk_add_f32 v[36:37], v[92:93], v[94:95]
	v_or_b32_e32 v80, 19, v107
	v_fma_f32 v87, v38, s20, -v37
	v_or_b32_e32 v38, 11, v107
	v_cmp_lt_i32_e64 s[40:41], v80, v72
	v_cmp_lt_i32_e64 s[56:57], v38, v73
	v_pk_add_f32 v[80:81], v[96:97], v[98:99]
	v_or_b32_e32 v108, 1, v107
	v_fma_f32 v89, v39, s20, -v81
	v_cndmask_b32_e64 v39, 0, -v35, s[48:49]
	v_cndmask_b32_e64 v38, 0, -v34, vcc
	v_fma_f32 v91, v40, s20, -v34
	v_cndmask_b32_e64 v35, 0, -v79, s[52:53]
	v_cndmask_b32_e64 v34, 0, -v78, s[0:1]
	v_fma_f32 v78, v41, s20, -v78
	v_cndmask_b32_e64 v41, 0, -v37, s[54:55]
	v_cndmask_b32_e64 v40, 0, -v36, s[38:39]
	v_fma_f32 v93, v42, s20, -v36
	v_cndmask_b32_e64 v37, 0, -v81, s[56:57]
	v_cndmask_b32_e64 v36, 0, -v80, s[40:41]
	v_add_u32_e32 v42, 24, v107
	v_cmp_lt_i32_e64 s[42:43], v108, v73
	v_fma_f32 v80, v43, s20, -v80
	v_cmp_lt_i32_e64 s[64:65], v107, v73
	v_cmp_lt_i32_e64 s[66:67], v42, v72
	v_pk_add_f32 v[42:43], v[64:65], v[66:67]
	v_pk_add_f32 v[38:39], v[38:39], v[34:35]
	v_pk_add_f32 v[40:41], v[40:41], v[36:37]
	v_cndmask_b32_e64 v65, 0, -v43, s[64:65]
	v_cndmask_b32_e64 v64, 0, -v42, s[66:67]
	v_fma_f32 v95, v44, s20, -v42
	v_cndmask_b32_e64 v67, 0, -v69, s[42:43]
	v_cndmask_b32_e64 v66, 0, -v68, s[58:59]
	v_fma_f32 v96, v45, s20, -v68
	v_cndmask_b32_e64 v45, 0, -v71, s[44:45]
	v_cndmask_b32_e64 v44, 0, -v70, s[60:61]
	v_cndmask_b32_e64 v69, 0, -v77, s[50:51]
	v_cndmask_b32_e64 v68, 0, -v76, s[62:63]
	v_pk_add_f32 v[38:39], v[38:39], v[40:41]
	v_fma_f32 v98, v46, s20, -v70
	v_fma_f32 v76, v47, s20, -v76
	v_pk_add_f32 v[46:47], v[64:65], v[66:67]
	v_pk_add_f32 v[44:45], v[44:45], v[68:69]
	v_mov_b32_e32 v64, v39
	v_mov_b32_e32 v65, v39
	v_mov_b32_e32 v77, v38
	v_mov_b32_e32 v107, v38
	v_pk_add_f32 v[46:47], v[46:47], v[44:45]
	v_permlane32_swap_b32_e32 v64, v65
	v_permlane32_swap_b32_e32 v77, v107
	v_mov_b32_e32 v70, v47
	v_mov_b32_e32 v71, v47
	v_cndmask_b32_e64 v65, v64, v65, s[36:37]
	v_cndmask_b32_e64 v64, v77, v107, s[36:37]
	v_mov_b32_e32 v77, v46
	v_mov_b32_e32 v107, v46
	v_cndmask_b32_e64 v84, 0, 32, s[52:53]
	v_cndmask_b32_e64 v79, 0, v199, s[38:39]
	v_cndmask_b32_e64 v94, 0, v200, s[40:41]
	v_permlane32_swap_b32_e32 v70, v71
	v_permlane32_swap_b32_e32 v77, v107
	v_cndmask_b32_e64 v112, 0, 8, s[50:51]
	v_cndmask_b32_e64 v83, 0, 16, s[48:49]
	v_cndmask_b32_e64 v71, v70, v71, s[36:37]
	v_cndmask_b32_e64 v70, v77, v107, s[36:37]
	v_or3_b32 v77, v84, v79, v94
	v_cndmask_b32_e64 v110, 0, 4, s[44:45]
	v_cndmask_b32_e64 v86, 0, 64, s[54:55]
	v_or3_b32 v77, v83, v112, v77
	v_cndmask_b32_e64 v108, 0, 2, s[42:43]
	v_cndmask_b32_e64 v88, 0, v196, s[56:57]
	v_or3_b32 v77, v110, v86, v77
	v_cndmask_b32_e32 v90, 0, v197, vcc
	v_cndmask_b32_e64 v92, 0, v198, s[0:1]
	v_or3_b32 v77, v108, v88, v77
	v_cndmask_b32_e64 v81, 0, v201, s[66:67]
	v_cndmask_b32_e64 v42, 0, v202, s[58:59]
	v_or3_b32 v77, v90, v92, v77
	v_pk_add_f32 v[38:39], v[38:39], v[64:65]
	v_pk_add_f32 v[46:47], v[46:47], v[70:71]
	v_or3_b32 v77, v81, v42, v77
	v_cndmask_b32_e64 v42, 0, v64, s[36:37]
	v_add_f32_e32 v64, v42, v46
	v_pk_add_f32 v[46:47], v[38:39], v[46:47]
	v_cndmask_b32_e64 v42, 0, v65, s[36:37]
	v_add_f32_e32 v38, v39, v46
	v_cndmask_b32_e64 v39, 0, v71, s[36:37]
	v_add_f32_e32 v38, v39, v38
	v_add_f32_e32 v65, v42, v46
	v_add_f32_e32 v39, v102, v38
	v_fma_f32 v43, v32, s20, -v43
	v_mov_b32_e32 v42, v67
	v_mov_b32_e32 v38, v45
	v_pk_add_f32 v[42:43], v[42:43], v[38:39]
	v_mov_b32_e32 v38, v41
	v_add_f32_e32 v32, v42, v43
	v_mul_f32_e32 v32, 0x3fb8aa3b, v32
	v_exp_f32_e32 v32, v32
	v_cndmask_b32_e64 v70, 0, v70, s[36:37]
	v_mov_b32_e32 v67, v95
	v_cndmask_b32_e64 v97, 0, v203, s[60:61]
	v_cndmask_b32_e64 v42, 0, v32, s[64:65]
	v_add_f32_e32 v32, v109, v39
	v_add_f32_e32 v32, v45, v32
	v_mul_f32_e32 v32, 0x3fb8aa3b, v32
	v_exp_f32_e32 v32, v32
	v_add_f32_e32 v45, v102, v70
	v_cndmask_b32_e64 v99, 0, v204, s[62:63]
	v_or3_b32 v79, v97, v99, v77
	v_cndmask_b32_e64 v43, 0, v32, s[42:43]
	v_add_f32_e32 v32, v111, v39
	v_add_f32_e32 v32, v69, v32
	v_mul_f32_e32 v32, 0x3fb8aa3b, v32
; __device__ __forceinline__ int fresh_lane() { int l; asm volatile("v_mbcnt_lo_u32_b32 %0, -1, 0\n\tv_mbcnt_hi_u32_b32 %0, -1, %0" : "=v"(l)); return l; }
; __device__ __forceinline__ void xcd_barrier(const XcdBarrier& b, const int wave_s) {
;     asm volatile("s_waitcnt vmcnt(0)" ::: "memory");
;     __syncthreads();
;     if (wave_s == 0 && fresh_lane() == 0) {
;         unsigned* bar = b.bar;
;         __builtin_amdgcn_s_waitcnt(0);
;         unsigned nloc = b.st[0], nx = b.st[1];
;         if (nloc == 0u) { xcd_barrier_complete(bar, b.x, nloc, nx); b.st[0] = nloc; b.st[1] = nx; }
; DI void sb_unit(const Params& P, LAS char* lds, int b, int hd, int qb, int wave, int lane) {
;     ...
;         for (int g = 0; g < 4; ++g) {
;             const float base = carry + aft[g];
;             const float w3 = 0.f, w2 = l1m[4 * g + 3], w1 = w2 + l1m[4 * g + 2], w0 = w1 + l1m[4 * g + 1];
;             p[4 * g + 0] = ((vm >> (4 * g + 0)) & 1u) ? __expf(ls[4 * g + 0] + base + w0) : 0.f;
;             p[4 * g + 1] = ((vm >> (4 * g + 1)) & 1u) ? __expf(ls[4 * g + 1] + base + w1) : 0.f;
;             p[4 * g + 2] = ((vm >> (4 * g + 2)) & 1u) ? __expf(ls[4 * g + 2] + base + w2) : 0.f;
;             p[4 * g + 3] = ((vm >> (4 * g + 3)) & 1u) ? __expf(ls[4 * g + 3] + base + w3) : 0.f;
;         }
;         carry += (tot[0] + tot[1]) + (tot[2] + tot[3]);
;         bf16x8 pf[2]; pack_p(p, pf);
;         pv_rows(o, Vl, 0, pf, lane);
;         asm volatile("" ::: "memory");
;         if (__builtin_amdgcn_ballot_w64(carry >= -120.0f) == 0ull) break;
	v_exp_f32_e32 v32, v32
	s_nop 0
	v_cndmask_b32_e64 v69, 0, v32, s[44:45]
	v_add_f32_e32 v32, v82, v39
	v_add_f32_e32 v32, 0, v32
	v_mul_f32_e32 v32, 0x3fb8aa3b, v32
	v_exp_f32_e32 v32, v32
	v_add_f32_e32 v39, v102, v65
	v_cndmask_b32_e64 v71, 0, v32, s[50:51]
	v_mov_b32_e32 v32, v35
	v_pk_add_f32 v[32:33], v[32:33], v[38:39]
	v_mov_b32_e32 v35, v91
	v_add_f32_e32 v32, v32, v33
	v_mul_f32_e32 v32, 0x3fb8aa3b, v32
	v_exp_f32_e32 v32, v32
	s_nop 0
	v_cndmask_b32_e64 v38, 0, v32, s[48:49]
	v_add_f32_e32 v32, v85, v39
	v_add_f32_e32 v32, v41, v32
	v_mul_f32_e32 v32, 0x3fb8aa3b, v32
	v_exp_f32_e32 v32, v32
	v_add_f32_e32 v41, v102, v64
	v_cndmask_b32_e64 v65, 0, v32, s[52:53]
	v_add_f32_e32 v32, v87, v39
	v_add_f32_e32 v32, v37, v32
	v_mul_f32_e32 v32, 0x3fb8aa3b, v32
	v_exp_f32_e32 v32, v32
	v_cvt_pk_bf16_f32 v37, v69, v71
	v_cvt_pk_bf16_f32 v38, v38, v65
	v_cndmask_b32_e64 v81, 0, v32, s[54:55]
	v_add_f32_e32 v32, v89, v39
	v_add_f32_e32 v32, 0, v32
	v_mul_f32_e32 v32, 0x3fb8aa3b, v32
	v_exp_f32_e32 v32, v32
	s_nop 0
	v_cndmask_b32_e64 v39, 0, v32, s[56:57]
	v_pk_add_f32 v[32:33], v[34:35], v[40:41]
	v_cvt_pk_bf16_f32 v39, v81, v39
	v_add_f32_e32 v32, v32, v33
	v_mul_f32_e32 v32, 0x3fb8aa3b, v32
	v_exp_f32_e32 v32, v32
	s_nop 0
	v_cndmask_b32_e32 v34, 0, v32, vcc
	v_add_f32_e32 v32, v78, v41
	v_add_f32_e32 v32, v40, v32
	v_mul_f32_e32 v32, 0x3fb8aa3b, v32
	v_exp_f32_e32 v32, v32
	s_nop 0
	v_cndmask_b32_e64 v35, 0, v32, s[0:1]
	v_add_f32_e32 v32, v93, v41
	v_add_f32_e32 v32, v36, v32
	v_mul_f32_e32 v32, 0x3fb8aa3b, v32
	v_exp_f32_e32 v32, v32
	v_cvt_pk_bf16_f32 v36, v42, v43
	v_cndmask_b32_e64 v40, 0, v32, s[38:39]
	v_add_f32_e32 v32, v80, v41
	v_add_f32_e32 v32, 0, v32
	v_mul_f32_e32 v32, 0x3fb8aa3b, v32
	v_exp_f32_e32 v32, v32
	s_nop 0
	v_cndmask_b32_e64 v41, 0, v32, s[40:41]
	v_pk_add_f32 v[32:33], v[66:67], v[44:45]
	s_nop 0
	v_add_f32_e32 v32, v32, v33
	v_mul_f32_e32 v32, 0x3fb8aa3b, v32
	v_exp_f32_e32 v32, v32
	v_and_b32_e32 v33, 0x1000, v77
	v_cmp_ne_u32_e32 vcc, 0, v33
	v_and_b32_e32 v33, 0x2000, v77
	s_nop 0
	v_cndmask_b32_e32 v64, 0, v32, vcc
	v_add_f32_e32 v32, v96, v45
	v_add_f32_e32 v32, v44, v32
	v_mul_f32_e32 v32, 0x3fb8aa3b, v32
	v_exp_f32_e32 v32, v32
	v_cmp_ne_u32_e32 vcc, 0, v33
	v_and_b32_e32 v33, 0x4000, v79
	s_nop 0
	v_cndmask_b32_e32 v44, 0, v32, vcc
	v_add_f32_e32 v32, v98, v45
	v_add_f32_e32 v32, v68, v32
	v_mul_f32_e32 v32, 0x3fb8aa3b, v32
	v_exp_f32_e32 v32, v32
	v_cmp_ne_u32_e32 vcc, 0, v33
	v_and_b32_e32 v33, 0x8000, v79
	s_nop 0
	v_cndmask_b32_e32 v66, 0, v32, vcc
	v_add_f32_e32 v32, v76, v45
	v_add_f32_e32 v32, 0, v32
	v_mul_f32_e32 v32, 0x3fb8aa3b, v32
	v_exp_f32_e32 v32, v32
	v_cmp_ne_u32_e32 vcc, 0, v33
	v_cvt_pk_bf16_f32 v33, v40, v41
	s_nop 0
	v_cndmask_b32_e32 v45, 0, v32, vcc
	v_add_f32_e32 v32, v46, v47
	v_add_f32_e32 v102, v102, v32
	v_cvt_pk_bf16_f32 v32, v34, v35
	v_cvt_pk_bf16_f32 v34, v64, v44
	v_cvt_pk_bf16_f32 v35, v66, v45
	s_nop 0
	s_waitcnt lgkmcnt(0)
	v_mfma_f32_32x32x16_bf16 v[16:31], v[116:119], v[36:39], v[16:31]
	v_mfma_f32_32x32x16_bf16 v[0:15], v[120:123], v[36:39], v[0:15]
	v_mfma_f32_32x32x16_bf16 v[16:31], v[124:127], v[32:35], v[16:31]
	v_mfma_f32_32x32x16_bf16 v[0:15], v[160:163], v[32:35], v[0:15]
	s_nop 0
	s_mov_b32 s0, 0xc2f00000
	v_cmp_le_f32_e32 vcc, s0, v102
	s_cmp_lg_u64 vcc, 0
	s_cselect_b64 s[0:1], -1, 0
	v_add_co_u32_e32 v103, vcc, -1, v103
	s_and_b64 s[0:1], vcc, s[0:1]
	s_sub_i32 s34, s34, 32
	s_and_b64 vcc, exec, s[0:1]
	s_cbranch_vccnz .LBB0_940
	v_mov_b32_e32 v168, v100
	s_branch .LBB0_933
.LBB0_942:
	s_setprio 0
	s_waitcnt vmcnt(0)
	v_readlane_b32 s0, v255, 21
	v_readlane_b32 s1, v255, 22
	s_and_b64 vcc, exec, s[0:1]
	s_waitcnt lgkmcnt(0)
	s_barrier
	s_cbranch_vccnz .LBB0_996
	v_mbcnt_lo_u32_b32 v0, -1, 0
	v_mbcnt_hi_u32_b32 v0, -1, v0
	s_nop 0
	v_cmp_eq_u32_e32 vcc, 0, v0
	s_and_saveexec_b64 s[0:1], vcc
	s_cbranch_execz .LBB0_995
	v_readlane_b32 s10, v254, 52
	s_waitcnt vmcnt(0) expcnt(0) lgkmcnt(0)
	s_nop 0
	v_mov_b32_e32 v0, s10
	ds_read_b32 v2, v0
	v_readlane_b32 s10, v254, 53
	s_waitcnt lgkmcnt(0)
	v_cmp_ne_u32_e32 vcc, 0, v2
	v_mov_b32_e32 v0, s10
	ds_read_b32 v0, v0
	s_cbranch_vccnz .LBB0_959
	s_mov_b32 s10, 1
	s_branch .LBB0_947
